# plus: trailing-half restore barrier moved before K-loop, first K iteration peeled with srcC=0 (no acc zeroing), MFMA-block transitions trimmed (setprio/waitcnt placement)
# speedup vs baseline: 1.0107x; 1.0107x over previous
.LBB0_197:
	ds_read_b128 v[146:149], v161
	ds_read_b128 v[150:153], v161 offset:1024
	ds_read_b128 v[154:157], v161 offset:2048
	ds_read_b128 v[166:169], v161 offset:3072
	ds_read_b128 v[170:173], v162
	ds_read_b128 v[174:177], v162 offset:1024
	ds_read_b128 v[178:181], v162 offset:2048
	ds_read_b128 v[182:185], v162 offset:3072
	s_add_u32 s38, s36, 0xfffc0080
	s_addc_u32 s39, s37, -1
	s_cmp_eq_u32 s62, 12
	s_cselect_b32 s41, s17, s39
	s_cselect_b32 s40, s23, s38
	s_cselect_b32 s39, s15, s61
	s_cselect_b32 s38, s59, s60
	v_lshl_add_u64 v[218:219], s[36:37], 0, v[138:139]
	s_add_i32 m0, s45, 0xc000
	ds_read_b128 v[186:189], v163
	ds_read_b128 v[190:193], v163 offset:1024
	ds_read_b128 v[194:197], v163 offset:2048
	ds_read_b128 v[198:201], v163 offset:3072
	ds_read_b128 v[202:205], v163 offset:4096
	ds_read_b128 v[206:209], v163 offset:5120
	ds_read_b128 v[210:213], v163 offset:6144
	ds_read_b128 v[214:217], v163 offset:7168
	global_load_lds_dwordx4 v[218:219], off
	v_lshl_add_u64 v[218:219], s[36:37], 0, v[140:141]
	s_add_i32 m0, s45, 0xe000
	s_nop 0
	global_load_lds_dwordx4 v[218:219], off
	s_waitcnt vmcnt(8)
	s_waitcnt lgkmcnt(0)
	s_setprio 1
	s_barrier
	v_mfma_f32_16x16x32_bf16 v[124:127], v[146:149], v[186:189], v[124:127]
	v_mfma_f32_16x16x32_bf16 v[120:123], v[154:157], v[186:189], v[120:123]
	v_mfma_f32_16x16x32_bf16 v[116:119], v[146:149], v[194:197], v[116:119]
	v_mfma_f32_16x16x32_bf16 v[112:115], v[154:157], v[194:197], v[112:115]
	v_mfma_f32_16x16x32_bf16 v[92:95], v[146:149], v[202:205], v[92:95]
	v_mfma_f32_16x16x32_bf16 v[88:91], v[154:157], v[202:205], v[88:91]
	v_mfma_f32_16x16x32_bf16 v[76:79], v[146:149], v[210:213], v[76:79]
	v_mfma_f32_16x16x32_bf16 v[72:75], v[154:157], v[210:213], v[72:75]
	v_mfma_f32_16x16x32_bf16 v[124:127], v[150:153], v[190:193], v[124:127]
	v_mfma_f32_16x16x32_bf16 v[120:123], v[166:169], v[190:193], v[120:123]
	v_mfma_f32_16x16x32_bf16 v[116:119], v[150:153], v[198:201], v[116:119]
	v_mfma_f32_16x16x32_bf16 v[112:115], v[166:169], v[198:201], v[112:115]
	v_mfma_f32_16x16x32_bf16 v[92:95], v[150:153], v[206:209], v[92:95]
	v_mfma_f32_16x16x32_bf16 v[88:91], v[166:169], v[206:209], v[88:91]
	v_mfma_f32_16x16x32_bf16 v[76:79], v[150:153], v[214:217], v[76:79]
	v_mfma_f32_16x16x32_bf16 v[72:75], v[166:169], v[214:217], v[72:75]
	v_mfma_f32_16x16x32_bf16 v[108:111], v[170:173], v[186:189], v[108:111]
	v_mfma_f32_16x16x32_bf16 v[104:107], v[178:181], v[186:189], v[104:107]
	v_mfma_f32_16x16x32_bf16 v[100:103], v[170:173], v[194:197], v[100:103]
	v_mfma_f32_16x16x32_bf16 v[96:99], v[178:181], v[194:197], v[96:99]
	v_mfma_f32_16x16x32_bf16 v[84:87], v[170:173], v[202:205], v[84:87]
	v_mfma_f32_16x16x32_bf16 v[80:83], v[178:181], v[202:205], v[80:83]
	v_mfma_f32_16x16x32_bf16 v[68:71], v[170:173], v[210:213], v[68:71]
	v_mfma_f32_16x16x32_bf16 v[64:67], v[178:181], v[210:213], v[64:67]
	v_mfma_f32_16x16x32_bf16 v[108:111], v[174:177], v[190:193], v[108:111]
	v_mfma_f32_16x16x32_bf16 v[104:107], v[182:185], v[190:193], v[104:107]
	v_mfma_f32_16x16x32_bf16 v[100:103], v[174:177], v[198:201], v[100:103]
	v_mfma_f32_16x16x32_bf16 v[96:99], v[182:185], v[198:201], v[96:99]
	v_mfma_f32_16x16x32_bf16 v[84:87], v[174:177], v[206:209], v[84:87]
	v_mfma_f32_16x16x32_bf16 v[80:83], v[182:185], v[206:209], v[80:83]
	v_mfma_f32_16x16x32_bf16 v[68:71], v[174:177], v[214:217], v[68:71]
	v_mfma_f32_16x16x32_bf16 v[64:67], v[182:185], v[214:217], v[64:67]
	s_barrier
	s_setprio 0
	s_add_i32 s63, s56, s44
	v_lshl_add_u64 v[218:219], s[38:39], 0, v[130:131]
	s_mov_b32 m0, s63
	ds_read_b128 v[186:189], v163 offset:16384
	ds_read_b128 v[190:193], v163 offset:17408
	ds_read_b128 v[194:197], v163 offset:18432
	ds_read_b128 v[198:201], v163 offset:19456
	ds_read_b128 v[202:205], v163 offset:20480
	ds_read_b128 v[206:209], v163 offset:21504
	ds_read_b128 v[210:213], v163 offset:22528
	ds_read_b128 v[214:217], v163 offset:23552
	global_load_lds_dwordx4 v[218:219], off
	s_add_i32 m0, s63, 0x2000
	s_add_u32 s64, s38, 0x40000
	v_lshl_add_u64 v[220:221], s[38:39], 0, v[134:135]
	s_addc_u32 s65, s39, 0
	s_add_i32 s63, s57, s44
	global_load_lds_dwordx4 v[220:221], off
	v_lshl_add_u64 v[222:223], s[64:65], 0, v[130:131]
	s_mov_b32 m0, s63
	v_lshl_add_u64 v[224:225], s[40:41], 0, v[132:133]
	global_load_lds_dwordx4 v[222:223], off
	v_lshl_add_u64 v[222:223], s[64:65], 0, v[134:135]
	s_add_i32 m0, s63, 0x2000
	s_nop 0
	global_load_lds_dwordx4 v[222:223], off
	v_lshl_add_u64 v[222:223], s[40:41], 0, v[128:129]
	s_mov_b32 m0, s45
	s_nop 0
	global_load_lds_dwordx4 v[222:223], off
	s_mov_b32 m0, s46
	s_nop 0
	global_load_lds_dwordx4 v[224:225], off
	s_waitcnt vmcnt(8)
	s_waitcnt lgkmcnt(0)
	s_setprio 1
	s_barrier
	v_mfma_f32_16x16x32_bf16 v[60:63], v[146:149], v[186:189], v[60:63]
	v_mfma_f32_16x16x32_bf16 v[56:59], v[154:157], v[186:189], v[56:59]
	v_mfma_f32_16x16x32_bf16 v[44:47], v[146:149], v[194:197], v[44:47]
	v_mfma_f32_16x16x32_bf16 v[40:43], v[154:157], v[194:197], v[40:43]
	v_mfma_f32_16x16x32_bf16 v[28:31], v[146:149], v[202:205], v[28:31]
	v_mfma_f32_16x16x32_bf16 v[24:27], v[154:157], v[202:205], v[24:27]
	v_mfma_f32_16x16x32_bf16 v[12:15], v[146:149], v[210:213], v[12:15]
	v_mfma_f32_16x16x32_bf16 v[8:11], v[154:157], v[210:213], v[8:11]
	v_mfma_f32_16x16x32_bf16 v[60:63], v[150:153], v[190:193], v[60:63]
	v_mfma_f32_16x16x32_bf16 v[56:59], v[166:169], v[190:193], v[56:59]
	v_mfma_f32_16x16x32_bf16 v[44:47], v[150:153], v[198:201], v[44:47]
	v_mfma_f32_16x16x32_bf16 v[40:43], v[166:169], v[198:201], v[40:43]
	v_mfma_f32_16x16x32_bf16 v[28:31], v[150:153], v[206:209], v[28:31]
	v_mfma_f32_16x16x32_bf16 v[24:27], v[166:169], v[206:209], v[24:27]
	v_mfma_f32_16x16x32_bf16 v[12:15], v[150:153], v[214:217], v[12:15]
	v_mfma_f32_16x16x32_bf16 v[8:11], v[166:169], v[214:217], v[8:11]
	v_mfma_f32_16x16x32_bf16 v[52:55], v[170:173], v[186:189], v[52:55]
	v_mfma_f32_16x16x32_bf16 v[48:51], v[178:181], v[186:189], v[48:51]
	v_mfma_f32_16x16x32_bf16 v[36:39], v[170:173], v[194:197], v[36:39]
	v_mfma_f32_16x16x32_bf16 v[32:35], v[178:181], v[194:197], v[32:35]
	v_mfma_f32_16x16x32_bf16 v[20:23], v[170:173], v[202:205], v[20:23]
	v_mfma_f32_16x16x32_bf16 v[16:19], v[178:181], v[202:205], v[16:19]
	v_mfma_f32_16x16x32_bf16 v[4:7], v[170:173], v[210:213], v[4:7]
	v_mfma_f32_16x16x32_bf16 v[0:3], v[178:181], v[210:213], v[0:3]
	v_mfma_f32_16x16x32_bf16 v[52:55], v[174:177], v[190:193], v[52:55]
	v_mfma_f32_16x16x32_bf16 v[48:51], v[182:185], v[190:193], v[48:51]
	v_mfma_f32_16x16x32_bf16 v[36:39], v[174:177], v[198:201], v[36:39]
	v_mfma_f32_16x16x32_bf16 v[32:35], v[182:185], v[198:201], v[32:35]
	v_mfma_f32_16x16x32_bf16 v[20:23], v[174:177], v[206:209], v[20:23]
	v_mfma_f32_16x16x32_bf16 v[16:19], v[182:185], v[206:209], v[16:19]
	v_mfma_f32_16x16x32_bf16 v[4:7], v[174:177], v[214:217], v[4:7]
	v_mfma_f32_16x16x32_bf16 v[0:3], v[182:185], v[214:217], v[0:3]
	s_barrier
	s_setprio 0
	s_add_i32 s63, 0, 0x18000
	v_add_u32_e32 v136, s63, v160
	s_add_i32 s64, 0, 0x1c000
	ds_read_b128 v[146:149], v136
	ds_read_b128 v[150:153], v136 offset:1024
	ds_read_b128 v[154:157], v136 offset:2048
	ds_read_b128 v[166:169], v136 offset:3072
	v_add_u32_e32 v136, s64, v160
	ds_read_b128 v[170:173], v136
	ds_read_b128 v[174:177], v136 offset:1024
	ds_read_b128 v[178:181], v136 offset:2048
	ds_read_b128 v[182:185], v136 offset:3072
	s_add_u32 s40, s40, 0x40000
	s_addc_u32 s41, s41, 0
	s_mov_b32 m0, s47
	v_lshl_add_u64 v[226:227], s[40:41], 0, v[128:129]
	ds_read_b128 v[186:189], v163 offset:32768
	ds_read_b128 v[190:193], v163 offset:33792
	ds_read_b128 v[194:197], v163 offset:34816
	ds_read_b128 v[198:201], v163 offset:35840
	ds_read_b128 v[202:205], v163 offset:36864
	ds_read_b128 v[206:209], v163 offset:37888
	ds_read_b128 v[210:213], v163 offset:38912
	ds_read_b128 v[214:217], v163 offset:39936
	global_load_lds_dwordx4 v[226:227], off
	v_lshl_add_u64 v[226:227], s[40:41], 0, v[132:133]
	s_mov_b32 m0, s48
	s_nop 0
	global_load_lds_dwordx4 v[226:227], off
	s_waitcnt vmcnt(8)
	s_waitcnt lgkmcnt(0)
	s_setprio 1
	s_barrier
	v_mfma_f32_16x16x32_bf16 v[124:127], v[146:149], v[186:189], v[124:127]
	v_mfma_f32_16x16x32_bf16 v[120:123], v[154:157], v[186:189], v[120:123]
	v_mfma_f32_16x16x32_bf16 v[116:119], v[146:149], v[194:197], v[116:119]
	v_mfma_f32_16x16x32_bf16 v[112:115], v[154:157], v[194:197], v[112:115]
	v_mfma_f32_16x16x32_bf16 v[92:95], v[146:149], v[202:205], v[92:95]
	v_mfma_f32_16x16x32_bf16 v[88:91], v[154:157], v[202:205], v[88:91]
	v_mfma_f32_16x16x32_bf16 v[76:79], v[146:149], v[210:213], v[76:79]
	v_mfma_f32_16x16x32_bf16 v[72:75], v[154:157], v[210:213], v[72:75]
	v_mfma_f32_16x16x32_bf16 v[124:127], v[150:153], v[190:193], v[124:127]
	v_mfma_f32_16x16x32_bf16 v[120:123], v[166:169], v[190:193], v[120:123]
	v_mfma_f32_16x16x32_bf16 v[116:119], v[150:153], v[198:201], v[116:119]
	v_mfma_f32_16x16x32_bf16 v[112:115], v[166:169], v[198:201], v[112:115]
	v_mfma_f32_16x16x32_bf16 v[92:95], v[150:153], v[206:209], v[92:95]
	v_mfma_f32_16x16x32_bf16 v[88:91], v[166:169], v[206:209], v[88:91]
	v_mfma_f32_16x16x32_bf16 v[76:79], v[150:153], v[214:217], v[76:79]
	v_mfma_f32_16x16x32_bf16 v[72:75], v[166:169], v[214:217], v[72:75]
	v_mfma_f32_16x16x32_bf16 v[108:111], v[170:173], v[186:189], v[108:111]
	v_mfma_f32_16x16x32_bf16 v[104:107], v[178:181], v[186:189], v[104:107]
	v_mfma_f32_16x16x32_bf16 v[100:103], v[170:173], v[194:197], v[100:103]
	v_mfma_f32_16x16x32_bf16 v[96:99], v[178:181], v[194:197], v[96:99]
	v_mfma_f32_16x16x32_bf16 v[84:87], v[170:173], v[202:205], v[84:87]
	v_mfma_f32_16x16x32_bf16 v[80:83], v[178:181], v[202:205], v[80:83]
	v_mfma_f32_16x16x32_bf16 v[68:71], v[170:173], v[210:213], v[68:71]
	v_mfma_f32_16x16x32_bf16 v[64:67], v[178:181], v[210:213], v[64:67]
	v_mfma_f32_16x16x32_bf16 v[108:111], v[174:177], v[190:193], v[108:111]
	v_mfma_f32_16x16x32_bf16 v[104:107], v[182:185], v[190:193], v[104:107]
	v_mfma_f32_16x16x32_bf16 v[100:103], v[174:177], v[198:201], v[100:103]
	v_mfma_f32_16x16x32_bf16 v[96:99], v[182:185], v[198:201], v[96:99]
	v_mfma_f32_16x16x32_bf16 v[84:87], v[174:177], v[206:209], v[84:87]
	v_mfma_f32_16x16x32_bf16 v[80:83], v[182:185], v[206:209], v[80:83]
	v_mfma_f32_16x16x32_bf16 v[68:71], v[174:177], v[214:217], v[68:71]
	v_mfma_f32_16x16x32_bf16 v[64:67], v[182:185], v[214:217], v[64:67]
	s_barrier
	s_setprio 0
	s_add_i32 s40, s63, s44
	v_lshl_add_u64 v[218:219], v[218:219], 0, s[8:9]
	s_mov_b32 m0, s40
	ds_read_b128 v[186:189], v163 offset:49152
	ds_read_b128 v[190:193], v163 offset:50176
	ds_read_b128 v[194:197], v163 offset:51200
	ds_read_b128 v[198:201], v163 offset:52224
	ds_read_b128 v[202:205], v163 offset:53248
	ds_read_b128 v[206:209], v163 offset:54272
	ds_read_b128 v[210:213], v163 offset:55296
	ds_read_b128 v[214:217], v163 offset:56320
	global_load_lds_dwordx4 v[218:219], off
	s_add_i32 m0, s40, 0x2000
	s_add_u32 s38, s38, 0x40080
	v_lshl_add_u64 v[218:219], v[220:221], 0, s[8:9]
	s_addc_u32 s39, s39, 0
	s_add_i32 s40, s64, s44
	global_load_lds_dwordx4 v[218:219], off
	v_lshl_add_u64 v[218:219], s[38:39], 0, v[130:131]
	s_mov_b32 m0, s40
	s_nop 0
	global_load_lds_dwordx4 v[218:219], off
	v_lshl_add_u64 v[218:219], s[38:39], 0, v[134:135]
	s_add_i32 m0, s40, 0x2000
	s_nop 0
	global_load_lds_dwordx4 v[218:219], off
	v_lshl_add_u64 v[218:219], v[222:223], 0, s[8:9]
	s_mov_b32 m0, s54
	s_nop 0
	global_load_lds_dwordx4 v[218:219], off
	v_lshl_add_u64 v[218:219], v[224:225], 0, s[8:9]
	s_mov_b32 m0, s55
	s_nop 0
	global_load_lds_dwordx4 v[218:219], off
	s_waitcnt vmcnt(8)
	s_waitcnt lgkmcnt(0)
	s_setprio 1
	s_barrier
	v_mfma_f32_16x16x32_bf16 v[60:63], v[146:149], v[186:189], v[60:63]
	v_mfma_f32_16x16x32_bf16 v[56:59], v[154:157], v[186:189], v[56:59]
	v_mfma_f32_16x16x32_bf16 v[44:47], v[146:149], v[194:197], v[44:47]
	v_mfma_f32_16x16x32_bf16 v[40:43], v[154:157], v[194:197], v[40:43]
	v_mfma_f32_16x16x32_bf16 v[28:31], v[146:149], v[202:205], v[28:31]
	v_mfma_f32_16x16x32_bf16 v[24:27], v[154:157], v[202:205], v[24:27]
	v_mfma_f32_16x16x32_bf16 v[12:15], v[146:149], v[210:213], v[12:15]
	v_mfma_f32_16x16x32_bf16 v[8:11], v[154:157], v[210:213], v[8:11]
	v_mfma_f32_16x16x32_bf16 v[60:63], v[150:153], v[190:193], v[60:63]
	v_mfma_f32_16x16x32_bf16 v[56:59], v[166:169], v[190:193], v[56:59]
	v_mfma_f32_16x16x32_bf16 v[44:47], v[150:153], v[198:201], v[44:47]
	v_mfma_f32_16x16x32_bf16 v[40:43], v[166:169], v[198:201], v[40:43]
	v_mfma_f32_16x16x32_bf16 v[28:31], v[150:153], v[206:209], v[28:31]
	v_mfma_f32_16x16x32_bf16 v[24:27], v[166:169], v[206:209], v[24:27]
	v_mfma_f32_16x16x32_bf16 v[12:15], v[150:153], v[214:217], v[12:15]
	v_mfma_f32_16x16x32_bf16 v[8:11], v[166:169], v[214:217], v[8:11]
	v_mfma_f32_16x16x32_bf16 v[52:55], v[170:173], v[186:189], v[52:55]
	v_mfma_f32_16x16x32_bf16 v[48:51], v[178:181], v[186:189], v[48:51]
	v_mfma_f32_16x16x32_bf16 v[36:39], v[170:173], v[194:197], v[36:39]
	v_mfma_f32_16x16x32_bf16 v[32:35], v[178:181], v[194:197], v[32:35]
	v_mfma_f32_16x16x32_bf16 v[20:23], v[170:173], v[202:205], v[20:23]
	v_mfma_f32_16x16x32_bf16 v[16:19], v[178:181], v[202:205], v[16:19]
	v_mfma_f32_16x16x32_bf16 v[4:7], v[170:173], v[210:213], v[4:7]
	v_mfma_f32_16x16x32_bf16 v[0:3], v[178:181], v[210:213], v[0:3]
	v_mfma_f32_16x16x32_bf16 v[52:55], v[174:177], v[190:193], v[52:55]
	v_mfma_f32_16x16x32_bf16 v[48:51], v[182:185], v[190:193], v[48:51]
	v_mfma_f32_16x16x32_bf16 v[36:39], v[174:177], v[198:201], v[36:39]
	v_mfma_f32_16x16x32_bf16 v[32:35], v[182:185], v[198:201], v[32:35]
	v_mfma_f32_16x16x32_bf16 v[20:23], v[174:177], v[206:209], v[20:23]
	v_mfma_f32_16x16x32_bf16 v[16:19], v[182:185], v[206:209], v[16:19]
	v_mfma_f32_16x16x32_bf16 v[4:7], v[174:177], v[214:217], v[4:7]
	v_mfma_f32_16x16x32_bf16 v[0:3], v[182:185], v[214:217], v[0:3]
	s_barrier
	s_setprio 0
	s_add_i32 s62, s62, 2
	s_add_u32 s36, s36, 0x100
	s_addc_u32 s37, s37, 0
	s_add_u32 s60, s60, 0x100
	s_addc_u32 s61, s61, 0
	s_cmp_gt_u32 s62, 13
	s_cbranch_scc0 .LBB0_197
	s_and_b64 vcc, exec, s[12:13]
	s_cbranch_vccz .LBB0_200
	s_barrier

.LBB0_223:
	v_mov_b32_e32 v135, v1
	v_lshl_add_u64 v[8:9], s[48:49], 0, v[134:135]
	v_mov_b32_e32 v131, v1
	v_readlane_b32 s46, v251, 11
	v_bfe_u32 v143, v7, 4, 2
	s_lshl_b32 s19, s19, 5
	v_lshl_add_u64 v[10:11], s[48:49], 0, v[130:131]
	v_mov_b32_e32 v137, v1
	v_readlane_b32 s47, v251, 12
	v_and_b32_e32 v142, 15, v7
	v_lshlrev_b32_e32 v16, 4, v143
	v_lshlrev_b32_e32 v7, 2, v7
	s_and_b32 s54, s19, 0x60
	s_add_i32 m0, s5, 0x18000
	v_lshl_add_u64 v[8:9], v[8:9], 0, s[16:17]
	v_lshl_add_u64 v[12:13], s[46:47], 0, v[136:137]
	v_mov_b32_e32 v133, v1
	s_lshl_b32 s53, s20, 6
	v_lshl_or_b32 v16, v142, 6, v16
	s_lshl_b32 s20, s20, 13
	v_and_b32_e32 v7, 32, v7
	s_lshl_b32 s19, s54, 7
	s_waitcnt vmcnt(2)
	s_barrier
	global_load_lds_dwordx4 v[8:9], off
	v_lshl_add_u64 v[8:9], v[10:11], 0, s[16:17]
	s_add_i32 m0, s5, 0x1a000
	s_add_i32 s55, s5, 0x8000
	s_add_i32 s56, s5, 0xa000
	v_lshl_add_u64 v[14:15], s[46:47], 0, v[132:133]
	v_bitop3_b32 v17, v16, s20, v7 bitop3:0xde
	global_load_lds_dwordx4 v[8:9], off
	v_lshl_add_u64 v[8:9], v[12:13], 0, s[16:17]
	s_mov_b32 m0, s55
	s_add_u32 s20, s48, 0x40080
	global_load_lds_dwordx4 v[8:9], off
	v_lshl_add_u64 v[8:9], v[14:15], 0, s[16:17]
	s_mov_b32 m0, s56
	s_addc_u32 s21, s49, 0
	global_load_lds_dwordx4 v[8:9], off
	s_add_i32 m0, s5, 0x1c000
	v_lshl_add_u64 v[8:9], s[20:21], 0, v[134:135]
	global_load_lds_dwordx4 v[8:9], off
	v_lshl_add_u64 v[8:9], s[20:21], 0, v[130:131]
	s_add_i32 m0, s5, 0x1e000
	s_waitcnt vmcnt(0)
	v_bitop3_b32 v144, v16, s19, v7 bitop3:0xde
	global_load_lds_dwordx4 v[8:9], off
	v_lshlrev_b32_e32 v7, 14, v5
	v_and_b32_e32 v7, 0xffff8000, v7
	v_lshl_add_u32 v4, v4, 11, v7
	v_and_b32_e32 v5, 1, v5
	v_lshl_or_b32 v4, v5, 6, v4
	v_lshl_add_u32 v138, v6, 1, v4
	v_lshlrev_b32_e32 v4, 14, v0
	v_and_b32_e32 v4, 0xffff8000, v4
	s_waitcnt vmcnt(6)
	v_lshl_add_u32 v2, v2, 11, v4
	v_and_b32_e32 v0, 1, v0
	s_cmpk_lt_u32 s18, 0x100
	v_lshl_or_b32 v0, v0, 6, v2
	v_readlane_b32 s22, v251, 9
	s_cselect_b64 s[20:21], -1, 0
	v_mov_b32_e32 v139, v1
	v_lshl_add_u32 v140, v3, 1, v0
	v_mov_b32_e32 v141, v1
	s_mov_b32 s57, 0
	v_add_u32_e32 v145, 0, v17
	v_readlane_b32 s19, v251, 6
	s_mov_b32 s18, s22
	s_barrier
	v_readlane_b32 s23, v251, 10
	s_mov_b32 s63, 0
	s_branch .LBB0_226

.LBB0_228:
	s_ashr_i32 s39, s38, 31
	s_lshl_b64 s[42:43], s[38:39], 19
	s_add_u32 s42, s96, s42
	s_addc_u32 s43, s97, s43
	s_and_b64 s[44:45], s[40:41], exec
	s_cselect_b32 s39, s43, s47
	s_cselect_b32 s58, s42, s46
	s_ashr_i32 s23, s22, 31
	s_lshl_b64 s[44:45], s[22:23], 19
	v_readlane_b32 s50, v250, 18
	v_readlane_b32 s51, v250, 19
	s_add_u32 s44, s50, s44
	s_addc_u32 s45, s51, s45
	s_and_b64 s[50:51], s[40:41], exec
	s_cselect_b32 s23, s45, s49
	s_cselect_b32 s59, s44, s48
	s_add_u32 s46, s46, 0x40080
	s_addc_u32 s47, s47, 0
	s_add_u32 s60, s48, 0x100
	s_addc_u32 s61, s49, 0
	s_mov_b32 s62, -2
	s_cmp_eq_u32 s63, 0
	s_cbranch_scc1 .Lrb0_skip
	s_barrier
.Lrb0_skip:
	s_add_u32 s48, s46, 0xfffc0080
	s_addc_u32 s49, s47, -1
	s_add_i32 s63, 0, 0x10000
	s_cmp_eq_u32 s62, 12
	s_cselect_b32 s51, s39, s49
	s_cselect_b32 s50, s58, s48
	v_add_u32_e32 v0, s63, v144
	s_cselect_b32 s49, s23, s61
	s_cselect_b32 s48, s59, s60
	s_add_i32 s66, 0, 0x14000
	ds_read_b128 v[146:149], v0
	ds_read_b128 v[150:153], v0 offset:1024
	ds_read_b128 v[154:157], v0 offset:2048
	ds_read_b128 v[158:161], v0 offset:3072
	v_add_u32_e32 v0, s66, v144
	ds_read_b128 v[162:165], v0
	ds_read_b128 v[166:169], v0 offset:1024
	ds_read_b128 v[170:173], v0 offset:2048
	ds_read_b128 v[174:177], v0 offset:3072
	v_lshl_add_u64 v[228:229], s[46:47], 0, v[138:139]
	s_add_i32 m0, s5, 0xc000
	ds_read_b128 v[178:181], v145
	ds_read_b128 v[182:185], v145 offset:1024
	ds_read_b128 v[204:207], v145 offset:2048
	ds_read_b128 v[208:211], v145 offset:3072
	ds_read_b128 v[212:215], v145 offset:4096
	ds_read_b128 v[216:219], v145 offset:5120
	ds_read_b128 v[220:223], v145 offset:6144
	ds_read_b128 v[224:227], v145 offset:7168
	global_load_lds_dwordx4 v[228:229], off
	v_lshl_add_u64 v[228:229], s[46:47], 0, v[140:141]
	s_add_i32 m0, s5, 0xe000
	s_nop 0
	global_load_lds_dwordx4 v[228:229], off
	s_waitcnt vmcnt(8)
	s_waitcnt lgkmcnt(0)
	s_setprio 1
	s_barrier
	v_mfma_f32_16x16x32_bf16 v[118:121], v[146:149], v[178:181], 0
	v_mfma_f32_16x16x32_bf16 v[114:117], v[154:157], v[178:181], 0
	v_mfma_f32_16x16x32_bf16 v[110:113], v[146:149], v[204:207], 0
	v_mfma_f32_16x16x32_bf16 v[102:105], v[154:157], v[204:207], 0
	v_mfma_f32_16x16x32_bf16 v[94:97], v[146:149], v[212:215], 0
	v_mfma_f32_16x16x32_bf16 v[86:89], v[154:157], v[212:215], 0
	v_mfma_f32_16x16x32_bf16 v[78:81], v[146:149], v[220:223], 0
	v_mfma_f32_16x16x32_bf16 v[70:73], v[154:157], v[220:223], 0
	v_mfma_f32_16x16x32_bf16 v[118:121], v[150:153], v[182:185], v[118:121]
	v_mfma_f32_16x16x32_bf16 v[114:117], v[158:161], v[182:185], v[114:117]
	v_mfma_f32_16x16x32_bf16 v[110:113], v[150:153], v[208:211], v[110:113]
	v_mfma_f32_16x16x32_bf16 v[102:105], v[158:161], v[208:211], v[102:105]
	v_mfma_f32_16x16x32_bf16 v[94:97], v[150:153], v[216:219], v[94:97]
	v_mfma_f32_16x16x32_bf16 v[86:89], v[158:161], v[216:219], v[86:89]
	v_mfma_f32_16x16x32_bf16 v[78:81], v[150:153], v[224:227], v[78:81]
	v_mfma_f32_16x16x32_bf16 v[70:73], v[158:161], v[224:227], v[70:73]
	v_mfma_f32_16x16x32_bf16 v[126:129], v[162:165], v[178:181], 0
	v_mfma_f32_16x16x32_bf16 v[122:125], v[170:173], v[178:181], 0
	v_mfma_f32_16x16x32_bf16 v[106:109], v[162:165], v[204:207], 0
	v_mfma_f32_16x16x32_bf16 v[98:101], v[170:173], v[204:207], 0
	v_mfma_f32_16x16x32_bf16 v[90:93], v[162:165], v[212:215], 0
	v_mfma_f32_16x16x32_bf16 v[82:85], v[170:173], v[212:215], 0
	v_mfma_f32_16x16x32_bf16 v[74:77], v[162:165], v[220:223], 0
	v_mfma_f32_16x16x32_bf16 v[66:69], v[170:173], v[220:223], 0
	v_mfma_f32_16x16x32_bf16 v[126:129], v[166:169], v[182:185], v[126:129]
	v_mfma_f32_16x16x32_bf16 v[122:125], v[174:177], v[182:185], v[122:125]
	v_mfma_f32_16x16x32_bf16 v[106:109], v[166:169], v[208:211], v[106:109]
	v_mfma_f32_16x16x32_bf16 v[98:101], v[174:177], v[208:211], v[98:101]
	v_mfma_f32_16x16x32_bf16 v[90:93], v[166:169], v[216:219], v[90:93]
	v_mfma_f32_16x16x32_bf16 v[82:85], v[174:177], v[216:219], v[82:85]
	v_mfma_f32_16x16x32_bf16 v[74:77], v[166:169], v[224:227], v[74:77]
	v_mfma_f32_16x16x32_bf16 v[66:69], v[174:177], v[224:227], v[66:69]
	s_barrier
	s_setprio 0
	s_add_i32 s63, s63, s4
	v_lshl_add_u64 v[228:229], s[48:49], 0, v[134:135]
	s_mov_b32 m0, s63
	ds_read_b128 v[178:181], v145 offset:16384
	ds_read_b128 v[182:185], v145 offset:17408
	ds_read_b128 v[204:207], v145 offset:18432
	ds_read_b128 v[208:211], v145 offset:19456
	ds_read_b128 v[212:215], v145 offset:20480
	ds_read_b128 v[216:219], v145 offset:21504
	ds_read_b128 v[220:223], v145 offset:22528
	ds_read_b128 v[224:227], v145 offset:23552
	global_load_lds_dwordx4 v[228:229], off
	s_add_i32 m0, s63, 0x2000
	s_add_u32 s64, s48, 0x40000
	v_lshl_add_u64 v[230:231], s[48:49], 0, v[130:131]
	s_addc_u32 s65, s49, 0
	s_add_i32 s63, s66, s4
	global_load_lds_dwordx4 v[230:231], off
	v_lshl_add_u64 v[240:241], s[64:65], 0, v[134:135]
	s_mov_b32 m0, s63
	v_lshl_add_u64 v[242:243], s[50:51], 0, v[132:133]
	global_load_lds_dwordx4 v[240:241], off
	v_lshl_add_u64 v[240:241], s[64:65], 0, v[130:131]
	s_add_i32 m0, s63, 0x2000
	s_nop 0
	global_load_lds_dwordx4 v[240:241], off
	v_lshl_add_u64 v[240:241], s[50:51], 0, v[136:137]
	s_mov_b32 m0, s5
	s_nop 0
	global_load_lds_dwordx4 v[240:241], off
	s_mov_b32 m0, s6
	s_nop 0
	global_load_lds_dwordx4 v[242:243], off
	s_waitcnt vmcnt(8)
	s_waitcnt lgkmcnt(0)
	s_setprio 1
	s_barrier
	v_mfma_f32_16x16x32_bf16 v[62:65], v[146:149], v[178:181], 0
	v_mfma_f32_16x16x32_bf16 v[54:57], v[154:157], v[178:181], 0
	v_mfma_f32_16x16x32_bf16 v[46:49], v[146:149], v[204:207], 0
	v_mfma_f32_16x16x32_bf16 v[38:41], v[154:157], v[204:207], 0
	v_mfma_f32_16x16x32_bf16 v[30:33], v[146:149], v[212:215], 0
	v_mfma_f32_16x16x32_bf16 v[22:25], v[154:157], v[212:215], 0
	v_mfma_f32_16x16x32_bf16 v[14:17], v[146:149], v[220:223], 0
	v_mfma_f32_16x16x32_bf16 v[6:9], v[154:157], v[220:223], 0
	v_mfma_f32_16x16x32_bf16 v[62:65], v[150:153], v[182:185], v[62:65]
	v_mfma_f32_16x16x32_bf16 v[54:57], v[158:161], v[182:185], v[54:57]
	v_mfma_f32_16x16x32_bf16 v[46:49], v[150:153], v[208:211], v[46:49]
	v_mfma_f32_16x16x32_bf16 v[38:41], v[158:161], v[208:211], v[38:41]
	v_mfma_f32_16x16x32_bf16 v[30:33], v[150:153], v[216:219], v[30:33]
	v_mfma_f32_16x16x32_bf16 v[22:25], v[158:161], v[216:219], v[22:25]
	v_mfma_f32_16x16x32_bf16 v[14:17], v[150:153], v[224:227], v[14:17]
	v_mfma_f32_16x16x32_bf16 v[6:9], v[158:161], v[224:227], v[6:9]
	v_mfma_f32_16x16x32_bf16 v[58:61], v[162:165], v[178:181], 0
	v_mfma_f32_16x16x32_bf16 v[50:53], v[170:173], v[178:181], 0
	v_mfma_f32_16x16x32_bf16 v[42:45], v[162:165], v[204:207], 0
	v_mfma_f32_16x16x32_bf16 v[34:37], v[170:173], v[204:207], 0
	v_mfma_f32_16x16x32_bf16 v[26:29], v[162:165], v[212:215], 0
	v_mfma_f32_16x16x32_bf16 v[18:21], v[170:173], v[212:215], 0
	v_mfma_f32_16x16x32_bf16 v[10:13], v[162:165], v[220:223], 0
	v_mfma_f32_16x16x32_bf16 v[2:5], v[170:173], v[220:223], 0
	v_mfma_f32_16x16x32_bf16 v[58:61], v[166:169], v[182:185], v[58:61]
	v_mfma_f32_16x16x32_bf16 v[50:53], v[174:177], v[182:185], v[50:53]
	v_mfma_f32_16x16x32_bf16 v[42:45], v[166:169], v[208:211], v[42:45]
	v_mfma_f32_16x16x32_bf16 v[34:37], v[174:177], v[208:211], v[34:37]
	v_mfma_f32_16x16x32_bf16 v[26:29], v[166:169], v[216:219], v[26:29]
	v_mfma_f32_16x16x32_bf16 v[18:21], v[174:177], v[216:219], v[18:21]
	v_mfma_f32_16x16x32_bf16 v[10:13], v[166:169], v[224:227], v[10:13]
	v_mfma_f32_16x16x32_bf16 v[2:5], v[174:177], v[224:227], v[2:5]
	s_barrier
	s_setprio 0
	s_add_i32 s63, 0, 0x18000
	v_add_u32_e32 v0, s63, v144
	s_add_i32 s64, 0, 0x1c000
	ds_read_b128 v[146:149], v0
	ds_read_b128 v[150:153], v0 offset:1024
	ds_read_b128 v[154:157], v0 offset:2048
	ds_read_b128 v[158:161], v0 offset:3072
	v_add_u32_e32 v0, s64, v144
	ds_read_b128 v[162:165], v0
	ds_read_b128 v[166:169], v0 offset:1024
	ds_read_b128 v[170:173], v0 offset:2048
	ds_read_b128 v[174:177], v0 offset:3072
	s_add_u32 s50, s50, 0x40000
	s_addc_u32 s51, s51, 0
	s_mov_b32 m0, s7
	v_lshl_add_u64 v[244:245], s[50:51], 0, v[136:137]
	ds_read_b128 v[178:181], v145 offset:32768
	ds_read_b128 v[182:185], v145 offset:33792
	ds_read_b128 v[204:207], v145 offset:34816
	ds_read_b128 v[208:211], v145 offset:35840
	ds_read_b128 v[212:215], v145 offset:36864
	ds_read_b128 v[216:219], v145 offset:37888
	ds_read_b128 v[220:223], v145 offset:38912
	ds_read_b128 v[224:227], v145 offset:39936
	global_load_lds_dwordx4 v[244:245], off
	v_lshl_add_u64 v[244:245], s[50:51], 0, v[132:133]
	s_mov_b32 m0, s52
	s_nop 0
	global_load_lds_dwordx4 v[244:245], off
	s_waitcnt vmcnt(8)
	s_waitcnt lgkmcnt(0)
	s_setprio 1
	s_barrier
	v_mfma_f32_16x16x32_bf16 v[118:121], v[146:149], v[178:181], v[118:121]
	v_mfma_f32_16x16x32_bf16 v[114:117], v[154:157], v[178:181], v[114:117]
	v_mfma_f32_16x16x32_bf16 v[110:113], v[146:149], v[204:207], v[110:113]
	v_mfma_f32_16x16x32_bf16 v[102:105], v[154:157], v[204:207], v[102:105]
	v_mfma_f32_16x16x32_bf16 v[94:97], v[146:149], v[212:215], v[94:97]
	v_mfma_f32_16x16x32_bf16 v[86:89], v[154:157], v[212:215], v[86:89]
	v_mfma_f32_16x16x32_bf16 v[78:81], v[146:149], v[220:223], v[78:81]
	v_mfma_f32_16x16x32_bf16 v[70:73], v[154:157], v[220:223], v[70:73]
	v_mfma_f32_16x16x32_bf16 v[118:121], v[150:153], v[182:185], v[118:121]
	v_mfma_f32_16x16x32_bf16 v[114:117], v[158:161], v[182:185], v[114:117]
	v_mfma_f32_16x16x32_bf16 v[110:113], v[150:153], v[208:211], v[110:113]
	v_mfma_f32_16x16x32_bf16 v[102:105], v[158:161], v[208:211], v[102:105]
	v_mfma_f32_16x16x32_bf16 v[94:97], v[150:153], v[216:219], v[94:97]
	v_mfma_f32_16x16x32_bf16 v[86:89], v[158:161], v[216:219], v[86:89]
	v_mfma_f32_16x16x32_bf16 v[78:81], v[150:153], v[224:227], v[78:81]
	v_mfma_f32_16x16x32_bf16 v[70:73], v[158:161], v[224:227], v[70:73]
	v_mfma_f32_16x16x32_bf16 v[126:129], v[162:165], v[178:181], v[126:129]
	v_mfma_f32_16x16x32_bf16 v[122:125], v[170:173], v[178:181], v[122:125]
	v_mfma_f32_16x16x32_bf16 v[106:109], v[162:165], v[204:207], v[106:109]
	v_mfma_f32_16x16x32_bf16 v[98:101], v[170:173], v[204:207], v[98:101]
	v_mfma_f32_16x16x32_bf16 v[90:93], v[162:165], v[212:215], v[90:93]
	v_mfma_f32_16x16x32_bf16 v[82:85], v[170:173], v[212:215], v[82:85]
	v_mfma_f32_16x16x32_bf16 v[74:77], v[162:165], v[220:223], v[74:77]
	v_mfma_f32_16x16x32_bf16 v[66:69], v[170:173], v[220:223], v[66:69]
	v_mfma_f32_16x16x32_bf16 v[126:129], v[166:169], v[182:185], v[126:129]
	v_mfma_f32_16x16x32_bf16 v[122:125], v[174:177], v[182:185], v[122:125]
	v_mfma_f32_16x16x32_bf16 v[106:109], v[166:169], v[208:211], v[106:109]
	v_mfma_f32_16x16x32_bf16 v[98:101], v[174:177], v[208:211], v[98:101]
	v_mfma_f32_16x16x32_bf16 v[90:93], v[166:169], v[216:219], v[90:93]
	v_mfma_f32_16x16x32_bf16 v[82:85], v[174:177], v[216:219], v[82:85]
	v_mfma_f32_16x16x32_bf16 v[74:77], v[166:169], v[224:227], v[74:77]
	v_mfma_f32_16x16x32_bf16 v[66:69], v[174:177], v[224:227], v[66:69]
	s_barrier
	s_setprio 0
	s_add_i32 s50, s63, s4
	v_lshl_add_u64 v[228:229], v[228:229], 0, s[16:17]
	s_mov_b32 m0, s50
	ds_read_b128 v[178:181], v145 offset:49152
	ds_read_b128 v[182:185], v145 offset:50176
	ds_read_b128 v[204:207], v145 offset:51200
	ds_read_b128 v[208:211], v145 offset:52224
	ds_read_b128 v[212:215], v145 offset:53248
	ds_read_b128 v[216:219], v145 offset:54272
	ds_read_b128 v[220:223], v145 offset:55296
	ds_read_b128 v[224:227], v145 offset:56320
	global_load_lds_dwordx4 v[228:229], off
	s_add_i32 m0, s50, 0x2000
	s_add_u32 s48, s48, 0x40080
	v_lshl_add_u64 v[228:229], v[230:231], 0, s[16:17]
	s_addc_u32 s49, s49, 0
	s_add_i32 s50, s64, s4
	global_load_lds_dwordx4 v[228:229], off
	v_lshl_add_u64 v[228:229], s[48:49], 0, v[134:135]
	s_mov_b32 m0, s50
	s_nop 0
	global_load_lds_dwordx4 v[228:229], off
	v_lshl_add_u64 v[228:229], s[48:49], 0, v[130:131]
	s_add_i32 m0, s50, 0x2000
	s_nop 0
	global_load_lds_dwordx4 v[228:229], off
	v_lshl_add_u64 v[228:229], v[240:241], 0, s[16:17]
	s_mov_b32 m0, s55
	s_nop 0
	global_load_lds_dwordx4 v[228:229], off
	v_lshl_add_u64 v[228:229], v[242:243], 0, s[16:17]
	s_mov_b32 m0, s56
	s_nop 0
	global_load_lds_dwordx4 v[228:229], off
	s_waitcnt vmcnt(8)
	s_waitcnt lgkmcnt(0)
	s_setprio 1
	s_barrier
	v_mfma_f32_16x16x32_bf16 v[62:65], v[146:149], v[178:181], v[62:65]
	v_mfma_f32_16x16x32_bf16 v[54:57], v[154:157], v[178:181], v[54:57]
	v_mfma_f32_16x16x32_bf16 v[46:49], v[146:149], v[204:207], v[46:49]
	v_mfma_f32_16x16x32_bf16 v[38:41], v[154:157], v[204:207], v[38:41]
	v_mfma_f32_16x16x32_bf16 v[30:33], v[146:149], v[212:215], v[30:33]
	v_mfma_f32_16x16x32_bf16 v[22:25], v[154:157], v[212:215], v[22:25]
	v_mfma_f32_16x16x32_bf16 v[14:17], v[146:149], v[220:223], v[14:17]
	v_mfma_f32_16x16x32_bf16 v[6:9], v[154:157], v[220:223], v[6:9]
	v_mfma_f32_16x16x32_bf16 v[62:65], v[150:153], v[182:185], v[62:65]
	v_mfma_f32_16x16x32_bf16 v[54:57], v[158:161], v[182:185], v[54:57]
	v_mfma_f32_16x16x32_bf16 v[46:49], v[150:153], v[208:211], v[46:49]
	v_mfma_f32_16x16x32_bf16 v[38:41], v[158:161], v[208:211], v[38:41]
	v_mfma_f32_16x16x32_bf16 v[30:33], v[150:153], v[216:219], v[30:33]
	v_mfma_f32_16x16x32_bf16 v[22:25], v[158:161], v[216:219], v[22:25]
	v_mfma_f32_16x16x32_bf16 v[14:17], v[150:153], v[224:227], v[14:17]
	v_mfma_f32_16x16x32_bf16 v[6:9], v[158:161], v[224:227], v[6:9]
	v_mfma_f32_16x16x32_bf16 v[58:61], v[162:165], v[178:181], v[58:61]
	v_mfma_f32_16x16x32_bf16 v[50:53], v[170:173], v[178:181], v[50:53]
	v_mfma_f32_16x16x32_bf16 v[42:45], v[162:165], v[204:207], v[42:45]
	v_mfma_f32_16x16x32_bf16 v[34:37], v[170:173], v[204:207], v[34:37]
	v_mfma_f32_16x16x32_bf16 v[26:29], v[162:165], v[212:215], v[26:29]
	v_mfma_f32_16x16x32_bf16 v[18:21], v[170:173], v[212:215], v[18:21]
	v_mfma_f32_16x16x32_bf16 v[10:13], v[162:165], v[220:223], v[10:13]
	v_mfma_f32_16x16x32_bf16 v[2:5], v[170:173], v[220:223], v[2:5]
	v_mfma_f32_16x16x32_bf16 v[58:61], v[166:169], v[182:185], v[58:61]
	v_mfma_f32_16x16x32_bf16 v[50:53], v[174:177], v[182:185], v[50:53]
	v_mfma_f32_16x16x32_bf16 v[42:45], v[166:169], v[208:211], v[42:45]
	v_mfma_f32_16x16x32_bf16 v[34:37], v[174:177], v[208:211], v[34:37]
	v_mfma_f32_16x16x32_bf16 v[26:29], v[166:169], v[216:219], v[26:29]
	v_mfma_f32_16x16x32_bf16 v[18:21], v[174:177], v[216:219], v[18:21]
	v_mfma_f32_16x16x32_bf16 v[10:13], v[166:169], v[224:227], v[10:13]
	v_mfma_f32_16x16x32_bf16 v[2:5], v[174:177], v[224:227], v[2:5]
	s_barrier
	s_setprio 0
	s_add_i32 s62, s62, 2
	s_add_u32 s46, s46, 0x100
	s_addc_u32 s47, s47, 0
	s_add_u32 s60, s60, 0x100
	s_addc_u32 s61, s61, 0
	s_cmp_gt_u32 s62, 13
.LBB0_229:
	s_add_u32 s48, s46, 0xfffc0080
	s_addc_u32 s49, s47, -1
	s_add_i32 s63, 0, 0x10000
	s_cmp_eq_u32 s62, 12
	s_cselect_b32 s51, s39, s49
	s_cselect_b32 s50, s58, s48
	v_add_u32_e32 v0, s63, v144
	s_cselect_b32 s49, s23, s61
	s_cselect_b32 s48, s59, s60
	s_add_i32 s66, 0, 0x14000
	ds_read_b128 v[146:149], v0
	ds_read_b128 v[150:153], v0 offset:1024
	ds_read_b128 v[154:157], v0 offset:2048
	ds_read_b128 v[158:161], v0 offset:3072
	v_add_u32_e32 v0, s66, v144
	ds_read_b128 v[162:165], v0
	ds_read_b128 v[166:169], v0 offset:1024
	ds_read_b128 v[170:173], v0 offset:2048
	ds_read_b128 v[174:177], v0 offset:3072
	v_lshl_add_u64 v[228:229], s[46:47], 0, v[138:139]
	s_add_i32 m0, s5, 0xc000
	ds_read_b128 v[178:181], v145
	ds_read_b128 v[182:185], v145 offset:1024
	ds_read_b128 v[204:207], v145 offset:2048
	ds_read_b128 v[208:211], v145 offset:3072
	ds_read_b128 v[212:215], v145 offset:4096
	ds_read_b128 v[216:219], v145 offset:5120
	ds_read_b128 v[220:223], v145 offset:6144
	ds_read_b128 v[224:227], v145 offset:7168
	global_load_lds_dwordx4 v[228:229], off
	v_lshl_add_u64 v[228:229], s[46:47], 0, v[140:141]
	s_add_i32 m0, s5, 0xe000
	s_nop 0
	global_load_lds_dwordx4 v[228:229], off
	s_waitcnt vmcnt(8)
	s_waitcnt lgkmcnt(0)
	s_setprio 1
	s_barrier
	v_mfma_f32_16x16x32_bf16 v[118:121], v[146:149], v[178:181], v[118:121]
	v_mfma_f32_16x16x32_bf16 v[114:117], v[154:157], v[178:181], v[114:117]
	v_mfma_f32_16x16x32_bf16 v[110:113], v[146:149], v[204:207], v[110:113]
	v_mfma_f32_16x16x32_bf16 v[102:105], v[154:157], v[204:207], v[102:105]
	v_mfma_f32_16x16x32_bf16 v[94:97], v[146:149], v[212:215], v[94:97]
	v_mfma_f32_16x16x32_bf16 v[86:89], v[154:157], v[212:215], v[86:89]
	v_mfma_f32_16x16x32_bf16 v[78:81], v[146:149], v[220:223], v[78:81]
	v_mfma_f32_16x16x32_bf16 v[70:73], v[154:157], v[220:223], v[70:73]
	v_mfma_f32_16x16x32_bf16 v[118:121], v[150:153], v[182:185], v[118:121]
	v_mfma_f32_16x16x32_bf16 v[114:117], v[158:161], v[182:185], v[114:117]
	v_mfma_f32_16x16x32_bf16 v[110:113], v[150:153], v[208:211], v[110:113]
	v_mfma_f32_16x16x32_bf16 v[102:105], v[158:161], v[208:211], v[102:105]
	v_mfma_f32_16x16x32_bf16 v[94:97], v[150:153], v[216:219], v[94:97]
	v_mfma_f32_16x16x32_bf16 v[86:89], v[158:161], v[216:219], v[86:89]
	v_mfma_f32_16x16x32_bf16 v[78:81], v[150:153], v[224:227], v[78:81]
	v_mfma_f32_16x16x32_bf16 v[70:73], v[158:161], v[224:227], v[70:73]
	v_mfma_f32_16x16x32_bf16 v[126:129], v[162:165], v[178:181], v[126:129]
	v_mfma_f32_16x16x32_bf16 v[122:125], v[170:173], v[178:181], v[122:125]
	v_mfma_f32_16x16x32_bf16 v[106:109], v[162:165], v[204:207], v[106:109]
	v_mfma_f32_16x16x32_bf16 v[98:101], v[170:173], v[204:207], v[98:101]
	v_mfma_f32_16x16x32_bf16 v[90:93], v[162:165], v[212:215], v[90:93]
	v_mfma_f32_16x16x32_bf16 v[82:85], v[170:173], v[212:215], v[82:85]
	v_mfma_f32_16x16x32_bf16 v[74:77], v[162:165], v[220:223], v[74:77]
	v_mfma_f32_16x16x32_bf16 v[66:69], v[170:173], v[220:223], v[66:69]
	v_mfma_f32_16x16x32_bf16 v[126:129], v[166:169], v[182:185], v[126:129]
	v_mfma_f32_16x16x32_bf16 v[122:125], v[174:177], v[182:185], v[122:125]
	v_mfma_f32_16x16x32_bf16 v[106:109], v[166:169], v[208:211], v[106:109]
	v_mfma_f32_16x16x32_bf16 v[98:101], v[174:177], v[208:211], v[98:101]
	v_mfma_f32_16x16x32_bf16 v[90:93], v[166:169], v[216:219], v[90:93]
	v_mfma_f32_16x16x32_bf16 v[82:85], v[174:177], v[216:219], v[82:85]
	v_mfma_f32_16x16x32_bf16 v[74:77], v[166:169], v[224:227], v[74:77]
	v_mfma_f32_16x16x32_bf16 v[66:69], v[174:177], v[224:227], v[66:69]
	s_barrier
	s_setprio 0
	s_add_i32 s63, s63, s4
	v_lshl_add_u64 v[228:229], s[48:49], 0, v[134:135]
	s_mov_b32 m0, s63
	ds_read_b128 v[178:181], v145 offset:16384
	ds_read_b128 v[182:185], v145 offset:17408
	ds_read_b128 v[204:207], v145 offset:18432
	ds_read_b128 v[208:211], v145 offset:19456
	ds_read_b128 v[212:215], v145 offset:20480
	ds_read_b128 v[216:219], v145 offset:21504
	ds_read_b128 v[220:223], v145 offset:22528
	ds_read_b128 v[224:227], v145 offset:23552
	global_load_lds_dwordx4 v[228:229], off
	s_add_i32 m0, s63, 0x2000
	s_add_u32 s64, s48, 0x40000
	v_lshl_add_u64 v[230:231], s[48:49], 0, v[130:131]
	s_addc_u32 s65, s49, 0
	s_add_i32 s63, s66, s4
	global_load_lds_dwordx4 v[230:231], off
	v_lshl_add_u64 v[240:241], s[64:65], 0, v[134:135]
	s_mov_b32 m0, s63
	v_lshl_add_u64 v[242:243], s[50:51], 0, v[132:133]
	global_load_lds_dwordx4 v[240:241], off
	v_lshl_add_u64 v[240:241], s[64:65], 0, v[130:131]
	s_add_i32 m0, s63, 0x2000
	s_nop 0
	global_load_lds_dwordx4 v[240:241], off
	v_lshl_add_u64 v[240:241], s[50:51], 0, v[136:137]
	s_mov_b32 m0, s5
	s_nop 0
	global_load_lds_dwordx4 v[240:241], off
	s_mov_b32 m0, s6
	s_nop 0
	global_load_lds_dwordx4 v[242:243], off
	s_waitcnt vmcnt(8)
	s_waitcnt lgkmcnt(0)
	s_setprio 1
	s_barrier
	v_mfma_f32_16x16x32_bf16 v[62:65], v[146:149], v[178:181], v[62:65]
	v_mfma_f32_16x16x32_bf16 v[54:57], v[154:157], v[178:181], v[54:57]
	v_mfma_f32_16x16x32_bf16 v[46:49], v[146:149], v[204:207], v[46:49]
	v_mfma_f32_16x16x32_bf16 v[38:41], v[154:157], v[204:207], v[38:41]
	v_mfma_f32_16x16x32_bf16 v[30:33], v[146:149], v[212:215], v[30:33]
	v_mfma_f32_16x16x32_bf16 v[22:25], v[154:157], v[212:215], v[22:25]
	v_mfma_f32_16x16x32_bf16 v[14:17], v[146:149], v[220:223], v[14:17]
	v_mfma_f32_16x16x32_bf16 v[6:9], v[154:157], v[220:223], v[6:9]
	v_mfma_f32_16x16x32_bf16 v[62:65], v[150:153], v[182:185], v[62:65]
	v_mfma_f32_16x16x32_bf16 v[54:57], v[158:161], v[182:185], v[54:57]
	v_mfma_f32_16x16x32_bf16 v[46:49], v[150:153], v[208:211], v[46:49]
	v_mfma_f32_16x16x32_bf16 v[38:41], v[158:161], v[208:211], v[38:41]
	v_mfma_f32_16x16x32_bf16 v[30:33], v[150:153], v[216:219], v[30:33]
	v_mfma_f32_16x16x32_bf16 v[22:25], v[158:161], v[216:219], v[22:25]
	v_mfma_f32_16x16x32_bf16 v[14:17], v[150:153], v[224:227], v[14:17]
	v_mfma_f32_16x16x32_bf16 v[6:9], v[158:161], v[224:227], v[6:9]
	v_mfma_f32_16x16x32_bf16 v[58:61], v[162:165], v[178:181], v[58:61]
	v_mfma_f32_16x16x32_bf16 v[50:53], v[170:173], v[178:181], v[50:53]
	v_mfma_f32_16x16x32_bf16 v[42:45], v[162:165], v[204:207], v[42:45]
	v_mfma_f32_16x16x32_bf16 v[34:37], v[170:173], v[204:207], v[34:37]
	v_mfma_f32_16x16x32_bf16 v[26:29], v[162:165], v[212:215], v[26:29]
	v_mfma_f32_16x16x32_bf16 v[18:21], v[170:173], v[212:215], v[18:21]
	v_mfma_f32_16x16x32_bf16 v[10:13], v[162:165], v[220:223], v[10:13]
	v_mfma_f32_16x16x32_bf16 v[2:5], v[170:173], v[220:223], v[2:5]
	v_mfma_f32_16x16x32_bf16 v[58:61], v[166:169], v[182:185], v[58:61]
	v_mfma_f32_16x16x32_bf16 v[50:53], v[174:177], v[182:185], v[50:53]
	v_mfma_f32_16x16x32_bf16 v[42:45], v[166:169], v[208:211], v[42:45]
	v_mfma_f32_16x16x32_bf16 v[34:37], v[174:177], v[208:211], v[34:37]
	v_mfma_f32_16x16x32_bf16 v[26:29], v[166:169], v[216:219], v[26:29]
	v_mfma_f32_16x16x32_bf16 v[18:21], v[174:177], v[216:219], v[18:21]
	v_mfma_f32_16x16x32_bf16 v[10:13], v[166:169], v[224:227], v[10:13]
	v_mfma_f32_16x16x32_bf16 v[2:5], v[174:177], v[224:227], v[2:5]
	s_barrier
	s_setprio 0
	s_add_i32 s63, 0, 0x18000
	v_add_u32_e32 v0, s63, v144
	s_add_i32 s64, 0, 0x1c000
	ds_read_b128 v[146:149], v0
	ds_read_b128 v[150:153], v0 offset:1024
	ds_read_b128 v[154:157], v0 offset:2048
	ds_read_b128 v[158:161], v0 offset:3072
	v_add_u32_e32 v0, s64, v144
	ds_read_b128 v[162:165], v0
	ds_read_b128 v[166:169], v0 offset:1024
	ds_read_b128 v[170:173], v0 offset:2048
	ds_read_b128 v[174:177], v0 offset:3072
	s_add_u32 s50, s50, 0x40000
	s_addc_u32 s51, s51, 0
	s_mov_b32 m0, s7
	v_lshl_add_u64 v[244:245], s[50:51], 0, v[136:137]
	ds_read_b128 v[178:181], v145 offset:32768
	ds_read_b128 v[182:185], v145 offset:33792
	ds_read_b128 v[204:207], v145 offset:34816
	ds_read_b128 v[208:211], v145 offset:35840
	ds_read_b128 v[212:215], v145 offset:36864
	ds_read_b128 v[216:219], v145 offset:37888
	ds_read_b128 v[220:223], v145 offset:38912
	ds_read_b128 v[224:227], v145 offset:39936
	global_load_lds_dwordx4 v[244:245], off
	v_lshl_add_u64 v[244:245], s[50:51], 0, v[132:133]
	s_mov_b32 m0, s52
	s_nop 0
	global_load_lds_dwordx4 v[244:245], off
	s_waitcnt vmcnt(8)
	s_waitcnt lgkmcnt(0)
	s_setprio 1
	s_barrier
	v_mfma_f32_16x16x32_bf16 v[118:121], v[146:149], v[178:181], v[118:121]
	v_mfma_f32_16x16x32_bf16 v[114:117], v[154:157], v[178:181], v[114:117]
	v_mfma_f32_16x16x32_bf16 v[110:113], v[146:149], v[204:207], v[110:113]
	v_mfma_f32_16x16x32_bf16 v[102:105], v[154:157], v[204:207], v[102:105]
	v_mfma_f32_16x16x32_bf16 v[94:97], v[146:149], v[212:215], v[94:97]
	v_mfma_f32_16x16x32_bf16 v[86:89], v[154:157], v[212:215], v[86:89]
	v_mfma_f32_16x16x32_bf16 v[78:81], v[146:149], v[220:223], v[78:81]
	v_mfma_f32_16x16x32_bf16 v[70:73], v[154:157], v[220:223], v[70:73]
	v_mfma_f32_16x16x32_bf16 v[118:121], v[150:153], v[182:185], v[118:121]
	v_mfma_f32_16x16x32_bf16 v[114:117], v[158:161], v[182:185], v[114:117]
	v_mfma_f32_16x16x32_bf16 v[110:113], v[150:153], v[208:211], v[110:113]
	v_mfma_f32_16x16x32_bf16 v[102:105], v[158:161], v[208:211], v[102:105]
	v_mfma_f32_16x16x32_bf16 v[94:97], v[150:153], v[216:219], v[94:97]
	v_mfma_f32_16x16x32_bf16 v[86:89], v[158:161], v[216:219], v[86:89]
	v_mfma_f32_16x16x32_bf16 v[78:81], v[150:153], v[224:227], v[78:81]
	v_mfma_f32_16x16x32_bf16 v[70:73], v[158:161], v[224:227], v[70:73]
	v_mfma_f32_16x16x32_bf16 v[126:129], v[162:165], v[178:181], v[126:129]
	v_mfma_f32_16x16x32_bf16 v[122:125], v[170:173], v[178:181], v[122:125]
	v_mfma_f32_16x16x32_bf16 v[106:109], v[162:165], v[204:207], v[106:109]
	v_mfma_f32_16x16x32_bf16 v[98:101], v[170:173], v[204:207], v[98:101]
	v_mfma_f32_16x16x32_bf16 v[90:93], v[162:165], v[212:215], v[90:93]
	v_mfma_f32_16x16x32_bf16 v[82:85], v[170:173], v[212:215], v[82:85]
	v_mfma_f32_16x16x32_bf16 v[74:77], v[162:165], v[220:223], v[74:77]
	v_mfma_f32_16x16x32_bf16 v[66:69], v[170:173], v[220:223], v[66:69]
	v_mfma_f32_16x16x32_bf16 v[126:129], v[166:169], v[182:185], v[126:129]
	v_mfma_f32_16x16x32_bf16 v[122:125], v[174:177], v[182:185], v[122:125]
	v_mfma_f32_16x16x32_bf16 v[106:109], v[166:169], v[208:211], v[106:109]
	v_mfma_f32_16x16x32_bf16 v[98:101], v[174:177], v[208:211], v[98:101]
	v_mfma_f32_16x16x32_bf16 v[90:93], v[166:169], v[216:219], v[90:93]
	v_mfma_f32_16x16x32_bf16 v[82:85], v[174:177], v[216:219], v[82:85]
	v_mfma_f32_16x16x32_bf16 v[74:77], v[166:169], v[224:227], v[74:77]
	v_mfma_f32_16x16x32_bf16 v[66:69], v[174:177], v[224:227], v[66:69]
	s_barrier
	s_setprio 0
	s_add_i32 s50, s63, s4
	v_lshl_add_u64 v[228:229], v[228:229], 0, s[16:17]
	s_mov_b32 m0, s50
	ds_read_b128 v[178:181], v145 offset:49152
	ds_read_b128 v[182:185], v145 offset:50176
	ds_read_b128 v[204:207], v145 offset:51200
	ds_read_b128 v[208:211], v145 offset:52224
	ds_read_b128 v[212:215], v145 offset:53248
	ds_read_b128 v[216:219], v145 offset:54272
	ds_read_b128 v[220:223], v145 offset:55296
	ds_read_b128 v[224:227], v145 offset:56320
	global_load_lds_dwordx4 v[228:229], off
	s_add_i32 m0, s50, 0x2000
	s_add_u32 s48, s48, 0x40080
	v_lshl_add_u64 v[228:229], v[230:231], 0, s[16:17]
	s_addc_u32 s49, s49, 0
	s_add_i32 s50, s64, s4
	global_load_lds_dwordx4 v[228:229], off
	v_lshl_add_u64 v[228:229], s[48:49], 0, v[134:135]
	s_mov_b32 m0, s50
	s_nop 0
	global_load_lds_dwordx4 v[228:229], off
	v_lshl_add_u64 v[228:229], s[48:49], 0, v[130:131]
	s_add_i32 m0, s50, 0x2000
	s_nop 0
	global_load_lds_dwordx4 v[228:229], off
	v_lshl_add_u64 v[228:229], v[240:241], 0, s[16:17]
	s_mov_b32 m0, s55
	s_nop 0
	global_load_lds_dwordx4 v[228:229], off
	v_lshl_add_u64 v[228:229], v[242:243], 0, s[16:17]
	s_mov_b32 m0, s56
	s_nop 0
	global_load_lds_dwordx4 v[228:229], off
	s_waitcnt vmcnt(8)
	s_waitcnt lgkmcnt(0)
	s_setprio 1
	s_barrier
	v_mfma_f32_16x16x32_bf16 v[62:65], v[146:149], v[178:181], v[62:65]
	v_mfma_f32_16x16x32_bf16 v[54:57], v[154:157], v[178:181], v[54:57]
	v_mfma_f32_16x16x32_bf16 v[46:49], v[146:149], v[204:207], v[46:49]
	v_mfma_f32_16x16x32_bf16 v[38:41], v[154:157], v[204:207], v[38:41]
	v_mfma_f32_16x16x32_bf16 v[30:33], v[146:149], v[212:215], v[30:33]
	v_mfma_f32_16x16x32_bf16 v[22:25], v[154:157], v[212:215], v[22:25]
	v_mfma_f32_16x16x32_bf16 v[14:17], v[146:149], v[220:223], v[14:17]
	v_mfma_f32_16x16x32_bf16 v[6:9], v[154:157], v[220:223], v[6:9]
	v_mfma_f32_16x16x32_bf16 v[62:65], v[150:153], v[182:185], v[62:65]
	v_mfma_f32_16x16x32_bf16 v[54:57], v[158:161], v[182:185], v[54:57]
	v_mfma_f32_16x16x32_bf16 v[46:49], v[150:153], v[208:211], v[46:49]
	v_mfma_f32_16x16x32_bf16 v[38:41], v[158:161], v[208:211], v[38:41]
	v_mfma_f32_16x16x32_bf16 v[30:33], v[150:153], v[216:219], v[30:33]
	v_mfma_f32_16x16x32_bf16 v[22:25], v[158:161], v[216:219], v[22:25]
	v_mfma_f32_16x16x32_bf16 v[14:17], v[150:153], v[224:227], v[14:17]
	v_mfma_f32_16x16x32_bf16 v[6:9], v[158:161], v[224:227], v[6:9]
	v_mfma_f32_16x16x32_bf16 v[58:61], v[162:165], v[178:181], v[58:61]
	v_mfma_f32_16x16x32_bf16 v[50:53], v[170:173], v[178:181], v[50:53]
	v_mfma_f32_16x16x32_bf16 v[42:45], v[162:165], v[204:207], v[42:45]
	v_mfma_f32_16x16x32_bf16 v[34:37], v[170:173], v[204:207], v[34:37]
	v_mfma_f32_16x16x32_bf16 v[26:29], v[162:165], v[212:215], v[26:29]
	v_mfma_f32_16x16x32_bf16 v[18:21], v[170:173], v[212:215], v[18:21]
	v_mfma_f32_16x16x32_bf16 v[10:13], v[162:165], v[220:223], v[10:13]
	v_mfma_f32_16x16x32_bf16 v[2:5], v[170:173], v[220:223], v[2:5]
	v_mfma_f32_16x16x32_bf16 v[58:61], v[166:169], v[182:185], v[58:61]
	v_mfma_f32_16x16x32_bf16 v[50:53], v[174:177], v[182:185], v[50:53]
	v_mfma_f32_16x16x32_bf16 v[42:45], v[166:169], v[208:211], v[42:45]
	v_mfma_f32_16x16x32_bf16 v[34:37], v[174:177], v[208:211], v[34:37]
	v_mfma_f32_16x16x32_bf16 v[26:29], v[166:169], v[216:219], v[26:29]
	v_mfma_f32_16x16x32_bf16 v[18:21], v[174:177], v[216:219], v[18:21]
	v_mfma_f32_16x16x32_bf16 v[10:13], v[166:169], v[224:227], v[10:13]
	v_mfma_f32_16x16x32_bf16 v[2:5], v[174:177], v[224:227], v[2:5]
	s_barrier
	s_setprio 0
	s_add_i32 s62, s62, 2
	s_add_u32 s46, s46, 0x100
	s_addc_u32 s47, s47, 0
	s_add_u32 s60, s60, 0x100
	s_addc_u32 s61, s61, 0
	s_cmp_gt_u32 s62, 13
	s_cbranch_scc0 .LBB0_229
	s_and_b64 vcc, exec, s[20:21]
	s_cbranch_vccz .LBB0_232
	s_barrier
.LBB0_232:
	s_lshl_b32 s48, s18, 8
	s_lshl_b32 s46, s19, 7
	s_ashr_i32 s49, s48, 31
	v_mov_b32_e32 v0, v142
	v_mov_b32_e32 v148, v143
	s_ashr_i32 s47, s46, 31
	s_lshl_b64 s[48:49], s[48:49], 2
	s_add_u32 s48, s12, s48
	s_addc_u32 s49, s13, s49
	v_add_u32_e32 v0, s53, v0
	v_lshl_add_u64 v[146:147], v[0:1], 2, s[48:49]
	global_load_dword v160, v[146:147], off
	v_add_u32_e32 v146, 16, v0
	v_mov_b32_e32 v147, v1
	v_lshl_add_u64 v[146:147], v[146:147], 2, s[48:49]
	global_load_dword v161, v[146:147], off
	v_mov_b32_e32 v147, v1
	v_mov_b32_e32 v149, v1
	v_mov_b32_e32 v151, v1
	v_mov_b32_e32 v153, v1
	v_lshlrev_b32_e32 v162, 3, v148
	v_add_u32_e32 v146, 32, v0
	v_add_u32_e32 v148, 48, v0
	v_add_u32_e32 v150, 0x80, v0
	v_add_u32_e32 v152, 0x90, v0
	s_movk_i32 s23, 0xb00
	v_mov_b32_e32 v155, v1
	v_mov_b32_e32 v157, v1
	v_pk_mul_f32 v[158:159], v[114:115], v[122:123]
	v_add_u32_e32 v154, 0xa0, v0
	v_add_u32_e32 v156, 0xb0, v0
	v_mul_lo_u32 v0, v0, s23
	v_lshl_add_u64 v[122:123], v[146:147], 2, s[48:49]
	v_lshl_add_u64 v[146:147], v[148:149], 2, s[48:49]
	v_lshl_add_u64 v[148:149], v[150:151], 2, s[48:49]
	v_lshl_add_u64 v[150:151], v[152:153], 2, s[48:49]
	v_lshl_add_u64 v[152:153], v[154:155], 2, s[48:49]
	v_lshl_add_u64 v[154:155], v[156:157], 2, s[48:49]
	v_add3_u32 v0, v162, s54, v0
	global_load_dword v156, v[122:123], off
	global_load_dword v157, v[146:147], off
	global_load_dword v162, v[148:149], off
	s_nop 0
	global_load_dword v151, v[150:151], off
	s_nop 0
	global_load_dword v123, v[152:153], off
	global_load_dword v122, v[154:155], off
	v_pk_mul_f32 v[124:125], v[116:117], v[124:125]
	v_pk_mul_f32 v[128:129], v[120:121], v[128:129]
	v_pk_mul_f32 v[126:127], v[118:119], v[126:127]
	s_mul_hi_i32 s19, s18, 0x160000
	s_mul_i32 s18, s18, 0x160000
	s_add_u32 s23, s93, s18
	s_addc_u32 s39, s76, s19
	s_lshl_b64 s[18:19], s[46:47], 1
	s_add_u32 s46, s23, s18
	s_addc_u32 s47, s39, s19
	v_pk_mul_f32 v[108:109], v[112:113], v[108:109]
	v_pk_mul_f32 v[106:107], v[110:111], v[106:107]
	v_pk_mul_f32 v[100:101], v[104:105], v[100:101]
	v_pk_mul_f32 v[98:99], v[102:103], v[98:99]
	v_pk_mul_f32 v[92:93], v[96:97], v[92:93]
	v_pk_mul_f32 v[90:91], v[94:95], v[90:91]
	v_pk_mul_f32 v[84:85], v[88:89], v[84:85]
	v_pk_mul_f32 v[82:83], v[86:87], v[82:83]
	v_pk_mul_f32 v[76:77], v[80:81], v[76:77]
	v_pk_mul_f32 v[74:75], v[78:79], v[74:75]
	v_pk_mul_f32 v[68:69], v[72:73], v[68:69]
	v_pk_mul_f32 v[66:67], v[70:71], v[66:67]
	v_pk_mul_f32 v[60:61], v[64:65], v[60:61]
	v_pk_mul_f32 v[58:59], v[62:63], v[58:59]
	v_pk_mul_f32 v[52:53], v[56:57], v[52:53]
	v_pk_mul_f32 v[50:51], v[54:55], v[50:51]
	v_pk_mul_f32 v[44:45], v[48:49], v[44:45]
	v_pk_mul_f32 v[42:43], v[46:47], v[42:43]
	v_pk_mul_f32 v[36:37], v[40:41], v[36:37]
	v_pk_mul_f32 v[34:35], v[38:39], v[34:35]
	v_pk_mul_f32 v[28:29], v[32:33], v[28:29]
	v_pk_mul_f32 v[26:27], v[30:31], v[26:27]
	v_pk_mul_f32 v[20:21], v[24:25], v[20:21]
	v_pk_mul_f32 v[18:19], v[22:23], v[18:19]
	v_pk_mul_f32 v[12:13], v[16:17], v[12:13]
	v_pk_mul_f32 v[10:11], v[14:15], v[10:11]
	v_pk_mul_f32 v[4:5], v[8:9], v[4:5]
	v_pk_mul_f32 v[2:3], v[6:7], v[2:3]
	s_andn2_b64 vcc, exec, s[40:41]
	s_mov_b64 s[40:41], -1
	s_waitcnt vmcnt(0)
	v_fmamk_f32 v146, v160, 0x3a800000, v234
	v_rsq_f32_e32 v149, v146
	v_fmamk_f32 v146, v161, 0x3a800000, v234
	v_mul_f32_e32 v148, 0xbfb8aa3b, v149
	v_pk_mul_f32 v[116:117], v[116:117], v[148:149] op_sel_hi:[1,0]
	v_pk_mul_f32 v[114:115], v[114:115], v[148:149] op_sel_hi:[1,0]
	v_pk_mul_f32 v[120:121], v[120:121], v[148:149] op_sel_hi:[1,0]
	v_pk_mul_f32 v[118:119], v[118:119], v[148:149] op_sel_hi:[1,0]
	v_exp_f32_e32 v114, v114
	v_exp_f32_e32 v115, v115
	v_exp_f32_e32 v116, v116
	v_exp_f32_e32 v117, v117
	v_exp_f32_e32 v118, v118
	v_exp_f32_e32 v119, v119
	v_exp_f32_e32 v120, v120
	v_exp_f32_e32 v121, v121
	v_rsq_f32_e32 v153, v146
	v_pk_add_f32 v[116:117], v[116:117], 1.0 op_sel_hi:[1,0]
	v_pk_add_f32 v[114:115], v[114:115], 1.0 op_sel_hi:[1,0]
	v_pk_add_f32 v[120:121], v[120:121], 1.0 op_sel_hi:[1,0]
	v_pk_add_f32 v[118:119], v[118:119], 1.0 op_sel_hi:[1,0]
	v_rcp_f32_e32 v114, v114
	v_rcp_f32_e32 v115, v115
	v_rcp_f32_e32 v116, v116
	v_rcp_f32_e32 v117, v117
	v_mul_f32_e32 v152, 0xbfb8aa3b, v153
	v_rcp_f32_e32 v118, v118
	v_rcp_f32_e32 v119, v119
	v_rcp_f32_e32 v120, v120
	v_rcp_f32_e32 v121, v121
	v_mul_f32_e32 v150, v149, v149
	v_pk_mul_f32 v[148:149], v[112:113], v[152:153] op_sel_hi:[1,0]
	v_pk_mul_f32 v[154:155], v[110:111], v[152:153] op_sel_hi:[1,0]
	v_exp_f32_e32 v148, v148
	v_exp_f32_e32 v154, v154
	v_exp_f32_e32 v155, v155
	v_exp_f32_e32 v149, v149
	v_pk_mul_f32 v[114:115], v[150:151], v[114:115] op_sel_hi:[0,1]
	v_pk_mul_f32 v[116:117], v[150:151], v[116:117] op_sel_hi:[0,1]
	v_pk_mul_f32 v[118:119], v[150:151], v[118:119] op_sel_hi:[0,1]
	v_pk_mul_f32 v[120:121], v[150:151], v[120:121] op_sel_hi:[0,1]
	v_pk_mul_f32 v[124:125], v[124:125], v[116:117]
	v_pk_mul_f32 v[116:117], v[158:159], v[114:115]
	v_lshl_add_u64 v[146:147], v[0:1], 1, s[46:47]
	v_pk_mul_f32 v[120:121], v[128:129], v[120:121]
	v_pk_mul_f32 v[118:119], v[126:127], v[118:119]
	s_nop 0
	v_cvt_pk_bf16_f32 v114, v118, v119
	v_cvt_pk_bf16_f32 v115, v120, v121
	v_cvt_pk_bf16_f32 v116, v116, v117
	v_cvt_pk_bf16_f32 v117, v124, v125
	global_store_dwordx4 v[146:147], v[114:117], off
	v_pk_add_f32 v[118:119], v[154:155], 1.0 op_sel_hi:[1,0]
	s_nop 0
	v_pk_add_f32 v[116:117], v[148:149], 1.0 op_sel_hi:[1,0]
	v_rcp_f32_e32 v118, v118
	v_rcp_f32_e32 v119, v119
	v_rcp_f32_e32 v116, v116
	v_rcp_f32_e32 v117, v117
	v_mul_f32_e32 v114, v153, v153
	v_pk_mul_f32 v[110:111], v[114:115], v[118:119] op_sel_hi:[0,1]
	v_pk_mul_f32 v[118:119], v[102:103], v[152:153] op_sel_hi:[1,0]
	v_pk_mul_f32 v[112:113], v[114:115], v[116:117] op_sel_hi:[0,1]
	v_pk_mul_f32 v[116:117], v[104:105], v[152:153] op_sel_hi:[1,0]
	v_exp_f32_e32 v118, v118
	v_exp_f32_e32 v116, v116
	v_exp_f32_e32 v117, v117
	v_exp_f32_e32 v119, v119
	v_pk_mul_f32 v[108:109], v[108:109], v[112:113]
	v_pk_mul_f32 v[106:107], v[106:107], v[110:111]
	v_pk_add_f32 v[110:111], v[116:117], 1.0 op_sel_hi:[1,0]
	v_pk_add_f32 v[112:113], v[118:119], 1.0 op_sel_hi:[1,0]
	v_rcp_f32_e32 v110, v110
	v_rcp_f32_e32 v112, v112
	v_rcp_f32_e32 v113, v113
	v_rcp_f32_e32 v111, v111
	v_pk_mul_f32 v[102:103], v[114:115], v[112:113] op_sel_hi:[0,1]
	v_pk_mul_f32 v[104:105], v[114:115], v[110:111] op_sel_hi:[0,1]
	v_pk_mul_f32 v[104:105], v[100:101], v[104:105]
	v_pk_mul_f32 v[100:101], v[98:99], v[102:103]
	v_fmamk_f32 v102, v156, 0x3a800000, v234
	v_cvt_pk_bf16_f32 v98, v106, v107
	v_cvt_pk_bf16_f32 v99, v108, v109
	v_cvt_pk_bf16_f32 v100, v100, v101
	v_cvt_pk_bf16_f32 v101, v104, v105
	v_rsq_f32_e32 v105, v102
	v_add_u32_e32 v102, 0xb000, v0
	v_mov_b32_e32 v103, v1
	v_lshl_add_u64 v[102:103], v[102:103], 1, s[46:47]
	v_mul_f32_e32 v104, 0xbfb8aa3b, v105
	v_pk_mul_f32 v[106:107], v[96:97], v[104:105] op_sel_hi:[1,0]
	v_pk_mul_f32 v[108:109], v[94:95], v[104:105] op_sel_hi:[1,0]
	v_exp_f32_e32 v106, v106
	v_exp_f32_e32 v108, v108
	v_exp_f32_e32 v107, v107
	v_exp_f32_e32 v109, v109
	global_store_dwordx4 v[102:103], v[98:101], off
	v_pk_add_f32 v[102:103], v[108:109], 1.0 op_sel_hi:[1,0]
	s_nop 0
	v_pk_add_f32 v[100:101], v[106:107], 1.0 op_sel_hi:[1,0]
	v_rcp_f32_e32 v102, v102
	v_rcp_f32_e32 v103, v103
	v_rcp_f32_e32 v100, v100
	v_rcp_f32_e32 v101, v101
	v_mul_f32_e32 v98, v105, v105
	v_pk_mul_f32 v[94:95], v[98:99], v[102:103] op_sel_hi:[0,1]
	v_pk_mul_f32 v[102:103], v[86:87], v[104:105] op_sel_hi:[1,0]
	v_pk_mul_f32 v[96:97], v[98:99], v[100:101] op_sel_hi:[0,1]
	v_pk_mul_f32 v[100:101], v[88:89], v[104:105] op_sel_hi:[1,0]
	v_exp_f32_e32 v102, v102
	v_exp_f32_e32 v100, v100
	v_exp_f32_e32 v101, v101
	v_exp_f32_e32 v103, v103
	v_pk_mul_f32 v[92:93], v[92:93], v[96:97]
	v_pk_mul_f32 v[90:91], v[90:91], v[94:95]
	v_pk_add_f32 v[94:95], v[100:101], 1.0 op_sel_hi:[1,0]
	v_pk_add_f32 v[96:97], v[102:103], 1.0 op_sel_hi:[1,0]
	v_rcp_f32_e32 v94, v94
	v_rcp_f32_e32 v96, v96
	v_rcp_f32_e32 v97, v97
	v_rcp_f32_e32 v95, v95
	v_pk_mul_f32 v[86:87], v[98:99], v[96:97] op_sel_hi:[0,1]
	v_pk_mul_f32 v[88:89], v[98:99], v[94:95] op_sel_hi:[0,1]
	v_pk_mul_f32 v[88:89], v[84:85], v[88:89]
	v_pk_mul_f32 v[84:85], v[82:83], v[86:87]
	v_fmamk_f32 v86, v157, 0x3a800000, v234
	v_cvt_pk_bf16_f32 v82, v90, v91
	v_cvt_pk_bf16_f32 v83, v92, v93
	v_cvt_pk_bf16_f32 v84, v84, v85
	v_cvt_pk_bf16_f32 v85, v88, v89
	v_rsq_f32_e32 v89, v86
	v_add_u32_e32 v86, 0x16000, v0
	v_mov_b32_e32 v87, v1
	v_lshl_add_u64 v[86:87], v[86:87], 1, s[46:47]
	v_mul_f32_e32 v88, 0xbfb8aa3b, v89
	v_pk_mul_f32 v[90:91], v[80:81], v[88:89] op_sel_hi:[1,0]
	v_pk_mul_f32 v[92:93], v[78:79], v[88:89] op_sel_hi:[1,0]
	v_exp_f32_e32 v90, v90
	v_exp_f32_e32 v92, v92
	v_exp_f32_e32 v91, v91
	v_exp_f32_e32 v93, v93
	global_store_dwordx4 v[86:87], v[82:85], off
	v_pk_add_f32 v[86:87], v[92:93], 1.0 op_sel_hi:[1,0]
	s_nop 0
	v_pk_add_f32 v[84:85], v[90:91], 1.0 op_sel_hi:[1,0]
	v_rcp_f32_e32 v86, v86
	v_rcp_f32_e32 v87, v87
	v_rcp_f32_e32 v84, v84
	v_rcp_f32_e32 v85, v85
	v_mul_f32_e32 v82, v89, v89
	v_pk_mul_f32 v[78:79], v[82:83], v[86:87] op_sel_hi:[0,1]
	v_pk_mul_f32 v[86:87], v[70:71], v[88:89] op_sel_hi:[1,0]
	v_pk_mul_f32 v[80:81], v[82:83], v[84:85] op_sel_hi:[0,1]
	v_pk_mul_f32 v[84:85], v[72:73], v[88:89] op_sel_hi:[1,0]
	v_exp_f32_e32 v86, v86
	v_exp_f32_e32 v84, v84
	v_exp_f32_e32 v85, v85
	v_exp_f32_e32 v87, v87
	v_pk_mul_f32 v[76:77], v[76:77], v[80:81]
	v_pk_mul_f32 v[74:75], v[74:75], v[78:79]
	v_pk_add_f32 v[78:79], v[84:85], 1.0 op_sel_hi:[1,0]
	v_pk_add_f32 v[80:81], v[86:87], 1.0 op_sel_hi:[1,0]
	v_rcp_f32_e32 v78, v78
	v_rcp_f32_e32 v80, v80
	v_rcp_f32_e32 v81, v81
	v_rcp_f32_e32 v79, v79
	v_pk_mul_f32 v[70:71], v[82:83], v[80:81] op_sel_hi:[0,1]
	v_pk_mul_f32 v[72:73], v[82:83], v[78:79] op_sel_hi:[0,1]
	v_pk_mul_f32 v[72:73], v[68:69], v[72:73]
	v_pk_mul_f32 v[68:69], v[66:67], v[70:71]
	v_fmamk_f32 v70, v162, 0x3a800000, v234
	v_cvt_pk_bf16_f32 v66, v74, v75
	v_cvt_pk_bf16_f32 v67, v76, v77
	v_cvt_pk_bf16_f32 v68, v68, v69
	v_cvt_pk_bf16_f32 v69, v72, v73
	v_rsq_f32_e32 v73, v70
	v_add_u32_e32 v70, 0x21000, v0
	v_mov_b32_e32 v71, v1
	v_lshl_add_u64 v[70:71], v[70:71], 1, s[46:47]
	v_mul_f32_e32 v72, 0xbfb8aa3b, v73
	v_pk_mul_f32 v[74:75], v[64:65], v[72:73] op_sel_hi:[1,0]
	v_pk_mul_f32 v[76:77], v[62:63], v[72:73] op_sel_hi:[1,0]
	v_exp_f32_e32 v74, v74
	v_exp_f32_e32 v76, v76
	v_exp_f32_e32 v75, v75
	v_exp_f32_e32 v77, v77
	global_store_dwordx4 v[70:71], v[66:69], off
	v_pk_add_f32 v[70:71], v[76:77], 1.0 op_sel_hi:[1,0]
	s_nop 0
	v_pk_add_f32 v[68:69], v[74:75], 1.0 op_sel_hi:[1,0]
	v_rcp_f32_e32 v70, v70
	v_rcp_f32_e32 v71, v71
	v_rcp_f32_e32 v68, v68
	v_rcp_f32_e32 v69, v69
	v_mul_f32_e32 v66, v73, v73
	v_pk_mul_f32 v[62:63], v[66:67], v[70:71] op_sel_hi:[0,1]
	v_pk_mul_f32 v[70:71], v[54:55], v[72:73] op_sel_hi:[1,0]
	v_pk_mul_f32 v[64:65], v[66:67], v[68:69] op_sel_hi:[0,1]
	v_pk_mul_f32 v[68:69], v[56:57], v[72:73] op_sel_hi:[1,0]
	v_exp_f32_e32 v70, v70
	v_exp_f32_e32 v68, v68
	v_exp_f32_e32 v69, v69
	v_exp_f32_e32 v71, v71
	v_pk_mul_f32 v[60:61], v[60:61], v[64:65]
	v_pk_mul_f32 v[58:59], v[58:59], v[62:63]
	v_pk_add_f32 v[62:63], v[68:69], 1.0 op_sel_hi:[1,0]
	v_pk_add_f32 v[64:65], v[70:71], 1.0 op_sel_hi:[1,0]
	v_rcp_f32_e32 v62, v62
	v_rcp_f32_e32 v64, v64
	v_rcp_f32_e32 v65, v65
	v_rcp_f32_e32 v63, v63
	v_pk_mul_f32 v[54:55], v[66:67], v[64:65] op_sel_hi:[0,1]
	v_pk_mul_f32 v[56:57], v[66:67], v[62:63] op_sel_hi:[0,1]
	v_pk_mul_f32 v[56:57], v[52:53], v[56:57]
	v_pk_mul_f32 v[52:53], v[50:51], v[54:55]
	v_fmamk_f32 v54, v151, 0x3a800000, v234
	v_cvt_pk_bf16_f32 v50, v58, v59
	v_cvt_pk_bf16_f32 v51, v60, v61
	v_cvt_pk_bf16_f32 v52, v52, v53
	v_cvt_pk_bf16_f32 v53, v56, v57
	v_rsq_f32_e32 v57, v54
	v_add_u32_e32 v54, 0x58000, v0
	v_mov_b32_e32 v55, v1
	v_lshl_add_u64 v[54:55], v[54:55], 1, s[46:47]
	v_mul_f32_e32 v56, 0xbfb8aa3b, v57
	v_pk_mul_f32 v[58:59], v[48:49], v[56:57] op_sel_hi:[1,0]
	v_pk_mul_f32 v[60:61], v[46:47], v[56:57] op_sel_hi:[1,0]
	v_exp_f32_e32 v58, v58
	v_exp_f32_e32 v60, v60
	v_exp_f32_e32 v59, v59
	v_exp_f32_e32 v61, v61
	global_store_dwordx4 v[54:55], v[50:53], off
	v_pk_add_f32 v[54:55], v[60:61], 1.0 op_sel_hi:[1,0]
	s_nop 0
	v_pk_add_f32 v[52:53], v[58:59], 1.0 op_sel_hi:[1,0]
	v_rcp_f32_e32 v54, v54
	v_rcp_f32_e32 v55, v55
	v_rcp_f32_e32 v52, v52
	v_rcp_f32_e32 v53, v53
	v_mul_f32_e32 v50, v57, v57
	v_pk_mul_f32 v[46:47], v[50:51], v[54:55] op_sel_hi:[0,1]
	v_pk_mul_f32 v[54:55], v[38:39], v[56:57] op_sel_hi:[1,0]
	v_pk_mul_f32 v[48:49], v[50:51], v[52:53] op_sel_hi:[0,1]
	v_pk_mul_f32 v[52:53], v[40:41], v[56:57] op_sel_hi:[1,0]
	v_exp_f32_e32 v54, v54
	v_exp_f32_e32 v52, v52
	v_exp_f32_e32 v53, v53
	v_exp_f32_e32 v55, v55
	v_pk_mul_f32 v[44:45], v[44:45], v[48:49]
	v_pk_mul_f32 v[42:43], v[42:43], v[46:47]
	v_pk_add_f32 v[46:47], v[52:53], 1.0 op_sel_hi:[1,0]
	v_pk_add_f32 v[48:49], v[54:55], 1.0 op_sel_hi:[1,0]
	v_rcp_f32_e32 v46, v46
	v_rcp_f32_e32 v48, v48
	v_rcp_f32_e32 v49, v49
	v_rcp_f32_e32 v47, v47
	v_pk_mul_f32 v[38:39], v[50:51], v[48:49] op_sel_hi:[0,1]
	v_pk_mul_f32 v[40:41], v[50:51], v[46:47] op_sel_hi:[0,1]
	v_pk_mul_f32 v[40:41], v[36:37], v[40:41]
	v_pk_mul_f32 v[36:37], v[34:35], v[38:39]
	v_fmamk_f32 v38, v123, 0x3a800000, v234
	v_cvt_pk_bf16_f32 v34, v42, v43
	v_cvt_pk_bf16_f32 v35, v44, v45
	v_cvt_pk_bf16_f32 v36, v36, v37
	v_cvt_pk_bf16_f32 v37, v40, v41
	v_rsq_f32_e32 v41, v38
	v_add_u32_e32 v38, 0x63000, v0
	v_mov_b32_e32 v39, v1
	v_lshl_add_u64 v[38:39], v[38:39], 1, s[46:47]
	v_mul_f32_e32 v40, 0xbfb8aa3b, v41
	v_pk_mul_f32 v[42:43], v[32:33], v[40:41] op_sel_hi:[1,0]
	v_pk_mul_f32 v[44:45], v[30:31], v[40:41] op_sel_hi:[1,0]
	v_exp_f32_e32 v42, v42
	v_exp_f32_e32 v44, v44
	v_exp_f32_e32 v43, v43
	v_exp_f32_e32 v45, v45
	global_store_dwordx4 v[38:39], v[34:37], off
	v_pk_add_f32 v[38:39], v[44:45], 1.0 op_sel_hi:[1,0]
	s_nop 0
	v_pk_add_f32 v[36:37], v[42:43], 1.0 op_sel_hi:[1,0]
	v_rcp_f32_e32 v38, v38
	v_rcp_f32_e32 v39, v39
	v_rcp_f32_e32 v36, v36
	v_rcp_f32_e32 v37, v37
	v_mul_f32_e32 v34, v41, v41
	v_pk_mul_f32 v[30:31], v[34:35], v[38:39] op_sel_hi:[0,1]
	v_pk_mul_f32 v[38:39], v[22:23], v[40:41] op_sel_hi:[1,0]
	v_pk_mul_f32 v[32:33], v[34:35], v[36:37] op_sel_hi:[0,1]
	v_pk_mul_f32 v[36:37], v[24:25], v[40:41] op_sel_hi:[1,0]
	v_exp_f32_e32 v38, v38
	v_exp_f32_e32 v36, v36
	v_exp_f32_e32 v37, v37
	v_exp_f32_e32 v39, v39
	v_pk_mul_f32 v[28:29], v[28:29], v[32:33]
	v_pk_mul_f32 v[26:27], v[26:27], v[30:31]
	v_pk_add_f32 v[30:31], v[36:37], 1.0 op_sel_hi:[1,0]
	v_pk_add_f32 v[32:33], v[38:39], 1.0 op_sel_hi:[1,0]
	v_rcp_f32_e32 v30, v30
	v_rcp_f32_e32 v32, v32
	v_rcp_f32_e32 v33, v33
	v_rcp_f32_e32 v31, v31
	v_pk_mul_f32 v[22:23], v[34:35], v[32:33] op_sel_hi:[0,1]
	v_pk_mul_f32 v[24:25], v[34:35], v[30:31] op_sel_hi:[0,1]
	v_pk_mul_f32 v[24:25], v[20:21], v[24:25]
	v_pk_mul_f32 v[20:21], v[18:19], v[22:23]
	v_fmamk_f32 v22, v122, 0x3a800000, v234
	v_cvt_pk_bf16_f32 v18, v26, v27
	v_cvt_pk_bf16_f32 v19, v28, v29
	v_cvt_pk_bf16_f32 v20, v20, v21
	v_cvt_pk_bf16_f32 v21, v24, v25
	v_rsq_f32_e32 v25, v22
	v_add_u32_e32 v22, 0x6e000, v0
	v_mov_b32_e32 v23, v1
	v_lshl_add_u64 v[22:23], v[22:23], 1, s[46:47]
	v_mul_f32_e32 v24, 0xbfb8aa3b, v25
	v_pk_mul_f32 v[26:27], v[16:17], v[24:25] op_sel_hi:[1,0]
	v_pk_mul_f32 v[28:29], v[14:15], v[24:25] op_sel_hi:[1,0]
	v_exp_f32_e32 v26, v26
	v_exp_f32_e32 v28, v28
	v_exp_f32_e32 v27, v27
	v_exp_f32_e32 v29, v29
	global_store_dwordx4 v[22:23], v[18:21], off
	v_add_u32_e32 v0, 0x79000, v0
	v_pk_add_f32 v[22:23], v[28:29], 1.0 op_sel_hi:[1,0]
	v_pk_add_f32 v[20:21], v[26:27], 1.0 op_sel_hi:[1,0]
	v_rcp_f32_e32 v22, v22
	v_rcp_f32_e32 v23, v23
	v_rcp_f32_e32 v20, v20
	v_rcp_f32_e32 v21, v21
	v_mul_f32_e32 v18, v25, v25
	v_pk_mul_f32 v[14:15], v[18:19], v[22:23] op_sel_hi:[0,1]
	v_pk_mul_f32 v[22:23], v[6:7], v[24:25] op_sel_hi:[1,0]
	v_pk_mul_f32 v[16:17], v[18:19], v[20:21] op_sel_hi:[0,1]
	v_pk_mul_f32 v[20:21], v[8:9], v[24:25] op_sel_hi:[1,0]
	v_exp_f32_e32 v22, v22
	v_exp_f32_e32 v20, v20
	v_exp_f32_e32 v21, v21
	v_exp_f32_e32 v23, v23
	v_pk_mul_f32 v[12:13], v[12:13], v[16:17]
	v_pk_mul_f32 v[10:11], v[10:11], v[14:15]
	v_pk_add_f32 v[14:15], v[20:21], 1.0 op_sel_hi:[1,0]
	v_pk_add_f32 v[16:17], v[22:23], 1.0 op_sel_hi:[1,0]
	v_rcp_f32_e32 v14, v14
	v_rcp_f32_e32 v16, v16
	v_rcp_f32_e32 v17, v17
	v_rcp_f32_e32 v15, v15
	v_pk_mul_f32 v[6:7], v[18:19], v[16:17] op_sel_hi:[0,1]
	v_pk_mul_f32 v[8:9], v[18:19], v[14:15] op_sel_hi:[0,1]
	v_pk_mul_f32 v[8:9], v[4:5], v[8:9]
	v_pk_mul_f32 v[4:5], v[2:3], v[6:7]
	v_lshl_add_u64 v[6:7], v[0:1], 1, s[46:47]
	v_cvt_pk_bf16_f32 v2, v10, v11
	v_cvt_pk_bf16_f32 v3, v12, v13
	v_cvt_pk_bf16_f32 v4, v4, v5
	v_cvt_pk_bf16_f32 v5, v8, v9
	global_store_dwordx4 v[6:7], v[2:5], off
	s_cbranch_vccnz .LBB0_225
	s_mov_b32 s63, 0
	s_andn2_b64 vcc, exec, s[0:1]
	s_cbranch_vccnz .LBB0_224
	s_mov_b32 s63, 1
	s_branch .LBB0_224

.LBB0_306:
	v_readlane_b32 s48, v251, 25
	v_bfe_u32 v199, v13, 4, 2
	s_lshl_b32 s1, s1, 5
	v_mov_b32_e32 v211, v1
	v_readlane_b32 s49, v251, 26
	v_and_b32_e32 v218, 15, v13
	v_lshlrev_b32_e32 v18, 4, v199
	v_lshlrev_b32_e32 v13, 2, v13
	s_and_b32 s62, s1, 0x60
	s_add_i32 m0, s57, 0x18000
	v_lshl_add_u64 v[2:3], v[2:3], 0, s[16:17]
	v_lshl_add_u64 v[14:15], s[48:49], 0, v[210:211]
	v_mov_b32_e32 v207, v1
	s_lshl_b32 s61, s4, 6
	v_lshl_or_b32 v18, v218, 6, v18
	s_lshl_b32 s4, s4, 13
	v_and_b32_e32 v13, 32, v13
	s_lshl_b32 s1, s62, 7
	s_waitcnt vmcnt(2)
	s_barrier
	global_load_lds_dwordx4 v[2:3], off
	v_lshl_add_u64 v[2:3], v[4:5], 0, s[16:17]
	s_add_i32 m0, s57, 0x1a000
	s_add_i32 s63, s57, 0x8000
	s_add_i32 s64, s57, 0xa000
	v_lshl_add_u64 v[16:17], s[48:49], 0, v[206:207]
	v_bitop3_b32 v19, v18, s4, v13 bitop3:0xde
	global_load_lds_dwordx4 v[2:3], off
	v_lshl_add_u64 v[2:3], v[14:15], 0, s[16:17]
	s_mov_b32 m0, s63
	s_add_u32 s4, s52, 0xb0080
	global_load_lds_dwordx4 v[2:3], off
	v_lshl_add_u64 v[2:3], v[16:17], 0, s[16:17]
	s_mov_b32 m0, s64
	s_addc_u32 s5, s53, 0
	global_load_lds_dwordx4 v[2:3], off
	s_add_i32 m0, s57, 0x1c000
	v_lshl_add_u64 v[2:3], s[4:5], 0, v[208:209]
	global_load_lds_dwordx4 v[2:3], off
	v_lshl_add_u64 v[2:3], s[4:5], 0, v[204:205]
	s_add_i32 m0, s57, 0x1e000
	s_movk_i32 s4, 0xb00
	global_load_lds_dwordx4 v[2:3], off
	v_lshrrev_b32_e32 v2, 1, v10
	v_mul_lo_u32 v0, v0, s4
	s_mov_b32 s5, 0xb000
	v_bitop3_b32 v219, v18, s1, v13 bitop3:0xde
	s_cmpk_lt_u32 s0, 0x100
	v_mad_u64_u32 v[2:3], s[0:1], v2, s5, v[0:1]
	v_or_b32_e32 v0, v2, v11
	v_add_lshl_u32 v0, v0, v12, 1
	s_mov_b64 s[6:7], 0xb0080
	v_lshl_add_u64 v[212:213], v[0:1], 0, s[6:7]
	v_lshrrev_b32_e32 v2, 1, v6
	v_mul_lo_u32 v0, v7, s4
	v_mad_u64_u32 v[2:3], s[0:1], v2, s5, v[0:1]
	s_waitcnt vmcnt(6)
	v_or_b32_e32 v0, v2, v8
	v_add_lshl_u32 v0, v0, v9, 1
	s_cselect_b64 s[40:41], -1, 0
	v_lshl_add_u64 v[214:215], v[0:1], 0, s[6:7]
	s_mov_b32 s65, 0
	v_add_u32_e32 v220, 0, v19
	v_readlane_b32 s6, v251, 63
	v_readlane_b32 s50, v251, 23
	s_barrier
	v_readlane_b32 s51, v251, 24
	s_mov_b32 s51, 0
	s_branch .LBB0_309

.LBB0_319:
	s_add_u32 s7, s52, 0x100
	s_addc_u32 s18, s53, 0
	s_mov_b32 s19, -2
	s_waitcnt lgkmcnt(0)
	s_waitcnt vmcnt(0)
	s_cmp_eq_u32 s51, 0
	s_cbranch_scc1 .Lrb1_skip
	s_barrier
.Lrb1_skip:
	s_add_u32 s0, s48, 0x100
	s_addc_u32 s1, s49, 0
	s_add_i32 s51, 0, 0x10000
	s_cmp_eq_u32 s19, 40
	s_cselect_b32 s55, s45, s1
	s_cselect_b32 s54, s44, s0
	v_add_u32_e32 v0, s51, v219
	s_cselect_b32 s53, s47, s18
	s_cselect_b32 s52, s46, s7
	s_add_i32 s66, 0, 0x14000
	ds_read_b128 v[106:109], v0
	ds_read_b128 v[110:113], v0 offset:1024
	ds_read_b128 v[126:129], v0 offset:2048
	ds_read_b128 v[134:137], v0 offset:3072
	v_add_u32_e32 v0, s66, v219
	ds_read_b128 v[146:149], v0
	ds_read_b128 v[150:153], v0 offset:1024
	ds_read_b128 v[154:157], v0 offset:2048
	ds_read_b128 v[158:161], v0 offset:3072
	v_lshl_add_u64 v[216:217], s[48:49], 0, v[212:213]
	s_add_i32 m0, s57, 0xc000
	ds_read_b128 v[162:165], v220
	ds_read_b128 v[166:169], v220 offset:1024
	ds_read_b128 v[170:173], v220 offset:2048
	ds_read_b128 v[174:177], v220 offset:3072
	ds_read_b128 v[178:181], v220 offset:4096
	ds_read_b128 v[182:185], v220 offset:5120
	ds_read_b128 v[222:225], v220 offset:6144
	ds_read_b128 v[226:229], v220 offset:7168
	global_load_lds_dwordx4 v[216:217], off
	v_lshl_add_u64 v[216:217], s[48:49], 0, v[214:215]
	s_add_i32 m0, s57, 0xe000
	s_nop 0
	global_load_lds_dwordx4 v[216:217], off
	s_waitcnt vmcnt(8)
	s_waitcnt lgkmcnt(0)
	s_setprio 1
	s_barrier
	v_mfma_f32_16x16x32_bf16 v[142:145], v[106:109], v[162:165], 0
	v_mfma_f32_16x16x32_bf16 v[138:141], v[126:129], v[162:165], 0
	v_mfma_f32_16x16x32_bf16 v[118:121], v[106:109], v[170:173], 0
	v_mfma_f32_16x16x32_bf16 v[114:117], v[126:129], v[170:173], 0
	v_mfma_f32_16x16x32_bf16 v[94:97], v[106:109], v[178:181], 0
	v_mfma_f32_16x16x32_bf16 v[90:93], v[126:129], v[178:181], 0
	v_mfma_f32_16x16x32_bf16 v[78:81], v[106:109], v[222:225], 0
	v_mfma_f32_16x16x32_bf16 v[74:77], v[126:129], v[222:225], 0
	v_mfma_f32_16x16x32_bf16 v[142:145], v[110:113], v[166:169], v[142:145]
	v_mfma_f32_16x16x32_bf16 v[138:141], v[134:137], v[166:169], v[138:141]
	v_mfma_f32_16x16x32_bf16 v[118:121], v[110:113], v[174:177], v[118:121]
	v_mfma_f32_16x16x32_bf16 v[114:117], v[134:137], v[174:177], v[114:117]
	v_mfma_f32_16x16x32_bf16 v[94:97], v[110:113], v[182:185], v[94:97]
	v_mfma_f32_16x16x32_bf16 v[90:93], v[134:137], v[182:185], v[90:93]
	v_mfma_f32_16x16x32_bf16 v[78:81], v[110:113], v[226:229], v[78:81]
	v_mfma_f32_16x16x32_bf16 v[74:77], v[134:137], v[226:229], v[74:77]
	v_mfma_f32_16x16x32_bf16 v[130:133], v[146:149], v[162:165], 0
	v_mfma_f32_16x16x32_bf16 v[122:125], v[154:157], v[162:165], 0
	v_mfma_f32_16x16x32_bf16 v[102:105], v[146:149], v[170:173], 0
	v_mfma_f32_16x16x32_bf16 v[98:101], v[154:157], v[170:173], 0
	v_mfma_f32_16x16x32_bf16 v[86:89], v[146:149], v[178:181], 0
	v_mfma_f32_16x16x32_bf16 v[82:85], v[154:157], v[178:181], 0
	v_mfma_f32_16x16x32_bf16 v[70:73], v[146:149], v[222:225], 0
	v_mfma_f32_16x16x32_bf16 v[66:69], v[154:157], v[222:225], 0
	v_mfma_f32_16x16x32_bf16 v[130:133], v[150:153], v[166:169], v[130:133]
	v_mfma_f32_16x16x32_bf16 v[122:125], v[158:161], v[166:169], v[122:125]
	v_mfma_f32_16x16x32_bf16 v[102:105], v[150:153], v[174:177], v[102:105]
	v_mfma_f32_16x16x32_bf16 v[98:101], v[158:161], v[174:177], v[98:101]
	v_mfma_f32_16x16x32_bf16 v[86:89], v[150:153], v[182:185], v[86:89]
	v_mfma_f32_16x16x32_bf16 v[82:85], v[158:161], v[182:185], v[82:85]
	v_mfma_f32_16x16x32_bf16 v[70:73], v[150:153], v[226:229], v[70:73]
	v_mfma_f32_16x16x32_bf16 v[66:69], v[158:161], v[226:229], v[66:69]
	s_barrier
	s_setprio 0
	s_add_i32 s48, s51, s56
	v_lshl_add_u64 v[216:217], s[52:53], 0, v[208:209]
	s_mov_b32 m0, s48
	ds_read_b128 v[162:165], v220 offset:16384
	ds_read_b128 v[166:169], v220 offset:17408
	ds_read_b128 v[170:173], v220 offset:18432
	ds_read_b128 v[174:177], v220 offset:19456
	ds_read_b128 v[178:181], v220 offset:20480
	ds_read_b128 v[182:185], v220 offset:21504
	ds_read_b128 v[222:225], v220 offset:22528
	ds_read_b128 v[226:229], v220 offset:23552
	global_load_lds_dwordx4 v[216:217], off
	s_add_i32 m0, s48, 0x2000
	s_add_u32 s48, s52, 0xb0000
	v_lshl_add_u64 v[230:231], s[52:53], 0, v[204:205]
	s_addc_u32 s49, s53, 0
	s_add_i32 s51, s66, s56
	global_load_lds_dwordx4 v[230:231], off
	v_lshl_add_u64 v[240:241], s[48:49], 0, v[208:209]
	s_mov_b32 m0, s51
	v_lshl_add_u64 v[242:243], s[54:55], 0, v[206:207]
	global_load_lds_dwordx4 v[240:241], off
	v_lshl_add_u64 v[240:241], s[48:49], 0, v[204:205]
	s_add_i32 m0, s51, 0x2000
	s_nop 0
	global_load_lds_dwordx4 v[240:241], off
	v_lshl_add_u64 v[240:241], s[54:55], 0, v[210:211]
	s_mov_b32 m0, s57
	s_nop 0
	global_load_lds_dwordx4 v[240:241], off
	s_mov_b32 m0, s58
	s_nop 0
	global_load_lds_dwordx4 v[242:243], off
	s_waitcnt vmcnt(8)
	s_waitcnt lgkmcnt(0)
	s_setprio 1
	s_barrier
	v_mfma_f32_16x16x32_bf16 v[62:65], v[106:109], v[162:165], 0
	v_mfma_f32_16x16x32_bf16 v[58:61], v[126:129], v[162:165], 0
	v_mfma_f32_16x16x32_bf16 v[46:49], v[106:109], v[170:173], 0
	v_mfma_f32_16x16x32_bf16 v[42:45], v[126:129], v[170:173], 0
	v_mfma_f32_16x16x32_bf16 v[30:33], v[106:109], v[178:181], 0
	v_mfma_f32_16x16x32_bf16 v[26:29], v[126:129], v[178:181], 0
	v_mfma_f32_16x16x32_bf16 v[14:17], v[106:109], v[222:225], 0
	v_mfma_f32_16x16x32_bf16 v[10:13], v[126:129], v[222:225], 0
	v_mfma_f32_16x16x32_bf16 v[62:65], v[110:113], v[166:169], v[62:65]
	v_mfma_f32_16x16x32_bf16 v[58:61], v[134:137], v[166:169], v[58:61]
	v_mfma_f32_16x16x32_bf16 v[46:49], v[110:113], v[174:177], v[46:49]
	v_mfma_f32_16x16x32_bf16 v[42:45], v[134:137], v[174:177], v[42:45]
	v_mfma_f32_16x16x32_bf16 v[30:33], v[110:113], v[182:185], v[30:33]
	v_mfma_f32_16x16x32_bf16 v[26:29], v[134:137], v[182:185], v[26:29]
	v_mfma_f32_16x16x32_bf16 v[14:17], v[110:113], v[226:229], v[14:17]
	v_mfma_f32_16x16x32_bf16 v[10:13], v[134:137], v[226:229], v[10:13]
	v_mfma_f32_16x16x32_bf16 v[54:57], v[146:149], v[162:165], 0
	v_mfma_f32_16x16x32_bf16 v[50:53], v[154:157], v[162:165], 0
	v_mfma_f32_16x16x32_bf16 v[38:41], v[146:149], v[170:173], 0
	v_mfma_f32_16x16x32_bf16 v[34:37], v[154:157], v[170:173], 0
	v_mfma_f32_16x16x32_bf16 v[22:25], v[146:149], v[178:181], 0
	v_mfma_f32_16x16x32_bf16 v[18:21], v[154:157], v[178:181], 0
	v_mfma_f32_16x16x32_bf16 v[6:9], v[146:149], v[222:225], 0
	v_mfma_f32_16x16x32_bf16 v[2:5], v[154:157], v[222:225], 0
	v_mfma_f32_16x16x32_bf16 v[54:57], v[150:153], v[166:169], v[54:57]
	v_mfma_f32_16x16x32_bf16 v[50:53], v[158:161], v[166:169], v[50:53]
	v_mfma_f32_16x16x32_bf16 v[38:41], v[150:153], v[174:177], v[38:41]
	v_mfma_f32_16x16x32_bf16 v[34:37], v[158:161], v[174:177], v[34:37]
	v_mfma_f32_16x16x32_bf16 v[22:25], v[150:153], v[182:185], v[22:25]
	v_mfma_f32_16x16x32_bf16 v[18:21], v[158:161], v[182:185], v[18:21]
	v_mfma_f32_16x16x32_bf16 v[6:9], v[150:153], v[226:229], v[6:9]
	v_mfma_f32_16x16x32_bf16 v[2:5], v[158:161], v[226:229], v[2:5]
	s_barrier
	s_setprio 0
	s_add_i32 s51, 0, 0x18000
	v_add_u32_e32 v0, s51, v219
	s_add_i32 s66, 0, 0x1c000
	ds_read_b128 v[106:109], v0
	ds_read_b128 v[110:113], v0 offset:1024
	ds_read_b128 v[126:129], v0 offset:2048
	ds_read_b128 v[134:137], v0 offset:3072
	v_add_u32_e32 v0, s66, v219
	ds_read_b128 v[146:149], v0
	ds_read_b128 v[150:153], v0 offset:1024
	ds_read_b128 v[154:157], v0 offset:2048
	ds_read_b128 v[158:161], v0 offset:3072
	s_add_u32 s48, s54, 0xb0000
	s_addc_u32 s49, s55, 0
	s_mov_b32 m0, s59
	v_lshl_add_u64 v[244:245], s[48:49], 0, v[210:211]
	ds_read_b128 v[162:165], v220 offset:32768
	ds_read_b128 v[166:169], v220 offset:33792
	ds_read_b128 v[170:173], v220 offset:34816
	ds_read_b128 v[174:177], v220 offset:35840
	ds_read_b128 v[178:181], v220 offset:36864
	ds_read_b128 v[182:185], v220 offset:37888
	ds_read_b128 v[222:225], v220 offset:38912
	ds_read_b128 v[226:229], v220 offset:39936
	global_load_lds_dwordx4 v[244:245], off
	v_lshl_add_u64 v[244:245], s[48:49], 0, v[206:207]
	s_mov_b32 m0, s60
	s_nop 0
	global_load_lds_dwordx4 v[244:245], off
	s_waitcnt vmcnt(8)
	s_waitcnt lgkmcnt(0)
	s_setprio 1
	s_barrier
	v_mfma_f32_16x16x32_bf16 v[142:145], v[106:109], v[162:165], v[142:145]
	v_mfma_f32_16x16x32_bf16 v[138:141], v[126:129], v[162:165], v[138:141]
	v_mfma_f32_16x16x32_bf16 v[118:121], v[106:109], v[170:173], v[118:121]
	v_mfma_f32_16x16x32_bf16 v[114:117], v[126:129], v[170:173], v[114:117]
	v_mfma_f32_16x16x32_bf16 v[94:97], v[106:109], v[178:181], v[94:97]
	v_mfma_f32_16x16x32_bf16 v[90:93], v[126:129], v[178:181], v[90:93]
	v_mfma_f32_16x16x32_bf16 v[78:81], v[106:109], v[222:225], v[78:81]
	v_mfma_f32_16x16x32_bf16 v[74:77], v[126:129], v[222:225], v[74:77]
	v_mfma_f32_16x16x32_bf16 v[142:145], v[110:113], v[166:169], v[142:145]
	v_mfma_f32_16x16x32_bf16 v[138:141], v[134:137], v[166:169], v[138:141]
	v_mfma_f32_16x16x32_bf16 v[118:121], v[110:113], v[174:177], v[118:121]
	v_mfma_f32_16x16x32_bf16 v[114:117], v[134:137], v[174:177], v[114:117]
	v_mfma_f32_16x16x32_bf16 v[94:97], v[110:113], v[182:185], v[94:97]
	v_mfma_f32_16x16x32_bf16 v[90:93], v[134:137], v[182:185], v[90:93]
	v_mfma_f32_16x16x32_bf16 v[78:81], v[110:113], v[226:229], v[78:81]
	v_mfma_f32_16x16x32_bf16 v[74:77], v[134:137], v[226:229], v[74:77]
	v_mfma_f32_16x16x32_bf16 v[130:133], v[146:149], v[162:165], v[130:133]
	v_mfma_f32_16x16x32_bf16 v[122:125], v[154:157], v[162:165], v[122:125]
	v_mfma_f32_16x16x32_bf16 v[102:105], v[146:149], v[170:173], v[102:105]
	v_mfma_f32_16x16x32_bf16 v[98:101], v[154:157], v[170:173], v[98:101]
	v_mfma_f32_16x16x32_bf16 v[86:89], v[146:149], v[178:181], v[86:89]
	v_mfma_f32_16x16x32_bf16 v[82:85], v[154:157], v[178:181], v[82:85]
	v_mfma_f32_16x16x32_bf16 v[70:73], v[146:149], v[222:225], v[70:73]
	v_mfma_f32_16x16x32_bf16 v[66:69], v[154:157], v[222:225], v[66:69]
	v_mfma_f32_16x16x32_bf16 v[130:133], v[150:153], v[166:169], v[130:133]
	v_mfma_f32_16x16x32_bf16 v[122:125], v[158:161], v[166:169], v[122:125]
	v_mfma_f32_16x16x32_bf16 v[102:105], v[150:153], v[174:177], v[102:105]
	v_mfma_f32_16x16x32_bf16 v[98:101], v[158:161], v[174:177], v[98:101]
	v_mfma_f32_16x16x32_bf16 v[86:89], v[150:153], v[182:185], v[86:89]
	v_mfma_f32_16x16x32_bf16 v[82:85], v[158:161], v[182:185], v[82:85]
	v_mfma_f32_16x16x32_bf16 v[70:73], v[150:153], v[226:229], v[70:73]
	v_mfma_f32_16x16x32_bf16 v[66:69], v[158:161], v[226:229], v[66:69]
	s_barrier
	s_setprio 0
	s_add_i32 s48, s51, s56
	v_lshl_add_u64 v[216:217], v[216:217], 0, s[16:17]
	s_mov_b32 m0, s48
	ds_read_b128 v[162:165], v220 offset:49152
	ds_read_b128 v[166:169], v220 offset:50176
	ds_read_b128 v[170:173], v220 offset:51200
	ds_read_b128 v[174:177], v220 offset:52224
	ds_read_b128 v[178:181], v220 offset:53248
	ds_read_b128 v[182:185], v220 offset:54272
	ds_read_b128 v[222:225], v220 offset:55296
	ds_read_b128 v[226:229], v220 offset:56320
	global_load_lds_dwordx4 v[216:217], off
	s_add_i32 m0, s48, 0x2000
	s_add_u32 s48, s52, 0xb0080
	v_lshl_add_u64 v[216:217], v[230:231], 0, s[16:17]
	s_addc_u32 s49, s53, 0
	s_add_i32 s51, s66, s56
	global_load_lds_dwordx4 v[216:217], off
	v_lshl_add_u64 v[216:217], s[48:49], 0, v[208:209]
	s_mov_b32 m0, s51
	s_nop 0
	global_load_lds_dwordx4 v[216:217], off
	v_lshl_add_u64 v[216:217], s[48:49], 0, v[204:205]
	s_add_i32 m0, s51, 0x2000
	s_nop 0
	global_load_lds_dwordx4 v[216:217], off
	v_lshl_add_u64 v[216:217], v[240:241], 0, s[16:17]
	s_mov_b32 m0, s63
	s_nop 0
	global_load_lds_dwordx4 v[216:217], off
	v_lshl_add_u64 v[216:217], v[242:243], 0, s[16:17]
	s_mov_b32 m0, s64
	s_nop 0
	global_load_lds_dwordx4 v[216:217], off
	s_waitcnt vmcnt(8)
	s_waitcnt lgkmcnt(0)
	s_setprio 1
	s_barrier
	v_mfma_f32_16x16x32_bf16 v[62:65], v[106:109], v[162:165], v[62:65]
	v_mfma_f32_16x16x32_bf16 v[58:61], v[126:129], v[162:165], v[58:61]
	v_mfma_f32_16x16x32_bf16 v[46:49], v[106:109], v[170:173], v[46:49]
	v_mfma_f32_16x16x32_bf16 v[42:45], v[126:129], v[170:173], v[42:45]
	v_mfma_f32_16x16x32_bf16 v[30:33], v[106:109], v[178:181], v[30:33]
	v_mfma_f32_16x16x32_bf16 v[26:29], v[126:129], v[178:181], v[26:29]
	v_mfma_f32_16x16x32_bf16 v[14:17], v[106:109], v[222:225], v[14:17]
	v_mfma_f32_16x16x32_bf16 v[10:13], v[126:129], v[222:225], v[10:13]
	v_mfma_f32_16x16x32_bf16 v[62:65], v[110:113], v[166:169], v[62:65]
	v_mfma_f32_16x16x32_bf16 v[58:61], v[134:137], v[166:169], v[58:61]
	v_mfma_f32_16x16x32_bf16 v[46:49], v[110:113], v[174:177], v[46:49]
	v_mfma_f32_16x16x32_bf16 v[42:45], v[134:137], v[174:177], v[42:45]
	v_mfma_f32_16x16x32_bf16 v[30:33], v[110:113], v[182:185], v[30:33]
	v_mfma_f32_16x16x32_bf16 v[26:29], v[134:137], v[182:185], v[26:29]
	v_mfma_f32_16x16x32_bf16 v[14:17], v[110:113], v[226:229], v[14:17]
	v_mfma_f32_16x16x32_bf16 v[10:13], v[134:137], v[226:229], v[10:13]
	v_mfma_f32_16x16x32_bf16 v[54:57], v[146:149], v[162:165], v[54:57]
	v_mfma_f32_16x16x32_bf16 v[50:53], v[154:157], v[162:165], v[50:53]
	v_mfma_f32_16x16x32_bf16 v[38:41], v[146:149], v[170:173], v[38:41]
	v_mfma_f32_16x16x32_bf16 v[34:37], v[154:157], v[170:173], v[34:37]
	v_mfma_f32_16x16x32_bf16 v[22:25], v[146:149], v[178:181], v[22:25]
	v_mfma_f32_16x16x32_bf16 v[18:21], v[154:157], v[178:181], v[18:21]
	v_mfma_f32_16x16x32_bf16 v[6:9], v[146:149], v[222:225], v[6:9]
	v_mfma_f32_16x16x32_bf16 v[2:5], v[154:157], v[222:225], v[2:5]
	v_mfma_f32_16x16x32_bf16 v[54:57], v[150:153], v[166:169], v[54:57]
	v_mfma_f32_16x16x32_bf16 v[50:53], v[158:161], v[166:169], v[50:53]
	v_mfma_f32_16x16x32_bf16 v[38:41], v[150:153], v[174:177], v[38:41]
	v_mfma_f32_16x16x32_bf16 v[34:37], v[158:161], v[174:177], v[34:37]
	v_mfma_f32_16x16x32_bf16 v[22:25], v[150:153], v[182:185], v[22:25]
	v_mfma_f32_16x16x32_bf16 v[18:21], v[158:161], v[182:185], v[18:21]
	v_mfma_f32_16x16x32_bf16 v[6:9], v[150:153], v[226:229], v[6:9]
	v_mfma_f32_16x16x32_bf16 v[2:5], v[158:161], v[226:229], v[2:5]
	s_barrier
	s_setprio 0
	s_add_i32 s19, s19, 2
	s_add_u32 s7, s7, 0x100
	s_addc_u32 s18, s18, 0
	s_cmp_gt_u32 s19, 41
	s_mov_b64 s[48:49], s[0:1]
.LBB0_320:
	s_add_u32 s0, s48, 0x100
	s_addc_u32 s1, s49, 0
	s_add_i32 s51, 0, 0x10000
	s_cmp_eq_u32 s19, 40
	s_cselect_b32 s55, s45, s1
	s_cselect_b32 s54, s44, s0
	v_add_u32_e32 v0, s51, v219
	s_cselect_b32 s53, s47, s18
	s_cselect_b32 s52, s46, s7
	s_add_i32 s66, 0, 0x14000
	ds_read_b128 v[106:109], v0
	ds_read_b128 v[110:113], v0 offset:1024
	ds_read_b128 v[126:129], v0 offset:2048
	ds_read_b128 v[134:137], v0 offset:3072
	v_add_u32_e32 v0, s66, v219
	ds_read_b128 v[146:149], v0
	ds_read_b128 v[150:153], v0 offset:1024
	ds_read_b128 v[154:157], v0 offset:2048
	ds_read_b128 v[158:161], v0 offset:3072
	v_lshl_add_u64 v[216:217], s[48:49], 0, v[212:213]
	s_add_i32 m0, s57, 0xc000
	ds_read_b128 v[162:165], v220
	ds_read_b128 v[166:169], v220 offset:1024
	ds_read_b128 v[170:173], v220 offset:2048
	ds_read_b128 v[174:177], v220 offset:3072
	ds_read_b128 v[178:181], v220 offset:4096
	ds_read_b128 v[182:185], v220 offset:5120
	ds_read_b128 v[222:225], v220 offset:6144
	ds_read_b128 v[226:229], v220 offset:7168
	global_load_lds_dwordx4 v[216:217], off
	v_lshl_add_u64 v[216:217], s[48:49], 0, v[214:215]
	s_add_i32 m0, s57, 0xe000
	s_nop 0
	global_load_lds_dwordx4 v[216:217], off
	s_waitcnt vmcnt(8)
	s_waitcnt lgkmcnt(0)
	s_setprio 1
	s_barrier
	v_mfma_f32_16x16x32_bf16 v[142:145], v[106:109], v[162:165], v[142:145]
	v_mfma_f32_16x16x32_bf16 v[138:141], v[126:129], v[162:165], v[138:141]
	v_mfma_f32_16x16x32_bf16 v[118:121], v[106:109], v[170:173], v[118:121]
	v_mfma_f32_16x16x32_bf16 v[114:117], v[126:129], v[170:173], v[114:117]
	v_mfma_f32_16x16x32_bf16 v[94:97], v[106:109], v[178:181], v[94:97]
	v_mfma_f32_16x16x32_bf16 v[90:93], v[126:129], v[178:181], v[90:93]
	v_mfma_f32_16x16x32_bf16 v[78:81], v[106:109], v[222:225], v[78:81]
	v_mfma_f32_16x16x32_bf16 v[74:77], v[126:129], v[222:225], v[74:77]
	v_mfma_f32_16x16x32_bf16 v[142:145], v[110:113], v[166:169], v[142:145]
	v_mfma_f32_16x16x32_bf16 v[138:141], v[134:137], v[166:169], v[138:141]
	v_mfma_f32_16x16x32_bf16 v[118:121], v[110:113], v[174:177], v[118:121]
	v_mfma_f32_16x16x32_bf16 v[114:117], v[134:137], v[174:177], v[114:117]
	v_mfma_f32_16x16x32_bf16 v[94:97], v[110:113], v[182:185], v[94:97]
	v_mfma_f32_16x16x32_bf16 v[90:93], v[134:137], v[182:185], v[90:93]
	v_mfma_f32_16x16x32_bf16 v[78:81], v[110:113], v[226:229], v[78:81]
	v_mfma_f32_16x16x32_bf16 v[74:77], v[134:137], v[226:229], v[74:77]
	v_mfma_f32_16x16x32_bf16 v[130:133], v[146:149], v[162:165], v[130:133]
	v_mfma_f32_16x16x32_bf16 v[122:125], v[154:157], v[162:165], v[122:125]
	v_mfma_f32_16x16x32_bf16 v[102:105], v[146:149], v[170:173], v[102:105]
	v_mfma_f32_16x16x32_bf16 v[98:101], v[154:157], v[170:173], v[98:101]
	v_mfma_f32_16x16x32_bf16 v[86:89], v[146:149], v[178:181], v[86:89]
	v_mfma_f32_16x16x32_bf16 v[82:85], v[154:157], v[178:181], v[82:85]
	v_mfma_f32_16x16x32_bf16 v[70:73], v[146:149], v[222:225], v[70:73]
	v_mfma_f32_16x16x32_bf16 v[66:69], v[154:157], v[222:225], v[66:69]
	v_mfma_f32_16x16x32_bf16 v[130:133], v[150:153], v[166:169], v[130:133]
	v_mfma_f32_16x16x32_bf16 v[122:125], v[158:161], v[166:169], v[122:125]
	v_mfma_f32_16x16x32_bf16 v[102:105], v[150:153], v[174:177], v[102:105]
	v_mfma_f32_16x16x32_bf16 v[98:101], v[158:161], v[174:177], v[98:101]
	v_mfma_f32_16x16x32_bf16 v[86:89], v[150:153], v[182:185], v[86:89]
	v_mfma_f32_16x16x32_bf16 v[82:85], v[158:161], v[182:185], v[82:85]
	v_mfma_f32_16x16x32_bf16 v[70:73], v[150:153], v[226:229], v[70:73]
	v_mfma_f32_16x16x32_bf16 v[66:69], v[158:161], v[226:229], v[66:69]
	s_barrier
	s_setprio 0
	s_add_i32 s48, s51, s56
	v_lshl_add_u64 v[216:217], s[52:53], 0, v[208:209]
	s_mov_b32 m0, s48
	ds_read_b128 v[162:165], v220 offset:16384
	ds_read_b128 v[166:169], v220 offset:17408
	ds_read_b128 v[170:173], v220 offset:18432
	ds_read_b128 v[174:177], v220 offset:19456
	ds_read_b128 v[178:181], v220 offset:20480
	ds_read_b128 v[182:185], v220 offset:21504
	ds_read_b128 v[222:225], v220 offset:22528
	ds_read_b128 v[226:229], v220 offset:23552
	global_load_lds_dwordx4 v[216:217], off
	s_add_i32 m0, s48, 0x2000
	s_add_u32 s48, s52, 0xb0000
	v_lshl_add_u64 v[230:231], s[52:53], 0, v[204:205]
	s_addc_u32 s49, s53, 0
	s_add_i32 s51, s66, s56
	global_load_lds_dwordx4 v[230:231], off
	v_lshl_add_u64 v[240:241], s[48:49], 0, v[208:209]
	s_mov_b32 m0, s51
	v_lshl_add_u64 v[242:243], s[54:55], 0, v[206:207]
	global_load_lds_dwordx4 v[240:241], off
	v_lshl_add_u64 v[240:241], s[48:49], 0, v[204:205]
	s_add_i32 m0, s51, 0x2000
	s_nop 0
	global_load_lds_dwordx4 v[240:241], off
	v_lshl_add_u64 v[240:241], s[54:55], 0, v[210:211]
	s_mov_b32 m0, s57
	s_nop 0
	global_load_lds_dwordx4 v[240:241], off
	s_mov_b32 m0, s58
	s_nop 0
	global_load_lds_dwordx4 v[242:243], off
	s_waitcnt vmcnt(8)
	s_waitcnt lgkmcnt(0)
	s_setprio 1
	s_barrier
	v_mfma_f32_16x16x32_bf16 v[62:65], v[106:109], v[162:165], v[62:65]
	v_mfma_f32_16x16x32_bf16 v[58:61], v[126:129], v[162:165], v[58:61]
	v_mfma_f32_16x16x32_bf16 v[46:49], v[106:109], v[170:173], v[46:49]
	v_mfma_f32_16x16x32_bf16 v[42:45], v[126:129], v[170:173], v[42:45]
	v_mfma_f32_16x16x32_bf16 v[30:33], v[106:109], v[178:181], v[30:33]
	v_mfma_f32_16x16x32_bf16 v[26:29], v[126:129], v[178:181], v[26:29]
	v_mfma_f32_16x16x32_bf16 v[14:17], v[106:109], v[222:225], v[14:17]
	v_mfma_f32_16x16x32_bf16 v[10:13], v[126:129], v[222:225], v[10:13]
	v_mfma_f32_16x16x32_bf16 v[62:65], v[110:113], v[166:169], v[62:65]
	v_mfma_f32_16x16x32_bf16 v[58:61], v[134:137], v[166:169], v[58:61]
	v_mfma_f32_16x16x32_bf16 v[46:49], v[110:113], v[174:177], v[46:49]
	v_mfma_f32_16x16x32_bf16 v[42:45], v[134:137], v[174:177], v[42:45]
	v_mfma_f32_16x16x32_bf16 v[30:33], v[110:113], v[182:185], v[30:33]
	v_mfma_f32_16x16x32_bf16 v[26:29], v[134:137], v[182:185], v[26:29]
	v_mfma_f32_16x16x32_bf16 v[14:17], v[110:113], v[226:229], v[14:17]
	v_mfma_f32_16x16x32_bf16 v[10:13], v[134:137], v[226:229], v[10:13]
	v_mfma_f32_16x16x32_bf16 v[54:57], v[146:149], v[162:165], v[54:57]
	v_mfma_f32_16x16x32_bf16 v[50:53], v[154:157], v[162:165], v[50:53]
	v_mfma_f32_16x16x32_bf16 v[38:41], v[146:149], v[170:173], v[38:41]
	v_mfma_f32_16x16x32_bf16 v[34:37], v[154:157], v[170:173], v[34:37]
	v_mfma_f32_16x16x32_bf16 v[22:25], v[146:149], v[178:181], v[22:25]
	v_mfma_f32_16x16x32_bf16 v[18:21], v[154:157], v[178:181], v[18:21]
	v_mfma_f32_16x16x32_bf16 v[6:9], v[146:149], v[222:225], v[6:9]
	v_mfma_f32_16x16x32_bf16 v[2:5], v[154:157], v[222:225], v[2:5]
	v_mfma_f32_16x16x32_bf16 v[54:57], v[150:153], v[166:169], v[54:57]
	v_mfma_f32_16x16x32_bf16 v[50:53], v[158:161], v[166:169], v[50:53]
	v_mfma_f32_16x16x32_bf16 v[38:41], v[150:153], v[174:177], v[38:41]
	v_mfma_f32_16x16x32_bf16 v[34:37], v[158:161], v[174:177], v[34:37]
	v_mfma_f32_16x16x32_bf16 v[22:25], v[150:153], v[182:185], v[22:25]
	v_mfma_f32_16x16x32_bf16 v[18:21], v[158:161], v[182:185], v[18:21]
	v_mfma_f32_16x16x32_bf16 v[6:9], v[150:153], v[226:229], v[6:9]
	v_mfma_f32_16x16x32_bf16 v[2:5], v[158:161], v[226:229], v[2:5]
	s_barrier
	s_setprio 0
	s_add_i32 s51, 0, 0x18000
	v_add_u32_e32 v0, s51, v219
	s_add_i32 s66, 0, 0x1c000
	ds_read_b128 v[106:109], v0
	ds_read_b128 v[110:113], v0 offset:1024
	ds_read_b128 v[126:129], v0 offset:2048
	ds_read_b128 v[134:137], v0 offset:3072
	v_add_u32_e32 v0, s66, v219
	ds_read_b128 v[146:149], v0
	ds_read_b128 v[150:153], v0 offset:1024
	ds_read_b128 v[154:157], v0 offset:2048
	ds_read_b128 v[158:161], v0 offset:3072
	s_add_u32 s48, s54, 0xb0000
	s_addc_u32 s49, s55, 0
	s_mov_b32 m0, s59
	v_lshl_add_u64 v[244:245], s[48:49], 0, v[210:211]
	ds_read_b128 v[162:165], v220 offset:32768
	ds_read_b128 v[166:169], v220 offset:33792
	ds_read_b128 v[170:173], v220 offset:34816
	ds_read_b128 v[174:177], v220 offset:35840
	ds_read_b128 v[178:181], v220 offset:36864
	ds_read_b128 v[182:185], v220 offset:37888
	ds_read_b128 v[222:225], v220 offset:38912
	ds_read_b128 v[226:229], v220 offset:39936
	global_load_lds_dwordx4 v[244:245], off
	v_lshl_add_u64 v[244:245], s[48:49], 0, v[206:207]
	s_mov_b32 m0, s60
	s_nop 0
	global_load_lds_dwordx4 v[244:245], off
	s_waitcnt vmcnt(8)
	s_waitcnt lgkmcnt(0)
	s_setprio 1
	s_barrier
	v_mfma_f32_16x16x32_bf16 v[142:145], v[106:109], v[162:165], v[142:145]
	v_mfma_f32_16x16x32_bf16 v[138:141], v[126:129], v[162:165], v[138:141]
	v_mfma_f32_16x16x32_bf16 v[118:121], v[106:109], v[170:173], v[118:121]
	v_mfma_f32_16x16x32_bf16 v[114:117], v[126:129], v[170:173], v[114:117]
	v_mfma_f32_16x16x32_bf16 v[94:97], v[106:109], v[178:181], v[94:97]
	v_mfma_f32_16x16x32_bf16 v[90:93], v[126:129], v[178:181], v[90:93]
	v_mfma_f32_16x16x32_bf16 v[78:81], v[106:109], v[222:225], v[78:81]
	v_mfma_f32_16x16x32_bf16 v[74:77], v[126:129], v[222:225], v[74:77]
	v_mfma_f32_16x16x32_bf16 v[142:145], v[110:113], v[166:169], v[142:145]
	v_mfma_f32_16x16x32_bf16 v[138:141], v[134:137], v[166:169], v[138:141]
	v_mfma_f32_16x16x32_bf16 v[118:121], v[110:113], v[174:177], v[118:121]
	v_mfma_f32_16x16x32_bf16 v[114:117], v[134:137], v[174:177], v[114:117]
	v_mfma_f32_16x16x32_bf16 v[94:97], v[110:113], v[182:185], v[94:97]
	v_mfma_f32_16x16x32_bf16 v[90:93], v[134:137], v[182:185], v[90:93]
	v_mfma_f32_16x16x32_bf16 v[78:81], v[110:113], v[226:229], v[78:81]
	v_mfma_f32_16x16x32_bf16 v[74:77], v[134:137], v[226:229], v[74:77]
	v_mfma_f32_16x16x32_bf16 v[130:133], v[146:149], v[162:165], v[130:133]
	v_mfma_f32_16x16x32_bf16 v[122:125], v[154:157], v[162:165], v[122:125]
	v_mfma_f32_16x16x32_bf16 v[102:105], v[146:149], v[170:173], v[102:105]
	v_mfma_f32_16x16x32_bf16 v[98:101], v[154:157], v[170:173], v[98:101]
	v_mfma_f32_16x16x32_bf16 v[86:89], v[146:149], v[178:181], v[86:89]
	v_mfma_f32_16x16x32_bf16 v[82:85], v[154:157], v[178:181], v[82:85]
	v_mfma_f32_16x16x32_bf16 v[70:73], v[146:149], v[222:225], v[70:73]
	v_mfma_f32_16x16x32_bf16 v[66:69], v[154:157], v[222:225], v[66:69]
	v_mfma_f32_16x16x32_bf16 v[130:133], v[150:153], v[166:169], v[130:133]
	v_mfma_f32_16x16x32_bf16 v[122:125], v[158:161], v[166:169], v[122:125]
	v_mfma_f32_16x16x32_bf16 v[102:105], v[150:153], v[174:177], v[102:105]
	v_mfma_f32_16x16x32_bf16 v[98:101], v[158:161], v[174:177], v[98:101]
	v_mfma_f32_16x16x32_bf16 v[86:89], v[150:153], v[182:185], v[86:89]
	v_mfma_f32_16x16x32_bf16 v[82:85], v[158:161], v[182:185], v[82:85]
	v_mfma_f32_16x16x32_bf16 v[70:73], v[150:153], v[226:229], v[70:73]
	v_mfma_f32_16x16x32_bf16 v[66:69], v[158:161], v[226:229], v[66:69]
	s_barrier
	s_setprio 0
	s_add_i32 s48, s51, s56
	v_lshl_add_u64 v[216:217], v[216:217], 0, s[16:17]
	s_mov_b32 m0, s48
	ds_read_b128 v[162:165], v220 offset:49152
	ds_read_b128 v[166:169], v220 offset:50176
	ds_read_b128 v[170:173], v220 offset:51200
	ds_read_b128 v[174:177], v220 offset:52224
	ds_read_b128 v[178:181], v220 offset:53248
	ds_read_b128 v[182:185], v220 offset:54272
	ds_read_b128 v[222:225], v220 offset:55296
	ds_read_b128 v[226:229], v220 offset:56320
	global_load_lds_dwordx4 v[216:217], off
	s_add_i32 m0, s48, 0x2000
	s_add_u32 s48, s52, 0xb0080
	v_lshl_add_u64 v[216:217], v[230:231], 0, s[16:17]
	s_addc_u32 s49, s53, 0
	s_add_i32 s51, s66, s56
	global_load_lds_dwordx4 v[216:217], off
	v_lshl_add_u64 v[216:217], s[48:49], 0, v[208:209]
	s_mov_b32 m0, s51
	s_nop 0
	global_load_lds_dwordx4 v[216:217], off
	v_lshl_add_u64 v[216:217], s[48:49], 0, v[204:205]
	s_add_i32 m0, s51, 0x2000
	s_nop 0
	global_load_lds_dwordx4 v[216:217], off
	v_lshl_add_u64 v[216:217], v[240:241], 0, s[16:17]
	s_mov_b32 m0, s63
	s_nop 0
	global_load_lds_dwordx4 v[216:217], off
	v_lshl_add_u64 v[216:217], v[242:243], 0, s[16:17]
	s_mov_b32 m0, s64
	s_nop 0
	global_load_lds_dwordx4 v[216:217], off
	s_waitcnt vmcnt(8)
	s_waitcnt lgkmcnt(0)
	s_setprio 1
	s_barrier
	v_mfma_f32_16x16x32_bf16 v[62:65], v[106:109], v[162:165], v[62:65]
	v_mfma_f32_16x16x32_bf16 v[58:61], v[126:129], v[162:165], v[58:61]
	v_mfma_f32_16x16x32_bf16 v[46:49], v[106:109], v[170:173], v[46:49]
	v_mfma_f32_16x16x32_bf16 v[42:45], v[126:129], v[170:173], v[42:45]
	v_mfma_f32_16x16x32_bf16 v[30:33], v[106:109], v[178:181], v[30:33]
	v_mfma_f32_16x16x32_bf16 v[26:29], v[126:129], v[178:181], v[26:29]
	v_mfma_f32_16x16x32_bf16 v[14:17], v[106:109], v[222:225], v[14:17]
	v_mfma_f32_16x16x32_bf16 v[10:13], v[126:129], v[222:225], v[10:13]
	v_mfma_f32_16x16x32_bf16 v[62:65], v[110:113], v[166:169], v[62:65]
	v_mfma_f32_16x16x32_bf16 v[58:61], v[134:137], v[166:169], v[58:61]
	v_mfma_f32_16x16x32_bf16 v[46:49], v[110:113], v[174:177], v[46:49]
	v_mfma_f32_16x16x32_bf16 v[42:45], v[134:137], v[174:177], v[42:45]
	v_mfma_f32_16x16x32_bf16 v[30:33], v[110:113], v[182:185], v[30:33]
	v_mfma_f32_16x16x32_bf16 v[26:29], v[134:137], v[182:185], v[26:29]
	v_mfma_f32_16x16x32_bf16 v[14:17], v[110:113], v[226:229], v[14:17]
	v_mfma_f32_16x16x32_bf16 v[10:13], v[134:137], v[226:229], v[10:13]
	v_mfma_f32_16x16x32_bf16 v[54:57], v[146:149], v[162:165], v[54:57]
	v_mfma_f32_16x16x32_bf16 v[50:53], v[154:157], v[162:165], v[50:53]
	v_mfma_f32_16x16x32_bf16 v[38:41], v[146:149], v[170:173], v[38:41]
	v_mfma_f32_16x16x32_bf16 v[34:37], v[154:157], v[170:173], v[34:37]
	v_mfma_f32_16x16x32_bf16 v[22:25], v[146:149], v[178:181], v[22:25]
	v_mfma_f32_16x16x32_bf16 v[18:21], v[154:157], v[178:181], v[18:21]
	v_mfma_f32_16x16x32_bf16 v[6:9], v[146:149], v[222:225], v[6:9]
	v_mfma_f32_16x16x32_bf16 v[2:5], v[154:157], v[222:225], v[2:5]
	v_mfma_f32_16x16x32_bf16 v[54:57], v[150:153], v[166:169], v[54:57]
	v_mfma_f32_16x16x32_bf16 v[50:53], v[158:161], v[166:169], v[50:53]
	v_mfma_f32_16x16x32_bf16 v[38:41], v[150:153], v[174:177], v[38:41]
	v_mfma_f32_16x16x32_bf16 v[34:37], v[158:161], v[174:177], v[34:37]
	v_mfma_f32_16x16x32_bf16 v[22:25], v[150:153], v[182:185], v[22:25]
	v_mfma_f32_16x16x32_bf16 v[18:21], v[158:161], v[182:185], v[18:21]
	v_mfma_f32_16x16x32_bf16 v[6:9], v[150:153], v[226:229], v[6:9]
	v_mfma_f32_16x16x32_bf16 v[2:5], v[158:161], v[226:229], v[2:5]
	s_barrier
	s_setprio 0
	s_add_i32 s19, s19, 2
	s_add_u32 s7, s7, 0x100
	s_addc_u32 s18, s18, 0
	s_cmp_gt_u32 s19, 41
	s_mov_b64 s[48:49], s[0:1]
	s_cbranch_scc0 .LBB0_320
	s_and_b64 vcc, exec, s[40:41]
	s_cbranch_vccz .LBB0_323
	s_barrier

.LBB0_339:
	s_or_b64 exec, exec, s[0:1]
	s_and_b64 vcc, exec, s[42:43]
	s_mov_b64 s[0:1], -1
	s_cbranch_vccnz .LBB0_308
	s_mov_b32 s51, 0
	s_andn2_b64 vcc, exec, s[38:39]
	s_cbranch_vccnz .LBB0_307
	s_mov_b32 s51, 1
	s_branch .LBB0_307

.LBB0_412:
	s_waitcnt vmcnt(0)
	v_bfe_u32 v157, v7, 4, 2
	v_mov_b32_e32 v135, v1
	v_and_b32_e32 v156, 15, v7
	v_lshlrev_b32_e32 v16, 4, v157
	v_lshlrev_b32_e32 v7, 2, v7
	s_lshl_b32 s4, s4, 5
	v_lshl_add_u64 v[8:9], s[54:55], 0, v[134:135]
	v_mov_b32_e32 v131, v1
	v_readlane_b32 s52, v251, 17
	s_lshl_b32 s63, s5, 6
	v_lshl_or_b32 v16, v156, 6, v16
	s_lshl_b32 s5, s5, 13
	v_and_b32_e32 v7, 32, v7
	s_and_b32 s4, s4, 0x60
	v_lshl_add_u64 v[10:11], s[54:55], 0, v[130:131]
	v_mov_b32_e32 v137, v1
	v_readlane_b32 s53, v251, 18
	v_bitop3_b32 v17, v16, s5, v7 bitop3:0xde
	s_lshl_b32 s5, s4, 7
	s_add_i32 m0, s59, 0x18000
	v_lshl_add_u64 v[8:9], v[8:9], 0, s[16:17]
	v_lshl_add_u64 v[12:13], s[52:53], 0, v[136:137]
	v_mov_b32_e32 v133, v1
	v_bitop3_b32 v158, v16, s5, v7 bitop3:0xde
	s_waitcnt vmcnt(2)
	s_barrier
	global_load_lds_dwordx4 v[8:9], off
	v_lshl_add_u64 v[8:9], v[10:11], 0, s[16:17]
	s_add_i32 m0, s59, 0x1a000
	s_add_i32 s5, s59, 0x8000
	s_add_i32 s6, s59, 0xa000
	v_lshl_add_u64 v[14:15], s[52:53], 0, v[132:133]
	global_load_lds_dwordx4 v[8:9], off
	v_lshl_add_u64 v[8:9], v[12:13], 0, s[16:17]
	s_mov_b32 m0, s5
	s_add_u32 s18, s54, 0x40080
	global_load_lds_dwordx4 v[8:9], off
	v_lshl_add_u64 v[8:9], v[14:15], 0, s[16:17]
	s_mov_b32 m0, s6
	s_addc_u32 s19, s55, 0
	global_load_lds_dwordx4 v[8:9], off
	s_add_i32 m0, s59, 0x1c000
	v_lshl_add_u64 v[8:9], s[18:19], 0, v[134:135]
	global_load_lds_dwordx4 v[8:9], off
	v_lshl_add_u64 v[8:9], s[18:19], 0, v[130:131]
	s_add_i32 m0, s59, 0x1e000
	v_lshlrev_b32_e32 v7, 14, v5
	global_load_lds_dwordx4 v[8:9], off
	v_and_b32_e32 v7, 0xffff8000, v7
	v_lshl_add_u32 v4, v4, 11, v7
	v_and_b32_e32 v5, 1, v5
	v_lshl_or_b32 v4, v5, 6, v4
	v_lshl_add_u32 v138, v6, 1, v4
	v_lshlrev_b32_e32 v4, 14, v0
	v_and_b32_e32 v4, 0xffff8000, v4
	s_waitcnt vmcnt(6)
	v_lshl_add_u32 v2, v2, 11, v4
	v_and_b32_e32 v0, 1, v0
	s_cmpk_lt_u32 s7, 0x100
	v_lshl_or_b32 v0, v0, 6, v2
	s_cselect_b64 s[38:39], -1, 0
	v_mov_b32_e32 v139, v1
	v_lshl_add_u32 v140, v3, 1, v0
	v_mov_b32_e32 v141, v1
	s_mov_b32 s7, 0
	v_add_u32_e32 v159, 0, v17
	v_readlane_b32 s18, v251, 63
	v_readlane_b32 s50, v251, 23
	s_barrier
	v_readlane_b32 s51, v251, 24
	s_mov_b32 s67, 0
	s_branch .LBB0_415

.LBB0_421:
	s_ashr_i32 s45, s44, 31
	s_lshl_b64 s[46:47], s[44:45], 19
	s_add_u32 s46, s96, s46
	s_addc_u32 s47, s97, s47
	s_and_b64 s[48:49], s[42:43], exec
	s_cselect_b32 s19, s47, s53
	s_cselect_b32 s45, s46, s52
	s_ashr_i32 s41, s40, 31
	s_lshl_b64 s[48:49], s[40:41], 19
	s_add_u32 s48, s0, s48
	s_addc_u32 s49, s1, s49
	s_and_b64 s[56:57], s[42:43], exec
	s_cselect_b32 s41, s49, s55
	s_cselect_b32 s51, s48, s54
	s_add_u32 s52, s52, 0x40080
	s_addc_u32 s53, s53, 0
	s_add_u32 s64, s54, 0x100
	s_addc_u32 s65, s55, 0
	s_mov_b32 s66, -2
	s_cmp_eq_u32 s67, 0
	s_cbranch_scc1 .Lrb2_skip
	s_barrier
.Lrb2_skip:
	s_add_u32 s54, s52, 0xfffc0080
	s_addc_u32 s55, s53, -1
	s_add_i32 s67, 0, 0x10000
	s_cmp_eq_u32 s66, 12
	s_cselect_b32 s57, s19, s55
	s_cselect_b32 s56, s45, s54
	v_add_u32_e32 v0, s67, v158
	s_cselect_b32 s55, s41, s65
	s_cselect_b32 s54, s51, s64
	s_add_i32 s70, 0, 0x14000
	ds_read_b128 v[142:145], v0
	ds_read_b128 v[146:149], v0 offset:1024
	ds_read_b128 v[150:153], v0 offset:2048
	ds_read_b128 v[160:163], v0 offset:3072
	v_add_u32_e32 v0, s70, v158
	ds_read_b128 v[164:167], v0
	ds_read_b128 v[168:171], v0 offset:1024
	ds_read_b128 v[172:175], v0 offset:2048
	ds_read_b128 v[176:179], v0 offset:3072
	v_lshl_add_u64 v[154:155], s[52:53], 0, v[138:139]
	s_add_i32 m0, s59, 0xc000
	ds_read_b128 v[180:183], v159
	ds_read_b128 v[204:207], v159 offset:1024
	ds_read_b128 v[208:211], v159 offset:2048
	ds_read_b128 v[212:215], v159 offset:3072
	ds_read_b128 v[216:219], v159 offset:4096
	ds_read_b128 v[220:223], v159 offset:5120
	ds_read_b128 v[224:227], v159 offset:6144
	ds_read_b128 v[228:231], v159 offset:7168
	global_load_lds_dwordx4 v[154:155], off
	v_lshl_add_u64 v[154:155], s[52:53], 0, v[140:141]
	s_add_i32 m0, s59, 0xe000
	s_nop 0
	global_load_lds_dwordx4 v[154:155], off
	s_waitcnt vmcnt(8)
	s_waitcnt lgkmcnt(0)
	s_setprio 1
	s_barrier
	v_mfma_f32_16x16x32_bf16 v[126:129], v[142:145], v[180:183], 0
	v_mfma_f32_16x16x32_bf16 v[122:125], v[150:153], v[180:183], 0
	v_mfma_f32_16x16x32_bf16 v[110:113], v[142:145], v[208:211], 0
	v_mfma_f32_16x16x32_bf16 v[106:109], v[150:153], v[208:211], 0
	v_mfma_f32_16x16x32_bf16 v[94:97], v[142:145], v[216:219], 0
	v_mfma_f32_16x16x32_bf16 v[90:93], v[150:153], v[216:219], 0
	v_mfma_f32_16x16x32_bf16 v[78:81], v[142:145], v[224:227], 0
	v_mfma_f32_16x16x32_bf16 v[74:77], v[150:153], v[224:227], 0
	v_mfma_f32_16x16x32_bf16 v[126:129], v[146:149], v[204:207], v[126:129]
	v_mfma_f32_16x16x32_bf16 v[122:125], v[160:163], v[204:207], v[122:125]
	v_mfma_f32_16x16x32_bf16 v[110:113], v[146:149], v[212:215], v[110:113]
	v_mfma_f32_16x16x32_bf16 v[106:109], v[160:163], v[212:215], v[106:109]
	v_mfma_f32_16x16x32_bf16 v[94:97], v[146:149], v[220:223], v[94:97]
	v_mfma_f32_16x16x32_bf16 v[90:93], v[160:163], v[220:223], v[90:93]
	v_mfma_f32_16x16x32_bf16 v[78:81], v[146:149], v[228:231], v[78:81]
	v_mfma_f32_16x16x32_bf16 v[74:77], v[160:163], v[228:231], v[74:77]
	v_mfma_f32_16x16x32_bf16 v[118:121], v[164:167], v[180:183], 0
	v_mfma_f32_16x16x32_bf16 v[114:117], v[172:175], v[180:183], 0
	v_mfma_f32_16x16x32_bf16 v[102:105], v[164:167], v[208:211], 0
	v_mfma_f32_16x16x32_bf16 v[98:101], v[172:175], v[208:211], 0
	v_mfma_f32_16x16x32_bf16 v[86:89], v[164:167], v[216:219], 0
	v_mfma_f32_16x16x32_bf16 v[82:85], v[172:175], v[216:219], 0
	v_mfma_f32_16x16x32_bf16 v[70:73], v[164:167], v[224:227], 0
	v_mfma_f32_16x16x32_bf16 v[66:69], v[172:175], v[224:227], 0
	v_mfma_f32_16x16x32_bf16 v[118:121], v[168:171], v[204:207], v[118:121]
	v_mfma_f32_16x16x32_bf16 v[114:117], v[176:179], v[204:207], v[114:117]
	v_mfma_f32_16x16x32_bf16 v[102:105], v[168:171], v[212:215], v[102:105]
	v_mfma_f32_16x16x32_bf16 v[98:101], v[176:179], v[212:215], v[98:101]
	v_mfma_f32_16x16x32_bf16 v[86:89], v[168:171], v[220:223], v[86:89]
	v_mfma_f32_16x16x32_bf16 v[82:85], v[176:179], v[220:223], v[82:85]
	v_mfma_f32_16x16x32_bf16 v[70:73], v[168:171], v[228:231], v[70:73]
	v_mfma_f32_16x16x32_bf16 v[66:69], v[176:179], v[228:231], v[66:69]
	s_barrier
	s_setprio 0
	s_add_i32 s67, s67, s58
	v_lshl_add_u64 v[154:155], s[54:55], 0, v[134:135]
	s_mov_b32 m0, s67
	ds_read_b128 v[180:183], v159 offset:16384
	ds_read_b128 v[204:207], v159 offset:17408
	ds_read_b128 v[208:211], v159 offset:18432
	ds_read_b128 v[212:215], v159 offset:19456
	ds_read_b128 v[216:219], v159 offset:20480
	ds_read_b128 v[220:223], v159 offset:21504
	ds_read_b128 v[224:227], v159 offset:22528
	ds_read_b128 v[228:231], v159 offset:23552
	global_load_lds_dwordx4 v[154:155], off
	s_add_i32 m0, s67, 0x2000
	s_add_u32 s68, s54, 0x40000
	v_lshl_add_u64 v[184:185], s[54:55], 0, v[130:131]
	s_addc_u32 s69, s55, 0
	s_add_i32 s67, s70, s58
	global_load_lds_dwordx4 v[184:185], off
	v_lshl_add_u64 v[240:241], s[68:69], 0, v[134:135]
	s_mov_b32 m0, s67
	v_lshl_add_u64 v[242:243], s[56:57], 0, v[132:133]
	global_load_lds_dwordx4 v[240:241], off
	v_lshl_add_u64 v[240:241], s[68:69], 0, v[130:131]
	s_add_i32 m0, s67, 0x2000
	s_nop 0
	global_load_lds_dwordx4 v[240:241], off
	v_lshl_add_u64 v[240:241], s[56:57], 0, v[136:137]
	s_mov_b32 m0, s59
	s_nop 0
	global_load_lds_dwordx4 v[240:241], off
	s_mov_b32 m0, s60
	s_nop 0
	global_load_lds_dwordx4 v[242:243], off
	s_waitcnt vmcnt(8)
	s_waitcnt lgkmcnt(0)
	s_setprio 1
	s_barrier
	v_mfma_f32_16x16x32_bf16 v[62:65], v[142:145], v[180:183], 0
	v_mfma_f32_16x16x32_bf16 v[58:61], v[150:153], v[180:183], 0
	v_mfma_f32_16x16x32_bf16 v[46:49], v[142:145], v[208:211], 0
	v_mfma_f32_16x16x32_bf16 v[42:45], v[150:153], v[208:211], 0
	v_mfma_f32_16x16x32_bf16 v[30:33], v[142:145], v[216:219], 0
	v_mfma_f32_16x16x32_bf16 v[26:29], v[150:153], v[216:219], 0
	v_mfma_f32_16x16x32_bf16 v[14:17], v[142:145], v[224:227], 0
	v_mfma_f32_16x16x32_bf16 v[10:13], v[150:153], v[224:227], 0
	v_mfma_f32_16x16x32_bf16 v[62:65], v[146:149], v[204:207], v[62:65]
	v_mfma_f32_16x16x32_bf16 v[58:61], v[160:163], v[204:207], v[58:61]
	v_mfma_f32_16x16x32_bf16 v[46:49], v[146:149], v[212:215], v[46:49]
	v_mfma_f32_16x16x32_bf16 v[42:45], v[160:163], v[212:215], v[42:45]
	v_mfma_f32_16x16x32_bf16 v[30:33], v[146:149], v[220:223], v[30:33]
	v_mfma_f32_16x16x32_bf16 v[26:29], v[160:163], v[220:223], v[26:29]
	v_mfma_f32_16x16x32_bf16 v[14:17], v[146:149], v[228:231], v[14:17]
	v_mfma_f32_16x16x32_bf16 v[10:13], v[160:163], v[228:231], v[10:13]
	v_mfma_f32_16x16x32_bf16 v[54:57], v[164:167], v[180:183], 0
	v_mfma_f32_16x16x32_bf16 v[50:53], v[172:175], v[180:183], 0
	v_mfma_f32_16x16x32_bf16 v[38:41], v[164:167], v[208:211], 0
	v_mfma_f32_16x16x32_bf16 v[34:37], v[172:175], v[208:211], 0
	v_mfma_f32_16x16x32_bf16 v[22:25], v[164:167], v[216:219], 0
	v_mfma_f32_16x16x32_bf16 v[18:21], v[172:175], v[216:219], 0
	v_mfma_f32_16x16x32_bf16 v[6:9], v[164:167], v[224:227], 0
	v_mfma_f32_16x16x32_bf16 v[2:5], v[172:175], v[224:227], 0
	v_mfma_f32_16x16x32_bf16 v[54:57], v[168:171], v[204:207], v[54:57]
	v_mfma_f32_16x16x32_bf16 v[50:53], v[176:179], v[204:207], v[50:53]
	v_mfma_f32_16x16x32_bf16 v[38:41], v[168:171], v[212:215], v[38:41]
	v_mfma_f32_16x16x32_bf16 v[34:37], v[176:179], v[212:215], v[34:37]
	v_mfma_f32_16x16x32_bf16 v[22:25], v[168:171], v[220:223], v[22:25]
	v_mfma_f32_16x16x32_bf16 v[18:21], v[176:179], v[220:223], v[18:21]
	v_mfma_f32_16x16x32_bf16 v[6:9], v[168:171], v[228:231], v[6:9]
	v_mfma_f32_16x16x32_bf16 v[2:5], v[176:179], v[228:231], v[2:5]
	s_barrier
	s_setprio 0
	s_add_i32 s67, 0, 0x18000
	v_add_u32_e32 v0, s67, v158
	s_add_i32 s68, 0, 0x1c000
	ds_read_b128 v[142:145], v0
	ds_read_b128 v[146:149], v0 offset:1024
	ds_read_b128 v[150:153], v0 offset:2048
	ds_read_b128 v[160:163], v0 offset:3072
	v_add_u32_e32 v0, s68, v158
	ds_read_b128 v[164:167], v0
	ds_read_b128 v[168:171], v0 offset:1024
	ds_read_b128 v[172:175], v0 offset:2048
	ds_read_b128 v[176:179], v0 offset:3072
	s_add_u32 s56, s56, 0x40000
	s_addc_u32 s57, s57, 0
	s_mov_b32 m0, s61
	v_lshl_add_u64 v[244:245], s[56:57], 0, v[136:137]
	ds_read_b128 v[180:183], v159 offset:32768
	ds_read_b128 v[204:207], v159 offset:33792
	ds_read_b128 v[208:211], v159 offset:34816
	ds_read_b128 v[212:215], v159 offset:35840
	ds_read_b128 v[216:219], v159 offset:36864
	ds_read_b128 v[220:223], v159 offset:37888
	ds_read_b128 v[224:227], v159 offset:38912
	ds_read_b128 v[228:231], v159 offset:39936
	global_load_lds_dwordx4 v[244:245], off
	v_lshl_add_u64 v[244:245], s[56:57], 0, v[132:133]
	s_mov_b32 m0, s62
	s_nop 0
	global_load_lds_dwordx4 v[244:245], off
	s_waitcnt vmcnt(8)
	s_waitcnt lgkmcnt(0)
	s_setprio 1
	s_barrier
	v_mfma_f32_16x16x32_bf16 v[126:129], v[142:145], v[180:183], v[126:129]
	v_mfma_f32_16x16x32_bf16 v[122:125], v[150:153], v[180:183], v[122:125]
	v_mfma_f32_16x16x32_bf16 v[110:113], v[142:145], v[208:211], v[110:113]
	v_mfma_f32_16x16x32_bf16 v[106:109], v[150:153], v[208:211], v[106:109]
	v_mfma_f32_16x16x32_bf16 v[94:97], v[142:145], v[216:219], v[94:97]
	v_mfma_f32_16x16x32_bf16 v[90:93], v[150:153], v[216:219], v[90:93]
	v_mfma_f32_16x16x32_bf16 v[78:81], v[142:145], v[224:227], v[78:81]
	v_mfma_f32_16x16x32_bf16 v[74:77], v[150:153], v[224:227], v[74:77]
	v_mfma_f32_16x16x32_bf16 v[126:129], v[146:149], v[204:207], v[126:129]
	v_mfma_f32_16x16x32_bf16 v[122:125], v[160:163], v[204:207], v[122:125]
	v_mfma_f32_16x16x32_bf16 v[110:113], v[146:149], v[212:215], v[110:113]
	v_mfma_f32_16x16x32_bf16 v[106:109], v[160:163], v[212:215], v[106:109]
	v_mfma_f32_16x16x32_bf16 v[94:97], v[146:149], v[220:223], v[94:97]
	v_mfma_f32_16x16x32_bf16 v[90:93], v[160:163], v[220:223], v[90:93]
	v_mfma_f32_16x16x32_bf16 v[78:81], v[146:149], v[228:231], v[78:81]
	v_mfma_f32_16x16x32_bf16 v[74:77], v[160:163], v[228:231], v[74:77]
	v_mfma_f32_16x16x32_bf16 v[118:121], v[164:167], v[180:183], v[118:121]
	v_mfma_f32_16x16x32_bf16 v[114:117], v[172:175], v[180:183], v[114:117]
	v_mfma_f32_16x16x32_bf16 v[102:105], v[164:167], v[208:211], v[102:105]
	v_mfma_f32_16x16x32_bf16 v[98:101], v[172:175], v[208:211], v[98:101]
	v_mfma_f32_16x16x32_bf16 v[86:89], v[164:167], v[216:219], v[86:89]
	v_mfma_f32_16x16x32_bf16 v[82:85], v[172:175], v[216:219], v[82:85]
	v_mfma_f32_16x16x32_bf16 v[70:73], v[164:167], v[224:227], v[70:73]
	v_mfma_f32_16x16x32_bf16 v[66:69], v[172:175], v[224:227], v[66:69]
	v_mfma_f32_16x16x32_bf16 v[118:121], v[168:171], v[204:207], v[118:121]
	v_mfma_f32_16x16x32_bf16 v[114:117], v[176:179], v[204:207], v[114:117]
	v_mfma_f32_16x16x32_bf16 v[102:105], v[168:171], v[212:215], v[102:105]
	v_mfma_f32_16x16x32_bf16 v[98:101], v[176:179], v[212:215], v[98:101]
	v_mfma_f32_16x16x32_bf16 v[86:89], v[168:171], v[220:223], v[86:89]
	v_mfma_f32_16x16x32_bf16 v[82:85], v[176:179], v[220:223], v[82:85]
	v_mfma_f32_16x16x32_bf16 v[70:73], v[168:171], v[228:231], v[70:73]
	v_mfma_f32_16x16x32_bf16 v[66:69], v[176:179], v[228:231], v[66:69]
	s_barrier
	s_setprio 0
	s_add_i32 s56, s67, s58
	v_lshl_add_u64 v[154:155], v[154:155], 0, s[16:17]
	s_mov_b32 m0, s56
	ds_read_b128 v[180:183], v159 offset:49152
	ds_read_b128 v[204:207], v159 offset:50176
	ds_read_b128 v[208:211], v159 offset:51200
	ds_read_b128 v[212:215], v159 offset:52224
	ds_read_b128 v[216:219], v159 offset:53248
	ds_read_b128 v[220:223], v159 offset:54272
	ds_read_b128 v[224:227], v159 offset:55296
	ds_read_b128 v[228:231], v159 offset:56320
	global_load_lds_dwordx4 v[154:155], off
	s_add_i32 m0, s56, 0x2000
	s_add_u32 s54, s54, 0x40080
	v_lshl_add_u64 v[154:155], v[184:185], 0, s[16:17]
	s_addc_u32 s55, s55, 0
	s_add_i32 s56, s68, s58
	global_load_lds_dwordx4 v[154:155], off
	v_lshl_add_u64 v[154:155], s[54:55], 0, v[134:135]
	s_mov_b32 m0, s56
	s_nop 0
	global_load_lds_dwordx4 v[154:155], off
	v_lshl_add_u64 v[154:155], s[54:55], 0, v[130:131]
	s_add_i32 m0, s56, 0x2000
	s_nop 0
	global_load_lds_dwordx4 v[154:155], off
	v_lshl_add_u64 v[154:155], v[240:241], 0, s[16:17]
	s_mov_b32 m0, s5
	s_nop 0
	global_load_lds_dwordx4 v[154:155], off
	v_lshl_add_u64 v[154:155], v[242:243], 0, s[16:17]
	s_mov_b32 m0, s6
	s_nop 0
	global_load_lds_dwordx4 v[154:155], off
	s_waitcnt vmcnt(8)
	s_waitcnt lgkmcnt(0)
	s_setprio 1
	s_barrier
	v_mfma_f32_16x16x32_bf16 v[62:65], v[142:145], v[180:183], v[62:65]
	v_mfma_f32_16x16x32_bf16 v[58:61], v[150:153], v[180:183], v[58:61]
	v_mfma_f32_16x16x32_bf16 v[46:49], v[142:145], v[208:211], v[46:49]
	v_mfma_f32_16x16x32_bf16 v[42:45], v[150:153], v[208:211], v[42:45]
	v_mfma_f32_16x16x32_bf16 v[30:33], v[142:145], v[216:219], v[30:33]
	v_mfma_f32_16x16x32_bf16 v[26:29], v[150:153], v[216:219], v[26:29]
	v_mfma_f32_16x16x32_bf16 v[14:17], v[142:145], v[224:227], v[14:17]
	v_mfma_f32_16x16x32_bf16 v[10:13], v[150:153], v[224:227], v[10:13]
	v_mfma_f32_16x16x32_bf16 v[62:65], v[146:149], v[204:207], v[62:65]
	v_mfma_f32_16x16x32_bf16 v[58:61], v[160:163], v[204:207], v[58:61]
	v_mfma_f32_16x16x32_bf16 v[46:49], v[146:149], v[212:215], v[46:49]
	v_mfma_f32_16x16x32_bf16 v[42:45], v[160:163], v[212:215], v[42:45]
	v_mfma_f32_16x16x32_bf16 v[30:33], v[146:149], v[220:223], v[30:33]
	v_mfma_f32_16x16x32_bf16 v[26:29], v[160:163], v[220:223], v[26:29]
	v_mfma_f32_16x16x32_bf16 v[14:17], v[146:149], v[228:231], v[14:17]
	v_mfma_f32_16x16x32_bf16 v[10:13], v[160:163], v[228:231], v[10:13]
	v_mfma_f32_16x16x32_bf16 v[54:57], v[164:167], v[180:183], v[54:57]
	v_mfma_f32_16x16x32_bf16 v[50:53], v[172:175], v[180:183], v[50:53]
	v_mfma_f32_16x16x32_bf16 v[38:41], v[164:167], v[208:211], v[38:41]
	v_mfma_f32_16x16x32_bf16 v[34:37], v[172:175], v[208:211], v[34:37]
	v_mfma_f32_16x16x32_bf16 v[22:25], v[164:167], v[216:219], v[22:25]
	v_mfma_f32_16x16x32_bf16 v[18:21], v[172:175], v[216:219], v[18:21]
	v_mfma_f32_16x16x32_bf16 v[6:9], v[164:167], v[224:227], v[6:9]
	v_mfma_f32_16x16x32_bf16 v[2:5], v[172:175], v[224:227], v[2:5]
	v_mfma_f32_16x16x32_bf16 v[54:57], v[168:171], v[204:207], v[54:57]
	v_mfma_f32_16x16x32_bf16 v[50:53], v[176:179], v[204:207], v[50:53]
	v_mfma_f32_16x16x32_bf16 v[38:41], v[168:171], v[212:215], v[38:41]
	v_mfma_f32_16x16x32_bf16 v[34:37], v[176:179], v[212:215], v[34:37]
	v_mfma_f32_16x16x32_bf16 v[22:25], v[168:171], v[220:223], v[22:25]
	v_mfma_f32_16x16x32_bf16 v[18:21], v[176:179], v[220:223], v[18:21]
	v_mfma_f32_16x16x32_bf16 v[6:9], v[168:171], v[228:231], v[6:9]
	v_mfma_f32_16x16x32_bf16 v[2:5], v[176:179], v[228:231], v[2:5]
	s_barrier
	s_setprio 0
	s_add_i32 s66, s66, 2
	s_add_u32 s52, s52, 0x100
	s_addc_u32 s53, s53, 0
	s_add_u32 s64, s64, 0x100
	s_addc_u32 s65, s65, 0
	s_cmp_gt_u32 s66, 13
.LBB0_422:
	s_add_u32 s54, s52, 0xfffc0080
	s_addc_u32 s55, s53, -1
	s_add_i32 s67, 0, 0x10000
	s_cmp_eq_u32 s66, 12
	s_cselect_b32 s57, s19, s55
	s_cselect_b32 s56, s45, s54
	v_add_u32_e32 v0, s67, v158
	s_cselect_b32 s55, s41, s65
	s_cselect_b32 s54, s51, s64
	s_add_i32 s70, 0, 0x14000
	ds_read_b128 v[142:145], v0
	ds_read_b128 v[146:149], v0 offset:1024
	ds_read_b128 v[150:153], v0 offset:2048
	ds_read_b128 v[160:163], v0 offset:3072
	v_add_u32_e32 v0, s70, v158
	ds_read_b128 v[164:167], v0
	ds_read_b128 v[168:171], v0 offset:1024
	ds_read_b128 v[172:175], v0 offset:2048
	ds_read_b128 v[176:179], v0 offset:3072
	v_lshl_add_u64 v[154:155], s[52:53], 0, v[138:139]
	s_add_i32 m0, s59, 0xc000
	ds_read_b128 v[180:183], v159
	ds_read_b128 v[204:207], v159 offset:1024
	ds_read_b128 v[208:211], v159 offset:2048
	ds_read_b128 v[212:215], v159 offset:3072
	ds_read_b128 v[216:219], v159 offset:4096
	ds_read_b128 v[220:223], v159 offset:5120
	ds_read_b128 v[224:227], v159 offset:6144
	ds_read_b128 v[228:231], v159 offset:7168
	global_load_lds_dwordx4 v[154:155], off
	v_lshl_add_u64 v[154:155], s[52:53], 0, v[140:141]
	s_add_i32 m0, s59, 0xe000
	s_nop 0
	global_load_lds_dwordx4 v[154:155], off
	s_waitcnt vmcnt(8)
	s_waitcnt lgkmcnt(0)
	s_setprio 1
	s_barrier
	v_mfma_f32_16x16x32_bf16 v[126:129], v[142:145], v[180:183], v[126:129]
	v_mfma_f32_16x16x32_bf16 v[122:125], v[150:153], v[180:183], v[122:125]
	v_mfma_f32_16x16x32_bf16 v[110:113], v[142:145], v[208:211], v[110:113]
	v_mfma_f32_16x16x32_bf16 v[106:109], v[150:153], v[208:211], v[106:109]
	v_mfma_f32_16x16x32_bf16 v[94:97], v[142:145], v[216:219], v[94:97]
	v_mfma_f32_16x16x32_bf16 v[90:93], v[150:153], v[216:219], v[90:93]
	v_mfma_f32_16x16x32_bf16 v[78:81], v[142:145], v[224:227], v[78:81]
	v_mfma_f32_16x16x32_bf16 v[74:77], v[150:153], v[224:227], v[74:77]
	v_mfma_f32_16x16x32_bf16 v[126:129], v[146:149], v[204:207], v[126:129]
	v_mfma_f32_16x16x32_bf16 v[122:125], v[160:163], v[204:207], v[122:125]
	v_mfma_f32_16x16x32_bf16 v[110:113], v[146:149], v[212:215], v[110:113]
	v_mfma_f32_16x16x32_bf16 v[106:109], v[160:163], v[212:215], v[106:109]
	v_mfma_f32_16x16x32_bf16 v[94:97], v[146:149], v[220:223], v[94:97]
	v_mfma_f32_16x16x32_bf16 v[90:93], v[160:163], v[220:223], v[90:93]
	v_mfma_f32_16x16x32_bf16 v[78:81], v[146:149], v[228:231], v[78:81]
	v_mfma_f32_16x16x32_bf16 v[74:77], v[160:163], v[228:231], v[74:77]
	v_mfma_f32_16x16x32_bf16 v[118:121], v[164:167], v[180:183], v[118:121]
	v_mfma_f32_16x16x32_bf16 v[114:117], v[172:175], v[180:183], v[114:117]
	v_mfma_f32_16x16x32_bf16 v[102:105], v[164:167], v[208:211], v[102:105]
	v_mfma_f32_16x16x32_bf16 v[98:101], v[172:175], v[208:211], v[98:101]
	v_mfma_f32_16x16x32_bf16 v[86:89], v[164:167], v[216:219], v[86:89]
	v_mfma_f32_16x16x32_bf16 v[82:85], v[172:175], v[216:219], v[82:85]
	v_mfma_f32_16x16x32_bf16 v[70:73], v[164:167], v[224:227], v[70:73]
	v_mfma_f32_16x16x32_bf16 v[66:69], v[172:175], v[224:227], v[66:69]
	v_mfma_f32_16x16x32_bf16 v[118:121], v[168:171], v[204:207], v[118:121]
	v_mfma_f32_16x16x32_bf16 v[114:117], v[176:179], v[204:207], v[114:117]
	v_mfma_f32_16x16x32_bf16 v[102:105], v[168:171], v[212:215], v[102:105]
	v_mfma_f32_16x16x32_bf16 v[98:101], v[176:179], v[212:215], v[98:101]
	v_mfma_f32_16x16x32_bf16 v[86:89], v[168:171], v[220:223], v[86:89]
	v_mfma_f32_16x16x32_bf16 v[82:85], v[176:179], v[220:223], v[82:85]
	v_mfma_f32_16x16x32_bf16 v[70:73], v[168:171], v[228:231], v[70:73]
	v_mfma_f32_16x16x32_bf16 v[66:69], v[176:179], v[228:231], v[66:69]
	s_barrier
	s_setprio 0
	s_add_i32 s67, s67, s58
	v_lshl_add_u64 v[154:155], s[54:55], 0, v[134:135]
	s_mov_b32 m0, s67
	ds_read_b128 v[180:183], v159 offset:16384
	ds_read_b128 v[204:207], v159 offset:17408
	ds_read_b128 v[208:211], v159 offset:18432
	ds_read_b128 v[212:215], v159 offset:19456
	ds_read_b128 v[216:219], v159 offset:20480
	ds_read_b128 v[220:223], v159 offset:21504
	ds_read_b128 v[224:227], v159 offset:22528
	ds_read_b128 v[228:231], v159 offset:23552
	global_load_lds_dwordx4 v[154:155], off
	s_add_i32 m0, s67, 0x2000
	s_add_u32 s68, s54, 0x40000
	v_lshl_add_u64 v[184:185], s[54:55], 0, v[130:131]
	s_addc_u32 s69, s55, 0
	s_add_i32 s67, s70, s58
	global_load_lds_dwordx4 v[184:185], off
	v_lshl_add_u64 v[240:241], s[68:69], 0, v[134:135]
	s_mov_b32 m0, s67
	v_lshl_add_u64 v[242:243], s[56:57], 0, v[132:133]
	global_load_lds_dwordx4 v[240:241], off
	v_lshl_add_u64 v[240:241], s[68:69], 0, v[130:131]
	s_add_i32 m0, s67, 0x2000
	s_nop 0
	global_load_lds_dwordx4 v[240:241], off
	v_lshl_add_u64 v[240:241], s[56:57], 0, v[136:137]
	s_mov_b32 m0, s59
	s_nop 0
	global_load_lds_dwordx4 v[240:241], off
	s_mov_b32 m0, s60
	s_nop 0
	global_load_lds_dwordx4 v[242:243], off
	s_waitcnt vmcnt(8)
	s_waitcnt lgkmcnt(0)
	s_setprio 1
	s_barrier
	v_mfma_f32_16x16x32_bf16 v[62:65], v[142:145], v[180:183], v[62:65]
	v_mfma_f32_16x16x32_bf16 v[58:61], v[150:153], v[180:183], v[58:61]
	v_mfma_f32_16x16x32_bf16 v[46:49], v[142:145], v[208:211], v[46:49]
	v_mfma_f32_16x16x32_bf16 v[42:45], v[150:153], v[208:211], v[42:45]
	v_mfma_f32_16x16x32_bf16 v[30:33], v[142:145], v[216:219], v[30:33]
	v_mfma_f32_16x16x32_bf16 v[26:29], v[150:153], v[216:219], v[26:29]
	v_mfma_f32_16x16x32_bf16 v[14:17], v[142:145], v[224:227], v[14:17]
	v_mfma_f32_16x16x32_bf16 v[10:13], v[150:153], v[224:227], v[10:13]
	v_mfma_f32_16x16x32_bf16 v[62:65], v[146:149], v[204:207], v[62:65]
	v_mfma_f32_16x16x32_bf16 v[58:61], v[160:163], v[204:207], v[58:61]
	v_mfma_f32_16x16x32_bf16 v[46:49], v[146:149], v[212:215], v[46:49]
	v_mfma_f32_16x16x32_bf16 v[42:45], v[160:163], v[212:215], v[42:45]
	v_mfma_f32_16x16x32_bf16 v[30:33], v[146:149], v[220:223], v[30:33]
	v_mfma_f32_16x16x32_bf16 v[26:29], v[160:163], v[220:223], v[26:29]
	v_mfma_f32_16x16x32_bf16 v[14:17], v[146:149], v[228:231], v[14:17]
	v_mfma_f32_16x16x32_bf16 v[10:13], v[160:163], v[228:231], v[10:13]
	v_mfma_f32_16x16x32_bf16 v[54:57], v[164:167], v[180:183], v[54:57]
	v_mfma_f32_16x16x32_bf16 v[50:53], v[172:175], v[180:183], v[50:53]
	v_mfma_f32_16x16x32_bf16 v[38:41], v[164:167], v[208:211], v[38:41]
	v_mfma_f32_16x16x32_bf16 v[34:37], v[172:175], v[208:211], v[34:37]
	v_mfma_f32_16x16x32_bf16 v[22:25], v[164:167], v[216:219], v[22:25]
	v_mfma_f32_16x16x32_bf16 v[18:21], v[172:175], v[216:219], v[18:21]
	v_mfma_f32_16x16x32_bf16 v[6:9], v[164:167], v[224:227], v[6:9]
	v_mfma_f32_16x16x32_bf16 v[2:5], v[172:175], v[224:227], v[2:5]
	v_mfma_f32_16x16x32_bf16 v[54:57], v[168:171], v[204:207], v[54:57]
	v_mfma_f32_16x16x32_bf16 v[50:53], v[176:179], v[204:207], v[50:53]
	v_mfma_f32_16x16x32_bf16 v[38:41], v[168:171], v[212:215], v[38:41]
	v_mfma_f32_16x16x32_bf16 v[34:37], v[176:179], v[212:215], v[34:37]
	v_mfma_f32_16x16x32_bf16 v[22:25], v[168:171], v[220:223], v[22:25]
	v_mfma_f32_16x16x32_bf16 v[18:21], v[176:179], v[220:223], v[18:21]
	v_mfma_f32_16x16x32_bf16 v[6:9], v[168:171], v[228:231], v[6:9]
	v_mfma_f32_16x16x32_bf16 v[2:5], v[176:179], v[228:231], v[2:5]
	s_barrier
	s_setprio 0
	s_add_i32 s67, 0, 0x18000
	v_add_u32_e32 v0, s67, v158
	s_add_i32 s68, 0, 0x1c000
	ds_read_b128 v[142:145], v0
	ds_read_b128 v[146:149], v0 offset:1024
	ds_read_b128 v[150:153], v0 offset:2048
	ds_read_b128 v[160:163], v0 offset:3072
	v_add_u32_e32 v0, s68, v158
	ds_read_b128 v[164:167], v0
	ds_read_b128 v[168:171], v0 offset:1024
	ds_read_b128 v[172:175], v0 offset:2048
	ds_read_b128 v[176:179], v0 offset:3072
	s_add_u32 s56, s56, 0x40000
	s_addc_u32 s57, s57, 0
	s_mov_b32 m0, s61
	v_lshl_add_u64 v[244:245], s[56:57], 0, v[136:137]
	ds_read_b128 v[180:183], v159 offset:32768
	ds_read_b128 v[204:207], v159 offset:33792
	ds_read_b128 v[208:211], v159 offset:34816
	ds_read_b128 v[212:215], v159 offset:35840
	ds_read_b128 v[216:219], v159 offset:36864
	ds_read_b128 v[220:223], v159 offset:37888
	ds_read_b128 v[224:227], v159 offset:38912
	ds_read_b128 v[228:231], v159 offset:39936
	global_load_lds_dwordx4 v[244:245], off
	v_lshl_add_u64 v[244:245], s[56:57], 0, v[132:133]
	s_mov_b32 m0, s62
	s_nop 0
	global_load_lds_dwordx4 v[244:245], off
	s_waitcnt vmcnt(8)
	s_waitcnt lgkmcnt(0)
	s_setprio 1
	s_barrier
	v_mfma_f32_16x16x32_bf16 v[126:129], v[142:145], v[180:183], v[126:129]
	v_mfma_f32_16x16x32_bf16 v[122:125], v[150:153], v[180:183], v[122:125]
	v_mfma_f32_16x16x32_bf16 v[110:113], v[142:145], v[208:211], v[110:113]
	v_mfma_f32_16x16x32_bf16 v[106:109], v[150:153], v[208:211], v[106:109]
	v_mfma_f32_16x16x32_bf16 v[94:97], v[142:145], v[216:219], v[94:97]
	v_mfma_f32_16x16x32_bf16 v[90:93], v[150:153], v[216:219], v[90:93]
	v_mfma_f32_16x16x32_bf16 v[78:81], v[142:145], v[224:227], v[78:81]
	v_mfma_f32_16x16x32_bf16 v[74:77], v[150:153], v[224:227], v[74:77]
	v_mfma_f32_16x16x32_bf16 v[126:129], v[146:149], v[204:207], v[126:129]
	v_mfma_f32_16x16x32_bf16 v[122:125], v[160:163], v[204:207], v[122:125]
	v_mfma_f32_16x16x32_bf16 v[110:113], v[146:149], v[212:215], v[110:113]
	v_mfma_f32_16x16x32_bf16 v[106:109], v[160:163], v[212:215], v[106:109]
	v_mfma_f32_16x16x32_bf16 v[94:97], v[146:149], v[220:223], v[94:97]
	v_mfma_f32_16x16x32_bf16 v[90:93], v[160:163], v[220:223], v[90:93]
	v_mfma_f32_16x16x32_bf16 v[78:81], v[146:149], v[228:231], v[78:81]
	v_mfma_f32_16x16x32_bf16 v[74:77], v[160:163], v[228:231], v[74:77]
	v_mfma_f32_16x16x32_bf16 v[118:121], v[164:167], v[180:183], v[118:121]
	v_mfma_f32_16x16x32_bf16 v[114:117], v[172:175], v[180:183], v[114:117]
	v_mfma_f32_16x16x32_bf16 v[102:105], v[164:167], v[208:211], v[102:105]
	v_mfma_f32_16x16x32_bf16 v[98:101], v[172:175], v[208:211], v[98:101]
	v_mfma_f32_16x16x32_bf16 v[86:89], v[164:167], v[216:219], v[86:89]
	v_mfma_f32_16x16x32_bf16 v[82:85], v[172:175], v[216:219], v[82:85]
	v_mfma_f32_16x16x32_bf16 v[70:73], v[164:167], v[224:227], v[70:73]
	v_mfma_f32_16x16x32_bf16 v[66:69], v[172:175], v[224:227], v[66:69]
	v_mfma_f32_16x16x32_bf16 v[118:121], v[168:171], v[204:207], v[118:121]
	v_mfma_f32_16x16x32_bf16 v[114:117], v[176:179], v[204:207], v[114:117]
	v_mfma_f32_16x16x32_bf16 v[102:105], v[168:171], v[212:215], v[102:105]
	v_mfma_f32_16x16x32_bf16 v[98:101], v[176:179], v[212:215], v[98:101]
	v_mfma_f32_16x16x32_bf16 v[86:89], v[168:171], v[220:223], v[86:89]
	v_mfma_f32_16x16x32_bf16 v[82:85], v[176:179], v[220:223], v[82:85]
	v_mfma_f32_16x16x32_bf16 v[70:73], v[168:171], v[228:231], v[70:73]
	v_mfma_f32_16x16x32_bf16 v[66:69], v[176:179], v[228:231], v[66:69]
	s_barrier
	s_setprio 0
	s_add_i32 s56, s67, s58
	v_lshl_add_u64 v[154:155], v[154:155], 0, s[16:17]
	s_mov_b32 m0, s56
	ds_read_b128 v[180:183], v159 offset:49152
	ds_read_b128 v[204:207], v159 offset:50176
	ds_read_b128 v[208:211], v159 offset:51200
	ds_read_b128 v[212:215], v159 offset:52224
	ds_read_b128 v[216:219], v159 offset:53248
	ds_read_b128 v[220:223], v159 offset:54272
	ds_read_b128 v[224:227], v159 offset:55296
	ds_read_b128 v[228:231], v159 offset:56320
	global_load_lds_dwordx4 v[154:155], off
	s_add_i32 m0, s56, 0x2000
	s_add_u32 s54, s54, 0x40080
	v_lshl_add_u64 v[154:155], v[184:185], 0, s[16:17]
	s_addc_u32 s55, s55, 0
	s_add_i32 s56, s68, s58
	global_load_lds_dwordx4 v[154:155], off
	v_lshl_add_u64 v[154:155], s[54:55], 0, v[134:135]
	s_mov_b32 m0, s56
	s_nop 0
	global_load_lds_dwordx4 v[154:155], off
	v_lshl_add_u64 v[154:155], s[54:55], 0, v[130:131]
	s_add_i32 m0, s56, 0x2000
	s_nop 0
	global_load_lds_dwordx4 v[154:155], off
	v_lshl_add_u64 v[154:155], v[240:241], 0, s[16:17]
	s_mov_b32 m0, s5
	s_nop 0
	global_load_lds_dwordx4 v[154:155], off
	v_lshl_add_u64 v[154:155], v[242:243], 0, s[16:17]
	s_mov_b32 m0, s6
	s_nop 0
	global_load_lds_dwordx4 v[154:155], off
	s_waitcnt vmcnt(8)
	s_waitcnt lgkmcnt(0)
	s_setprio 1
	s_barrier
	v_mfma_f32_16x16x32_bf16 v[62:65], v[142:145], v[180:183], v[62:65]
	v_mfma_f32_16x16x32_bf16 v[58:61], v[150:153], v[180:183], v[58:61]
	v_mfma_f32_16x16x32_bf16 v[46:49], v[142:145], v[208:211], v[46:49]
	v_mfma_f32_16x16x32_bf16 v[42:45], v[150:153], v[208:211], v[42:45]
	v_mfma_f32_16x16x32_bf16 v[30:33], v[142:145], v[216:219], v[30:33]
	v_mfma_f32_16x16x32_bf16 v[26:29], v[150:153], v[216:219], v[26:29]
	v_mfma_f32_16x16x32_bf16 v[14:17], v[142:145], v[224:227], v[14:17]
	v_mfma_f32_16x16x32_bf16 v[10:13], v[150:153], v[224:227], v[10:13]
	v_mfma_f32_16x16x32_bf16 v[62:65], v[146:149], v[204:207], v[62:65]
	v_mfma_f32_16x16x32_bf16 v[58:61], v[160:163], v[204:207], v[58:61]
	v_mfma_f32_16x16x32_bf16 v[46:49], v[146:149], v[212:215], v[46:49]
	v_mfma_f32_16x16x32_bf16 v[42:45], v[160:163], v[212:215], v[42:45]
	v_mfma_f32_16x16x32_bf16 v[30:33], v[146:149], v[220:223], v[30:33]
	v_mfma_f32_16x16x32_bf16 v[26:29], v[160:163], v[220:223], v[26:29]
	v_mfma_f32_16x16x32_bf16 v[14:17], v[146:149], v[228:231], v[14:17]
	v_mfma_f32_16x16x32_bf16 v[10:13], v[160:163], v[228:231], v[10:13]
	v_mfma_f32_16x16x32_bf16 v[54:57], v[164:167], v[180:183], v[54:57]
	v_mfma_f32_16x16x32_bf16 v[50:53], v[172:175], v[180:183], v[50:53]
	v_mfma_f32_16x16x32_bf16 v[38:41], v[164:167], v[208:211], v[38:41]
	v_mfma_f32_16x16x32_bf16 v[34:37], v[172:175], v[208:211], v[34:37]
	v_mfma_f32_16x16x32_bf16 v[22:25], v[164:167], v[216:219], v[22:25]
	v_mfma_f32_16x16x32_bf16 v[18:21], v[172:175], v[216:219], v[18:21]
	v_mfma_f32_16x16x32_bf16 v[6:9], v[164:167], v[224:227], v[6:9]
	v_mfma_f32_16x16x32_bf16 v[2:5], v[172:175], v[224:227], v[2:5]
	v_mfma_f32_16x16x32_bf16 v[54:57], v[168:171], v[204:207], v[54:57]
	v_mfma_f32_16x16x32_bf16 v[50:53], v[176:179], v[204:207], v[50:53]
	v_mfma_f32_16x16x32_bf16 v[38:41], v[168:171], v[212:215], v[38:41]
	v_mfma_f32_16x16x32_bf16 v[34:37], v[176:179], v[212:215], v[34:37]
	v_mfma_f32_16x16x32_bf16 v[22:25], v[168:171], v[220:223], v[22:25]
	v_mfma_f32_16x16x32_bf16 v[18:21], v[176:179], v[220:223], v[18:21]
	v_mfma_f32_16x16x32_bf16 v[6:9], v[168:171], v[228:231], v[6:9]
	v_mfma_f32_16x16x32_bf16 v[2:5], v[176:179], v[228:231], v[2:5]
	s_barrier
	s_setprio 0
	s_add_i32 s66, s66, 2
	s_add_u32 s52, s52, 0x100
	s_addc_u32 s53, s53, 0
	s_add_u32 s64, s64, 0x100
	s_addc_u32 s65, s65, 0
	s_cmp_gt_u32 s66, 13
	s_cbranch_scc0 .LBB0_422
	s_and_b64 vcc, exec, s[38:39]
	s_cbranch_vccz .LBB0_425
	s_barrier
.LBB0_425:
	s_ashr_i32 s51, s50, 31
	s_lshl_b64 s[52:53], s[50:51], 19
	s_add_u32 s41, s93, s52
	s_addc_u32 s45, s76, s53
	s_lshl_b32 s18, s18, 8
	s_ashr_i32 s19, s18, 31
	s_lshl_b64 s[18:19], s[18:19], 1
	s_add_u32 s52, s41, s18
	s_addc_u32 s53, s45, s19
	s_lshl_b32 s18, s50, 8
	s_ashr_i32 s19, s18, 31
	v_mov_b32_e32 v0, v156
	v_mov_b32_e32 v162, v157
	s_lshl_b64 s[18:19], s[18:19], 2
	s_add_u32 s50, s20, s18
	v_add_u32_e32 v0, s63, v0
	s_addc_u32 s51, s21, s19
	v_lshl_add_u64 v[142:143], v[0:1], 2, s[50:51]
	global_load_dword v163, v[142:143], off
	v_add_u32_e32 v154, 16, v0
	v_mov_b32_e32 v155, v1
	v_lshl_add_u64 v[142:143], v[154:155], 2, s[50:51]
	global_load_dword v155, v[142:143], off
	v_add_u32_e32 v152, 32, v0
	v_mov_b32_e32 v153, v1
	v_lshl_add_u64 v[142:143], v[152:153], 2, s[50:51]
	global_load_dword v164, v[142:143], off
	v_add_u32_e32 v150, 48, v0
	v_mov_b32_e32 v151, v1
	v_lshl_add_u64 v[142:143], v[150:151], 2, s[50:51]
	global_load_dword v153, v[142:143], off
	v_add_u32_e32 v148, 0x80, v0
	v_mov_b32_e32 v149, v1
	v_lshl_add_u64 v[142:143], v[148:149], 2, s[50:51]
	global_load_dword v151, v[142:143], off
	v_add_u32_e32 v146, 0x90, v0
	v_mov_b32_e32 v147, v1
	v_lshl_add_u64 v[142:143], v[146:147], 2, s[50:51]
	global_load_dword v149, v[142:143], off
	v_add_u32_e32 v144, 0xa0, v0
	v_mov_b32_e32 v145, v1
	v_lshl_add_u64 v[142:143], v[144:145], 2, s[50:51]
	global_load_dword v147, v[142:143], off
	v_add_u32_e32 v142, 0xb0, v0
	v_mov_b32_e32 v143, v1
	v_lshl_add_u64 v[160:161], v[142:143], 2, s[50:51]
	global_load_dword v145, v[160:161], off
	v_lshl_add_u32 v143, v162, 3, s4
	v_lshlrev_b32_e32 v161, 10, v0
	v_add_u32_e32 v0, v161, v143
	s_mov_b64 s[50:51], -1
	s_andn2_b64 vcc, exec, s[42:43]
	s_waitcnt vmcnt(0)
	v_fmamk_f32 v160, v163, 0x3a800000, v234
	v_rsq_f32_e32 v160, v160
	s_nop 0
	v_pk_mul_f32 v[126:127], v[126:127], v[160:161] op_sel_hi:[1,0]
	v_pk_mul_f32 v[162:163], v[124:125], v[160:161] op_sel_hi:[1,0]
	v_pk_mul_f32 v[124:125], v[122:123], v[160:161] op_sel_hi:[1,0]
	v_pk_mul_f32 v[128:129], v[128:129], v[160:161] op_sel_hi:[1,0]
	v_cvt_pk_bf16_f32 v122, v126, v127
	v_lshl_add_u64 v[126:127], v[0:1], 1, s[52:53]
	v_cvt_pk_bf16_f32 v123, v128, v129
	v_cvt_pk_bf16_f32 v124, v124, v125
	v_cvt_pk_bf16_f32 v125, v162, v163
	global_store_dwordx4 v[126:127], v[122:125], off
	v_pk_mul_f32 v[120:121], v[120:121], v[160:161] op_sel_hi:[1,0]
	v_pk_mul_f32 v[118:119], v[118:119], v[160:161] op_sel_hi:[1,0]
	v_pk_mul_f32 v[124:125], v[114:115], v[160:161] op_sel_hi:[1,0]
	v_add_u32_e32 v114, 0x80, v143
	v_add_u32_e32 v0, v114, v161
	v_pk_mul_f32 v[122:123], v[116:117], v[160:161] op_sel_hi:[1,0]
	v_cvt_pk_bf16_f32 v116, v118, v119
	v_cvt_pk_bf16_f32 v117, v120, v121
	v_lshl_add_u64 v[120:121], v[0:1], 1, s[52:53]
	v_fmamk_f32 v0, v155, 0x3a800000, v234
	v_cvt_pk_bf16_f32 v118, v124, v125
	v_cvt_pk_bf16_f32 v119, v122, v123
	global_store_dwordx4 v[120:121], v[116:119], off
	v_lshlrev_b32_e32 v115, 10, v154
	s_nop 0
	v_rsq_f32_e32 v116, v0
	v_add_u32_e32 v0, v115, v143
	v_pk_mul_f32 v[110:111], v[110:111], v[116:117] op_sel_hi:[1,0]
	v_pk_mul_f32 v[112:113], v[112:113], v[116:117] op_sel_hi:[1,0]
	v_pk_mul_f32 v[118:119], v[108:109], v[116:117] op_sel_hi:[1,0]
	v_pk_mul_f32 v[108:109], v[106:107], v[116:117] op_sel_hi:[1,0]
	v_cvt_pk_bf16_f32 v106, v110, v111
	v_cvt_pk_bf16_f32 v107, v112, v113
	v_lshl_add_u64 v[110:111], v[0:1], 1, s[52:53]
	v_pk_mul_f32 v[102:103], v[102:103], v[116:117] op_sel_hi:[1,0]
	v_add_u32_e32 v0, v115, v114
	v_cvt_pk_bf16_f32 v108, v108, v109
	v_cvt_pk_bf16_f32 v109, v118, v119
	global_store_dwordx4 v[110:111], v[106:109], off
	v_pk_mul_f32 v[104:105], v[104:105], v[116:117] op_sel_hi:[1,0]
	s_nop 0
	v_pk_mul_f32 v[106:107], v[100:101], v[116:117] op_sel_hi:[1,0]
	v_pk_mul_f32 v[100:101], v[98:99], v[116:117] op_sel_hi:[1,0]
	v_cvt_pk_bf16_f32 v98, v102, v103
	v_lshl_add_u64 v[102:103], v[0:1], 1, s[52:53]
	v_fmamk_f32 v0, v164, 0x3a800000, v234
	v_cvt_pk_bf16_f32 v99, v104, v105
	v_cvt_pk_bf16_f32 v100, v100, v101
	v_cvt_pk_bf16_f32 v101, v106, v107
	global_store_dwordx4 v[102:103], v[98:101], off
	s_nop 1
	v_rsq_f32_e32 v98, v0
	v_lshlrev_b32_e32 v99, 10, v152
	v_add_u32_e32 v0, v99, v143
	v_pk_mul_f32 v[94:95], v[94:95], v[98:99] op_sel_hi:[1,0]
	v_pk_mul_f32 v[96:97], v[96:97], v[98:99] op_sel_hi:[1,0]
	v_pk_mul_f32 v[100:101], v[92:93], v[98:99] op_sel_hi:[1,0]
	v_pk_mul_f32 v[92:93], v[90:91], v[98:99] op_sel_hi:[1,0]
	v_cvt_pk_bf16_f32 v90, v94, v95
	v_cvt_pk_bf16_f32 v91, v96, v97
	v_lshl_add_u64 v[94:95], v[0:1], 1, s[52:53]
	v_pk_mul_f32 v[86:87], v[86:87], v[98:99] op_sel_hi:[1,0]
	v_add_u32_e32 v0, v99, v114
	v_cvt_pk_bf16_f32 v92, v92, v93
	v_cvt_pk_bf16_f32 v93, v100, v101
	global_store_dwordx4 v[94:95], v[90:93], off
	v_pk_mul_f32 v[88:89], v[88:89], v[98:99] op_sel_hi:[1,0]
	s_nop 0
	v_pk_mul_f32 v[90:91], v[84:85], v[98:99] op_sel_hi:[1,0]
	v_pk_mul_f32 v[84:85], v[82:83], v[98:99] op_sel_hi:[1,0]
	v_cvt_pk_bf16_f32 v82, v86, v87
	v_lshl_add_u64 v[86:87], v[0:1], 1, s[52:53]
	v_fmamk_f32 v0, v153, 0x3a800000, v234
	v_cvt_pk_bf16_f32 v83, v88, v89
	v_cvt_pk_bf16_f32 v84, v84, v85
	v_cvt_pk_bf16_f32 v85, v90, v91
	global_store_dwordx4 v[86:87], v[82:85], off
	s_nop 1
	v_rsq_f32_e32 v82, v0
	v_lshlrev_b32_e32 v83, 10, v150
	v_add_u32_e32 v0, v83, v143
	v_pk_mul_f32 v[78:79], v[78:79], v[82:83] op_sel_hi:[1,0]
	v_pk_mul_f32 v[80:81], v[80:81], v[82:83] op_sel_hi:[1,0]
	v_pk_mul_f32 v[84:85], v[76:77], v[82:83] op_sel_hi:[1,0]
	v_pk_mul_f32 v[76:77], v[74:75], v[82:83] op_sel_hi:[1,0]
	v_cvt_pk_bf16_f32 v74, v78, v79
	v_cvt_pk_bf16_f32 v75, v80, v81
	v_lshl_add_u64 v[78:79], v[0:1], 1, s[52:53]
	v_pk_mul_f32 v[70:71], v[70:71], v[82:83] op_sel_hi:[1,0]
	v_add_u32_e32 v0, v83, v114
	v_cvt_pk_bf16_f32 v76, v76, v77
	v_cvt_pk_bf16_f32 v77, v84, v85
	global_store_dwordx4 v[78:79], v[74:77], off
	v_pk_mul_f32 v[72:73], v[72:73], v[82:83] op_sel_hi:[1,0]
	s_nop 0
	v_pk_mul_f32 v[74:75], v[68:69], v[82:83] op_sel_hi:[1,0]
	v_pk_mul_f32 v[68:69], v[66:67], v[82:83] op_sel_hi:[1,0]
	v_cvt_pk_bf16_f32 v66, v70, v71
	v_lshl_add_u64 v[70:71], v[0:1], 1, s[52:53]
	v_fmamk_f32 v0, v151, 0x3a800000, v234
	v_cvt_pk_bf16_f32 v67, v72, v73
	v_cvt_pk_bf16_f32 v68, v68, v69
	v_cvt_pk_bf16_f32 v69, v74, v75
	global_store_dwordx4 v[70:71], v[66:69], off
	s_nop 1
	v_rsq_f32_e32 v66, v0
	v_lshlrev_b32_e32 v67, 10, v148
	v_add_u32_e32 v0, v67, v143
	v_pk_mul_f32 v[62:63], v[62:63], v[66:67] op_sel_hi:[1,0]
	v_pk_mul_f32 v[64:65], v[64:65], v[66:67] op_sel_hi:[1,0]
	v_pk_mul_f32 v[68:69], v[60:61], v[66:67] op_sel_hi:[1,0]
	v_pk_mul_f32 v[60:61], v[58:59], v[66:67] op_sel_hi:[1,0]
	v_cvt_pk_bf16_f32 v58, v62, v63
	v_cvt_pk_bf16_f32 v59, v64, v65
	v_lshl_add_u64 v[62:63], v[0:1], 1, s[52:53]
	v_pk_mul_f32 v[54:55], v[54:55], v[66:67] op_sel_hi:[1,0]
	v_add_u32_e32 v0, v67, v114
	v_cvt_pk_bf16_f32 v60, v60, v61
	v_cvt_pk_bf16_f32 v61, v68, v69
	global_store_dwordx4 v[62:63], v[58:61], off
	v_pk_mul_f32 v[56:57], v[56:57], v[66:67] op_sel_hi:[1,0]
	s_nop 0
	v_pk_mul_f32 v[58:59], v[52:53], v[66:67] op_sel_hi:[1,0]
	v_pk_mul_f32 v[52:53], v[50:51], v[66:67] op_sel_hi:[1,0]
	v_cvt_pk_bf16_f32 v50, v54, v55
	v_lshl_add_u64 v[54:55], v[0:1], 1, s[52:53]
	v_fmamk_f32 v0, v149, 0x3a800000, v234
	v_cvt_pk_bf16_f32 v51, v56, v57
	v_cvt_pk_bf16_f32 v52, v52, v53
	v_cvt_pk_bf16_f32 v53, v58, v59
	global_store_dwordx4 v[54:55], v[50:53], off
	s_nop 1
	v_rsq_f32_e32 v50, v0
	v_lshlrev_b32_e32 v51, 10, v146
	v_add_u32_e32 v0, v51, v143
	v_pk_mul_f32 v[46:47], v[46:47], v[50:51] op_sel_hi:[1,0]
	v_pk_mul_f32 v[48:49], v[48:49], v[50:51] op_sel_hi:[1,0]
	v_pk_mul_f32 v[52:53], v[44:45], v[50:51] op_sel_hi:[1,0]
	v_pk_mul_f32 v[44:45], v[42:43], v[50:51] op_sel_hi:[1,0]
	v_cvt_pk_bf16_f32 v42, v46, v47
	v_cvt_pk_bf16_f32 v43, v48, v49
	v_lshl_add_u64 v[46:47], v[0:1], 1, s[52:53]
	v_pk_mul_f32 v[38:39], v[38:39], v[50:51] op_sel_hi:[1,0]
	v_add_u32_e32 v0, v51, v114
	v_cvt_pk_bf16_f32 v44, v44, v45
	v_cvt_pk_bf16_f32 v45, v52, v53
	global_store_dwordx4 v[46:47], v[42:45], off
	v_pk_mul_f32 v[40:41], v[40:41], v[50:51] op_sel_hi:[1,0]
	s_nop 0
	v_pk_mul_f32 v[42:43], v[36:37], v[50:51] op_sel_hi:[1,0]
	v_pk_mul_f32 v[36:37], v[34:35], v[50:51] op_sel_hi:[1,0]
	v_cvt_pk_bf16_f32 v34, v38, v39
	v_lshl_add_u64 v[38:39], v[0:1], 1, s[52:53]
	v_fmamk_f32 v0, v147, 0x3a800000, v234
	v_cvt_pk_bf16_f32 v35, v40, v41
	v_cvt_pk_bf16_f32 v36, v36, v37
	v_cvt_pk_bf16_f32 v37, v42, v43
	global_store_dwordx4 v[38:39], v[34:37], off
	s_nop 1
	v_rsq_f32_e32 v34, v0
	v_lshlrev_b32_e32 v35, 10, v144
	v_add_u32_e32 v0, v35, v143
	v_pk_mul_f32 v[30:31], v[30:31], v[34:35] op_sel_hi:[1,0]
	v_pk_mul_f32 v[32:33], v[32:33], v[34:35] op_sel_hi:[1,0]
	v_pk_mul_f32 v[36:37], v[28:29], v[34:35] op_sel_hi:[1,0]
	v_pk_mul_f32 v[28:29], v[26:27], v[34:35] op_sel_hi:[1,0]
	v_cvt_pk_bf16_f32 v26, v30, v31
	v_cvt_pk_bf16_f32 v27, v32, v33
	v_lshl_add_u64 v[30:31], v[0:1], 1, s[52:53]
	v_pk_mul_f32 v[22:23], v[22:23], v[34:35] op_sel_hi:[1,0]
	v_add_u32_e32 v0, v35, v114
	v_cvt_pk_bf16_f32 v28, v28, v29
	v_cvt_pk_bf16_f32 v29, v36, v37
	global_store_dwordx4 v[30:31], v[26:29], off
	v_pk_mul_f32 v[24:25], v[24:25], v[34:35] op_sel_hi:[1,0]
	s_nop 0
	v_pk_mul_f32 v[26:27], v[20:21], v[34:35] op_sel_hi:[1,0]
	v_pk_mul_f32 v[20:21], v[18:19], v[34:35] op_sel_hi:[1,0]
	v_cvt_pk_bf16_f32 v18, v22, v23
	v_lshl_add_u64 v[22:23], v[0:1], 1, s[52:53]
	v_fmamk_f32 v0, v145, 0x3a800000, v234
	v_cvt_pk_bf16_f32 v19, v24, v25
	v_cvt_pk_bf16_f32 v20, v20, v21
	v_cvt_pk_bf16_f32 v21, v26, v27
	global_store_dwordx4 v[22:23], v[18:21], off
	s_nop 1
	v_rsq_f32_e32 v18, v0
	v_lshlrev_b32_e32 v19, 10, v142
	v_add_u32_e32 v0, v19, v143
	v_pk_mul_f32 v[14:15], v[14:15], v[18:19] op_sel_hi:[1,0]
	v_pk_mul_f32 v[16:17], v[16:17], v[18:19] op_sel_hi:[1,0]
	v_pk_mul_f32 v[20:21], v[12:13], v[18:19] op_sel_hi:[1,0]
	v_pk_mul_f32 v[12:13], v[10:11], v[18:19] op_sel_hi:[1,0]
	v_cvt_pk_bf16_f32 v10, v14, v15
	v_cvt_pk_bf16_f32 v11, v16, v17
	v_lshl_add_u64 v[14:15], v[0:1], 1, s[52:53]
	v_pk_mul_f32 v[6:7], v[6:7], v[18:19] op_sel_hi:[1,0]
	v_add_u32_e32 v0, v19, v114
	v_cvt_pk_bf16_f32 v12, v12, v13
	v_cvt_pk_bf16_f32 v13, v20, v21
	global_store_dwordx4 v[14:15], v[10:13], off
	v_pk_mul_f32 v[8:9], v[8:9], v[18:19] op_sel_hi:[1,0]
	s_nop 0
	v_pk_mul_f32 v[10:11], v[4:5], v[18:19] op_sel_hi:[1,0]
	v_pk_mul_f32 v[4:5], v[2:3], v[18:19] op_sel_hi:[1,0]
	v_cvt_pk_bf16_f32 v2, v6, v7
	v_lshl_add_u64 v[6:7], v[0:1], 1, s[52:53]
	v_cvt_pk_bf16_f32 v3, v8, v9
	v_cvt_pk_bf16_f32 v4, v4, v5
	v_cvt_pk_bf16_f32 v5, v10, v11
	global_store_dwordx4 v[6:7], v[2:5], off
	s_cbranch_vccnz .LBB0_414
	s_mov_b32 s67, 0
	s_andn2_b64 vcc, exec, s[22:23]
	s_cbranch_vccnz .LBB0_413
	s_mov_b32 s67, 1
	s_branch .LBB0_413

.LBB0_473:
	v_readlane_b32 s52, v251, 33
	s_waitcnt vmcnt(0)
	v_bfe_u32 v159, v11, 4, 2
	s_lshl_b32 s6, s6, 5
	v_mov_b32_e32 v137, v1
	v_readlane_b32 s53, v251, 34
	v_and_b32_e32 v158, 15, v11
	v_lshlrev_b32_e32 v16, 4, v159
	v_lshlrev_b32_e32 v11, 2, v11
	s_and_b32 s85, s6, 0x60
	s_add_i32 m0, s71, 0x18000
	v_lshl_add_u64 v[2:3], v[2:3], 0, s[16:17]
	v_lshl_add_u64 v[12:13], s[52:53], 0, v[136:137]
	v_mov_b32_e32 v133, v1
	s_lshl_b32 s75, s7, 6
	v_lshl_or_b32 v16, v158, 6, v16
	s_lshl_b32 s7, s7, 13
	v_and_b32_e32 v11, 32, v11
	s_lshl_b32 s6, s85, 7
	s_waitcnt vmcnt(2)
	s_barrier
	global_load_lds_dwordx4 v[2:3], off
	v_lshl_add_u64 v[2:3], v[4:5], 0, s[16:17]
	s_add_i32 m0, s71, 0x1a000
	s_add_i32 s86, s71, 0x8000
	s_add_i32 s87, s71, 0xa000
	v_lshl_add_u64 v[14:15], s[52:53], 0, v[132:133]
	v_bitop3_b32 v160, v16, s6, v11 bitop3:0xde
	global_load_lds_dwordx4 v[2:3], off
	v_lshl_add_u64 v[2:3], v[12:13], 0, s[16:17]
	s_mov_b32 m0, s86
	s_add_u32 s6, s54, 0x40080
	v_bitop3_b32 v17, v16, s7, v11 bitop3:0xde
	global_load_lds_dwordx4 v[2:3], off
	v_lshl_add_u64 v[2:3], v[14:15], 0, s[16:17]
	s_mov_b32 m0, s87
	s_addc_u32 s7, s55, 0
	global_load_lds_dwordx4 v[2:3], off
	s_add_i32 m0, s71, 0x1c000
	v_lshl_add_u64 v[2:3], s[6:7], 0, v[134:135]
	global_load_lds_dwordx4 v[2:3], off
	v_lshl_add_u64 v[2:3], s[6:7], 0, v[130:131]
	s_add_i32 m0, s71, 0x1e000
	v_readlane_b32 s6, v250, 20
	global_load_lds_dwordx4 v[2:3], off
	v_lshlrev_b32_e32 v2, 14, v9
	v_and_b32_e32 v2, 0xffff8000, v2
	v_lshl_add_u32 v2, v8, 11, v2
	v_and_b32_e32 v3, 1, v9
	v_lshl_or_b32 v2, v3, 6, v2
	s_cmpk_lt_u32 s5, 0x100
	s_mul_i32 s5, s6, 0xc000000
	v_lshl_add_u32 v138, v10, 1, v2
	v_lshlrev_b32_e32 v2, 14, v0
	s_cselect_b64 s[38:39], -1, 0
	s_add_u32 s5, s26, s5
	v_and_b32_e32 v2, 0xffff8000, v2
	s_waitcnt vmcnt(6)
	v_readlane_b32 s7, v250, 21
	s_addc_u32 s6, s27, 0
	v_lshl_add_u32 v2, v6, 11, v2
	v_and_b32_e32 v0, 1, v0
	s_add_u32 s7, s26, s4
	v_lshl_or_b32 v0, v0, 6, v2
	v_writelane_b32 v250, s5, 26
	s_addc_u32 s4, s27, 0
	v_mov_b32_e32 v139, v1
	v_lshl_add_u32 v140, v7, 1, v0
	v_mov_b32_e32 v141, v1
	s_mov_b32 s5, 0
	v_add_u32_e32 v161, 0, v17
	v_readlane_b32 s18, v251, 21
	v_readlane_b32 s44, v251, 31
	s_barrier
	v_readlane_b32 s45, v251, 32
	s_mov_b32 s61, 0
	s_branch .LBB0_476

.LBB0_478:
	s_ashr_i32 s47, s46, 31
	s_lshl_b64 s[48:49], s[46:47], 19
	s_add_u32 s48, s96, s48
	s_addc_u32 s49, s97, s49
	s_and_b64 s[50:51], s[42:43], exec
	s_cselect_b32 s19, s49, s53
	s_cselect_b32 s45, s48, s52
	s_ashr_i32 s41, s40, 31
	s_lshl_b64 s[50:51], s[40:41], 19
	s_add_u32 s50, s22, s50
	s_addc_u32 s51, s23, s51
	s_and_b64 s[56:57], s[42:43], exec
	s_cselect_b32 s41, s51, s55
	s_cselect_b32 s47, s50, s54
	s_add_u32 s52, s52, 0x40080
	s_addc_u32 s53, s53, 0
	s_add_u32 s58, s54, 0x100
	s_addc_u32 s59, s55, 0
	s_mov_b32 s60, -2
	s_cmp_eq_u32 s61, 0
	s_cbranch_scc1 .Lrb3_skip
	s_barrier
.Lrb3_skip:
	s_add_u32 s54, s52, 0xfffc0080
	s_addc_u32 s55, s53, -1
	s_add_i32 s61, 0, 0x10000
	s_cmp_eq_u32 s60, 12
	s_cselect_b32 s57, s19, s55
	s_cselect_b32 s56, s45, s54
	v_add_u32_e32 v0, s61, v160
	s_cselect_b32 s55, s41, s59
	s_cselect_b32 s54, s47, s58
	s_add_i32 s64, 0, 0x14000
	ds_read_b128 v[142:145], v0
	ds_read_b128 v[146:149], v0 offset:1024
	ds_read_b128 v[150:153], v0 offset:2048
	ds_read_b128 v[154:157], v0 offset:3072
	v_add_u32_e32 v0, s64, v160
	ds_read_b128 v[162:165], v0
	ds_read_b128 v[166:169], v0 offset:1024
	ds_read_b128 v[170:173], v0 offset:2048
	ds_read_b128 v[174:177], v0 offset:3072
	v_lshl_add_u64 v[228:229], s[52:53], 0, v[138:139]
	s_add_i32 m0, s71, 0xc000
	ds_read_b128 v[178:181], v161
	ds_read_b128 v[182:185], v161 offset:1024
	ds_read_b128 v[204:207], v161 offset:2048
	ds_read_b128 v[208:211], v161 offset:3072
	ds_read_b128 v[212:215], v161 offset:4096
	ds_read_b128 v[216:219], v161 offset:5120
	ds_read_b128 v[220:223], v161 offset:6144
	ds_read_b128 v[224:227], v161 offset:7168
	global_load_lds_dwordx4 v[228:229], off
	v_lshl_add_u64 v[228:229], s[52:53], 0, v[140:141]
	s_add_i32 m0, s71, 0xe000
	s_nop 0
	global_load_lds_dwordx4 v[228:229], off
	s_waitcnt vmcnt(8)
	s_waitcnt lgkmcnt(0)
	s_setprio 1
	s_barrier
	v_mfma_f32_16x16x32_bf16 v[126:129], v[142:145], v[178:181], 0
	v_mfma_f32_16x16x32_bf16 v[122:125], v[150:153], v[178:181], 0
	v_mfma_f32_16x16x32_bf16 v[110:113], v[142:145], v[204:207], 0
	v_mfma_f32_16x16x32_bf16 v[106:109], v[150:153], v[204:207], 0
	v_mfma_f32_16x16x32_bf16 v[94:97], v[142:145], v[212:215], 0
	v_mfma_f32_16x16x32_bf16 v[90:93], v[150:153], v[212:215], 0
	v_mfma_f32_16x16x32_bf16 v[78:81], v[142:145], v[220:223], 0
	v_mfma_f32_16x16x32_bf16 v[74:77], v[150:153], v[220:223], 0
	v_mfma_f32_16x16x32_bf16 v[126:129], v[146:149], v[182:185], v[126:129]
	v_mfma_f32_16x16x32_bf16 v[122:125], v[154:157], v[182:185], v[122:125]
	v_mfma_f32_16x16x32_bf16 v[110:113], v[146:149], v[208:211], v[110:113]
	v_mfma_f32_16x16x32_bf16 v[106:109], v[154:157], v[208:211], v[106:109]
	v_mfma_f32_16x16x32_bf16 v[94:97], v[146:149], v[216:219], v[94:97]
	v_mfma_f32_16x16x32_bf16 v[90:93], v[154:157], v[216:219], v[90:93]
	v_mfma_f32_16x16x32_bf16 v[78:81], v[146:149], v[224:227], v[78:81]
	v_mfma_f32_16x16x32_bf16 v[74:77], v[154:157], v[224:227], v[74:77]
	v_mfma_f32_16x16x32_bf16 v[118:121], v[162:165], v[178:181], 0
	v_mfma_f32_16x16x32_bf16 v[114:117], v[170:173], v[178:181], 0
	v_mfma_f32_16x16x32_bf16 v[102:105], v[162:165], v[204:207], 0
	v_mfma_f32_16x16x32_bf16 v[98:101], v[170:173], v[204:207], 0
	v_mfma_f32_16x16x32_bf16 v[86:89], v[162:165], v[212:215], 0
	v_mfma_f32_16x16x32_bf16 v[82:85], v[170:173], v[212:215], 0
	v_mfma_f32_16x16x32_bf16 v[70:73], v[162:165], v[220:223], 0
	v_mfma_f32_16x16x32_bf16 v[66:69], v[170:173], v[220:223], 0
	v_mfma_f32_16x16x32_bf16 v[118:121], v[166:169], v[182:185], v[118:121]
	v_mfma_f32_16x16x32_bf16 v[114:117], v[174:177], v[182:185], v[114:117]
	v_mfma_f32_16x16x32_bf16 v[102:105], v[166:169], v[208:211], v[102:105]
	v_mfma_f32_16x16x32_bf16 v[98:101], v[174:177], v[208:211], v[98:101]
	v_mfma_f32_16x16x32_bf16 v[86:89], v[166:169], v[216:219], v[86:89]
	v_mfma_f32_16x16x32_bf16 v[82:85], v[174:177], v[216:219], v[82:85]
	v_mfma_f32_16x16x32_bf16 v[70:73], v[166:169], v[224:227], v[70:73]
	v_mfma_f32_16x16x32_bf16 v[66:69], v[174:177], v[224:227], v[66:69]
	s_barrier
	s_setprio 0
	s_add_i32 s61, s61, s70
	v_lshl_add_u64 v[228:229], s[54:55], 0, v[134:135]
	s_mov_b32 m0, s61
	ds_read_b128 v[178:181], v161 offset:16384
	ds_read_b128 v[182:185], v161 offset:17408
	ds_read_b128 v[204:207], v161 offset:18432
	ds_read_b128 v[208:211], v161 offset:19456
	ds_read_b128 v[212:215], v161 offset:20480
	ds_read_b128 v[216:219], v161 offset:21504
	ds_read_b128 v[220:223], v161 offset:22528
	ds_read_b128 v[224:227], v161 offset:23552
	global_load_lds_dwordx4 v[228:229], off
	s_add_i32 m0, s61, 0x2000
	s_add_u32 s62, s54, 0x40000
	v_lshl_add_u64 v[230:231], s[54:55], 0, v[130:131]
	s_addc_u32 s63, s55, 0
	s_add_i32 s61, s64, s70
	global_load_lds_dwordx4 v[230:231], off
	v_lshl_add_u64 v[240:241], s[62:63], 0, v[134:135]
	s_mov_b32 m0, s61
	v_lshl_add_u64 v[242:243], s[56:57], 0, v[132:133]
	global_load_lds_dwordx4 v[240:241], off
	v_lshl_add_u64 v[240:241], s[62:63], 0, v[130:131]
	s_add_i32 m0, s61, 0x2000
	s_nop 0
	global_load_lds_dwordx4 v[240:241], off
	v_lshl_add_u64 v[240:241], s[56:57], 0, v[136:137]
	s_mov_b32 m0, s71
	s_nop 0
	global_load_lds_dwordx4 v[240:241], off
	s_mov_b32 m0, s72
	s_nop 0
	global_load_lds_dwordx4 v[242:243], off
	s_waitcnt vmcnt(8)
	s_waitcnt lgkmcnt(0)
	s_setprio 1
	s_barrier
	v_mfma_f32_16x16x32_bf16 v[62:65], v[142:145], v[178:181], 0
	v_mfma_f32_16x16x32_bf16 v[58:61], v[150:153], v[178:181], 0
	v_mfma_f32_16x16x32_bf16 v[46:49], v[142:145], v[204:207], 0
	v_mfma_f32_16x16x32_bf16 v[42:45], v[150:153], v[204:207], 0
	v_mfma_f32_16x16x32_bf16 v[30:33], v[142:145], v[212:215], 0
	v_mfma_f32_16x16x32_bf16 v[26:29], v[150:153], v[212:215], 0
	v_mfma_f32_16x16x32_bf16 v[14:17], v[142:145], v[220:223], 0
	v_mfma_f32_16x16x32_bf16 v[10:13], v[150:153], v[220:223], 0
	v_mfma_f32_16x16x32_bf16 v[62:65], v[146:149], v[182:185], v[62:65]
	v_mfma_f32_16x16x32_bf16 v[58:61], v[154:157], v[182:185], v[58:61]
	v_mfma_f32_16x16x32_bf16 v[46:49], v[146:149], v[208:211], v[46:49]
	v_mfma_f32_16x16x32_bf16 v[42:45], v[154:157], v[208:211], v[42:45]
	v_mfma_f32_16x16x32_bf16 v[30:33], v[146:149], v[216:219], v[30:33]
	v_mfma_f32_16x16x32_bf16 v[26:29], v[154:157], v[216:219], v[26:29]
	v_mfma_f32_16x16x32_bf16 v[14:17], v[146:149], v[224:227], v[14:17]
	v_mfma_f32_16x16x32_bf16 v[10:13], v[154:157], v[224:227], v[10:13]
	v_mfma_f32_16x16x32_bf16 v[54:57], v[162:165], v[178:181], 0
	v_mfma_f32_16x16x32_bf16 v[50:53], v[170:173], v[178:181], 0
	v_mfma_f32_16x16x32_bf16 v[38:41], v[162:165], v[204:207], 0
	v_mfma_f32_16x16x32_bf16 v[34:37], v[170:173], v[204:207], 0
	v_mfma_f32_16x16x32_bf16 v[22:25], v[162:165], v[212:215], 0
	v_mfma_f32_16x16x32_bf16 v[18:21], v[170:173], v[212:215], 0
	v_mfma_f32_16x16x32_bf16 v[6:9], v[162:165], v[220:223], 0
	v_mfma_f32_16x16x32_bf16 v[2:5], v[170:173], v[220:223], 0
	v_mfma_f32_16x16x32_bf16 v[54:57], v[166:169], v[182:185], v[54:57]
	v_mfma_f32_16x16x32_bf16 v[50:53], v[174:177], v[182:185], v[50:53]
	v_mfma_f32_16x16x32_bf16 v[38:41], v[166:169], v[208:211], v[38:41]
	v_mfma_f32_16x16x32_bf16 v[34:37], v[174:177], v[208:211], v[34:37]
	v_mfma_f32_16x16x32_bf16 v[22:25], v[166:169], v[216:219], v[22:25]
	v_mfma_f32_16x16x32_bf16 v[18:21], v[174:177], v[216:219], v[18:21]
	v_mfma_f32_16x16x32_bf16 v[6:9], v[166:169], v[224:227], v[6:9]
	v_mfma_f32_16x16x32_bf16 v[2:5], v[174:177], v[224:227], v[2:5]
	s_barrier
	s_setprio 0
	s_add_i32 s61, 0, 0x18000
	v_add_u32_e32 v0, s61, v160
	s_add_i32 s62, 0, 0x1c000
	ds_read_b128 v[142:145], v0
	ds_read_b128 v[146:149], v0 offset:1024
	ds_read_b128 v[150:153], v0 offset:2048
	ds_read_b128 v[154:157], v0 offset:3072
	v_add_u32_e32 v0, s62, v160
	ds_read_b128 v[162:165], v0
	ds_read_b128 v[166:169], v0 offset:1024
	ds_read_b128 v[170:173], v0 offset:2048
	ds_read_b128 v[174:177], v0 offset:3072
	s_add_u32 s56, s56, 0x40000
	s_addc_u32 s57, s57, 0
	s_mov_b32 m0, s73
	v_lshl_add_u64 v[244:245], s[56:57], 0, v[136:137]
	ds_read_b128 v[178:181], v161 offset:32768
	ds_read_b128 v[182:185], v161 offset:33792
	ds_read_b128 v[204:207], v161 offset:34816
	ds_read_b128 v[208:211], v161 offset:35840
	ds_read_b128 v[212:215], v161 offset:36864
	ds_read_b128 v[216:219], v161 offset:37888
	ds_read_b128 v[220:223], v161 offset:38912
	ds_read_b128 v[224:227], v161 offset:39936
	global_load_lds_dwordx4 v[244:245], off
	v_lshl_add_u64 v[244:245], s[56:57], 0, v[132:133]
	s_mov_b32 m0, s74
	s_nop 0
	global_load_lds_dwordx4 v[244:245], off
	s_waitcnt vmcnt(8)
	s_waitcnt lgkmcnt(0)
	s_setprio 1
	s_barrier
	v_mfma_f32_16x16x32_bf16 v[126:129], v[142:145], v[178:181], v[126:129]
	v_mfma_f32_16x16x32_bf16 v[122:125], v[150:153], v[178:181], v[122:125]
	v_mfma_f32_16x16x32_bf16 v[110:113], v[142:145], v[204:207], v[110:113]
	v_mfma_f32_16x16x32_bf16 v[106:109], v[150:153], v[204:207], v[106:109]
	v_mfma_f32_16x16x32_bf16 v[94:97], v[142:145], v[212:215], v[94:97]
	v_mfma_f32_16x16x32_bf16 v[90:93], v[150:153], v[212:215], v[90:93]
	v_mfma_f32_16x16x32_bf16 v[78:81], v[142:145], v[220:223], v[78:81]
	v_mfma_f32_16x16x32_bf16 v[74:77], v[150:153], v[220:223], v[74:77]
	v_mfma_f32_16x16x32_bf16 v[126:129], v[146:149], v[182:185], v[126:129]
	v_mfma_f32_16x16x32_bf16 v[122:125], v[154:157], v[182:185], v[122:125]
	v_mfma_f32_16x16x32_bf16 v[110:113], v[146:149], v[208:211], v[110:113]
	v_mfma_f32_16x16x32_bf16 v[106:109], v[154:157], v[208:211], v[106:109]
	v_mfma_f32_16x16x32_bf16 v[94:97], v[146:149], v[216:219], v[94:97]
	v_mfma_f32_16x16x32_bf16 v[90:93], v[154:157], v[216:219], v[90:93]
	v_mfma_f32_16x16x32_bf16 v[78:81], v[146:149], v[224:227], v[78:81]
	v_mfma_f32_16x16x32_bf16 v[74:77], v[154:157], v[224:227], v[74:77]
	v_mfma_f32_16x16x32_bf16 v[118:121], v[162:165], v[178:181], v[118:121]
	v_mfma_f32_16x16x32_bf16 v[114:117], v[170:173], v[178:181], v[114:117]
	v_mfma_f32_16x16x32_bf16 v[102:105], v[162:165], v[204:207], v[102:105]
	v_mfma_f32_16x16x32_bf16 v[98:101], v[170:173], v[204:207], v[98:101]
	v_mfma_f32_16x16x32_bf16 v[86:89], v[162:165], v[212:215], v[86:89]
	v_mfma_f32_16x16x32_bf16 v[82:85], v[170:173], v[212:215], v[82:85]
	v_mfma_f32_16x16x32_bf16 v[70:73], v[162:165], v[220:223], v[70:73]
	v_mfma_f32_16x16x32_bf16 v[66:69], v[170:173], v[220:223], v[66:69]
	v_mfma_f32_16x16x32_bf16 v[118:121], v[166:169], v[182:185], v[118:121]
	v_mfma_f32_16x16x32_bf16 v[114:117], v[174:177], v[182:185], v[114:117]
	v_mfma_f32_16x16x32_bf16 v[102:105], v[166:169], v[208:211], v[102:105]
	v_mfma_f32_16x16x32_bf16 v[98:101], v[174:177], v[208:211], v[98:101]
	v_mfma_f32_16x16x32_bf16 v[86:89], v[166:169], v[216:219], v[86:89]
	v_mfma_f32_16x16x32_bf16 v[82:85], v[174:177], v[216:219], v[82:85]
	v_mfma_f32_16x16x32_bf16 v[70:73], v[166:169], v[224:227], v[70:73]
	v_mfma_f32_16x16x32_bf16 v[66:69], v[174:177], v[224:227], v[66:69]
	s_barrier
	s_setprio 0
	s_add_i32 s56, s61, s70
	v_lshl_add_u64 v[228:229], v[228:229], 0, s[16:17]
	s_mov_b32 m0, s56
	ds_read_b128 v[178:181], v161 offset:49152
	ds_read_b128 v[182:185], v161 offset:50176
	ds_read_b128 v[204:207], v161 offset:51200
	ds_read_b128 v[208:211], v161 offset:52224
	ds_read_b128 v[212:215], v161 offset:53248
	ds_read_b128 v[216:219], v161 offset:54272
	ds_read_b128 v[220:223], v161 offset:55296
	ds_read_b128 v[224:227], v161 offset:56320
	global_load_lds_dwordx4 v[228:229], off
	s_add_i32 m0, s56, 0x2000
	s_add_u32 s54, s54, 0x40080
	v_lshl_add_u64 v[228:229], v[230:231], 0, s[16:17]
	s_addc_u32 s55, s55, 0
	s_add_i32 s56, s62, s70
	global_load_lds_dwordx4 v[228:229], off
	v_lshl_add_u64 v[228:229], s[54:55], 0, v[134:135]
	s_mov_b32 m0, s56
	s_nop 0
	global_load_lds_dwordx4 v[228:229], off
	v_lshl_add_u64 v[228:229], s[54:55], 0, v[130:131]
	s_add_i32 m0, s56, 0x2000
	s_nop 0
	global_load_lds_dwordx4 v[228:229], off
	v_lshl_add_u64 v[228:229], v[240:241], 0, s[16:17]
	s_mov_b32 m0, s86
	s_nop 0
	global_load_lds_dwordx4 v[228:229], off
	v_lshl_add_u64 v[228:229], v[242:243], 0, s[16:17]
	s_mov_b32 m0, s87
	s_nop 0
	global_load_lds_dwordx4 v[228:229], off
	s_waitcnt vmcnt(8)
	s_waitcnt lgkmcnt(0)
	s_setprio 1
	s_barrier
	v_mfma_f32_16x16x32_bf16 v[62:65], v[142:145], v[178:181], v[62:65]
	v_mfma_f32_16x16x32_bf16 v[58:61], v[150:153], v[178:181], v[58:61]
	v_mfma_f32_16x16x32_bf16 v[46:49], v[142:145], v[204:207], v[46:49]
	v_mfma_f32_16x16x32_bf16 v[42:45], v[150:153], v[204:207], v[42:45]
	v_mfma_f32_16x16x32_bf16 v[30:33], v[142:145], v[212:215], v[30:33]
	v_mfma_f32_16x16x32_bf16 v[26:29], v[150:153], v[212:215], v[26:29]
	v_mfma_f32_16x16x32_bf16 v[14:17], v[142:145], v[220:223], v[14:17]
	v_mfma_f32_16x16x32_bf16 v[10:13], v[150:153], v[220:223], v[10:13]
	v_mfma_f32_16x16x32_bf16 v[62:65], v[146:149], v[182:185], v[62:65]
	v_mfma_f32_16x16x32_bf16 v[58:61], v[154:157], v[182:185], v[58:61]
	v_mfma_f32_16x16x32_bf16 v[46:49], v[146:149], v[208:211], v[46:49]
	v_mfma_f32_16x16x32_bf16 v[42:45], v[154:157], v[208:211], v[42:45]
	v_mfma_f32_16x16x32_bf16 v[30:33], v[146:149], v[216:219], v[30:33]
	v_mfma_f32_16x16x32_bf16 v[26:29], v[154:157], v[216:219], v[26:29]
	v_mfma_f32_16x16x32_bf16 v[14:17], v[146:149], v[224:227], v[14:17]
	v_mfma_f32_16x16x32_bf16 v[10:13], v[154:157], v[224:227], v[10:13]
	v_mfma_f32_16x16x32_bf16 v[54:57], v[162:165], v[178:181], v[54:57]
	v_mfma_f32_16x16x32_bf16 v[50:53], v[170:173], v[178:181], v[50:53]
	v_mfma_f32_16x16x32_bf16 v[38:41], v[162:165], v[204:207], v[38:41]
	v_mfma_f32_16x16x32_bf16 v[34:37], v[170:173], v[204:207], v[34:37]
	v_mfma_f32_16x16x32_bf16 v[22:25], v[162:165], v[212:215], v[22:25]
	v_mfma_f32_16x16x32_bf16 v[18:21], v[170:173], v[212:215], v[18:21]
	v_mfma_f32_16x16x32_bf16 v[6:9], v[162:165], v[220:223], v[6:9]
	v_mfma_f32_16x16x32_bf16 v[2:5], v[170:173], v[220:223], v[2:5]
	v_mfma_f32_16x16x32_bf16 v[54:57], v[166:169], v[182:185], v[54:57]
	v_mfma_f32_16x16x32_bf16 v[50:53], v[174:177], v[182:185], v[50:53]
	v_mfma_f32_16x16x32_bf16 v[38:41], v[166:169], v[208:211], v[38:41]
	v_mfma_f32_16x16x32_bf16 v[34:37], v[174:177], v[208:211], v[34:37]
	v_mfma_f32_16x16x32_bf16 v[22:25], v[166:169], v[216:219], v[22:25]
	v_mfma_f32_16x16x32_bf16 v[18:21], v[174:177], v[216:219], v[18:21]
	v_mfma_f32_16x16x32_bf16 v[6:9], v[166:169], v[224:227], v[6:9]
	v_mfma_f32_16x16x32_bf16 v[2:5], v[174:177], v[224:227], v[2:5]
	s_barrier
	s_setprio 0
	s_add_i32 s60, s60, 2
	s_add_u32 s52, s52, 0x100
	s_addc_u32 s53, s53, 0
	s_add_u32 s58, s58, 0x100
	s_addc_u32 s59, s59, 0
	s_cmp_gt_u32 s60, 13
.LBB0_479:
	s_add_u32 s54, s52, 0xfffc0080
	s_addc_u32 s55, s53, -1
	s_add_i32 s61, 0, 0x10000
	s_cmp_eq_u32 s60, 12
	s_cselect_b32 s57, s19, s55
	s_cselect_b32 s56, s45, s54
	v_add_u32_e32 v0, s61, v160
	s_cselect_b32 s55, s41, s59
	s_cselect_b32 s54, s47, s58
	s_add_i32 s64, 0, 0x14000
	ds_read_b128 v[142:145], v0
	ds_read_b128 v[146:149], v0 offset:1024
	ds_read_b128 v[150:153], v0 offset:2048
	ds_read_b128 v[154:157], v0 offset:3072
	v_add_u32_e32 v0, s64, v160
	ds_read_b128 v[162:165], v0
	ds_read_b128 v[166:169], v0 offset:1024
	ds_read_b128 v[170:173], v0 offset:2048
	ds_read_b128 v[174:177], v0 offset:3072
	v_lshl_add_u64 v[228:229], s[52:53], 0, v[138:139]
	s_add_i32 m0, s71, 0xc000
	ds_read_b128 v[178:181], v161
	ds_read_b128 v[182:185], v161 offset:1024
	ds_read_b128 v[204:207], v161 offset:2048
	ds_read_b128 v[208:211], v161 offset:3072
	ds_read_b128 v[212:215], v161 offset:4096
	ds_read_b128 v[216:219], v161 offset:5120
	ds_read_b128 v[220:223], v161 offset:6144
	ds_read_b128 v[224:227], v161 offset:7168
	global_load_lds_dwordx4 v[228:229], off
	v_lshl_add_u64 v[228:229], s[52:53], 0, v[140:141]
	s_add_i32 m0, s71, 0xe000
	s_nop 0
	global_load_lds_dwordx4 v[228:229], off
	s_waitcnt vmcnt(8)
	s_waitcnt lgkmcnt(0)
	s_setprio 1
	s_barrier
	v_mfma_f32_16x16x32_bf16 v[126:129], v[142:145], v[178:181], v[126:129]
	v_mfma_f32_16x16x32_bf16 v[122:125], v[150:153], v[178:181], v[122:125]
	v_mfma_f32_16x16x32_bf16 v[110:113], v[142:145], v[204:207], v[110:113]
	v_mfma_f32_16x16x32_bf16 v[106:109], v[150:153], v[204:207], v[106:109]
	v_mfma_f32_16x16x32_bf16 v[94:97], v[142:145], v[212:215], v[94:97]
	v_mfma_f32_16x16x32_bf16 v[90:93], v[150:153], v[212:215], v[90:93]
	v_mfma_f32_16x16x32_bf16 v[78:81], v[142:145], v[220:223], v[78:81]
	v_mfma_f32_16x16x32_bf16 v[74:77], v[150:153], v[220:223], v[74:77]
	v_mfma_f32_16x16x32_bf16 v[126:129], v[146:149], v[182:185], v[126:129]
	v_mfma_f32_16x16x32_bf16 v[122:125], v[154:157], v[182:185], v[122:125]
	v_mfma_f32_16x16x32_bf16 v[110:113], v[146:149], v[208:211], v[110:113]
	v_mfma_f32_16x16x32_bf16 v[106:109], v[154:157], v[208:211], v[106:109]
	v_mfma_f32_16x16x32_bf16 v[94:97], v[146:149], v[216:219], v[94:97]
	v_mfma_f32_16x16x32_bf16 v[90:93], v[154:157], v[216:219], v[90:93]
	v_mfma_f32_16x16x32_bf16 v[78:81], v[146:149], v[224:227], v[78:81]
	v_mfma_f32_16x16x32_bf16 v[74:77], v[154:157], v[224:227], v[74:77]
	v_mfma_f32_16x16x32_bf16 v[118:121], v[162:165], v[178:181], v[118:121]
	v_mfma_f32_16x16x32_bf16 v[114:117], v[170:173], v[178:181], v[114:117]
	v_mfma_f32_16x16x32_bf16 v[102:105], v[162:165], v[204:207], v[102:105]
	v_mfma_f32_16x16x32_bf16 v[98:101], v[170:173], v[204:207], v[98:101]
	v_mfma_f32_16x16x32_bf16 v[86:89], v[162:165], v[212:215], v[86:89]
	v_mfma_f32_16x16x32_bf16 v[82:85], v[170:173], v[212:215], v[82:85]
	v_mfma_f32_16x16x32_bf16 v[70:73], v[162:165], v[220:223], v[70:73]
	v_mfma_f32_16x16x32_bf16 v[66:69], v[170:173], v[220:223], v[66:69]
	v_mfma_f32_16x16x32_bf16 v[118:121], v[166:169], v[182:185], v[118:121]
	v_mfma_f32_16x16x32_bf16 v[114:117], v[174:177], v[182:185], v[114:117]
	v_mfma_f32_16x16x32_bf16 v[102:105], v[166:169], v[208:211], v[102:105]
	v_mfma_f32_16x16x32_bf16 v[98:101], v[174:177], v[208:211], v[98:101]
	v_mfma_f32_16x16x32_bf16 v[86:89], v[166:169], v[216:219], v[86:89]
	v_mfma_f32_16x16x32_bf16 v[82:85], v[174:177], v[216:219], v[82:85]
	v_mfma_f32_16x16x32_bf16 v[70:73], v[166:169], v[224:227], v[70:73]
	v_mfma_f32_16x16x32_bf16 v[66:69], v[174:177], v[224:227], v[66:69]
	s_barrier
	s_setprio 0
	s_add_i32 s61, s61, s70
	v_lshl_add_u64 v[228:229], s[54:55], 0, v[134:135]
	s_mov_b32 m0, s61
	ds_read_b128 v[178:181], v161 offset:16384
	ds_read_b128 v[182:185], v161 offset:17408
	ds_read_b128 v[204:207], v161 offset:18432
	ds_read_b128 v[208:211], v161 offset:19456
	ds_read_b128 v[212:215], v161 offset:20480
	ds_read_b128 v[216:219], v161 offset:21504
	ds_read_b128 v[220:223], v161 offset:22528
	ds_read_b128 v[224:227], v161 offset:23552
	global_load_lds_dwordx4 v[228:229], off
	s_add_i32 m0, s61, 0x2000
	s_add_u32 s62, s54, 0x40000
	v_lshl_add_u64 v[230:231], s[54:55], 0, v[130:131]
	s_addc_u32 s63, s55, 0
	s_add_i32 s61, s64, s70
	global_load_lds_dwordx4 v[230:231], off
	v_lshl_add_u64 v[240:241], s[62:63], 0, v[134:135]
	s_mov_b32 m0, s61
	v_lshl_add_u64 v[242:243], s[56:57], 0, v[132:133]
	global_load_lds_dwordx4 v[240:241], off
	v_lshl_add_u64 v[240:241], s[62:63], 0, v[130:131]
	s_add_i32 m0, s61, 0x2000
	s_nop 0
	global_load_lds_dwordx4 v[240:241], off
	v_lshl_add_u64 v[240:241], s[56:57], 0, v[136:137]
	s_mov_b32 m0, s71
	s_nop 0
	global_load_lds_dwordx4 v[240:241], off
	s_mov_b32 m0, s72
	s_nop 0
	global_load_lds_dwordx4 v[242:243], off
	s_waitcnt vmcnt(8)
	s_waitcnt lgkmcnt(0)
	s_setprio 1
	s_barrier
	v_mfma_f32_16x16x32_bf16 v[62:65], v[142:145], v[178:181], v[62:65]
	v_mfma_f32_16x16x32_bf16 v[58:61], v[150:153], v[178:181], v[58:61]
	v_mfma_f32_16x16x32_bf16 v[46:49], v[142:145], v[204:207], v[46:49]
	v_mfma_f32_16x16x32_bf16 v[42:45], v[150:153], v[204:207], v[42:45]
	v_mfma_f32_16x16x32_bf16 v[30:33], v[142:145], v[212:215], v[30:33]
	v_mfma_f32_16x16x32_bf16 v[26:29], v[150:153], v[212:215], v[26:29]
	v_mfma_f32_16x16x32_bf16 v[14:17], v[142:145], v[220:223], v[14:17]
	v_mfma_f32_16x16x32_bf16 v[10:13], v[150:153], v[220:223], v[10:13]
	v_mfma_f32_16x16x32_bf16 v[62:65], v[146:149], v[182:185], v[62:65]
	v_mfma_f32_16x16x32_bf16 v[58:61], v[154:157], v[182:185], v[58:61]
	v_mfma_f32_16x16x32_bf16 v[46:49], v[146:149], v[208:211], v[46:49]
	v_mfma_f32_16x16x32_bf16 v[42:45], v[154:157], v[208:211], v[42:45]
	v_mfma_f32_16x16x32_bf16 v[30:33], v[146:149], v[216:219], v[30:33]
	v_mfma_f32_16x16x32_bf16 v[26:29], v[154:157], v[216:219], v[26:29]
	v_mfma_f32_16x16x32_bf16 v[14:17], v[146:149], v[224:227], v[14:17]
	v_mfma_f32_16x16x32_bf16 v[10:13], v[154:157], v[224:227], v[10:13]
	v_mfma_f32_16x16x32_bf16 v[54:57], v[162:165], v[178:181], v[54:57]
	v_mfma_f32_16x16x32_bf16 v[50:53], v[170:173], v[178:181], v[50:53]
	v_mfma_f32_16x16x32_bf16 v[38:41], v[162:165], v[204:207], v[38:41]
	v_mfma_f32_16x16x32_bf16 v[34:37], v[170:173], v[204:207], v[34:37]
	v_mfma_f32_16x16x32_bf16 v[22:25], v[162:165], v[212:215], v[22:25]
	v_mfma_f32_16x16x32_bf16 v[18:21], v[170:173], v[212:215], v[18:21]
	v_mfma_f32_16x16x32_bf16 v[6:9], v[162:165], v[220:223], v[6:9]
	v_mfma_f32_16x16x32_bf16 v[2:5], v[170:173], v[220:223], v[2:5]
	v_mfma_f32_16x16x32_bf16 v[54:57], v[166:169], v[182:185], v[54:57]
	v_mfma_f32_16x16x32_bf16 v[50:53], v[174:177], v[182:185], v[50:53]
	v_mfma_f32_16x16x32_bf16 v[38:41], v[166:169], v[208:211], v[38:41]
	v_mfma_f32_16x16x32_bf16 v[34:37], v[174:177], v[208:211], v[34:37]
	v_mfma_f32_16x16x32_bf16 v[22:25], v[166:169], v[216:219], v[22:25]
	v_mfma_f32_16x16x32_bf16 v[18:21], v[174:177], v[216:219], v[18:21]
	v_mfma_f32_16x16x32_bf16 v[6:9], v[166:169], v[224:227], v[6:9]
	v_mfma_f32_16x16x32_bf16 v[2:5], v[174:177], v[224:227], v[2:5]
	s_barrier
	s_setprio 0
	s_add_i32 s61, 0, 0x18000
	v_add_u32_e32 v0, s61, v160
	s_add_i32 s62, 0, 0x1c000
	ds_read_b128 v[142:145], v0
	ds_read_b128 v[146:149], v0 offset:1024
	ds_read_b128 v[150:153], v0 offset:2048
	ds_read_b128 v[154:157], v0 offset:3072
	v_add_u32_e32 v0, s62, v160
	ds_read_b128 v[162:165], v0
	ds_read_b128 v[166:169], v0 offset:1024
	ds_read_b128 v[170:173], v0 offset:2048
	ds_read_b128 v[174:177], v0 offset:3072
	s_add_u32 s56, s56, 0x40000
	s_addc_u32 s57, s57, 0
	s_mov_b32 m0, s73
	v_lshl_add_u64 v[244:245], s[56:57], 0, v[136:137]
	ds_read_b128 v[178:181], v161 offset:32768
	ds_read_b128 v[182:185], v161 offset:33792
	ds_read_b128 v[204:207], v161 offset:34816
	ds_read_b128 v[208:211], v161 offset:35840
	ds_read_b128 v[212:215], v161 offset:36864
	ds_read_b128 v[216:219], v161 offset:37888
	ds_read_b128 v[220:223], v161 offset:38912
	ds_read_b128 v[224:227], v161 offset:39936
	global_load_lds_dwordx4 v[244:245], off
	v_lshl_add_u64 v[244:245], s[56:57], 0, v[132:133]
	s_mov_b32 m0, s74
	s_nop 0
	global_load_lds_dwordx4 v[244:245], off
	s_waitcnt vmcnt(8)
	s_waitcnt lgkmcnt(0)
	s_setprio 1
	s_barrier
	v_mfma_f32_16x16x32_bf16 v[126:129], v[142:145], v[178:181], v[126:129]
	v_mfma_f32_16x16x32_bf16 v[122:125], v[150:153], v[178:181], v[122:125]
	v_mfma_f32_16x16x32_bf16 v[110:113], v[142:145], v[204:207], v[110:113]
	v_mfma_f32_16x16x32_bf16 v[106:109], v[150:153], v[204:207], v[106:109]
	v_mfma_f32_16x16x32_bf16 v[94:97], v[142:145], v[212:215], v[94:97]
	v_mfma_f32_16x16x32_bf16 v[90:93], v[150:153], v[212:215], v[90:93]
	v_mfma_f32_16x16x32_bf16 v[78:81], v[142:145], v[220:223], v[78:81]
	v_mfma_f32_16x16x32_bf16 v[74:77], v[150:153], v[220:223], v[74:77]
	v_mfma_f32_16x16x32_bf16 v[126:129], v[146:149], v[182:185], v[126:129]
	v_mfma_f32_16x16x32_bf16 v[122:125], v[154:157], v[182:185], v[122:125]
	v_mfma_f32_16x16x32_bf16 v[110:113], v[146:149], v[208:211], v[110:113]
	v_mfma_f32_16x16x32_bf16 v[106:109], v[154:157], v[208:211], v[106:109]
	v_mfma_f32_16x16x32_bf16 v[94:97], v[146:149], v[216:219], v[94:97]
	v_mfma_f32_16x16x32_bf16 v[90:93], v[154:157], v[216:219], v[90:93]
	v_mfma_f32_16x16x32_bf16 v[78:81], v[146:149], v[224:227], v[78:81]
	v_mfma_f32_16x16x32_bf16 v[74:77], v[154:157], v[224:227], v[74:77]
	v_mfma_f32_16x16x32_bf16 v[118:121], v[162:165], v[178:181], v[118:121]
	v_mfma_f32_16x16x32_bf16 v[114:117], v[170:173], v[178:181], v[114:117]
	v_mfma_f32_16x16x32_bf16 v[102:105], v[162:165], v[204:207], v[102:105]
	v_mfma_f32_16x16x32_bf16 v[98:101], v[170:173], v[204:207], v[98:101]
	v_mfma_f32_16x16x32_bf16 v[86:89], v[162:165], v[212:215], v[86:89]
	v_mfma_f32_16x16x32_bf16 v[82:85], v[170:173], v[212:215], v[82:85]
	v_mfma_f32_16x16x32_bf16 v[70:73], v[162:165], v[220:223], v[70:73]
	v_mfma_f32_16x16x32_bf16 v[66:69], v[170:173], v[220:223], v[66:69]
	v_mfma_f32_16x16x32_bf16 v[118:121], v[166:169], v[182:185], v[118:121]
	v_mfma_f32_16x16x32_bf16 v[114:117], v[174:177], v[182:185], v[114:117]
	v_mfma_f32_16x16x32_bf16 v[102:105], v[166:169], v[208:211], v[102:105]
	v_mfma_f32_16x16x32_bf16 v[98:101], v[174:177], v[208:211], v[98:101]
	v_mfma_f32_16x16x32_bf16 v[86:89], v[166:169], v[216:219], v[86:89]
	v_mfma_f32_16x16x32_bf16 v[82:85], v[174:177], v[216:219], v[82:85]
	v_mfma_f32_16x16x32_bf16 v[70:73], v[166:169], v[224:227], v[70:73]
	v_mfma_f32_16x16x32_bf16 v[66:69], v[174:177], v[224:227], v[66:69]
	s_barrier
	s_setprio 0
	s_add_i32 s56, s61, s70
	v_lshl_add_u64 v[228:229], v[228:229], 0, s[16:17]
	s_mov_b32 m0, s56
	ds_read_b128 v[178:181], v161 offset:49152
	ds_read_b128 v[182:185], v161 offset:50176
	ds_read_b128 v[204:207], v161 offset:51200
	ds_read_b128 v[208:211], v161 offset:52224
	ds_read_b128 v[212:215], v161 offset:53248
	ds_read_b128 v[216:219], v161 offset:54272
	ds_read_b128 v[220:223], v161 offset:55296
	ds_read_b128 v[224:227], v161 offset:56320
	global_load_lds_dwordx4 v[228:229], off
	s_add_i32 m0, s56, 0x2000
	s_add_u32 s54, s54, 0x40080
	v_lshl_add_u64 v[228:229], v[230:231], 0, s[16:17]
	s_addc_u32 s55, s55, 0
	s_add_i32 s56, s62, s70
	global_load_lds_dwordx4 v[228:229], off
	v_lshl_add_u64 v[228:229], s[54:55], 0, v[134:135]
	s_mov_b32 m0, s56
	s_nop 0
	global_load_lds_dwordx4 v[228:229], off
	v_lshl_add_u64 v[228:229], s[54:55], 0, v[130:131]
	s_add_i32 m0, s56, 0x2000
	s_nop 0
	global_load_lds_dwordx4 v[228:229], off
	v_lshl_add_u64 v[228:229], v[240:241], 0, s[16:17]
	s_mov_b32 m0, s86
	s_nop 0
	global_load_lds_dwordx4 v[228:229], off
	v_lshl_add_u64 v[228:229], v[242:243], 0, s[16:17]
	s_mov_b32 m0, s87
	s_nop 0
	global_load_lds_dwordx4 v[228:229], off
	s_waitcnt vmcnt(8)
	s_waitcnt lgkmcnt(0)
	s_setprio 1
	s_barrier
	v_mfma_f32_16x16x32_bf16 v[62:65], v[142:145], v[178:181], v[62:65]
	v_mfma_f32_16x16x32_bf16 v[58:61], v[150:153], v[178:181], v[58:61]
	v_mfma_f32_16x16x32_bf16 v[46:49], v[142:145], v[204:207], v[46:49]
	v_mfma_f32_16x16x32_bf16 v[42:45], v[150:153], v[204:207], v[42:45]
	v_mfma_f32_16x16x32_bf16 v[30:33], v[142:145], v[212:215], v[30:33]
	v_mfma_f32_16x16x32_bf16 v[26:29], v[150:153], v[212:215], v[26:29]
	v_mfma_f32_16x16x32_bf16 v[14:17], v[142:145], v[220:223], v[14:17]
	v_mfma_f32_16x16x32_bf16 v[10:13], v[150:153], v[220:223], v[10:13]
	v_mfma_f32_16x16x32_bf16 v[62:65], v[146:149], v[182:185], v[62:65]
	v_mfma_f32_16x16x32_bf16 v[58:61], v[154:157], v[182:185], v[58:61]
	v_mfma_f32_16x16x32_bf16 v[46:49], v[146:149], v[208:211], v[46:49]
	v_mfma_f32_16x16x32_bf16 v[42:45], v[154:157], v[208:211], v[42:45]
	v_mfma_f32_16x16x32_bf16 v[30:33], v[146:149], v[216:219], v[30:33]
	v_mfma_f32_16x16x32_bf16 v[26:29], v[154:157], v[216:219], v[26:29]
	v_mfma_f32_16x16x32_bf16 v[14:17], v[146:149], v[224:227], v[14:17]
	v_mfma_f32_16x16x32_bf16 v[10:13], v[154:157], v[224:227], v[10:13]
	v_mfma_f32_16x16x32_bf16 v[54:57], v[162:165], v[178:181], v[54:57]
	v_mfma_f32_16x16x32_bf16 v[50:53], v[170:173], v[178:181], v[50:53]
	v_mfma_f32_16x16x32_bf16 v[38:41], v[162:165], v[204:207], v[38:41]
	v_mfma_f32_16x16x32_bf16 v[34:37], v[170:173], v[204:207], v[34:37]
	v_mfma_f32_16x16x32_bf16 v[22:25], v[162:165], v[212:215], v[22:25]
	v_mfma_f32_16x16x32_bf16 v[18:21], v[170:173], v[212:215], v[18:21]
	v_mfma_f32_16x16x32_bf16 v[6:9], v[162:165], v[220:223], v[6:9]
	v_mfma_f32_16x16x32_bf16 v[2:5], v[170:173], v[220:223], v[2:5]
	v_mfma_f32_16x16x32_bf16 v[54:57], v[166:169], v[182:185], v[54:57]
	v_mfma_f32_16x16x32_bf16 v[50:53], v[174:177], v[182:185], v[50:53]
	v_mfma_f32_16x16x32_bf16 v[38:41], v[166:169], v[208:211], v[38:41]
	v_mfma_f32_16x16x32_bf16 v[34:37], v[174:177], v[208:211], v[34:37]
	v_mfma_f32_16x16x32_bf16 v[22:25], v[166:169], v[216:219], v[22:25]
	v_mfma_f32_16x16x32_bf16 v[18:21], v[174:177], v[216:219], v[18:21]
	v_mfma_f32_16x16x32_bf16 v[6:9], v[166:169], v[224:227], v[6:9]
	v_mfma_f32_16x16x32_bf16 v[2:5], v[174:177], v[224:227], v[2:5]
	s_barrier
	s_setprio 0
	s_add_i32 s60, s60, 2
	s_add_u32 s52, s52, 0x100
	s_addc_u32 s53, s53, 0
	s_add_u32 s58, s58, 0x100
	s_addc_u32 s59, s59, 0
	s_cmp_gt_u32 s60, 13
	s_cbranch_scc0 .LBB0_479
	s_and_b64 vcc, exec, s[38:39]
	s_cbranch_vccz .LBB0_482
	s_barrier

.LBB0_522:
	s_andn2_b64 vcc, exec, s[42:43]
	s_mov_b64 s[42:43], -1
	s_cbranch_vccnz .LBB0_475
	s_mov_b32 s61, 0
	s_andn2_b64 vcc, exec, s[0:1]
	s_cbranch_vccnz .LBB0_474
	s_mov_b32 s61, 1
	s_branch .LBB0_474

.Ltramp_205:
	s_branch .LBB0_205

.LBB0_890:
	v_mov_b32_e32 v209, v1
	v_lshl_add_u64 v[8:9], s[54:55], 0, v[208:209]
	v_mov_b32_e32 v205, v1
	v_readlane_b32 s52, v251, 37
	v_bfe_u32 v219, v7, 4, 2
	s_lshl_b32 s1, s1, 5
	v_lshl_add_u64 v[10:11], s[54:55], 0, v[204:205]
	v_mov_b32_e32 v211, v1
	v_readlane_b32 s53, v251, 38
	v_and_b32_e32 v220, 15, v7
	v_lshlrev_b32_e32 v16, 4, v219
	v_lshlrev_b32_e32 v7, 2, v7
	s_and_b32 s64, s1, 0x60
	s_add_i32 m0, s59, 0x18000
	v_lshl_add_u64 v[8:9], v[8:9], 0, s[16:17]
	v_lshl_add_u64 v[12:13], s[52:53], 0, v[210:211]
	v_mov_b32_e32 v207, v1
	s_lshl_b32 s63, s4, 6
	v_lshl_or_b32 v16, v220, 6, v16
	s_lshl_b32 s4, s4, 13
	v_and_b32_e32 v7, 32, v7
	s_lshl_b32 s1, s64, 7
	s_waitcnt vmcnt(2)
	s_barrier
	global_load_lds_dwordx4 v[8:9], off
	v_lshl_add_u64 v[8:9], v[10:11], 0, s[16:17]
	s_add_i32 m0, s59, 0x1a000
	s_add_i32 s65, s59, 0x8000
	s_add_i32 s66, s59, 0xa000
	v_lshl_add_u64 v[14:15], s[52:53], 0, v[206:207]
	v_bitop3_b32 v17, v16, s4, v7 bitop3:0xde
	global_load_lds_dwordx4 v[8:9], off
	v_lshl_add_u64 v[8:9], v[12:13], 0, s[16:17]
	s_mov_b32 m0, s65
	s_add_u32 s4, s54, 0x40080
	global_load_lds_dwordx4 v[8:9], off
	v_lshl_add_u64 v[8:9], v[14:15], 0, s[16:17]
	s_mov_b32 m0, s66
	s_addc_u32 s5, s55, 0
	global_load_lds_dwordx4 v[8:9], off
	s_add_i32 m0, s59, 0x1c000
	v_lshl_add_u64 v[8:9], s[4:5], 0, v[208:209]
	global_load_lds_dwordx4 v[8:9], off
	v_lshl_add_u64 v[8:9], s[4:5], 0, v[204:205]
	s_add_i32 m0, s59, 0x1e000
	v_bitop3_b32 v221, v16, s1, v7 bitop3:0xde
	global_load_lds_dwordx4 v[8:9], off
	v_lshlrev_b32_e32 v7, 14, v5
	v_and_b32_e32 v7, 0xffff8000, v7
	v_lshl_add_u32 v4, v4, 11, v7
	v_and_b32_e32 v5, 1, v5
	v_lshl_or_b32 v4, v5, 6, v4
	v_lshl_add_u32 v212, v6, 1, v4
	v_lshlrev_b32_e32 v4, 14, v0
	v_and_b32_e32 v4, 0xffff8000, v4
	s_waitcnt vmcnt(6)
	v_lshl_add_u32 v2, v2, 11, v4
	v_and_b32_e32 v0, 1, v0
	s_cmpk_lt_u32 s0, 0x100
	v_lshl_or_b32 v0, v0, 6, v2
	s_cselect_b64 s[40:41], -1, 0
	v_mov_b32_e32 v213, v1
	v_lshl_add_u32 v214, v3, 1, v0
	v_mov_b32_e32 v215, v1
	s_mov_b32 s67, 0
	v_add_u32_e32 v222, 0, v17
	v_readlane_b32 s4, v251, 63
	v_readlane_b32 s0, v251, 23
	s_barrier
	v_readlane_b32 s1, v251, 24
	s_mov_b32 s68, 0
	s_branch .LBB0_893

.LBB0_899:
	s_ashr_i32 s47, s46, 31
	s_lshl_b64 s[6:7], s[46:47], 19
	s_add_u32 s48, s93, s6
	s_addc_u32 s49, s76, s7
	s_and_b64 s[6:7], s[42:43], exec
	s_cselect_b32 s1, s49, s53
	s_cselect_b32 s5, s48, s52
	s_ashr_i32 s45, s44, 31
	s_lshl_b64 s[6:7], s[44:45], 19
	s_add_u32 s50, s22, s6
	s_addc_u32 s51, s23, s7
	s_and_b64 s[6:7], s[42:43], exec
	s_cselect_b32 s6, s51, s55
	s_cselect_b32 s7, s50, s54
	s_add_u32 s52, s52, 0x40080
	s_addc_u32 s53, s53, 0
	s_add_u32 s18, s54, 0x100
	s_addc_u32 s19, s55, 0
	s_mov_b32 s45, -2
	s_waitcnt lgkmcnt(0)
	s_waitcnt vmcnt(0)
	s_cmp_eq_u32 s68, 0
	s_cbranch_scc1 .Lrb4_skip
	s_barrier
.Lrb4_skip:
	s_add_u32 s47, s52, 0xfffc0080
	s_addc_u32 s54, s53, -1
	s_add_i32 s68, 0, 0x10000
	s_cmp_eq_u32 s45, 12
	s_cselect_b32 s57, s1, s54
	s_cselect_b32 s56, s5, s47
	v_add_u32_e32 v0, s68, v221
	s_cselect_b32 s55, s6, s19
	s_cselect_b32 s54, s7, s18
	s_add_i32 s47, 0, 0x14000
	ds_read_b128 v[106:109], v0
	ds_read_b128 v[110:113], v0 offset:1024
	ds_read_b128 v[126:129], v0 offset:2048
	ds_read_b128 v[134:137], v0 offset:3072
	v_add_u32_e32 v0, s47, v221
	ds_read_b128 v[146:149], v0
	ds_read_b128 v[150:153], v0 offset:1024
	ds_read_b128 v[154:157], v0 offset:2048
	ds_read_b128 v[158:161], v0 offset:3072
	v_lshl_add_u64 v[216:217], s[52:53], 0, v[212:213]
	s_add_i32 m0, s59, 0xc000
	ds_read_b128 v[162:165], v222
	ds_read_b128 v[166:169], v222 offset:1024
	ds_read_b128 v[170:173], v222 offset:2048
	ds_read_b128 v[174:177], v222 offset:3072
	ds_read_b128 v[178:181], v222 offset:4096
	ds_read_b128 v[182:185], v222 offset:5120
	ds_read_b128 v[224:227], v222 offset:6144
	ds_read_b128 v[228:231], v222 offset:7168
	global_load_lds_dwordx4 v[216:217], off
	v_lshl_add_u64 v[216:217], s[52:53], 0, v[214:215]
	s_add_i32 m0, s59, 0xe000
	s_nop 0
	global_load_lds_dwordx4 v[216:217], off
	s_waitcnt vmcnt(8)
	s_waitcnt lgkmcnt(0)
	s_setprio 1
	s_barrier
	v_mfma_f32_16x16x32_bf16 v[142:145], v[106:109], v[162:165], 0
	v_mfma_f32_16x16x32_bf16 v[138:141], v[126:129], v[162:165], 0
	v_mfma_f32_16x16x32_bf16 v[118:121], v[106:109], v[170:173], 0
	v_mfma_f32_16x16x32_bf16 v[114:117], v[126:129], v[170:173], 0
	v_mfma_f32_16x16x32_bf16 v[94:97], v[106:109], v[178:181], 0
	v_mfma_f32_16x16x32_bf16 v[90:93], v[126:129], v[178:181], 0
	v_mfma_f32_16x16x32_bf16 v[78:81], v[106:109], v[224:227], 0
	v_mfma_f32_16x16x32_bf16 v[74:77], v[126:129], v[224:227], 0
	v_mfma_f32_16x16x32_bf16 v[142:145], v[110:113], v[166:169], v[142:145]
	v_mfma_f32_16x16x32_bf16 v[138:141], v[134:137], v[166:169], v[138:141]
	v_mfma_f32_16x16x32_bf16 v[118:121], v[110:113], v[174:177], v[118:121]
	v_mfma_f32_16x16x32_bf16 v[114:117], v[134:137], v[174:177], v[114:117]
	v_mfma_f32_16x16x32_bf16 v[94:97], v[110:113], v[182:185], v[94:97]
	v_mfma_f32_16x16x32_bf16 v[90:93], v[134:137], v[182:185], v[90:93]
	v_mfma_f32_16x16x32_bf16 v[78:81], v[110:113], v[228:231], v[78:81]
	v_mfma_f32_16x16x32_bf16 v[74:77], v[134:137], v[228:231], v[74:77]
	v_mfma_f32_16x16x32_bf16 v[130:133], v[146:149], v[162:165], 0
	v_mfma_f32_16x16x32_bf16 v[122:125], v[154:157], v[162:165], 0
	v_mfma_f32_16x16x32_bf16 v[102:105], v[146:149], v[170:173], 0
	v_mfma_f32_16x16x32_bf16 v[98:101], v[154:157], v[170:173], 0
	v_mfma_f32_16x16x32_bf16 v[86:89], v[146:149], v[178:181], 0
	v_mfma_f32_16x16x32_bf16 v[82:85], v[154:157], v[178:181], 0
	v_mfma_f32_16x16x32_bf16 v[70:73], v[146:149], v[224:227], 0
	v_mfma_f32_16x16x32_bf16 v[66:69], v[154:157], v[224:227], 0
	v_mfma_f32_16x16x32_bf16 v[130:133], v[150:153], v[166:169], v[130:133]
	v_mfma_f32_16x16x32_bf16 v[122:125], v[158:161], v[166:169], v[122:125]
	v_mfma_f32_16x16x32_bf16 v[102:105], v[150:153], v[174:177], v[102:105]
	v_mfma_f32_16x16x32_bf16 v[98:101], v[158:161], v[174:177], v[98:101]
	v_mfma_f32_16x16x32_bf16 v[86:89], v[150:153], v[182:185], v[86:89]
	v_mfma_f32_16x16x32_bf16 v[82:85], v[158:161], v[182:185], v[82:85]
	v_mfma_f32_16x16x32_bf16 v[70:73], v[150:153], v[228:231], v[70:73]
	v_mfma_f32_16x16x32_bf16 v[66:69], v[158:161], v[228:231], v[66:69]
	s_barrier
	s_setprio 0
	s_add_i32 s68, s68, s58
	v_lshl_add_u64 v[216:217], s[54:55], 0, v[208:209]
	s_mov_b32 m0, s68
	ds_read_b128 v[162:165], v222 offset:16384
	ds_read_b128 v[166:169], v222 offset:17408
	ds_read_b128 v[170:173], v222 offset:18432
	ds_read_b128 v[174:177], v222 offset:19456
	ds_read_b128 v[178:181], v222 offset:20480
	ds_read_b128 v[182:185], v222 offset:21504
	ds_read_b128 v[224:227], v222 offset:22528
	ds_read_b128 v[228:231], v222 offset:23552
	global_load_lds_dwordx4 v[216:217], off
	s_add_i32 m0, s68, 0x2000
	s_add_u32 s68, s54, 0x40000
	v_lshl_add_u64 v[240:241], s[54:55], 0, v[204:205]
	s_addc_u32 s69, s55, 0
	s_add_i32 s47, s47, s58
	global_load_lds_dwordx4 v[240:241], off
	v_lshl_add_u64 v[242:243], s[68:69], 0, v[208:209]
	s_mov_b32 m0, s47
	v_lshl_add_u64 v[244:245], s[56:57], 0, v[206:207]
	global_load_lds_dwordx4 v[242:243], off
	v_lshl_add_u64 v[242:243], s[68:69], 0, v[204:205]
	s_add_i32 m0, s47, 0x2000
	s_nop 0
	global_load_lds_dwordx4 v[242:243], off
	v_lshl_add_u64 v[242:243], s[56:57], 0, v[210:211]
	s_mov_b32 m0, s59
	s_nop 0
	global_load_lds_dwordx4 v[242:243], off
	s_mov_b32 m0, s60
	s_nop 0
	global_load_lds_dwordx4 v[244:245], off
	s_waitcnt vmcnt(8)
	s_waitcnt lgkmcnt(0)
	s_setprio 1
	s_barrier
	v_mfma_f32_16x16x32_bf16 v[62:65], v[106:109], v[162:165], 0
	v_mfma_f32_16x16x32_bf16 v[58:61], v[126:129], v[162:165], 0
	v_mfma_f32_16x16x32_bf16 v[46:49], v[106:109], v[170:173], 0
	v_mfma_f32_16x16x32_bf16 v[42:45], v[126:129], v[170:173], 0
	v_mfma_f32_16x16x32_bf16 v[30:33], v[106:109], v[178:181], 0
	v_mfma_f32_16x16x32_bf16 v[26:29], v[126:129], v[178:181], 0
	v_mfma_f32_16x16x32_bf16 v[14:17], v[106:109], v[224:227], 0
	v_mfma_f32_16x16x32_bf16 v[10:13], v[126:129], v[224:227], 0
	v_mfma_f32_16x16x32_bf16 v[62:65], v[110:113], v[166:169], v[62:65]
	v_mfma_f32_16x16x32_bf16 v[58:61], v[134:137], v[166:169], v[58:61]
	v_mfma_f32_16x16x32_bf16 v[46:49], v[110:113], v[174:177], v[46:49]
	v_mfma_f32_16x16x32_bf16 v[42:45], v[134:137], v[174:177], v[42:45]
	v_mfma_f32_16x16x32_bf16 v[30:33], v[110:113], v[182:185], v[30:33]
	v_mfma_f32_16x16x32_bf16 v[26:29], v[134:137], v[182:185], v[26:29]
	v_mfma_f32_16x16x32_bf16 v[14:17], v[110:113], v[228:231], v[14:17]
	v_mfma_f32_16x16x32_bf16 v[10:13], v[134:137], v[228:231], v[10:13]
	v_mfma_f32_16x16x32_bf16 v[54:57], v[146:149], v[162:165], 0
	v_mfma_f32_16x16x32_bf16 v[50:53], v[154:157], v[162:165], 0
	v_mfma_f32_16x16x32_bf16 v[38:41], v[146:149], v[170:173], 0
	v_mfma_f32_16x16x32_bf16 v[34:37], v[154:157], v[170:173], 0
	v_mfma_f32_16x16x32_bf16 v[22:25], v[146:149], v[178:181], 0
	v_mfma_f32_16x16x32_bf16 v[18:21], v[154:157], v[178:181], 0
	v_mfma_f32_16x16x32_bf16 v[6:9], v[146:149], v[224:227], 0
	v_mfma_f32_16x16x32_bf16 v[2:5], v[154:157], v[224:227], 0
	v_mfma_f32_16x16x32_bf16 v[54:57], v[150:153], v[166:169], v[54:57]
	v_mfma_f32_16x16x32_bf16 v[50:53], v[158:161], v[166:169], v[50:53]
	v_mfma_f32_16x16x32_bf16 v[38:41], v[150:153], v[174:177], v[38:41]
	v_mfma_f32_16x16x32_bf16 v[34:37], v[158:161], v[174:177], v[34:37]
	v_mfma_f32_16x16x32_bf16 v[22:25], v[150:153], v[182:185], v[22:25]
	v_mfma_f32_16x16x32_bf16 v[18:21], v[158:161], v[182:185], v[18:21]
	v_mfma_f32_16x16x32_bf16 v[6:9], v[150:153], v[228:231], v[6:9]
	v_mfma_f32_16x16x32_bf16 v[2:5], v[158:161], v[228:231], v[2:5]
	s_barrier
	s_setprio 0
	s_add_i32 s47, 0, 0x18000
	v_add_u32_e32 v0, s47, v221
	s_add_i32 s68, 0, 0x1c000
	ds_read_b128 v[106:109], v0
	ds_read_b128 v[110:113], v0 offset:1024
	ds_read_b128 v[126:129], v0 offset:2048
	ds_read_b128 v[134:137], v0 offset:3072
	v_add_u32_e32 v0, s68, v221
	ds_read_b128 v[146:149], v0
	ds_read_b128 v[150:153], v0 offset:1024
	ds_read_b128 v[154:157], v0 offset:2048
	ds_read_b128 v[158:161], v0 offset:3072
	s_add_u32 s56, s56, 0x40000
	s_addc_u32 s57, s57, 0
	s_mov_b32 m0, s61
	v_lshl_add_u64 v[246:247], s[56:57], 0, v[210:211]
	ds_read_b128 v[162:165], v222 offset:32768
	ds_read_b128 v[166:169], v222 offset:33792
	ds_read_b128 v[170:173], v222 offset:34816
	ds_read_b128 v[174:177], v222 offset:35840
	ds_read_b128 v[178:181], v222 offset:36864
	ds_read_b128 v[182:185], v222 offset:37888
	ds_read_b128 v[224:227], v222 offset:38912
	ds_read_b128 v[228:231], v222 offset:39936
	global_load_lds_dwordx4 v[246:247], off
	v_lshl_add_u64 v[246:247], s[56:57], 0, v[206:207]
	s_mov_b32 m0, s62
	s_nop 0
	global_load_lds_dwordx4 v[246:247], off
	s_waitcnt vmcnt(8)
	s_waitcnt lgkmcnt(0)
	s_setprio 1
	s_barrier
	v_mfma_f32_16x16x32_bf16 v[142:145], v[106:109], v[162:165], v[142:145]
	v_mfma_f32_16x16x32_bf16 v[138:141], v[126:129], v[162:165], v[138:141]
	v_mfma_f32_16x16x32_bf16 v[118:121], v[106:109], v[170:173], v[118:121]
	v_mfma_f32_16x16x32_bf16 v[114:117], v[126:129], v[170:173], v[114:117]
	v_mfma_f32_16x16x32_bf16 v[94:97], v[106:109], v[178:181], v[94:97]
	v_mfma_f32_16x16x32_bf16 v[90:93], v[126:129], v[178:181], v[90:93]
	v_mfma_f32_16x16x32_bf16 v[78:81], v[106:109], v[224:227], v[78:81]
	v_mfma_f32_16x16x32_bf16 v[74:77], v[126:129], v[224:227], v[74:77]
	v_mfma_f32_16x16x32_bf16 v[142:145], v[110:113], v[166:169], v[142:145]
	v_mfma_f32_16x16x32_bf16 v[138:141], v[134:137], v[166:169], v[138:141]
	v_mfma_f32_16x16x32_bf16 v[118:121], v[110:113], v[174:177], v[118:121]
	v_mfma_f32_16x16x32_bf16 v[114:117], v[134:137], v[174:177], v[114:117]
	v_mfma_f32_16x16x32_bf16 v[94:97], v[110:113], v[182:185], v[94:97]
	v_mfma_f32_16x16x32_bf16 v[90:93], v[134:137], v[182:185], v[90:93]
	v_mfma_f32_16x16x32_bf16 v[78:81], v[110:113], v[228:231], v[78:81]
	v_mfma_f32_16x16x32_bf16 v[74:77], v[134:137], v[228:231], v[74:77]
	v_mfma_f32_16x16x32_bf16 v[130:133], v[146:149], v[162:165], v[130:133]
	v_mfma_f32_16x16x32_bf16 v[122:125], v[154:157], v[162:165], v[122:125]
	v_mfma_f32_16x16x32_bf16 v[102:105], v[146:149], v[170:173], v[102:105]
	v_mfma_f32_16x16x32_bf16 v[98:101], v[154:157], v[170:173], v[98:101]
	v_mfma_f32_16x16x32_bf16 v[86:89], v[146:149], v[178:181], v[86:89]
	v_mfma_f32_16x16x32_bf16 v[82:85], v[154:157], v[178:181], v[82:85]
	v_mfma_f32_16x16x32_bf16 v[70:73], v[146:149], v[224:227], v[70:73]
	v_mfma_f32_16x16x32_bf16 v[66:69], v[154:157], v[224:227], v[66:69]
	v_mfma_f32_16x16x32_bf16 v[130:133], v[150:153], v[166:169], v[130:133]
	v_mfma_f32_16x16x32_bf16 v[122:125], v[158:161], v[166:169], v[122:125]
	v_mfma_f32_16x16x32_bf16 v[102:105], v[150:153], v[174:177], v[102:105]
	v_mfma_f32_16x16x32_bf16 v[98:101], v[158:161], v[174:177], v[98:101]
	v_mfma_f32_16x16x32_bf16 v[86:89], v[150:153], v[182:185], v[86:89]
	v_mfma_f32_16x16x32_bf16 v[82:85], v[158:161], v[182:185], v[82:85]
	v_mfma_f32_16x16x32_bf16 v[70:73], v[150:153], v[228:231], v[70:73]
	v_mfma_f32_16x16x32_bf16 v[66:69], v[158:161], v[228:231], v[66:69]
	s_barrier
	s_setprio 0
	s_add_i32 s47, s47, s58
	v_lshl_add_u64 v[216:217], v[216:217], 0, s[16:17]
	s_mov_b32 m0, s47
	ds_read_b128 v[162:165], v222 offset:49152
	ds_read_b128 v[166:169], v222 offset:50176
	ds_read_b128 v[170:173], v222 offset:51200
	ds_read_b128 v[174:177], v222 offset:52224
	ds_read_b128 v[178:181], v222 offset:53248
	ds_read_b128 v[182:185], v222 offset:54272
	ds_read_b128 v[224:227], v222 offset:55296
	ds_read_b128 v[228:231], v222 offset:56320
	global_load_lds_dwordx4 v[216:217], off
	s_add_i32 m0, s47, 0x2000
	s_add_u32 s54, s54, 0x40080
	v_lshl_add_u64 v[216:217], v[240:241], 0, s[16:17]
	s_addc_u32 s55, s55, 0
	s_add_i32 s47, s68, s58
	global_load_lds_dwordx4 v[216:217], off
	v_lshl_add_u64 v[216:217], s[54:55], 0, v[208:209]
	s_mov_b32 m0, s47
	s_nop 0
	global_load_lds_dwordx4 v[216:217], off
	v_lshl_add_u64 v[216:217], s[54:55], 0, v[204:205]
	s_add_i32 m0, s47, 0x2000
	s_nop 0
	global_load_lds_dwordx4 v[216:217], off
	v_lshl_add_u64 v[216:217], v[242:243], 0, s[16:17]
	s_mov_b32 m0, s65
	s_nop 0
	global_load_lds_dwordx4 v[216:217], off
	v_lshl_add_u64 v[216:217], v[244:245], 0, s[16:17]
	s_mov_b32 m0, s66
	s_nop 0
	global_load_lds_dwordx4 v[216:217], off
	s_waitcnt vmcnt(8)
	s_waitcnt lgkmcnt(0)
	s_setprio 1
	s_barrier
	v_mfma_f32_16x16x32_bf16 v[62:65], v[106:109], v[162:165], v[62:65]
	v_mfma_f32_16x16x32_bf16 v[58:61], v[126:129], v[162:165], v[58:61]
	v_mfma_f32_16x16x32_bf16 v[46:49], v[106:109], v[170:173], v[46:49]
	v_mfma_f32_16x16x32_bf16 v[42:45], v[126:129], v[170:173], v[42:45]
	v_mfma_f32_16x16x32_bf16 v[30:33], v[106:109], v[178:181], v[30:33]
	v_mfma_f32_16x16x32_bf16 v[26:29], v[126:129], v[178:181], v[26:29]
	v_mfma_f32_16x16x32_bf16 v[14:17], v[106:109], v[224:227], v[14:17]
	v_mfma_f32_16x16x32_bf16 v[10:13], v[126:129], v[224:227], v[10:13]
	v_mfma_f32_16x16x32_bf16 v[62:65], v[110:113], v[166:169], v[62:65]
	v_mfma_f32_16x16x32_bf16 v[58:61], v[134:137], v[166:169], v[58:61]
	v_mfma_f32_16x16x32_bf16 v[46:49], v[110:113], v[174:177], v[46:49]
	v_mfma_f32_16x16x32_bf16 v[42:45], v[134:137], v[174:177], v[42:45]
	v_mfma_f32_16x16x32_bf16 v[30:33], v[110:113], v[182:185], v[30:33]
	v_mfma_f32_16x16x32_bf16 v[26:29], v[134:137], v[182:185], v[26:29]
	v_mfma_f32_16x16x32_bf16 v[14:17], v[110:113], v[228:231], v[14:17]
	v_mfma_f32_16x16x32_bf16 v[10:13], v[134:137], v[228:231], v[10:13]
	v_mfma_f32_16x16x32_bf16 v[54:57], v[146:149], v[162:165], v[54:57]
	v_mfma_f32_16x16x32_bf16 v[50:53], v[154:157], v[162:165], v[50:53]
	v_mfma_f32_16x16x32_bf16 v[38:41], v[146:149], v[170:173], v[38:41]
	v_mfma_f32_16x16x32_bf16 v[34:37], v[154:157], v[170:173], v[34:37]
	v_mfma_f32_16x16x32_bf16 v[22:25], v[146:149], v[178:181], v[22:25]
	v_mfma_f32_16x16x32_bf16 v[18:21], v[154:157], v[178:181], v[18:21]
	v_mfma_f32_16x16x32_bf16 v[6:9], v[146:149], v[224:227], v[6:9]
	v_mfma_f32_16x16x32_bf16 v[2:5], v[154:157], v[224:227], v[2:5]
	v_mfma_f32_16x16x32_bf16 v[54:57], v[150:153], v[166:169], v[54:57]
	v_mfma_f32_16x16x32_bf16 v[50:53], v[158:161], v[166:169], v[50:53]
	v_mfma_f32_16x16x32_bf16 v[38:41], v[150:153], v[174:177], v[38:41]
	v_mfma_f32_16x16x32_bf16 v[34:37], v[158:161], v[174:177], v[34:37]
	v_mfma_f32_16x16x32_bf16 v[22:25], v[150:153], v[182:185], v[22:25]
	v_mfma_f32_16x16x32_bf16 v[18:21], v[158:161], v[182:185], v[18:21]
	v_mfma_f32_16x16x32_bf16 v[6:9], v[150:153], v[228:231], v[6:9]
	v_mfma_f32_16x16x32_bf16 v[2:5], v[158:161], v[228:231], v[2:5]
	s_barrier
	s_setprio 0
	s_add_i32 s45, s45, 2
	s_add_u32 s52, s52, 0x100
	s_addc_u32 s53, s53, 0
	s_add_u32 s18, s18, 0x100
	s_addc_u32 s19, s19, 0
	s_cmp_gt_u32 s45, 13
.LBB0_900:
	s_add_u32 s47, s52, 0xfffc0080
	s_addc_u32 s54, s53, -1
	s_add_i32 s68, 0, 0x10000
	s_cmp_eq_u32 s45, 12
	s_cselect_b32 s57, s1, s54
	s_cselect_b32 s56, s5, s47
	v_add_u32_e32 v0, s68, v221
	s_cselect_b32 s55, s6, s19
	s_cselect_b32 s54, s7, s18
	s_add_i32 s47, 0, 0x14000
	ds_read_b128 v[106:109], v0
	ds_read_b128 v[110:113], v0 offset:1024
	ds_read_b128 v[126:129], v0 offset:2048
	ds_read_b128 v[134:137], v0 offset:3072
	v_add_u32_e32 v0, s47, v221
	ds_read_b128 v[146:149], v0
	ds_read_b128 v[150:153], v0 offset:1024
	ds_read_b128 v[154:157], v0 offset:2048
	ds_read_b128 v[158:161], v0 offset:3072
	v_lshl_add_u64 v[216:217], s[52:53], 0, v[212:213]
	s_add_i32 m0, s59, 0xc000
	ds_read_b128 v[162:165], v222
	ds_read_b128 v[166:169], v222 offset:1024
	ds_read_b128 v[170:173], v222 offset:2048
	ds_read_b128 v[174:177], v222 offset:3072
	ds_read_b128 v[178:181], v222 offset:4096
	ds_read_b128 v[182:185], v222 offset:5120
	ds_read_b128 v[224:227], v222 offset:6144
	ds_read_b128 v[228:231], v222 offset:7168
	global_load_lds_dwordx4 v[216:217], off
	v_lshl_add_u64 v[216:217], s[52:53], 0, v[214:215]
	s_add_i32 m0, s59, 0xe000
	s_nop 0
	global_load_lds_dwordx4 v[216:217], off
	s_waitcnt vmcnt(8)
	s_waitcnt lgkmcnt(0)
	s_setprio 1
	s_barrier
	v_mfma_f32_16x16x32_bf16 v[142:145], v[106:109], v[162:165], v[142:145]
	v_mfma_f32_16x16x32_bf16 v[138:141], v[126:129], v[162:165], v[138:141]
	v_mfma_f32_16x16x32_bf16 v[118:121], v[106:109], v[170:173], v[118:121]
	v_mfma_f32_16x16x32_bf16 v[114:117], v[126:129], v[170:173], v[114:117]
	v_mfma_f32_16x16x32_bf16 v[94:97], v[106:109], v[178:181], v[94:97]
	v_mfma_f32_16x16x32_bf16 v[90:93], v[126:129], v[178:181], v[90:93]
	v_mfma_f32_16x16x32_bf16 v[78:81], v[106:109], v[224:227], v[78:81]
	v_mfma_f32_16x16x32_bf16 v[74:77], v[126:129], v[224:227], v[74:77]
	v_mfma_f32_16x16x32_bf16 v[142:145], v[110:113], v[166:169], v[142:145]
	v_mfma_f32_16x16x32_bf16 v[138:141], v[134:137], v[166:169], v[138:141]
	v_mfma_f32_16x16x32_bf16 v[118:121], v[110:113], v[174:177], v[118:121]
	v_mfma_f32_16x16x32_bf16 v[114:117], v[134:137], v[174:177], v[114:117]
	v_mfma_f32_16x16x32_bf16 v[94:97], v[110:113], v[182:185], v[94:97]
	v_mfma_f32_16x16x32_bf16 v[90:93], v[134:137], v[182:185], v[90:93]
	v_mfma_f32_16x16x32_bf16 v[78:81], v[110:113], v[228:231], v[78:81]
	v_mfma_f32_16x16x32_bf16 v[74:77], v[134:137], v[228:231], v[74:77]
	v_mfma_f32_16x16x32_bf16 v[130:133], v[146:149], v[162:165], v[130:133]
	v_mfma_f32_16x16x32_bf16 v[122:125], v[154:157], v[162:165], v[122:125]
	v_mfma_f32_16x16x32_bf16 v[102:105], v[146:149], v[170:173], v[102:105]
	v_mfma_f32_16x16x32_bf16 v[98:101], v[154:157], v[170:173], v[98:101]
	v_mfma_f32_16x16x32_bf16 v[86:89], v[146:149], v[178:181], v[86:89]
	v_mfma_f32_16x16x32_bf16 v[82:85], v[154:157], v[178:181], v[82:85]
	v_mfma_f32_16x16x32_bf16 v[70:73], v[146:149], v[224:227], v[70:73]
	v_mfma_f32_16x16x32_bf16 v[66:69], v[154:157], v[224:227], v[66:69]
	v_mfma_f32_16x16x32_bf16 v[130:133], v[150:153], v[166:169], v[130:133]
	v_mfma_f32_16x16x32_bf16 v[122:125], v[158:161], v[166:169], v[122:125]
	v_mfma_f32_16x16x32_bf16 v[102:105], v[150:153], v[174:177], v[102:105]
	v_mfma_f32_16x16x32_bf16 v[98:101], v[158:161], v[174:177], v[98:101]
	v_mfma_f32_16x16x32_bf16 v[86:89], v[150:153], v[182:185], v[86:89]
	v_mfma_f32_16x16x32_bf16 v[82:85], v[158:161], v[182:185], v[82:85]
	v_mfma_f32_16x16x32_bf16 v[70:73], v[150:153], v[228:231], v[70:73]
	v_mfma_f32_16x16x32_bf16 v[66:69], v[158:161], v[228:231], v[66:69]
	s_barrier
	s_setprio 0
	s_add_i32 s68, s68, s58
	v_lshl_add_u64 v[216:217], s[54:55], 0, v[208:209]
	s_mov_b32 m0, s68
	ds_read_b128 v[162:165], v222 offset:16384
	ds_read_b128 v[166:169], v222 offset:17408
	ds_read_b128 v[170:173], v222 offset:18432
	ds_read_b128 v[174:177], v222 offset:19456
	ds_read_b128 v[178:181], v222 offset:20480
	ds_read_b128 v[182:185], v222 offset:21504
	ds_read_b128 v[224:227], v222 offset:22528
	ds_read_b128 v[228:231], v222 offset:23552
	global_load_lds_dwordx4 v[216:217], off
	s_add_i32 m0, s68, 0x2000
	s_add_u32 s68, s54, 0x40000
	v_lshl_add_u64 v[240:241], s[54:55], 0, v[204:205]
	s_addc_u32 s69, s55, 0
	s_add_i32 s47, s47, s58
	global_load_lds_dwordx4 v[240:241], off
	v_lshl_add_u64 v[242:243], s[68:69], 0, v[208:209]
	s_mov_b32 m0, s47
	v_lshl_add_u64 v[244:245], s[56:57], 0, v[206:207]
	global_load_lds_dwordx4 v[242:243], off
	v_lshl_add_u64 v[242:243], s[68:69], 0, v[204:205]
	s_add_i32 m0, s47, 0x2000
	s_nop 0
	global_load_lds_dwordx4 v[242:243], off
	v_lshl_add_u64 v[242:243], s[56:57], 0, v[210:211]
	s_mov_b32 m0, s59
	s_nop 0
	global_load_lds_dwordx4 v[242:243], off
	s_mov_b32 m0, s60
	s_nop 0
	global_load_lds_dwordx4 v[244:245], off
	s_waitcnt vmcnt(8)
	s_waitcnt lgkmcnt(0)
	s_setprio 1
	s_barrier
	v_mfma_f32_16x16x32_bf16 v[62:65], v[106:109], v[162:165], v[62:65]
	v_mfma_f32_16x16x32_bf16 v[58:61], v[126:129], v[162:165], v[58:61]
	v_mfma_f32_16x16x32_bf16 v[46:49], v[106:109], v[170:173], v[46:49]
	v_mfma_f32_16x16x32_bf16 v[42:45], v[126:129], v[170:173], v[42:45]
	v_mfma_f32_16x16x32_bf16 v[30:33], v[106:109], v[178:181], v[30:33]
	v_mfma_f32_16x16x32_bf16 v[26:29], v[126:129], v[178:181], v[26:29]
	v_mfma_f32_16x16x32_bf16 v[14:17], v[106:109], v[224:227], v[14:17]
	v_mfma_f32_16x16x32_bf16 v[10:13], v[126:129], v[224:227], v[10:13]
	v_mfma_f32_16x16x32_bf16 v[62:65], v[110:113], v[166:169], v[62:65]
	v_mfma_f32_16x16x32_bf16 v[58:61], v[134:137], v[166:169], v[58:61]
	v_mfma_f32_16x16x32_bf16 v[46:49], v[110:113], v[174:177], v[46:49]
	v_mfma_f32_16x16x32_bf16 v[42:45], v[134:137], v[174:177], v[42:45]
	v_mfma_f32_16x16x32_bf16 v[30:33], v[110:113], v[182:185], v[30:33]
	v_mfma_f32_16x16x32_bf16 v[26:29], v[134:137], v[182:185], v[26:29]
	v_mfma_f32_16x16x32_bf16 v[14:17], v[110:113], v[228:231], v[14:17]
	v_mfma_f32_16x16x32_bf16 v[10:13], v[134:137], v[228:231], v[10:13]
	v_mfma_f32_16x16x32_bf16 v[54:57], v[146:149], v[162:165], v[54:57]
	v_mfma_f32_16x16x32_bf16 v[50:53], v[154:157], v[162:165], v[50:53]
	v_mfma_f32_16x16x32_bf16 v[38:41], v[146:149], v[170:173], v[38:41]
	v_mfma_f32_16x16x32_bf16 v[34:37], v[154:157], v[170:173], v[34:37]
	v_mfma_f32_16x16x32_bf16 v[22:25], v[146:149], v[178:181], v[22:25]
	v_mfma_f32_16x16x32_bf16 v[18:21], v[154:157], v[178:181], v[18:21]
	v_mfma_f32_16x16x32_bf16 v[6:9], v[146:149], v[224:227], v[6:9]
	v_mfma_f32_16x16x32_bf16 v[2:5], v[154:157], v[224:227], v[2:5]
	v_mfma_f32_16x16x32_bf16 v[54:57], v[150:153], v[166:169], v[54:57]
	v_mfma_f32_16x16x32_bf16 v[50:53], v[158:161], v[166:169], v[50:53]
	v_mfma_f32_16x16x32_bf16 v[38:41], v[150:153], v[174:177], v[38:41]
	v_mfma_f32_16x16x32_bf16 v[34:37], v[158:161], v[174:177], v[34:37]
	v_mfma_f32_16x16x32_bf16 v[22:25], v[150:153], v[182:185], v[22:25]
	v_mfma_f32_16x16x32_bf16 v[18:21], v[158:161], v[182:185], v[18:21]
	v_mfma_f32_16x16x32_bf16 v[6:9], v[150:153], v[228:231], v[6:9]
	v_mfma_f32_16x16x32_bf16 v[2:5], v[158:161], v[228:231], v[2:5]
	s_barrier
	s_setprio 0
	s_add_i32 s47, 0, 0x18000
	v_add_u32_e32 v0, s47, v221
	s_add_i32 s68, 0, 0x1c000
	ds_read_b128 v[106:109], v0
	ds_read_b128 v[110:113], v0 offset:1024
	ds_read_b128 v[126:129], v0 offset:2048
	ds_read_b128 v[134:137], v0 offset:3072
	v_add_u32_e32 v0, s68, v221
	ds_read_b128 v[146:149], v0
	ds_read_b128 v[150:153], v0 offset:1024
	ds_read_b128 v[154:157], v0 offset:2048
	ds_read_b128 v[158:161], v0 offset:3072
	s_add_u32 s56, s56, 0x40000
	s_addc_u32 s57, s57, 0
	s_mov_b32 m0, s61
	v_lshl_add_u64 v[246:247], s[56:57], 0, v[210:211]
	ds_read_b128 v[162:165], v222 offset:32768
	ds_read_b128 v[166:169], v222 offset:33792
	ds_read_b128 v[170:173], v222 offset:34816
	ds_read_b128 v[174:177], v222 offset:35840
	ds_read_b128 v[178:181], v222 offset:36864
	ds_read_b128 v[182:185], v222 offset:37888
	ds_read_b128 v[224:227], v222 offset:38912
	ds_read_b128 v[228:231], v222 offset:39936
	global_load_lds_dwordx4 v[246:247], off
	v_lshl_add_u64 v[246:247], s[56:57], 0, v[206:207]
	s_mov_b32 m0, s62
	s_nop 0
	global_load_lds_dwordx4 v[246:247], off
	s_waitcnt vmcnt(8)
	s_waitcnt lgkmcnt(0)
	s_setprio 1
	s_barrier
	v_mfma_f32_16x16x32_bf16 v[142:145], v[106:109], v[162:165], v[142:145]
	v_mfma_f32_16x16x32_bf16 v[138:141], v[126:129], v[162:165], v[138:141]
	v_mfma_f32_16x16x32_bf16 v[118:121], v[106:109], v[170:173], v[118:121]
	v_mfma_f32_16x16x32_bf16 v[114:117], v[126:129], v[170:173], v[114:117]
	v_mfma_f32_16x16x32_bf16 v[94:97], v[106:109], v[178:181], v[94:97]
	v_mfma_f32_16x16x32_bf16 v[90:93], v[126:129], v[178:181], v[90:93]
	v_mfma_f32_16x16x32_bf16 v[78:81], v[106:109], v[224:227], v[78:81]
	v_mfma_f32_16x16x32_bf16 v[74:77], v[126:129], v[224:227], v[74:77]
	v_mfma_f32_16x16x32_bf16 v[142:145], v[110:113], v[166:169], v[142:145]
	v_mfma_f32_16x16x32_bf16 v[138:141], v[134:137], v[166:169], v[138:141]
	v_mfma_f32_16x16x32_bf16 v[118:121], v[110:113], v[174:177], v[118:121]
	v_mfma_f32_16x16x32_bf16 v[114:117], v[134:137], v[174:177], v[114:117]
	v_mfma_f32_16x16x32_bf16 v[94:97], v[110:113], v[182:185], v[94:97]
	v_mfma_f32_16x16x32_bf16 v[90:93], v[134:137], v[182:185], v[90:93]
	v_mfma_f32_16x16x32_bf16 v[78:81], v[110:113], v[228:231], v[78:81]
	v_mfma_f32_16x16x32_bf16 v[74:77], v[134:137], v[228:231], v[74:77]
	v_mfma_f32_16x16x32_bf16 v[130:133], v[146:149], v[162:165], v[130:133]
	v_mfma_f32_16x16x32_bf16 v[122:125], v[154:157], v[162:165], v[122:125]
	v_mfma_f32_16x16x32_bf16 v[102:105], v[146:149], v[170:173], v[102:105]
	v_mfma_f32_16x16x32_bf16 v[98:101], v[154:157], v[170:173], v[98:101]
	v_mfma_f32_16x16x32_bf16 v[86:89], v[146:149], v[178:181], v[86:89]
	v_mfma_f32_16x16x32_bf16 v[82:85], v[154:157], v[178:181], v[82:85]
	v_mfma_f32_16x16x32_bf16 v[70:73], v[146:149], v[224:227], v[70:73]
	v_mfma_f32_16x16x32_bf16 v[66:69], v[154:157], v[224:227], v[66:69]
	v_mfma_f32_16x16x32_bf16 v[130:133], v[150:153], v[166:169], v[130:133]
	v_mfma_f32_16x16x32_bf16 v[122:125], v[158:161], v[166:169], v[122:125]
	v_mfma_f32_16x16x32_bf16 v[102:105], v[150:153], v[174:177], v[102:105]
	v_mfma_f32_16x16x32_bf16 v[98:101], v[158:161], v[174:177], v[98:101]
	v_mfma_f32_16x16x32_bf16 v[86:89], v[150:153], v[182:185], v[86:89]
	v_mfma_f32_16x16x32_bf16 v[82:85], v[158:161], v[182:185], v[82:85]
	v_mfma_f32_16x16x32_bf16 v[70:73], v[150:153], v[228:231], v[70:73]
	v_mfma_f32_16x16x32_bf16 v[66:69], v[158:161], v[228:231], v[66:69]
	s_barrier
	s_setprio 0
	s_add_i32 s47, s47, s58
	v_lshl_add_u64 v[216:217], v[216:217], 0, s[16:17]
	s_mov_b32 m0, s47
	ds_read_b128 v[162:165], v222 offset:49152
	ds_read_b128 v[166:169], v222 offset:50176
	ds_read_b128 v[170:173], v222 offset:51200
	ds_read_b128 v[174:177], v222 offset:52224
	ds_read_b128 v[178:181], v222 offset:53248
	ds_read_b128 v[182:185], v222 offset:54272
	ds_read_b128 v[224:227], v222 offset:55296
	ds_read_b128 v[228:231], v222 offset:56320
	global_load_lds_dwordx4 v[216:217], off
	s_add_i32 m0, s47, 0x2000
	s_add_u32 s54, s54, 0x40080
	v_lshl_add_u64 v[216:217], v[240:241], 0, s[16:17]
	s_addc_u32 s55, s55, 0
	s_add_i32 s47, s68, s58
	global_load_lds_dwordx4 v[216:217], off
	v_lshl_add_u64 v[216:217], s[54:55], 0, v[208:209]
	s_mov_b32 m0, s47
	s_nop 0
	global_load_lds_dwordx4 v[216:217], off
	v_lshl_add_u64 v[216:217], s[54:55], 0, v[204:205]
	s_add_i32 m0, s47, 0x2000
	s_nop 0
	global_load_lds_dwordx4 v[216:217], off
	v_lshl_add_u64 v[216:217], v[242:243], 0, s[16:17]
	s_mov_b32 m0, s65
	s_nop 0
	global_load_lds_dwordx4 v[216:217], off
	v_lshl_add_u64 v[216:217], v[244:245], 0, s[16:17]
	s_mov_b32 m0, s66
	s_nop 0
	global_load_lds_dwordx4 v[216:217], off
	s_waitcnt vmcnt(8)
	s_waitcnt lgkmcnt(0)
	s_setprio 1
	s_barrier
	v_mfma_f32_16x16x32_bf16 v[62:65], v[106:109], v[162:165], v[62:65]
	v_mfma_f32_16x16x32_bf16 v[58:61], v[126:129], v[162:165], v[58:61]
	v_mfma_f32_16x16x32_bf16 v[46:49], v[106:109], v[170:173], v[46:49]
	v_mfma_f32_16x16x32_bf16 v[42:45], v[126:129], v[170:173], v[42:45]
	v_mfma_f32_16x16x32_bf16 v[30:33], v[106:109], v[178:181], v[30:33]
	v_mfma_f32_16x16x32_bf16 v[26:29], v[126:129], v[178:181], v[26:29]
	v_mfma_f32_16x16x32_bf16 v[14:17], v[106:109], v[224:227], v[14:17]
	v_mfma_f32_16x16x32_bf16 v[10:13], v[126:129], v[224:227], v[10:13]
	v_mfma_f32_16x16x32_bf16 v[62:65], v[110:113], v[166:169], v[62:65]
	v_mfma_f32_16x16x32_bf16 v[58:61], v[134:137], v[166:169], v[58:61]
	v_mfma_f32_16x16x32_bf16 v[46:49], v[110:113], v[174:177], v[46:49]
	v_mfma_f32_16x16x32_bf16 v[42:45], v[134:137], v[174:177], v[42:45]
	v_mfma_f32_16x16x32_bf16 v[30:33], v[110:113], v[182:185], v[30:33]
	v_mfma_f32_16x16x32_bf16 v[26:29], v[134:137], v[182:185], v[26:29]
	v_mfma_f32_16x16x32_bf16 v[14:17], v[110:113], v[228:231], v[14:17]
	v_mfma_f32_16x16x32_bf16 v[10:13], v[134:137], v[228:231], v[10:13]
	v_mfma_f32_16x16x32_bf16 v[54:57], v[146:149], v[162:165], v[54:57]
	v_mfma_f32_16x16x32_bf16 v[50:53], v[154:157], v[162:165], v[50:53]
	v_mfma_f32_16x16x32_bf16 v[38:41], v[146:149], v[170:173], v[38:41]
	v_mfma_f32_16x16x32_bf16 v[34:37], v[154:157], v[170:173], v[34:37]
	v_mfma_f32_16x16x32_bf16 v[22:25], v[146:149], v[178:181], v[22:25]
	v_mfma_f32_16x16x32_bf16 v[18:21], v[154:157], v[178:181], v[18:21]
	v_mfma_f32_16x16x32_bf16 v[6:9], v[146:149], v[224:227], v[6:9]
	v_mfma_f32_16x16x32_bf16 v[2:5], v[154:157], v[224:227], v[2:5]
	v_mfma_f32_16x16x32_bf16 v[54:57], v[150:153], v[166:169], v[54:57]
	v_mfma_f32_16x16x32_bf16 v[50:53], v[158:161], v[166:169], v[50:53]
	v_mfma_f32_16x16x32_bf16 v[38:41], v[150:153], v[174:177], v[38:41]
	v_mfma_f32_16x16x32_bf16 v[34:37], v[158:161], v[174:177], v[34:37]
	v_mfma_f32_16x16x32_bf16 v[22:25], v[150:153], v[182:185], v[22:25]
	v_mfma_f32_16x16x32_bf16 v[18:21], v[158:161], v[182:185], v[18:21]
	v_mfma_f32_16x16x32_bf16 v[6:9], v[150:153], v[228:231], v[6:9]
	v_mfma_f32_16x16x32_bf16 v[2:5], v[158:161], v[228:231], v[2:5]
	s_barrier
	s_setprio 0
	s_add_i32 s45, s45, 2
	s_add_u32 s52, s52, 0x100
	s_addc_u32 s53, s53, 0
	s_add_u32 s18, s18, 0x100
	s_addc_u32 s19, s19, 0
	s_cmp_gt_u32 s45, 13
	s_cbranch_scc0 .LBB0_900
	s_and_b64 vcc, exec, s[40:41]
	s_cbranch_vccz .LBB0_903
	s_barrier

.LBB0_919:
	s_or_b64 exec, exec, s[0:1]
	s_andn2_b64 vcc, exec, s[42:43]
	s_mov_b64 s[0:1], -1
	s_cbranch_vccnz .LBB0_892
	s_mov_b32 s68, 0
	s_andn2_b64 vcc, exec, s[38:39]
	s_cbranch_vccnz .LBB0_891
	s_mov_b32 s68, 1
	s_branch .LBB0_891

.LBB0_991:
	v_mov_b32_e32 v135, v1
	v_lshl_add_u64 v[8:9], s[52:53], 0, v[134:135]
	v_mov_b32_e32 v131, v1
	v_readlane_b32 s50, v251, 11
	v_bfe_u32 v143, v7, 4, 2
	s_lshl_b32 s19, s19, 5
	v_lshl_add_u64 v[10:11], s[52:53], 0, v[130:131]
	v_mov_b32_e32 v137, v1
	v_readlane_b32 s51, v251, 12
	v_and_b32_e32 v142, 15, v7
	v_lshlrev_b32_e32 v16, 4, v143
	v_lshlrev_b32_e32 v7, 2, v7
	s_and_b32 s58, s19, 0x60
	s_add_i32 m0, s5, 0x18000
	v_lshl_add_u64 v[8:9], v[8:9], 0, s[16:17]
	v_lshl_add_u64 v[12:13], s[50:51], 0, v[136:137]
	v_mov_b32_e32 v133, v1
	s_lshl_b32 s57, s38, 6
	v_lshl_or_b32 v16, v142, 6, v16
	s_lshl_b32 s38, s38, 13
	v_and_b32_e32 v7, 32, v7
	s_lshl_b32 s19, s58, 7
	s_waitcnt vmcnt(2)
	s_barrier
	global_load_lds_dwordx4 v[8:9], off
	v_lshl_add_u64 v[8:9], v[10:11], 0, s[16:17]
	s_add_i32 m0, s5, 0x1a000
	s_add_i32 s59, s5, 0x8000
	s_add_i32 s60, s5, 0xa000
	v_lshl_add_u64 v[14:15], s[50:51], 0, v[132:133]
	v_bitop3_b32 v17, v16, s38, v7 bitop3:0xde
	global_load_lds_dwordx4 v[8:9], off
	v_lshl_add_u64 v[8:9], v[12:13], 0, s[16:17]
	s_mov_b32 m0, s59
	s_add_u32 s38, s52, 0x40080
	global_load_lds_dwordx4 v[8:9], off
	v_lshl_add_u64 v[8:9], v[14:15], 0, s[16:17]
	s_mov_b32 m0, s60
	s_addc_u32 s39, s53, 0
	global_load_lds_dwordx4 v[8:9], off
	s_add_i32 m0, s5, 0x1c000
	v_lshl_add_u64 v[8:9], s[38:39], 0, v[134:135]
	global_load_lds_dwordx4 v[8:9], off
	v_lshl_add_u64 v[8:9], s[38:39], 0, v[130:131]
	s_add_i32 m0, s5, 0x1e000
	s_waitcnt vmcnt(0)
	v_bitop3_b32 v144, v16, s19, v7 bitop3:0xde
	global_load_lds_dwordx4 v[8:9], off
	v_lshlrev_b32_e32 v7, 14, v5
	v_and_b32_e32 v7, 0xffff8000, v7
	v_lshl_add_u32 v4, v4, 11, v7
	v_and_b32_e32 v5, 1, v5
	v_lshl_or_b32 v4, v5, 6, v4
	v_lshl_add_u32 v138, v6, 1, v4
	v_lshlrev_b32_e32 v4, 14, v0
	v_and_b32_e32 v4, 0xffff8000, v4
	s_waitcnt vmcnt(6)
	v_lshl_add_u32 v2, v2, 11, v4
	v_and_b32_e32 v0, 1, v0
	s_cmpk_lt_u32 s18, 0x100
	v_lshl_or_b32 v0, v0, 6, v2
	v_readlane_b32 s38, v251, 9
	s_cselect_b64 s[40:41], -1, 0
	v_mov_b32_e32 v139, v1
	v_lshl_add_u32 v140, v3, 1, v0
	v_mov_b32_e32 v141, v1
	s_mov_b32 s61, 0
	v_add_u32_e32 v145, 0, v17
	v_readlane_b32 s19, v251, 6
	s_mov_b32 s18, s38
	s_barrier
	v_readlane_b32 s39, v251, 10
	s_mov_b32 s67, 0
	s_branch .LBB0_994

.LBB0_996:
	s_ashr_i32 s45, s44, 31
	s_lshl_b64 s[46:47], s[44:45], 19
	s_add_u32 s46, s96, s46
	s_addc_u32 s47, s97, s47
	s_and_b64 s[48:49], s[38:39], exec
	s_cselect_b32 s45, s47, s51
	s_cselect_b32 s62, s46, s50
	s_ashr_i32 s43, s42, 31
	s_lshl_b64 s[48:49], s[42:43], 19
	s_add_u32 s48, s0, s48
	s_addc_u32 s49, s1, s49
	s_and_b64 s[54:55], s[38:39], exec
	s_cselect_b32 s43, s49, s53
	s_cselect_b32 s63, s48, s52
	s_add_u32 s50, s50, 0x40080
	s_addc_u32 s51, s51, 0
	s_add_u32 s64, s52, 0x100
	s_addc_u32 s65, s53, 0
	s_mov_b32 s66, -2
	s_cmp_eq_u32 s67, 0
	s_cbranch_scc1 .Lrb5_skip
	s_barrier
.Lrb5_skip:
	s_add_u32 s52, s50, 0xfffc0080
	s_addc_u32 s53, s51, -1
	s_add_i32 s67, 0, 0x10000
	s_cmp_eq_u32 s66, 12
	s_cselect_b32 s55, s45, s53
	s_cselect_b32 s54, s62, s52
	v_add_u32_e32 v0, s67, v144
	s_cselect_b32 s53, s43, s65
	s_cselect_b32 s52, s63, s64
	s_add_i32 s70, 0, 0x14000
	ds_read_b128 v[146:149], v0
	ds_read_b128 v[150:153], v0 offset:1024
	ds_read_b128 v[154:157], v0 offset:2048
	ds_read_b128 v[158:161], v0 offset:3072
	v_add_u32_e32 v0, s70, v144
	ds_read_b128 v[162:165], v0
	ds_read_b128 v[166:169], v0 offset:1024
	ds_read_b128 v[170:173], v0 offset:2048
	ds_read_b128 v[174:177], v0 offset:3072
	v_lshl_add_u64 v[216:217], s[50:51], 0, v[138:139]
	s_add_i32 m0, s5, 0xc000
	ds_read_b128 v[178:181], v145
	ds_read_b128 v[182:185], v145 offset:1024
	ds_read_b128 v[204:207], v145 offset:2048
	ds_read_b128 v[208:211], v145 offset:3072
	ds_read_b128 v[212:215], v145 offset:4096
	ds_read_b128 v[220:223], v145 offset:5120
	ds_read_b128 v[224:227], v145 offset:6144
	ds_read_b128 v[228:231], v145 offset:7168
	global_load_lds_dwordx4 v[216:217], off
	v_lshl_add_u64 v[216:217], s[50:51], 0, v[140:141]
	s_add_i32 m0, s5, 0xe000
	s_nop 0
	global_load_lds_dwordx4 v[216:217], off
	s_waitcnt vmcnt(8)
	s_waitcnt lgkmcnt(0)
	s_setprio 1
	s_barrier
	v_mfma_f32_16x16x32_bf16 v[118:121], v[146:149], v[178:181], 0
	v_mfma_f32_16x16x32_bf16 v[114:117], v[154:157], v[178:181], 0
	v_mfma_f32_16x16x32_bf16 v[110:113], v[146:149], v[204:207], 0
	v_mfma_f32_16x16x32_bf16 v[102:105], v[154:157], v[204:207], 0
	v_mfma_f32_16x16x32_bf16 v[94:97], v[146:149], v[212:215], 0
	v_mfma_f32_16x16x32_bf16 v[86:89], v[154:157], v[212:215], 0
	v_mfma_f32_16x16x32_bf16 v[78:81], v[146:149], v[224:227], 0
	v_mfma_f32_16x16x32_bf16 v[70:73], v[154:157], v[224:227], 0
	v_mfma_f32_16x16x32_bf16 v[118:121], v[150:153], v[182:185], v[118:121]
	v_mfma_f32_16x16x32_bf16 v[114:117], v[158:161], v[182:185], v[114:117]
	v_mfma_f32_16x16x32_bf16 v[110:113], v[150:153], v[208:211], v[110:113]
	v_mfma_f32_16x16x32_bf16 v[102:105], v[158:161], v[208:211], v[102:105]
	v_mfma_f32_16x16x32_bf16 v[94:97], v[150:153], v[220:223], v[94:97]
	v_mfma_f32_16x16x32_bf16 v[86:89], v[158:161], v[220:223], v[86:89]
	v_mfma_f32_16x16x32_bf16 v[78:81], v[150:153], v[228:231], v[78:81]
	v_mfma_f32_16x16x32_bf16 v[70:73], v[158:161], v[228:231], v[70:73]
	v_mfma_f32_16x16x32_bf16 v[126:129], v[162:165], v[178:181], 0
	v_mfma_f32_16x16x32_bf16 v[122:125], v[170:173], v[178:181], 0
	v_mfma_f32_16x16x32_bf16 v[106:109], v[162:165], v[204:207], 0
	v_mfma_f32_16x16x32_bf16 v[98:101], v[170:173], v[204:207], 0
	v_mfma_f32_16x16x32_bf16 v[90:93], v[162:165], v[212:215], 0
	v_mfma_f32_16x16x32_bf16 v[82:85], v[170:173], v[212:215], 0
	v_mfma_f32_16x16x32_bf16 v[74:77], v[162:165], v[224:227], 0
	v_mfma_f32_16x16x32_bf16 v[66:69], v[170:173], v[224:227], 0
	v_mfma_f32_16x16x32_bf16 v[126:129], v[166:169], v[182:185], v[126:129]
	v_mfma_f32_16x16x32_bf16 v[122:125], v[174:177], v[182:185], v[122:125]
	v_mfma_f32_16x16x32_bf16 v[106:109], v[166:169], v[208:211], v[106:109]
	v_mfma_f32_16x16x32_bf16 v[98:101], v[174:177], v[208:211], v[98:101]
	v_mfma_f32_16x16x32_bf16 v[90:93], v[166:169], v[220:223], v[90:93]
	v_mfma_f32_16x16x32_bf16 v[82:85], v[174:177], v[220:223], v[82:85]
	v_mfma_f32_16x16x32_bf16 v[74:77], v[166:169], v[228:231], v[74:77]
	v_mfma_f32_16x16x32_bf16 v[66:69], v[174:177], v[228:231], v[66:69]
	s_barrier
	s_setprio 0
	s_add_i32 s67, s67, s4
	v_lshl_add_u64 v[216:217], s[52:53], 0, v[134:135]
	s_mov_b32 m0, s67
	ds_read_b128 v[178:181], v145 offset:16384
	ds_read_b128 v[182:185], v145 offset:17408
	ds_read_b128 v[204:207], v145 offset:18432
	ds_read_b128 v[208:211], v145 offset:19456
	ds_read_b128 v[212:215], v145 offset:20480
	ds_read_b128 v[220:223], v145 offset:21504
	ds_read_b128 v[224:227], v145 offset:22528
	ds_read_b128 v[228:231], v145 offset:23552
	global_load_lds_dwordx4 v[216:217], off
	s_add_i32 m0, s67, 0x2000
	s_add_u32 s68, s52, 0x40000
	v_lshl_add_u64 v[240:241], s[52:53], 0, v[130:131]
	s_addc_u32 s69, s53, 0
	s_add_i32 s67, s70, s4
	global_load_lds_dwordx4 v[240:241], off
	v_lshl_add_u64 v[242:243], s[68:69], 0, v[134:135]
	s_mov_b32 m0, s67
	v_lshl_add_u64 v[244:245], s[54:55], 0, v[132:133]
	global_load_lds_dwordx4 v[242:243], off
	v_lshl_add_u64 v[242:243], s[68:69], 0, v[130:131]
	s_add_i32 m0, s67, 0x2000
	s_nop 0
	global_load_lds_dwordx4 v[242:243], off
	v_lshl_add_u64 v[242:243], s[54:55], 0, v[136:137]
	s_mov_b32 m0, s5
	s_nop 0
	global_load_lds_dwordx4 v[242:243], off
	s_mov_b32 m0, s6
	s_nop 0
	global_load_lds_dwordx4 v[244:245], off
	s_waitcnt vmcnt(8)
	s_waitcnt lgkmcnt(0)
	s_setprio 1
	s_barrier
	v_mfma_f32_16x16x32_bf16 v[62:65], v[146:149], v[178:181], 0
	v_mfma_f32_16x16x32_bf16 v[54:57], v[154:157], v[178:181], 0
	v_mfma_f32_16x16x32_bf16 v[46:49], v[146:149], v[204:207], 0
	v_mfma_f32_16x16x32_bf16 v[38:41], v[154:157], v[204:207], 0
	v_mfma_f32_16x16x32_bf16 v[30:33], v[146:149], v[212:215], 0
	v_mfma_f32_16x16x32_bf16 v[22:25], v[154:157], v[212:215], 0
	v_mfma_f32_16x16x32_bf16 v[14:17], v[146:149], v[224:227], 0
	v_mfma_f32_16x16x32_bf16 v[6:9], v[154:157], v[224:227], 0
	v_mfma_f32_16x16x32_bf16 v[62:65], v[150:153], v[182:185], v[62:65]
	v_mfma_f32_16x16x32_bf16 v[54:57], v[158:161], v[182:185], v[54:57]
	v_mfma_f32_16x16x32_bf16 v[46:49], v[150:153], v[208:211], v[46:49]
	v_mfma_f32_16x16x32_bf16 v[38:41], v[158:161], v[208:211], v[38:41]
	v_mfma_f32_16x16x32_bf16 v[30:33], v[150:153], v[220:223], v[30:33]
	v_mfma_f32_16x16x32_bf16 v[22:25], v[158:161], v[220:223], v[22:25]
	v_mfma_f32_16x16x32_bf16 v[14:17], v[150:153], v[228:231], v[14:17]
	v_mfma_f32_16x16x32_bf16 v[6:9], v[158:161], v[228:231], v[6:9]
	v_mfma_f32_16x16x32_bf16 v[58:61], v[162:165], v[178:181], 0
	v_mfma_f32_16x16x32_bf16 v[50:53], v[170:173], v[178:181], 0
	v_mfma_f32_16x16x32_bf16 v[42:45], v[162:165], v[204:207], 0
	v_mfma_f32_16x16x32_bf16 v[34:37], v[170:173], v[204:207], 0
	v_mfma_f32_16x16x32_bf16 v[26:29], v[162:165], v[212:215], 0
	v_mfma_f32_16x16x32_bf16 v[18:21], v[170:173], v[212:215], 0
	v_mfma_f32_16x16x32_bf16 v[10:13], v[162:165], v[224:227], 0
	v_mfma_f32_16x16x32_bf16 v[2:5], v[170:173], v[224:227], 0
	v_mfma_f32_16x16x32_bf16 v[58:61], v[166:169], v[182:185], v[58:61]
	v_mfma_f32_16x16x32_bf16 v[50:53], v[174:177], v[182:185], v[50:53]
	v_mfma_f32_16x16x32_bf16 v[42:45], v[166:169], v[208:211], v[42:45]
	v_mfma_f32_16x16x32_bf16 v[34:37], v[174:177], v[208:211], v[34:37]
	v_mfma_f32_16x16x32_bf16 v[26:29], v[166:169], v[220:223], v[26:29]
	v_mfma_f32_16x16x32_bf16 v[18:21], v[174:177], v[220:223], v[18:21]
	v_mfma_f32_16x16x32_bf16 v[10:13], v[166:169], v[228:231], v[10:13]
	v_mfma_f32_16x16x32_bf16 v[2:5], v[174:177], v[228:231], v[2:5]
	s_barrier
	s_setprio 0
	s_add_i32 s67, 0, 0x18000
	v_add_u32_e32 v0, s67, v144
	s_add_i32 s68, 0, 0x1c000
	ds_read_b128 v[146:149], v0
	ds_read_b128 v[150:153], v0 offset:1024
	ds_read_b128 v[154:157], v0 offset:2048
	ds_read_b128 v[158:161], v0 offset:3072
	v_add_u32_e32 v0, s68, v144
	ds_read_b128 v[162:165], v0
	ds_read_b128 v[166:169], v0 offset:1024
	ds_read_b128 v[170:173], v0 offset:2048
	ds_read_b128 v[174:177], v0 offset:3072
	s_add_u32 s54, s54, 0x40000
	s_addc_u32 s55, s55, 0
	s_mov_b32 m0, s7
	v_lshl_add_u64 v[246:247], s[54:55], 0, v[136:137]
	ds_read_b128 v[178:181], v145 offset:32768
	ds_read_b128 v[182:185], v145 offset:33792
	ds_read_b128 v[204:207], v145 offset:34816
	ds_read_b128 v[208:211], v145 offset:35840
	ds_read_b128 v[212:215], v145 offset:36864
	ds_read_b128 v[220:223], v145 offset:37888
	ds_read_b128 v[224:227], v145 offset:38912
	ds_read_b128 v[228:231], v145 offset:39936
	global_load_lds_dwordx4 v[246:247], off
	v_lshl_add_u64 v[246:247], s[54:55], 0, v[132:133]
	s_mov_b32 m0, s56
	s_nop 0
	global_load_lds_dwordx4 v[246:247], off
	s_waitcnt vmcnt(8)
	s_waitcnt lgkmcnt(0)
	s_setprio 1
	s_barrier
	v_mfma_f32_16x16x32_bf16 v[118:121], v[146:149], v[178:181], v[118:121]
	v_mfma_f32_16x16x32_bf16 v[114:117], v[154:157], v[178:181], v[114:117]
	v_mfma_f32_16x16x32_bf16 v[110:113], v[146:149], v[204:207], v[110:113]
	v_mfma_f32_16x16x32_bf16 v[102:105], v[154:157], v[204:207], v[102:105]
	v_mfma_f32_16x16x32_bf16 v[94:97], v[146:149], v[212:215], v[94:97]
	v_mfma_f32_16x16x32_bf16 v[86:89], v[154:157], v[212:215], v[86:89]
	v_mfma_f32_16x16x32_bf16 v[78:81], v[146:149], v[224:227], v[78:81]
	v_mfma_f32_16x16x32_bf16 v[70:73], v[154:157], v[224:227], v[70:73]
	v_mfma_f32_16x16x32_bf16 v[118:121], v[150:153], v[182:185], v[118:121]
	v_mfma_f32_16x16x32_bf16 v[114:117], v[158:161], v[182:185], v[114:117]
	v_mfma_f32_16x16x32_bf16 v[110:113], v[150:153], v[208:211], v[110:113]
	v_mfma_f32_16x16x32_bf16 v[102:105], v[158:161], v[208:211], v[102:105]
	v_mfma_f32_16x16x32_bf16 v[94:97], v[150:153], v[220:223], v[94:97]
	v_mfma_f32_16x16x32_bf16 v[86:89], v[158:161], v[220:223], v[86:89]
	v_mfma_f32_16x16x32_bf16 v[78:81], v[150:153], v[228:231], v[78:81]
	v_mfma_f32_16x16x32_bf16 v[70:73], v[158:161], v[228:231], v[70:73]
	v_mfma_f32_16x16x32_bf16 v[126:129], v[162:165], v[178:181], v[126:129]
	v_mfma_f32_16x16x32_bf16 v[122:125], v[170:173], v[178:181], v[122:125]
	v_mfma_f32_16x16x32_bf16 v[106:109], v[162:165], v[204:207], v[106:109]
	v_mfma_f32_16x16x32_bf16 v[98:101], v[170:173], v[204:207], v[98:101]
	v_mfma_f32_16x16x32_bf16 v[90:93], v[162:165], v[212:215], v[90:93]
	v_mfma_f32_16x16x32_bf16 v[82:85], v[170:173], v[212:215], v[82:85]
	v_mfma_f32_16x16x32_bf16 v[74:77], v[162:165], v[224:227], v[74:77]
	v_mfma_f32_16x16x32_bf16 v[66:69], v[170:173], v[224:227], v[66:69]
	v_mfma_f32_16x16x32_bf16 v[126:129], v[166:169], v[182:185], v[126:129]
	v_mfma_f32_16x16x32_bf16 v[122:125], v[174:177], v[182:185], v[122:125]
	v_mfma_f32_16x16x32_bf16 v[106:109], v[166:169], v[208:211], v[106:109]
	v_mfma_f32_16x16x32_bf16 v[98:101], v[174:177], v[208:211], v[98:101]
	v_mfma_f32_16x16x32_bf16 v[90:93], v[166:169], v[220:223], v[90:93]
	v_mfma_f32_16x16x32_bf16 v[82:85], v[174:177], v[220:223], v[82:85]
	v_mfma_f32_16x16x32_bf16 v[74:77], v[166:169], v[228:231], v[74:77]
	v_mfma_f32_16x16x32_bf16 v[66:69], v[174:177], v[228:231], v[66:69]
	s_barrier
	s_setprio 0
	s_add_i32 s54, s67, s4
	v_lshl_add_u64 v[216:217], v[216:217], 0, s[16:17]
	s_mov_b32 m0, s54
	ds_read_b128 v[178:181], v145 offset:49152
	ds_read_b128 v[182:185], v145 offset:50176
	ds_read_b128 v[204:207], v145 offset:51200
	ds_read_b128 v[208:211], v145 offset:52224
	ds_read_b128 v[212:215], v145 offset:53248
	ds_read_b128 v[220:223], v145 offset:54272
	ds_read_b128 v[224:227], v145 offset:55296
	ds_read_b128 v[228:231], v145 offset:56320
	global_load_lds_dwordx4 v[216:217], off
	s_add_i32 m0, s54, 0x2000
	s_add_u32 s52, s52, 0x40080
	v_lshl_add_u64 v[216:217], v[240:241], 0, s[16:17]
	s_addc_u32 s53, s53, 0
	s_add_i32 s54, s68, s4
	global_load_lds_dwordx4 v[216:217], off
	v_lshl_add_u64 v[216:217], s[52:53], 0, v[134:135]
	s_mov_b32 m0, s54
	s_nop 0
	global_load_lds_dwordx4 v[216:217], off
	v_lshl_add_u64 v[216:217], s[52:53], 0, v[130:131]
	s_add_i32 m0, s54, 0x2000
	s_nop 0
	global_load_lds_dwordx4 v[216:217], off
	v_lshl_add_u64 v[216:217], v[242:243], 0, s[16:17]
	s_mov_b32 m0, s59
	s_nop 0
	global_load_lds_dwordx4 v[216:217], off
	v_lshl_add_u64 v[216:217], v[244:245], 0, s[16:17]
	s_mov_b32 m0, s60
	s_nop 0
	global_load_lds_dwordx4 v[216:217], off
	s_waitcnt vmcnt(8)
	s_waitcnt lgkmcnt(0)
	s_setprio 1
	s_barrier
	v_mfma_f32_16x16x32_bf16 v[62:65], v[146:149], v[178:181], v[62:65]
	v_mfma_f32_16x16x32_bf16 v[54:57], v[154:157], v[178:181], v[54:57]
	v_mfma_f32_16x16x32_bf16 v[46:49], v[146:149], v[204:207], v[46:49]
	v_mfma_f32_16x16x32_bf16 v[38:41], v[154:157], v[204:207], v[38:41]
	v_mfma_f32_16x16x32_bf16 v[30:33], v[146:149], v[212:215], v[30:33]
	v_mfma_f32_16x16x32_bf16 v[22:25], v[154:157], v[212:215], v[22:25]
	v_mfma_f32_16x16x32_bf16 v[14:17], v[146:149], v[224:227], v[14:17]
	v_mfma_f32_16x16x32_bf16 v[6:9], v[154:157], v[224:227], v[6:9]
	v_mfma_f32_16x16x32_bf16 v[62:65], v[150:153], v[182:185], v[62:65]
	v_mfma_f32_16x16x32_bf16 v[54:57], v[158:161], v[182:185], v[54:57]
	v_mfma_f32_16x16x32_bf16 v[46:49], v[150:153], v[208:211], v[46:49]
	v_mfma_f32_16x16x32_bf16 v[38:41], v[158:161], v[208:211], v[38:41]
	v_mfma_f32_16x16x32_bf16 v[30:33], v[150:153], v[220:223], v[30:33]
	v_mfma_f32_16x16x32_bf16 v[22:25], v[158:161], v[220:223], v[22:25]
	v_mfma_f32_16x16x32_bf16 v[14:17], v[150:153], v[228:231], v[14:17]
	v_mfma_f32_16x16x32_bf16 v[6:9], v[158:161], v[228:231], v[6:9]
	v_mfma_f32_16x16x32_bf16 v[58:61], v[162:165], v[178:181], v[58:61]
	v_mfma_f32_16x16x32_bf16 v[50:53], v[170:173], v[178:181], v[50:53]
	v_mfma_f32_16x16x32_bf16 v[42:45], v[162:165], v[204:207], v[42:45]
	v_mfma_f32_16x16x32_bf16 v[34:37], v[170:173], v[204:207], v[34:37]
	v_mfma_f32_16x16x32_bf16 v[26:29], v[162:165], v[212:215], v[26:29]
	v_mfma_f32_16x16x32_bf16 v[18:21], v[170:173], v[212:215], v[18:21]
	v_mfma_f32_16x16x32_bf16 v[10:13], v[162:165], v[224:227], v[10:13]
	v_mfma_f32_16x16x32_bf16 v[2:5], v[170:173], v[224:227], v[2:5]
	v_mfma_f32_16x16x32_bf16 v[58:61], v[166:169], v[182:185], v[58:61]
	v_mfma_f32_16x16x32_bf16 v[50:53], v[174:177], v[182:185], v[50:53]
	v_mfma_f32_16x16x32_bf16 v[42:45], v[166:169], v[208:211], v[42:45]
	v_mfma_f32_16x16x32_bf16 v[34:37], v[174:177], v[208:211], v[34:37]
	v_mfma_f32_16x16x32_bf16 v[26:29], v[166:169], v[220:223], v[26:29]
	v_mfma_f32_16x16x32_bf16 v[18:21], v[174:177], v[220:223], v[18:21]
	v_mfma_f32_16x16x32_bf16 v[10:13], v[166:169], v[228:231], v[10:13]
	v_mfma_f32_16x16x32_bf16 v[2:5], v[174:177], v[228:231], v[2:5]
	s_barrier
	s_setprio 0
	s_add_i32 s66, s66, 2
	s_add_u32 s50, s50, 0x100
	s_addc_u32 s51, s51, 0
	s_add_u32 s64, s64, 0x100
	s_addc_u32 s65, s65, 0
	s_cmp_gt_u32 s66, 13
.LBB0_997:
	s_add_u32 s52, s50, 0xfffc0080
	s_addc_u32 s53, s51, -1
	s_add_i32 s67, 0, 0x10000
	s_cmp_eq_u32 s66, 12
	s_cselect_b32 s55, s45, s53
	s_cselect_b32 s54, s62, s52
	v_add_u32_e32 v0, s67, v144
	s_cselect_b32 s53, s43, s65
	s_cselect_b32 s52, s63, s64
	s_add_i32 s70, 0, 0x14000
	ds_read_b128 v[146:149], v0
	ds_read_b128 v[150:153], v0 offset:1024
	ds_read_b128 v[154:157], v0 offset:2048
	ds_read_b128 v[158:161], v0 offset:3072
	v_add_u32_e32 v0, s70, v144
	ds_read_b128 v[162:165], v0
	ds_read_b128 v[166:169], v0 offset:1024
	ds_read_b128 v[170:173], v0 offset:2048
	ds_read_b128 v[174:177], v0 offset:3072
	v_lshl_add_u64 v[216:217], s[50:51], 0, v[138:139]
	s_add_i32 m0, s5, 0xc000
	ds_read_b128 v[178:181], v145
	ds_read_b128 v[182:185], v145 offset:1024
	ds_read_b128 v[204:207], v145 offset:2048
	ds_read_b128 v[208:211], v145 offset:3072
	ds_read_b128 v[212:215], v145 offset:4096
	ds_read_b128 v[220:223], v145 offset:5120
	ds_read_b128 v[224:227], v145 offset:6144
	ds_read_b128 v[228:231], v145 offset:7168
	global_load_lds_dwordx4 v[216:217], off
	v_lshl_add_u64 v[216:217], s[50:51], 0, v[140:141]
	s_add_i32 m0, s5, 0xe000
	s_nop 0
	global_load_lds_dwordx4 v[216:217], off
	s_waitcnt vmcnt(8)
	s_waitcnt lgkmcnt(0)
	s_setprio 1
	s_barrier
	v_mfma_f32_16x16x32_bf16 v[118:121], v[146:149], v[178:181], v[118:121]
	v_mfma_f32_16x16x32_bf16 v[114:117], v[154:157], v[178:181], v[114:117]
	v_mfma_f32_16x16x32_bf16 v[110:113], v[146:149], v[204:207], v[110:113]
	v_mfma_f32_16x16x32_bf16 v[102:105], v[154:157], v[204:207], v[102:105]
	v_mfma_f32_16x16x32_bf16 v[94:97], v[146:149], v[212:215], v[94:97]
	v_mfma_f32_16x16x32_bf16 v[86:89], v[154:157], v[212:215], v[86:89]
	v_mfma_f32_16x16x32_bf16 v[78:81], v[146:149], v[224:227], v[78:81]
	v_mfma_f32_16x16x32_bf16 v[70:73], v[154:157], v[224:227], v[70:73]
	v_mfma_f32_16x16x32_bf16 v[118:121], v[150:153], v[182:185], v[118:121]
	v_mfma_f32_16x16x32_bf16 v[114:117], v[158:161], v[182:185], v[114:117]
	v_mfma_f32_16x16x32_bf16 v[110:113], v[150:153], v[208:211], v[110:113]
	v_mfma_f32_16x16x32_bf16 v[102:105], v[158:161], v[208:211], v[102:105]
	v_mfma_f32_16x16x32_bf16 v[94:97], v[150:153], v[220:223], v[94:97]
	v_mfma_f32_16x16x32_bf16 v[86:89], v[158:161], v[220:223], v[86:89]
	v_mfma_f32_16x16x32_bf16 v[78:81], v[150:153], v[228:231], v[78:81]
	v_mfma_f32_16x16x32_bf16 v[70:73], v[158:161], v[228:231], v[70:73]
	v_mfma_f32_16x16x32_bf16 v[126:129], v[162:165], v[178:181], v[126:129]
	v_mfma_f32_16x16x32_bf16 v[122:125], v[170:173], v[178:181], v[122:125]
	v_mfma_f32_16x16x32_bf16 v[106:109], v[162:165], v[204:207], v[106:109]
	v_mfma_f32_16x16x32_bf16 v[98:101], v[170:173], v[204:207], v[98:101]
	v_mfma_f32_16x16x32_bf16 v[90:93], v[162:165], v[212:215], v[90:93]
	v_mfma_f32_16x16x32_bf16 v[82:85], v[170:173], v[212:215], v[82:85]
	v_mfma_f32_16x16x32_bf16 v[74:77], v[162:165], v[224:227], v[74:77]
	v_mfma_f32_16x16x32_bf16 v[66:69], v[170:173], v[224:227], v[66:69]
	v_mfma_f32_16x16x32_bf16 v[126:129], v[166:169], v[182:185], v[126:129]
	v_mfma_f32_16x16x32_bf16 v[122:125], v[174:177], v[182:185], v[122:125]
	v_mfma_f32_16x16x32_bf16 v[106:109], v[166:169], v[208:211], v[106:109]
	v_mfma_f32_16x16x32_bf16 v[98:101], v[174:177], v[208:211], v[98:101]
	v_mfma_f32_16x16x32_bf16 v[90:93], v[166:169], v[220:223], v[90:93]
	v_mfma_f32_16x16x32_bf16 v[82:85], v[174:177], v[220:223], v[82:85]
	v_mfma_f32_16x16x32_bf16 v[74:77], v[166:169], v[228:231], v[74:77]
	v_mfma_f32_16x16x32_bf16 v[66:69], v[174:177], v[228:231], v[66:69]
	s_barrier
	s_setprio 0
	s_add_i32 s67, s67, s4
	v_lshl_add_u64 v[216:217], s[52:53], 0, v[134:135]
	s_mov_b32 m0, s67
	ds_read_b128 v[178:181], v145 offset:16384
	ds_read_b128 v[182:185], v145 offset:17408
	ds_read_b128 v[204:207], v145 offset:18432
	ds_read_b128 v[208:211], v145 offset:19456
	ds_read_b128 v[212:215], v145 offset:20480
	ds_read_b128 v[220:223], v145 offset:21504
	ds_read_b128 v[224:227], v145 offset:22528
	ds_read_b128 v[228:231], v145 offset:23552
	global_load_lds_dwordx4 v[216:217], off
	s_add_i32 m0, s67, 0x2000
	s_add_u32 s68, s52, 0x40000
	v_lshl_add_u64 v[240:241], s[52:53], 0, v[130:131]
	s_addc_u32 s69, s53, 0
	s_add_i32 s67, s70, s4
	global_load_lds_dwordx4 v[240:241], off
	v_lshl_add_u64 v[242:243], s[68:69], 0, v[134:135]
	s_mov_b32 m0, s67
	v_lshl_add_u64 v[244:245], s[54:55], 0, v[132:133]
	global_load_lds_dwordx4 v[242:243], off
	v_lshl_add_u64 v[242:243], s[68:69], 0, v[130:131]
	s_add_i32 m0, s67, 0x2000
	s_nop 0
	global_load_lds_dwordx4 v[242:243], off
	v_lshl_add_u64 v[242:243], s[54:55], 0, v[136:137]
	s_mov_b32 m0, s5
	s_nop 0
	global_load_lds_dwordx4 v[242:243], off
	s_mov_b32 m0, s6
	s_nop 0
	global_load_lds_dwordx4 v[244:245], off
	s_waitcnt vmcnt(8)
	s_waitcnt lgkmcnt(0)
	s_setprio 1
	s_barrier
	v_mfma_f32_16x16x32_bf16 v[62:65], v[146:149], v[178:181], v[62:65]
	v_mfma_f32_16x16x32_bf16 v[54:57], v[154:157], v[178:181], v[54:57]
	v_mfma_f32_16x16x32_bf16 v[46:49], v[146:149], v[204:207], v[46:49]
	v_mfma_f32_16x16x32_bf16 v[38:41], v[154:157], v[204:207], v[38:41]
	v_mfma_f32_16x16x32_bf16 v[30:33], v[146:149], v[212:215], v[30:33]
	v_mfma_f32_16x16x32_bf16 v[22:25], v[154:157], v[212:215], v[22:25]
	v_mfma_f32_16x16x32_bf16 v[14:17], v[146:149], v[224:227], v[14:17]
	v_mfma_f32_16x16x32_bf16 v[6:9], v[154:157], v[224:227], v[6:9]
	v_mfma_f32_16x16x32_bf16 v[62:65], v[150:153], v[182:185], v[62:65]
	v_mfma_f32_16x16x32_bf16 v[54:57], v[158:161], v[182:185], v[54:57]
	v_mfma_f32_16x16x32_bf16 v[46:49], v[150:153], v[208:211], v[46:49]
	v_mfma_f32_16x16x32_bf16 v[38:41], v[158:161], v[208:211], v[38:41]
	v_mfma_f32_16x16x32_bf16 v[30:33], v[150:153], v[220:223], v[30:33]
	v_mfma_f32_16x16x32_bf16 v[22:25], v[158:161], v[220:223], v[22:25]
	v_mfma_f32_16x16x32_bf16 v[14:17], v[150:153], v[228:231], v[14:17]
	v_mfma_f32_16x16x32_bf16 v[6:9], v[158:161], v[228:231], v[6:9]
	v_mfma_f32_16x16x32_bf16 v[58:61], v[162:165], v[178:181], v[58:61]
	v_mfma_f32_16x16x32_bf16 v[50:53], v[170:173], v[178:181], v[50:53]
	v_mfma_f32_16x16x32_bf16 v[42:45], v[162:165], v[204:207], v[42:45]
	v_mfma_f32_16x16x32_bf16 v[34:37], v[170:173], v[204:207], v[34:37]
	v_mfma_f32_16x16x32_bf16 v[26:29], v[162:165], v[212:215], v[26:29]
	v_mfma_f32_16x16x32_bf16 v[18:21], v[170:173], v[212:215], v[18:21]
	v_mfma_f32_16x16x32_bf16 v[10:13], v[162:165], v[224:227], v[10:13]
	v_mfma_f32_16x16x32_bf16 v[2:5], v[170:173], v[224:227], v[2:5]
	v_mfma_f32_16x16x32_bf16 v[58:61], v[166:169], v[182:185], v[58:61]
	v_mfma_f32_16x16x32_bf16 v[50:53], v[174:177], v[182:185], v[50:53]
	v_mfma_f32_16x16x32_bf16 v[42:45], v[166:169], v[208:211], v[42:45]
	v_mfma_f32_16x16x32_bf16 v[34:37], v[174:177], v[208:211], v[34:37]
	v_mfma_f32_16x16x32_bf16 v[26:29], v[166:169], v[220:223], v[26:29]
	v_mfma_f32_16x16x32_bf16 v[18:21], v[174:177], v[220:223], v[18:21]
	v_mfma_f32_16x16x32_bf16 v[10:13], v[166:169], v[228:231], v[10:13]
	v_mfma_f32_16x16x32_bf16 v[2:5], v[174:177], v[228:231], v[2:5]
	s_barrier
	s_setprio 0
	s_add_i32 s67, 0, 0x18000
	v_add_u32_e32 v0, s67, v144
	s_add_i32 s68, 0, 0x1c000
	ds_read_b128 v[146:149], v0
	ds_read_b128 v[150:153], v0 offset:1024
	ds_read_b128 v[154:157], v0 offset:2048
	ds_read_b128 v[158:161], v0 offset:3072
	v_add_u32_e32 v0, s68, v144
	ds_read_b128 v[162:165], v0
	ds_read_b128 v[166:169], v0 offset:1024
	ds_read_b128 v[170:173], v0 offset:2048
	ds_read_b128 v[174:177], v0 offset:3072
	s_add_u32 s54, s54, 0x40000
	s_addc_u32 s55, s55, 0
	s_mov_b32 m0, s7
	v_lshl_add_u64 v[246:247], s[54:55], 0, v[136:137]
	ds_read_b128 v[178:181], v145 offset:32768
	ds_read_b128 v[182:185], v145 offset:33792
	ds_read_b128 v[204:207], v145 offset:34816
	ds_read_b128 v[208:211], v145 offset:35840
	ds_read_b128 v[212:215], v145 offset:36864
	ds_read_b128 v[220:223], v145 offset:37888
	ds_read_b128 v[224:227], v145 offset:38912
	ds_read_b128 v[228:231], v145 offset:39936
	global_load_lds_dwordx4 v[246:247], off
	v_lshl_add_u64 v[246:247], s[54:55], 0, v[132:133]
	s_mov_b32 m0, s56
	s_nop 0
	global_load_lds_dwordx4 v[246:247], off
	s_waitcnt vmcnt(8)
	s_waitcnt lgkmcnt(0)
	s_setprio 1
	s_barrier
	v_mfma_f32_16x16x32_bf16 v[118:121], v[146:149], v[178:181], v[118:121]
	v_mfma_f32_16x16x32_bf16 v[114:117], v[154:157], v[178:181], v[114:117]
	v_mfma_f32_16x16x32_bf16 v[110:113], v[146:149], v[204:207], v[110:113]
	v_mfma_f32_16x16x32_bf16 v[102:105], v[154:157], v[204:207], v[102:105]
	v_mfma_f32_16x16x32_bf16 v[94:97], v[146:149], v[212:215], v[94:97]
	v_mfma_f32_16x16x32_bf16 v[86:89], v[154:157], v[212:215], v[86:89]
	v_mfma_f32_16x16x32_bf16 v[78:81], v[146:149], v[224:227], v[78:81]
	v_mfma_f32_16x16x32_bf16 v[70:73], v[154:157], v[224:227], v[70:73]
	v_mfma_f32_16x16x32_bf16 v[118:121], v[150:153], v[182:185], v[118:121]
	v_mfma_f32_16x16x32_bf16 v[114:117], v[158:161], v[182:185], v[114:117]
	v_mfma_f32_16x16x32_bf16 v[110:113], v[150:153], v[208:211], v[110:113]
	v_mfma_f32_16x16x32_bf16 v[102:105], v[158:161], v[208:211], v[102:105]
	v_mfma_f32_16x16x32_bf16 v[94:97], v[150:153], v[220:223], v[94:97]
	v_mfma_f32_16x16x32_bf16 v[86:89], v[158:161], v[220:223], v[86:89]
	v_mfma_f32_16x16x32_bf16 v[78:81], v[150:153], v[228:231], v[78:81]
	v_mfma_f32_16x16x32_bf16 v[70:73], v[158:161], v[228:231], v[70:73]
	v_mfma_f32_16x16x32_bf16 v[126:129], v[162:165], v[178:181], v[126:129]
	v_mfma_f32_16x16x32_bf16 v[122:125], v[170:173], v[178:181], v[122:125]
	v_mfma_f32_16x16x32_bf16 v[106:109], v[162:165], v[204:207], v[106:109]
	v_mfma_f32_16x16x32_bf16 v[98:101], v[170:173], v[204:207], v[98:101]
	v_mfma_f32_16x16x32_bf16 v[90:93], v[162:165], v[212:215], v[90:93]
	v_mfma_f32_16x16x32_bf16 v[82:85], v[170:173], v[212:215], v[82:85]
	v_mfma_f32_16x16x32_bf16 v[74:77], v[162:165], v[224:227], v[74:77]
	v_mfma_f32_16x16x32_bf16 v[66:69], v[170:173], v[224:227], v[66:69]
	v_mfma_f32_16x16x32_bf16 v[126:129], v[166:169], v[182:185], v[126:129]
	v_mfma_f32_16x16x32_bf16 v[122:125], v[174:177], v[182:185], v[122:125]
	v_mfma_f32_16x16x32_bf16 v[106:109], v[166:169], v[208:211], v[106:109]
	v_mfma_f32_16x16x32_bf16 v[98:101], v[174:177], v[208:211], v[98:101]
	v_mfma_f32_16x16x32_bf16 v[90:93], v[166:169], v[220:223], v[90:93]
	v_mfma_f32_16x16x32_bf16 v[82:85], v[174:177], v[220:223], v[82:85]
	v_mfma_f32_16x16x32_bf16 v[74:77], v[166:169], v[228:231], v[74:77]
	v_mfma_f32_16x16x32_bf16 v[66:69], v[174:177], v[228:231], v[66:69]
	s_barrier
	s_setprio 0
	s_add_i32 s54, s67, s4
	v_lshl_add_u64 v[216:217], v[216:217], 0, s[16:17]
	s_mov_b32 m0, s54
	ds_read_b128 v[178:181], v145 offset:49152
	ds_read_b128 v[182:185], v145 offset:50176
	ds_read_b128 v[204:207], v145 offset:51200
	ds_read_b128 v[208:211], v145 offset:52224
	ds_read_b128 v[212:215], v145 offset:53248
	ds_read_b128 v[220:223], v145 offset:54272
	ds_read_b128 v[224:227], v145 offset:55296
	ds_read_b128 v[228:231], v145 offset:56320
	global_load_lds_dwordx4 v[216:217], off
	s_add_i32 m0, s54, 0x2000
	s_add_u32 s52, s52, 0x40080
	v_lshl_add_u64 v[216:217], v[240:241], 0, s[16:17]
	s_addc_u32 s53, s53, 0
	s_add_i32 s54, s68, s4
	global_load_lds_dwordx4 v[216:217], off
	v_lshl_add_u64 v[216:217], s[52:53], 0, v[134:135]
	s_mov_b32 m0, s54
	s_nop 0
	global_load_lds_dwordx4 v[216:217], off
	v_lshl_add_u64 v[216:217], s[52:53], 0, v[130:131]
	s_add_i32 m0, s54, 0x2000
	s_nop 0
	global_load_lds_dwordx4 v[216:217], off
	v_lshl_add_u64 v[216:217], v[242:243], 0, s[16:17]
	s_mov_b32 m0, s59
	s_nop 0
	global_load_lds_dwordx4 v[216:217], off
	v_lshl_add_u64 v[216:217], v[244:245], 0, s[16:17]
	s_mov_b32 m0, s60
	s_nop 0
	global_load_lds_dwordx4 v[216:217], off
	s_waitcnt vmcnt(8)
	s_waitcnt lgkmcnt(0)
	s_setprio 1
	s_barrier
	v_mfma_f32_16x16x32_bf16 v[62:65], v[146:149], v[178:181], v[62:65]
	v_mfma_f32_16x16x32_bf16 v[54:57], v[154:157], v[178:181], v[54:57]
	v_mfma_f32_16x16x32_bf16 v[46:49], v[146:149], v[204:207], v[46:49]
	v_mfma_f32_16x16x32_bf16 v[38:41], v[154:157], v[204:207], v[38:41]
	v_mfma_f32_16x16x32_bf16 v[30:33], v[146:149], v[212:215], v[30:33]
	v_mfma_f32_16x16x32_bf16 v[22:25], v[154:157], v[212:215], v[22:25]
	v_mfma_f32_16x16x32_bf16 v[14:17], v[146:149], v[224:227], v[14:17]
	v_mfma_f32_16x16x32_bf16 v[6:9], v[154:157], v[224:227], v[6:9]
	v_mfma_f32_16x16x32_bf16 v[62:65], v[150:153], v[182:185], v[62:65]
	v_mfma_f32_16x16x32_bf16 v[54:57], v[158:161], v[182:185], v[54:57]
	v_mfma_f32_16x16x32_bf16 v[46:49], v[150:153], v[208:211], v[46:49]
	v_mfma_f32_16x16x32_bf16 v[38:41], v[158:161], v[208:211], v[38:41]
	v_mfma_f32_16x16x32_bf16 v[30:33], v[150:153], v[220:223], v[30:33]
	v_mfma_f32_16x16x32_bf16 v[22:25], v[158:161], v[220:223], v[22:25]
	v_mfma_f32_16x16x32_bf16 v[14:17], v[150:153], v[228:231], v[14:17]
	v_mfma_f32_16x16x32_bf16 v[6:9], v[158:161], v[228:231], v[6:9]
	v_mfma_f32_16x16x32_bf16 v[58:61], v[162:165], v[178:181], v[58:61]
	v_mfma_f32_16x16x32_bf16 v[50:53], v[170:173], v[178:181], v[50:53]
	v_mfma_f32_16x16x32_bf16 v[42:45], v[162:165], v[204:207], v[42:45]
	v_mfma_f32_16x16x32_bf16 v[34:37], v[170:173], v[204:207], v[34:37]
	v_mfma_f32_16x16x32_bf16 v[26:29], v[162:165], v[212:215], v[26:29]
	v_mfma_f32_16x16x32_bf16 v[18:21], v[170:173], v[212:215], v[18:21]
	v_mfma_f32_16x16x32_bf16 v[10:13], v[162:165], v[224:227], v[10:13]
	v_mfma_f32_16x16x32_bf16 v[2:5], v[170:173], v[224:227], v[2:5]
	v_mfma_f32_16x16x32_bf16 v[58:61], v[166:169], v[182:185], v[58:61]
	v_mfma_f32_16x16x32_bf16 v[50:53], v[174:177], v[182:185], v[50:53]
	v_mfma_f32_16x16x32_bf16 v[42:45], v[166:169], v[208:211], v[42:45]
	v_mfma_f32_16x16x32_bf16 v[34:37], v[174:177], v[208:211], v[34:37]
	v_mfma_f32_16x16x32_bf16 v[26:29], v[166:169], v[220:223], v[26:29]
	v_mfma_f32_16x16x32_bf16 v[18:21], v[174:177], v[220:223], v[18:21]
	v_mfma_f32_16x16x32_bf16 v[10:13], v[166:169], v[228:231], v[10:13]
	v_mfma_f32_16x16x32_bf16 v[2:5], v[174:177], v[228:231], v[2:5]
	s_barrier
	s_setprio 0
	s_add_i32 s66, s66, 2
	s_add_u32 s50, s50, 0x100
	s_addc_u32 s51, s51, 0
	s_add_u32 s64, s64, 0x100
	s_addc_u32 s65, s65, 0
	s_cmp_gt_u32 s66, 13
	s_cbranch_scc0 .LBB0_997
	s_and_b64 vcc, exec, s[40:41]
	s_cbranch_vccz .LBB0_1000
	s_barrier
.LBB0_1000:
	s_lshl_b32 s52, s18, 8
	s_lshl_b32 s50, s19, 7
	s_ashr_i32 s53, s52, 31
	v_mov_b32_e32 v0, v142
	v_mov_b32_e32 v148, v143
	s_ashr_i32 s51, s50, 31
	s_lshl_b64 s[52:53], s[52:53], 2
	s_add_u32 s52, s20, s52
	s_addc_u32 s53, s21, s53
	v_add_u32_e32 v0, s57, v0
	v_lshl_add_u64 v[146:147], v[0:1], 2, s[52:53]
	global_load_dword v160, v[146:147], off
	v_add_u32_e32 v146, 16, v0
	v_mov_b32_e32 v147, v1
	v_lshl_add_u64 v[146:147], v[146:147], 2, s[52:53]
	global_load_dword v161, v[146:147], off
	v_mov_b32_e32 v147, v1
	v_mov_b32_e32 v149, v1
	v_mov_b32_e32 v151, v1
	v_mov_b32_e32 v153, v1
	v_lshlrev_b32_e32 v162, 3, v148
	v_add_u32_e32 v146, 32, v0
	v_add_u32_e32 v148, 48, v0
	v_add_u32_e32 v150, 0x80, v0
	v_add_u32_e32 v152, 0x90, v0
	s_movk_i32 s43, 0xb00
	v_mov_b32_e32 v155, v1
	v_mov_b32_e32 v157, v1
	v_pk_mul_f32 v[158:159], v[114:115], v[122:123]
	v_add_u32_e32 v154, 0xa0, v0
	v_add_u32_e32 v156, 0xb0, v0
	v_mul_lo_u32 v0, v0, s43
	v_lshl_add_u64 v[122:123], v[146:147], 2, s[52:53]
	v_lshl_add_u64 v[146:147], v[148:149], 2, s[52:53]
	v_lshl_add_u64 v[148:149], v[150:151], 2, s[52:53]
	v_lshl_add_u64 v[150:151], v[152:153], 2, s[52:53]
	v_lshl_add_u64 v[152:153], v[154:155], 2, s[52:53]
	v_lshl_add_u64 v[154:155], v[156:157], 2, s[52:53]
	v_add3_u32 v0, v162, s58, v0
	global_load_dword v156, v[122:123], off
	global_load_dword v157, v[146:147], off
	global_load_dword v162, v[148:149], off
	s_nop 0
	global_load_dword v151, v[150:151], off
	s_nop 0
	global_load_dword v123, v[152:153], off
	global_load_dword v122, v[154:155], off
	v_pk_mul_f32 v[124:125], v[116:117], v[124:125]
	v_pk_mul_f32 v[128:129], v[120:121], v[128:129]
	v_pk_mul_f32 v[126:127], v[118:119], v[126:127]
	s_mul_hi_i32 s19, s18, 0x160000
	s_mul_i32 s18, s18, 0x160000
	s_add_u32 s43, s93, s18
	s_addc_u32 s45, s76, s19
	s_lshl_b64 s[18:19], s[50:51], 1
	s_add_u32 s50, s43, s18
	s_addc_u32 s51, s45, s19
	v_pk_mul_f32 v[108:109], v[112:113], v[108:109]
	v_pk_mul_f32 v[106:107], v[110:111], v[106:107]
	v_pk_mul_f32 v[100:101], v[104:105], v[100:101]
	v_pk_mul_f32 v[98:99], v[102:103], v[98:99]
	v_pk_mul_f32 v[92:93], v[96:97], v[92:93]
	v_pk_mul_f32 v[90:91], v[94:95], v[90:91]
	v_pk_mul_f32 v[84:85], v[88:89], v[84:85]
	v_pk_mul_f32 v[82:83], v[86:87], v[82:83]
	v_pk_mul_f32 v[76:77], v[80:81], v[76:77]
	v_pk_mul_f32 v[74:75], v[78:79], v[74:75]
	v_pk_mul_f32 v[68:69], v[72:73], v[68:69]
	v_pk_mul_f32 v[66:67], v[70:71], v[66:67]
	v_pk_mul_f32 v[60:61], v[64:65], v[60:61]
	v_pk_mul_f32 v[58:59], v[62:63], v[58:59]
	v_pk_mul_f32 v[52:53], v[56:57], v[52:53]
	v_pk_mul_f32 v[50:51], v[54:55], v[50:51]
	v_pk_mul_f32 v[44:45], v[48:49], v[44:45]
	v_pk_mul_f32 v[42:43], v[46:47], v[42:43]
	v_pk_mul_f32 v[36:37], v[40:41], v[36:37]
	v_pk_mul_f32 v[34:35], v[38:39], v[34:35]
	v_pk_mul_f32 v[28:29], v[32:33], v[28:29]
	v_pk_mul_f32 v[26:27], v[30:31], v[26:27]
	v_pk_mul_f32 v[20:21], v[24:25], v[20:21]
	v_pk_mul_f32 v[18:19], v[22:23], v[18:19]
	v_pk_mul_f32 v[12:13], v[16:17], v[12:13]
	v_pk_mul_f32 v[10:11], v[14:15], v[10:11]
	v_pk_mul_f32 v[4:5], v[8:9], v[4:5]
	v_pk_mul_f32 v[2:3], v[6:7], v[2:3]
	s_andn2_b64 vcc, exec, s[38:39]
	s_mov_b64 s[38:39], -1
	s_waitcnt vmcnt(0)
	v_fmamk_f32 v146, v160, 0x3a800000, v234
	v_rsq_f32_e32 v149, v146
	v_fmamk_f32 v146, v161, 0x3a800000, v234
	v_mul_f32_e32 v148, 0xbfb8aa3b, v149
	v_pk_mul_f32 v[116:117], v[116:117], v[148:149] op_sel_hi:[1,0]
	v_pk_mul_f32 v[114:115], v[114:115], v[148:149] op_sel_hi:[1,0]
	v_pk_mul_f32 v[120:121], v[120:121], v[148:149] op_sel_hi:[1,0]
	v_pk_mul_f32 v[118:119], v[118:119], v[148:149] op_sel_hi:[1,0]
	v_exp_f32_e32 v114, v114
	v_exp_f32_e32 v115, v115
	v_exp_f32_e32 v116, v116
	v_exp_f32_e32 v117, v117
	v_exp_f32_e32 v118, v118
	v_exp_f32_e32 v119, v119
	v_exp_f32_e32 v120, v120
	v_exp_f32_e32 v121, v121
	v_rsq_f32_e32 v153, v146
	v_pk_add_f32 v[116:117], v[116:117], 1.0 op_sel_hi:[1,0]
	v_pk_add_f32 v[114:115], v[114:115], 1.0 op_sel_hi:[1,0]
	v_pk_add_f32 v[120:121], v[120:121], 1.0 op_sel_hi:[1,0]
	v_pk_add_f32 v[118:119], v[118:119], 1.0 op_sel_hi:[1,0]
	v_rcp_f32_e32 v114, v114
	v_rcp_f32_e32 v115, v115
	v_rcp_f32_e32 v116, v116
	v_rcp_f32_e32 v117, v117
	v_mul_f32_e32 v152, 0xbfb8aa3b, v153
	v_rcp_f32_e32 v118, v118
	v_rcp_f32_e32 v119, v119
	v_rcp_f32_e32 v120, v120
	v_rcp_f32_e32 v121, v121
	v_mul_f32_e32 v150, v149, v149
	v_pk_mul_f32 v[148:149], v[112:113], v[152:153] op_sel_hi:[1,0]
	v_pk_mul_f32 v[154:155], v[110:111], v[152:153] op_sel_hi:[1,0]
	v_exp_f32_e32 v148, v148
	v_exp_f32_e32 v154, v154
	v_exp_f32_e32 v155, v155
	v_exp_f32_e32 v149, v149
	v_pk_mul_f32 v[114:115], v[150:151], v[114:115] op_sel_hi:[0,1]
	v_pk_mul_f32 v[116:117], v[150:151], v[116:117] op_sel_hi:[0,1]
	v_pk_mul_f32 v[118:119], v[150:151], v[118:119] op_sel_hi:[0,1]
	v_pk_mul_f32 v[120:121], v[150:151], v[120:121] op_sel_hi:[0,1]
	v_pk_mul_f32 v[124:125], v[124:125], v[116:117]
	v_pk_mul_f32 v[116:117], v[158:159], v[114:115]
	v_lshl_add_u64 v[146:147], v[0:1], 1, s[50:51]
	v_pk_mul_f32 v[120:121], v[128:129], v[120:121]
	v_pk_mul_f32 v[118:119], v[126:127], v[118:119]
	s_nop 0
	v_cvt_pk_bf16_f32 v114, v118, v119
	v_cvt_pk_bf16_f32 v115, v120, v121
	v_cvt_pk_bf16_f32 v116, v116, v117
	v_cvt_pk_bf16_f32 v117, v124, v125
	global_store_dwordx4 v[146:147], v[114:117], off
	v_pk_add_f32 v[118:119], v[154:155], 1.0 op_sel_hi:[1,0]
	s_nop 0
	v_pk_add_f32 v[116:117], v[148:149], 1.0 op_sel_hi:[1,0]
	v_rcp_f32_e32 v118, v118
	v_rcp_f32_e32 v119, v119
	v_rcp_f32_e32 v116, v116
	v_rcp_f32_e32 v117, v117
	v_mul_f32_e32 v114, v153, v153
	v_pk_mul_f32 v[110:111], v[114:115], v[118:119] op_sel_hi:[0,1]
	v_pk_mul_f32 v[118:119], v[102:103], v[152:153] op_sel_hi:[1,0]
	v_pk_mul_f32 v[112:113], v[114:115], v[116:117] op_sel_hi:[0,1]
	v_pk_mul_f32 v[116:117], v[104:105], v[152:153] op_sel_hi:[1,0]
	v_exp_f32_e32 v118, v118
	v_exp_f32_e32 v116, v116
	v_exp_f32_e32 v117, v117
	v_exp_f32_e32 v119, v119
	v_pk_mul_f32 v[108:109], v[108:109], v[112:113]
	v_pk_mul_f32 v[106:107], v[106:107], v[110:111]
	v_pk_add_f32 v[110:111], v[116:117], 1.0 op_sel_hi:[1,0]
	v_pk_add_f32 v[112:113], v[118:119], 1.0 op_sel_hi:[1,0]
	v_rcp_f32_e32 v110, v110
	v_rcp_f32_e32 v112, v112
	v_rcp_f32_e32 v113, v113
	v_rcp_f32_e32 v111, v111
	v_pk_mul_f32 v[102:103], v[114:115], v[112:113] op_sel_hi:[0,1]
	v_pk_mul_f32 v[104:105], v[114:115], v[110:111] op_sel_hi:[0,1]
	v_pk_mul_f32 v[104:105], v[100:101], v[104:105]
	v_pk_mul_f32 v[100:101], v[98:99], v[102:103]
	v_fmamk_f32 v102, v156, 0x3a800000, v234
	v_cvt_pk_bf16_f32 v98, v106, v107
	v_cvt_pk_bf16_f32 v99, v108, v109
	v_cvt_pk_bf16_f32 v100, v100, v101
	v_cvt_pk_bf16_f32 v101, v104, v105
	v_rsq_f32_e32 v105, v102
	v_add_u32_e32 v102, 0xb000, v0
	v_mov_b32_e32 v103, v1
	v_lshl_add_u64 v[102:103], v[102:103], 1, s[50:51]
	v_mul_f32_e32 v104, 0xbfb8aa3b, v105
	v_pk_mul_f32 v[106:107], v[96:97], v[104:105] op_sel_hi:[1,0]
	v_pk_mul_f32 v[108:109], v[94:95], v[104:105] op_sel_hi:[1,0]
	v_exp_f32_e32 v106, v106
	v_exp_f32_e32 v108, v108
	v_exp_f32_e32 v107, v107
	v_exp_f32_e32 v109, v109
	global_store_dwordx4 v[102:103], v[98:101], off
	v_pk_add_f32 v[102:103], v[108:109], 1.0 op_sel_hi:[1,0]
	s_nop 0
	v_pk_add_f32 v[100:101], v[106:107], 1.0 op_sel_hi:[1,0]
	v_rcp_f32_e32 v102, v102
	v_rcp_f32_e32 v103, v103
	v_rcp_f32_e32 v100, v100
	v_rcp_f32_e32 v101, v101
	v_mul_f32_e32 v98, v105, v105
	v_pk_mul_f32 v[94:95], v[98:99], v[102:103] op_sel_hi:[0,1]
	v_pk_mul_f32 v[102:103], v[86:87], v[104:105] op_sel_hi:[1,0]
	v_pk_mul_f32 v[96:97], v[98:99], v[100:101] op_sel_hi:[0,1]
	v_pk_mul_f32 v[100:101], v[88:89], v[104:105] op_sel_hi:[1,0]
	v_exp_f32_e32 v102, v102
	v_exp_f32_e32 v100, v100
	v_exp_f32_e32 v101, v101
	v_exp_f32_e32 v103, v103
	v_pk_mul_f32 v[92:93], v[92:93], v[96:97]
	v_pk_mul_f32 v[90:91], v[90:91], v[94:95]
	v_pk_add_f32 v[94:95], v[100:101], 1.0 op_sel_hi:[1,0]
	v_pk_add_f32 v[96:97], v[102:103], 1.0 op_sel_hi:[1,0]
	v_rcp_f32_e32 v94, v94
	v_rcp_f32_e32 v96, v96
	v_rcp_f32_e32 v97, v97
	v_rcp_f32_e32 v95, v95
	v_pk_mul_f32 v[86:87], v[98:99], v[96:97] op_sel_hi:[0,1]
	v_pk_mul_f32 v[88:89], v[98:99], v[94:95] op_sel_hi:[0,1]
	v_pk_mul_f32 v[88:89], v[84:85], v[88:89]
	v_pk_mul_f32 v[84:85], v[82:83], v[86:87]
	v_fmamk_f32 v86, v157, 0x3a800000, v234
	v_cvt_pk_bf16_f32 v82, v90, v91
	v_cvt_pk_bf16_f32 v83, v92, v93
	v_cvt_pk_bf16_f32 v84, v84, v85
	v_cvt_pk_bf16_f32 v85, v88, v89
	v_rsq_f32_e32 v89, v86
	v_add_u32_e32 v86, 0x16000, v0
	v_mov_b32_e32 v87, v1
	v_lshl_add_u64 v[86:87], v[86:87], 1, s[50:51]
	v_mul_f32_e32 v88, 0xbfb8aa3b, v89
	v_pk_mul_f32 v[90:91], v[80:81], v[88:89] op_sel_hi:[1,0]
	v_pk_mul_f32 v[92:93], v[78:79], v[88:89] op_sel_hi:[1,0]
	v_exp_f32_e32 v90, v90
	v_exp_f32_e32 v92, v92
	v_exp_f32_e32 v91, v91
	v_exp_f32_e32 v93, v93
	global_store_dwordx4 v[86:87], v[82:85], off
	v_pk_add_f32 v[86:87], v[92:93], 1.0 op_sel_hi:[1,0]
	s_nop 0
	v_pk_add_f32 v[84:85], v[90:91], 1.0 op_sel_hi:[1,0]
	v_rcp_f32_e32 v86, v86
	v_rcp_f32_e32 v87, v87
	v_rcp_f32_e32 v84, v84
	v_rcp_f32_e32 v85, v85
	v_mul_f32_e32 v82, v89, v89
	v_pk_mul_f32 v[78:79], v[82:83], v[86:87] op_sel_hi:[0,1]
	v_pk_mul_f32 v[86:87], v[70:71], v[88:89] op_sel_hi:[1,0]
	v_pk_mul_f32 v[80:81], v[82:83], v[84:85] op_sel_hi:[0,1]
	v_pk_mul_f32 v[84:85], v[72:73], v[88:89] op_sel_hi:[1,0]
	v_exp_f32_e32 v86, v86
	v_exp_f32_e32 v84, v84
	v_exp_f32_e32 v85, v85
	v_exp_f32_e32 v87, v87
	v_pk_mul_f32 v[76:77], v[76:77], v[80:81]
	v_pk_mul_f32 v[74:75], v[74:75], v[78:79]
	v_pk_add_f32 v[78:79], v[84:85], 1.0 op_sel_hi:[1,0]
	v_pk_add_f32 v[80:81], v[86:87], 1.0 op_sel_hi:[1,0]
	v_rcp_f32_e32 v78, v78
	v_rcp_f32_e32 v80, v80
	v_rcp_f32_e32 v81, v81
	v_rcp_f32_e32 v79, v79
	v_pk_mul_f32 v[70:71], v[82:83], v[80:81] op_sel_hi:[0,1]
	v_pk_mul_f32 v[72:73], v[82:83], v[78:79] op_sel_hi:[0,1]
	v_pk_mul_f32 v[72:73], v[68:69], v[72:73]
	v_pk_mul_f32 v[68:69], v[66:67], v[70:71]
	v_fmamk_f32 v70, v162, 0x3a800000, v234
	v_cvt_pk_bf16_f32 v66, v74, v75
	v_cvt_pk_bf16_f32 v67, v76, v77
	v_cvt_pk_bf16_f32 v68, v68, v69
	v_cvt_pk_bf16_f32 v69, v72, v73
	v_rsq_f32_e32 v73, v70
	v_add_u32_e32 v70, 0x21000, v0
	v_mov_b32_e32 v71, v1
	v_lshl_add_u64 v[70:71], v[70:71], 1, s[50:51]
	v_mul_f32_e32 v72, 0xbfb8aa3b, v73
	v_pk_mul_f32 v[74:75], v[64:65], v[72:73] op_sel_hi:[1,0]
	v_pk_mul_f32 v[76:77], v[62:63], v[72:73] op_sel_hi:[1,0]
	v_exp_f32_e32 v74, v74
	v_exp_f32_e32 v76, v76
	v_exp_f32_e32 v75, v75
	v_exp_f32_e32 v77, v77
	global_store_dwordx4 v[70:71], v[66:69], off
	v_pk_add_f32 v[70:71], v[76:77], 1.0 op_sel_hi:[1,0]
	s_nop 0
	v_pk_add_f32 v[68:69], v[74:75], 1.0 op_sel_hi:[1,0]
	v_rcp_f32_e32 v70, v70
	v_rcp_f32_e32 v71, v71
	v_rcp_f32_e32 v68, v68
	v_rcp_f32_e32 v69, v69
	v_mul_f32_e32 v66, v73, v73
	v_pk_mul_f32 v[62:63], v[66:67], v[70:71] op_sel_hi:[0,1]
	v_pk_mul_f32 v[70:71], v[54:55], v[72:73] op_sel_hi:[1,0]
	v_pk_mul_f32 v[64:65], v[66:67], v[68:69] op_sel_hi:[0,1]
	v_pk_mul_f32 v[68:69], v[56:57], v[72:73] op_sel_hi:[1,0]
	v_exp_f32_e32 v70, v70
	v_exp_f32_e32 v68, v68
	v_exp_f32_e32 v69, v69
	v_exp_f32_e32 v71, v71
	v_pk_mul_f32 v[60:61], v[60:61], v[64:65]
	v_pk_mul_f32 v[58:59], v[58:59], v[62:63]
	v_pk_add_f32 v[62:63], v[68:69], 1.0 op_sel_hi:[1,0]
	v_pk_add_f32 v[64:65], v[70:71], 1.0 op_sel_hi:[1,0]
	v_rcp_f32_e32 v62, v62
	v_rcp_f32_e32 v64, v64
	v_rcp_f32_e32 v65, v65
	v_rcp_f32_e32 v63, v63
	v_pk_mul_f32 v[54:55], v[66:67], v[64:65] op_sel_hi:[0,1]
	v_pk_mul_f32 v[56:57], v[66:67], v[62:63] op_sel_hi:[0,1]
	v_pk_mul_f32 v[56:57], v[52:53], v[56:57]
	v_pk_mul_f32 v[52:53], v[50:51], v[54:55]
	v_fmamk_f32 v54, v151, 0x3a800000, v234
	v_cvt_pk_bf16_f32 v50, v58, v59
	v_cvt_pk_bf16_f32 v51, v60, v61
	v_cvt_pk_bf16_f32 v52, v52, v53
	v_cvt_pk_bf16_f32 v53, v56, v57
	v_rsq_f32_e32 v57, v54
	v_add_u32_e32 v54, 0x58000, v0
	v_mov_b32_e32 v55, v1
	v_lshl_add_u64 v[54:55], v[54:55], 1, s[50:51]
	v_mul_f32_e32 v56, 0xbfb8aa3b, v57
	v_pk_mul_f32 v[58:59], v[48:49], v[56:57] op_sel_hi:[1,0]
	v_pk_mul_f32 v[60:61], v[46:47], v[56:57] op_sel_hi:[1,0]
	v_exp_f32_e32 v58, v58
	v_exp_f32_e32 v60, v60
	v_exp_f32_e32 v59, v59
	v_exp_f32_e32 v61, v61
	global_store_dwordx4 v[54:55], v[50:53], off
	v_pk_add_f32 v[54:55], v[60:61], 1.0 op_sel_hi:[1,0]
	s_nop 0
	v_pk_add_f32 v[52:53], v[58:59], 1.0 op_sel_hi:[1,0]
	v_rcp_f32_e32 v54, v54
	v_rcp_f32_e32 v55, v55
	v_rcp_f32_e32 v52, v52
	v_rcp_f32_e32 v53, v53
	v_mul_f32_e32 v50, v57, v57
	v_pk_mul_f32 v[46:47], v[50:51], v[54:55] op_sel_hi:[0,1]
	v_pk_mul_f32 v[54:55], v[38:39], v[56:57] op_sel_hi:[1,0]
	v_pk_mul_f32 v[48:49], v[50:51], v[52:53] op_sel_hi:[0,1]
	v_pk_mul_f32 v[52:53], v[40:41], v[56:57] op_sel_hi:[1,0]
	v_exp_f32_e32 v54, v54
	v_exp_f32_e32 v52, v52
	v_exp_f32_e32 v53, v53
	v_exp_f32_e32 v55, v55
	v_pk_mul_f32 v[44:45], v[44:45], v[48:49]
	v_pk_mul_f32 v[42:43], v[42:43], v[46:47]
	v_pk_add_f32 v[46:47], v[52:53], 1.0 op_sel_hi:[1,0]
	v_pk_add_f32 v[48:49], v[54:55], 1.0 op_sel_hi:[1,0]
	v_rcp_f32_e32 v46, v46
	v_rcp_f32_e32 v48, v48
	v_rcp_f32_e32 v49, v49
	v_rcp_f32_e32 v47, v47
	v_pk_mul_f32 v[38:39], v[50:51], v[48:49] op_sel_hi:[0,1]
	v_pk_mul_f32 v[40:41], v[50:51], v[46:47] op_sel_hi:[0,1]
	v_pk_mul_f32 v[40:41], v[36:37], v[40:41]
	v_pk_mul_f32 v[36:37], v[34:35], v[38:39]
	v_fmamk_f32 v38, v123, 0x3a800000, v234
	v_cvt_pk_bf16_f32 v34, v42, v43
	v_cvt_pk_bf16_f32 v35, v44, v45
	v_cvt_pk_bf16_f32 v36, v36, v37
	v_cvt_pk_bf16_f32 v37, v40, v41
	v_rsq_f32_e32 v41, v38
	v_add_u32_e32 v38, 0x63000, v0
	v_mov_b32_e32 v39, v1
	v_lshl_add_u64 v[38:39], v[38:39], 1, s[50:51]
	v_mul_f32_e32 v40, 0xbfb8aa3b, v41
	v_pk_mul_f32 v[42:43], v[32:33], v[40:41] op_sel_hi:[1,0]
	v_pk_mul_f32 v[44:45], v[30:31], v[40:41] op_sel_hi:[1,0]
	v_exp_f32_e32 v42, v42
	v_exp_f32_e32 v44, v44
	v_exp_f32_e32 v43, v43
	v_exp_f32_e32 v45, v45
	global_store_dwordx4 v[38:39], v[34:37], off
	v_pk_add_f32 v[38:39], v[44:45], 1.0 op_sel_hi:[1,0]
	s_nop 0
	v_pk_add_f32 v[36:37], v[42:43], 1.0 op_sel_hi:[1,0]
	v_rcp_f32_e32 v38, v38
	v_rcp_f32_e32 v39, v39
	v_rcp_f32_e32 v36, v36
	v_rcp_f32_e32 v37, v37
	v_mul_f32_e32 v34, v41, v41
	v_pk_mul_f32 v[30:31], v[34:35], v[38:39] op_sel_hi:[0,1]
	v_pk_mul_f32 v[38:39], v[22:23], v[40:41] op_sel_hi:[1,0]
	v_pk_mul_f32 v[32:33], v[34:35], v[36:37] op_sel_hi:[0,1]
	v_pk_mul_f32 v[36:37], v[24:25], v[40:41] op_sel_hi:[1,0]
	v_exp_f32_e32 v38, v38
	v_exp_f32_e32 v36, v36
	v_exp_f32_e32 v37, v37
	v_exp_f32_e32 v39, v39
	v_pk_mul_f32 v[28:29], v[28:29], v[32:33]
	v_pk_mul_f32 v[26:27], v[26:27], v[30:31]
	v_pk_add_f32 v[30:31], v[36:37], 1.0 op_sel_hi:[1,0]
	v_pk_add_f32 v[32:33], v[38:39], 1.0 op_sel_hi:[1,0]
	v_rcp_f32_e32 v30, v30
	v_rcp_f32_e32 v32, v32
	v_rcp_f32_e32 v33, v33
	v_rcp_f32_e32 v31, v31
	v_pk_mul_f32 v[22:23], v[34:35], v[32:33] op_sel_hi:[0,1]
	v_pk_mul_f32 v[24:25], v[34:35], v[30:31] op_sel_hi:[0,1]
	v_pk_mul_f32 v[24:25], v[20:21], v[24:25]
	v_pk_mul_f32 v[20:21], v[18:19], v[22:23]
	v_fmamk_f32 v22, v122, 0x3a800000, v234
	v_cvt_pk_bf16_f32 v18, v26, v27
	v_cvt_pk_bf16_f32 v19, v28, v29
	v_cvt_pk_bf16_f32 v20, v20, v21
	v_cvt_pk_bf16_f32 v21, v24, v25
	v_rsq_f32_e32 v25, v22
	v_add_u32_e32 v22, 0x6e000, v0
	v_mov_b32_e32 v23, v1
	v_lshl_add_u64 v[22:23], v[22:23], 1, s[50:51]
	v_mul_f32_e32 v24, 0xbfb8aa3b, v25
	v_pk_mul_f32 v[26:27], v[16:17], v[24:25] op_sel_hi:[1,0]
	v_pk_mul_f32 v[28:29], v[14:15], v[24:25] op_sel_hi:[1,0]
	v_exp_f32_e32 v26, v26
	v_exp_f32_e32 v28, v28
	v_exp_f32_e32 v27, v27
	v_exp_f32_e32 v29, v29
	global_store_dwordx4 v[22:23], v[18:21], off
	v_add_u32_e32 v0, 0x79000, v0
	v_pk_add_f32 v[22:23], v[28:29], 1.0 op_sel_hi:[1,0]
	v_pk_add_f32 v[20:21], v[26:27], 1.0 op_sel_hi:[1,0]
	v_rcp_f32_e32 v22, v22
	v_rcp_f32_e32 v23, v23
	v_rcp_f32_e32 v20, v20
	v_rcp_f32_e32 v21, v21
	v_mul_f32_e32 v18, v25, v25
	v_pk_mul_f32 v[14:15], v[18:19], v[22:23] op_sel_hi:[0,1]
	v_pk_mul_f32 v[22:23], v[6:7], v[24:25] op_sel_hi:[1,0]
	v_pk_mul_f32 v[16:17], v[18:19], v[20:21] op_sel_hi:[0,1]
	v_pk_mul_f32 v[20:21], v[8:9], v[24:25] op_sel_hi:[1,0]
	v_exp_f32_e32 v22, v22
	v_exp_f32_e32 v20, v20
	v_exp_f32_e32 v21, v21
	v_exp_f32_e32 v23, v23
	v_pk_mul_f32 v[12:13], v[12:13], v[16:17]
	v_pk_mul_f32 v[10:11], v[10:11], v[14:15]
	v_pk_add_f32 v[14:15], v[20:21], 1.0 op_sel_hi:[1,0]
	v_pk_add_f32 v[16:17], v[22:23], 1.0 op_sel_hi:[1,0]
	v_rcp_f32_e32 v14, v14
	v_rcp_f32_e32 v16, v16
	v_rcp_f32_e32 v17, v17
	v_rcp_f32_e32 v15, v15
	v_pk_mul_f32 v[6:7], v[18:19], v[16:17] op_sel_hi:[0,1]
	v_pk_mul_f32 v[8:9], v[18:19], v[14:15] op_sel_hi:[0,1]
	v_pk_mul_f32 v[8:9], v[4:5], v[8:9]
	v_pk_mul_f32 v[4:5], v[2:3], v[6:7]
	v_lshl_add_u64 v[6:7], v[0:1], 1, s[50:51]
	v_cvt_pk_bf16_f32 v2, v10, v11
	v_cvt_pk_bf16_f32 v3, v12, v13
	v_cvt_pk_bf16_f32 v4, v4, v5
	v_cvt_pk_bf16_f32 v5, v8, v9
	global_store_dwordx4 v[6:7], v[2:5], off
	s_cbranch_vccnz .LBB0_993
	s_mov_b32 s67, 0
	s_andn2_b64 vcc, exec, s[22:23]
	s_cbranch_vccnz .LBB0_992
	s_mov_b32 s67, 1
	s_branch .LBB0_992

.LBB0_1074:
	v_readlane_b32 s44, v251, 25
	v_bfe_u32 v219, v13, 4, 2
	s_lshl_b32 s1, s1, 5
	v_mov_b32_e32 v211, v1
	v_readlane_b32 s45, v251, 26
	v_and_b32_e32 v220, 15, v13
	v_lshlrev_b32_e32 v18, 4, v219
	v_lshlrev_b32_e32 v13, 2, v13
	s_and_b32 s58, s1, 0x60
	s_add_i32 m0, s53, 0x18000
	v_lshl_add_u64 v[2:3], v[2:3], 0, s[16:17]
	v_lshl_add_u64 v[14:15], s[44:45], 0, v[210:211]
	v_mov_b32_e32 v207, v1
	s_lshl_b32 s57, s4, 6
	v_lshl_or_b32 v18, v220, 6, v18
	s_lshl_b32 s4, s4, 13
	v_and_b32_e32 v13, 32, v13
	s_lshl_b32 s1, s58, 7
	s_waitcnt vmcnt(2)
	s_barrier
	global_load_lds_dwordx4 v[2:3], off
	v_lshl_add_u64 v[2:3], v[4:5], 0, s[16:17]
	s_add_i32 m0, s53, 0x1a000
	s_add_i32 s59, s53, 0x8000
	s_add_i32 s60, s53, 0xa000
	v_lshl_add_u64 v[16:17], s[44:45], 0, v[206:207]
	v_bitop3_b32 v19, v18, s4, v13 bitop3:0xde
	global_load_lds_dwordx4 v[2:3], off
	v_lshl_add_u64 v[2:3], v[14:15], 0, s[16:17]
	s_mov_b32 m0, s59
	s_add_u32 s4, s48, 0xb0080
	global_load_lds_dwordx4 v[2:3], off
	v_lshl_add_u64 v[2:3], v[16:17], 0, s[16:17]
	s_mov_b32 m0, s60
	s_addc_u32 s5, s49, 0
	global_load_lds_dwordx4 v[2:3], off
	s_add_i32 m0, s53, 0x1c000
	v_lshl_add_u64 v[2:3], s[4:5], 0, v[208:209]
	global_load_lds_dwordx4 v[2:3], off
	v_lshl_add_u64 v[2:3], s[4:5], 0, v[204:205]
	s_add_i32 m0, s53, 0x1e000
	s_movk_i32 s4, 0xb00
	global_load_lds_dwordx4 v[2:3], off
	v_lshrrev_b32_e32 v2, 1, v10
	v_mul_lo_u32 v0, v0, s4
	s_mov_b32 s5, 0xb000
	v_bitop3_b32 v221, v18, s1, v13 bitop3:0xde
	s_cmpk_lt_u32 s0, 0x100
	v_mad_u64_u32 v[2:3], s[0:1], v2, s5, v[0:1]
	v_or_b32_e32 v0, v2, v11
	v_add_lshl_u32 v0, v0, v12, 1
	s_mov_b64 s[6:7], 0xb0080
	v_lshl_add_u64 v[212:213], v[0:1], 0, s[6:7]
	v_lshrrev_b32_e32 v2, 1, v6
	v_mul_lo_u32 v0, v7, s4
	v_mad_u64_u32 v[2:3], s[0:1], v2, s5, v[0:1]
	s_waitcnt vmcnt(6)
	v_or_b32_e32 v0, v2, v8
	v_add_lshl_u32 v0, v0, v9, 1
	s_cselect_b64 s[22:23], -1, 0
	v_lshl_add_u64 v[214:215], v[0:1], 0, s[6:7]
	s_mov_b32 s61, 0
	v_add_u32_e32 v222, 0, v19
	v_readlane_b32 s6, v251, 63
	v_readlane_b32 s46, v251, 23
	s_barrier
	v_readlane_b32 s47, v251, 24
	s_mov_b32 s63, 0
	s_branch .LBB0_1077

.LBB0_1087:
	s_add_u32 s7, s48, 0x100
	s_addc_u32 s47, s49, 0
	s_mov_b32 s62, -2
	s_waitcnt lgkmcnt(0)
	s_waitcnt vmcnt(0)
	s_cmp_eq_u32 s63, 0
	s_cbranch_scc1 .Lrb6_skip
	s_barrier
.Lrb6_skip:
	s_add_u32 s0, s44, 0x100
	s_addc_u32 s1, s45, 0
	s_add_i32 s63, 0, 0x10000
	s_cmp_eq_u32 s62, 40
	s_cselect_b32 s51, s41, s1
	s_cselect_b32 s50, s40, s0
	v_add_u32_e32 v0, s63, v221
	s_cselect_b32 s49, s43, s47
	s_cselect_b32 s48, s42, s7
	s_add_i32 s64, 0, 0x14000
	ds_read_b128 v[106:109], v0
	ds_read_b128 v[110:113], v0 offset:1024
	ds_read_b128 v[126:129], v0 offset:2048
	ds_read_b128 v[134:137], v0 offset:3072
	v_add_u32_e32 v0, s64, v221
	ds_read_b128 v[146:149], v0
	ds_read_b128 v[150:153], v0 offset:1024
	ds_read_b128 v[154:157], v0 offset:2048
	ds_read_b128 v[158:161], v0 offset:3072
	v_lshl_add_u64 v[216:217], s[44:45], 0, v[212:213]
	s_add_i32 m0, s53, 0xc000
	ds_read_b128 v[162:165], v222
	ds_read_b128 v[166:169], v222 offset:1024
	ds_read_b128 v[170:173], v222 offset:2048
	ds_read_b128 v[174:177], v222 offset:3072
	ds_read_b128 v[178:181], v222 offset:4096
	ds_read_b128 v[182:185], v222 offset:5120
	ds_read_b128 v[224:227], v222 offset:6144
	ds_read_b128 v[228:231], v222 offset:7168
	global_load_lds_dwordx4 v[216:217], off
	v_lshl_add_u64 v[216:217], s[44:45], 0, v[214:215]
	s_add_i32 m0, s53, 0xe000
	s_nop 0
	global_load_lds_dwordx4 v[216:217], off
	s_waitcnt vmcnt(8)
	s_waitcnt lgkmcnt(0)
	s_setprio 1
	s_barrier
	v_mfma_f32_16x16x32_bf16 v[142:145], v[106:109], v[162:165], 0
	v_mfma_f32_16x16x32_bf16 v[138:141], v[126:129], v[162:165], 0
	v_mfma_f32_16x16x32_bf16 v[118:121], v[106:109], v[170:173], 0
	v_mfma_f32_16x16x32_bf16 v[114:117], v[126:129], v[170:173], 0
	v_mfma_f32_16x16x32_bf16 v[94:97], v[106:109], v[178:181], 0
	v_mfma_f32_16x16x32_bf16 v[90:93], v[126:129], v[178:181], 0
	v_mfma_f32_16x16x32_bf16 v[78:81], v[106:109], v[224:227], 0
	v_mfma_f32_16x16x32_bf16 v[74:77], v[126:129], v[224:227], 0
	v_mfma_f32_16x16x32_bf16 v[142:145], v[110:113], v[166:169], v[142:145]
	v_mfma_f32_16x16x32_bf16 v[138:141], v[134:137], v[166:169], v[138:141]
	v_mfma_f32_16x16x32_bf16 v[118:121], v[110:113], v[174:177], v[118:121]
	v_mfma_f32_16x16x32_bf16 v[114:117], v[134:137], v[174:177], v[114:117]
	v_mfma_f32_16x16x32_bf16 v[94:97], v[110:113], v[182:185], v[94:97]
	v_mfma_f32_16x16x32_bf16 v[90:93], v[134:137], v[182:185], v[90:93]
	v_mfma_f32_16x16x32_bf16 v[78:81], v[110:113], v[228:231], v[78:81]
	v_mfma_f32_16x16x32_bf16 v[74:77], v[134:137], v[228:231], v[74:77]
	v_mfma_f32_16x16x32_bf16 v[130:133], v[146:149], v[162:165], 0
	v_mfma_f32_16x16x32_bf16 v[122:125], v[154:157], v[162:165], 0
	v_mfma_f32_16x16x32_bf16 v[102:105], v[146:149], v[170:173], 0
	v_mfma_f32_16x16x32_bf16 v[98:101], v[154:157], v[170:173], 0
	v_mfma_f32_16x16x32_bf16 v[86:89], v[146:149], v[178:181], 0
	v_mfma_f32_16x16x32_bf16 v[82:85], v[154:157], v[178:181], 0
	v_mfma_f32_16x16x32_bf16 v[70:73], v[146:149], v[224:227], 0
	v_mfma_f32_16x16x32_bf16 v[66:69], v[154:157], v[224:227], 0
	v_mfma_f32_16x16x32_bf16 v[130:133], v[150:153], v[166:169], v[130:133]
	v_mfma_f32_16x16x32_bf16 v[122:125], v[158:161], v[166:169], v[122:125]
	v_mfma_f32_16x16x32_bf16 v[102:105], v[150:153], v[174:177], v[102:105]
	v_mfma_f32_16x16x32_bf16 v[98:101], v[158:161], v[174:177], v[98:101]
	v_mfma_f32_16x16x32_bf16 v[86:89], v[150:153], v[182:185], v[86:89]
	v_mfma_f32_16x16x32_bf16 v[82:85], v[158:161], v[182:185], v[82:85]
	v_mfma_f32_16x16x32_bf16 v[70:73], v[150:153], v[228:231], v[70:73]
	v_mfma_f32_16x16x32_bf16 v[66:69], v[158:161], v[228:231], v[66:69]
	s_barrier
	s_setprio 0
	s_add_i32 s44, s63, s52
	v_lshl_add_u64 v[216:217], s[48:49], 0, v[208:209]
	s_mov_b32 m0, s44
	ds_read_b128 v[162:165], v222 offset:16384
	ds_read_b128 v[166:169], v222 offset:17408
	ds_read_b128 v[170:173], v222 offset:18432
	ds_read_b128 v[174:177], v222 offset:19456
	ds_read_b128 v[178:181], v222 offset:20480
	ds_read_b128 v[182:185], v222 offset:21504
	ds_read_b128 v[224:227], v222 offset:22528
	ds_read_b128 v[228:231], v222 offset:23552
	global_load_lds_dwordx4 v[216:217], off
	s_add_i32 m0, s44, 0x2000
	s_add_u32 s44, s48, 0xb0000
	v_lshl_add_u64 v[240:241], s[48:49], 0, v[204:205]
	s_addc_u32 s45, s49, 0
	s_add_i32 s63, s64, s52
	global_load_lds_dwordx4 v[240:241], off
	v_lshl_add_u64 v[242:243], s[44:45], 0, v[208:209]
	s_mov_b32 m0, s63
	v_lshl_add_u64 v[244:245], s[50:51], 0, v[206:207]
	global_load_lds_dwordx4 v[242:243], off
	v_lshl_add_u64 v[242:243], s[44:45], 0, v[204:205]
	s_add_i32 m0, s63, 0x2000
	s_nop 0
	global_load_lds_dwordx4 v[242:243], off
	v_lshl_add_u64 v[242:243], s[50:51], 0, v[210:211]
	s_mov_b32 m0, s53
	s_nop 0
	global_load_lds_dwordx4 v[242:243], off
	s_mov_b32 m0, s54
	s_nop 0
	global_load_lds_dwordx4 v[244:245], off
	s_waitcnt vmcnt(8)
	s_waitcnt lgkmcnt(0)
	s_setprio 1
	s_barrier
	v_mfma_f32_16x16x32_bf16 v[62:65], v[106:109], v[162:165], 0
	v_mfma_f32_16x16x32_bf16 v[58:61], v[126:129], v[162:165], 0
	v_mfma_f32_16x16x32_bf16 v[46:49], v[106:109], v[170:173], 0
	v_mfma_f32_16x16x32_bf16 v[42:45], v[126:129], v[170:173], 0
	v_mfma_f32_16x16x32_bf16 v[30:33], v[106:109], v[178:181], 0
	v_mfma_f32_16x16x32_bf16 v[26:29], v[126:129], v[178:181], 0
	v_mfma_f32_16x16x32_bf16 v[14:17], v[106:109], v[224:227], 0
	v_mfma_f32_16x16x32_bf16 v[10:13], v[126:129], v[224:227], 0
	v_mfma_f32_16x16x32_bf16 v[62:65], v[110:113], v[166:169], v[62:65]
	v_mfma_f32_16x16x32_bf16 v[58:61], v[134:137], v[166:169], v[58:61]
	v_mfma_f32_16x16x32_bf16 v[46:49], v[110:113], v[174:177], v[46:49]
	v_mfma_f32_16x16x32_bf16 v[42:45], v[134:137], v[174:177], v[42:45]
	v_mfma_f32_16x16x32_bf16 v[30:33], v[110:113], v[182:185], v[30:33]
	v_mfma_f32_16x16x32_bf16 v[26:29], v[134:137], v[182:185], v[26:29]
	v_mfma_f32_16x16x32_bf16 v[14:17], v[110:113], v[228:231], v[14:17]
	v_mfma_f32_16x16x32_bf16 v[10:13], v[134:137], v[228:231], v[10:13]
	v_mfma_f32_16x16x32_bf16 v[54:57], v[146:149], v[162:165], 0
	v_mfma_f32_16x16x32_bf16 v[50:53], v[154:157], v[162:165], 0
	v_mfma_f32_16x16x32_bf16 v[38:41], v[146:149], v[170:173], 0
	v_mfma_f32_16x16x32_bf16 v[34:37], v[154:157], v[170:173], 0
	v_mfma_f32_16x16x32_bf16 v[22:25], v[146:149], v[178:181], 0
	v_mfma_f32_16x16x32_bf16 v[18:21], v[154:157], v[178:181], 0
	v_mfma_f32_16x16x32_bf16 v[6:9], v[146:149], v[224:227], 0
	v_mfma_f32_16x16x32_bf16 v[2:5], v[154:157], v[224:227], 0
	v_mfma_f32_16x16x32_bf16 v[54:57], v[150:153], v[166:169], v[54:57]
	v_mfma_f32_16x16x32_bf16 v[50:53], v[158:161], v[166:169], v[50:53]
	v_mfma_f32_16x16x32_bf16 v[38:41], v[150:153], v[174:177], v[38:41]
	v_mfma_f32_16x16x32_bf16 v[34:37], v[158:161], v[174:177], v[34:37]
	v_mfma_f32_16x16x32_bf16 v[22:25], v[150:153], v[182:185], v[22:25]
	v_mfma_f32_16x16x32_bf16 v[18:21], v[158:161], v[182:185], v[18:21]
	v_mfma_f32_16x16x32_bf16 v[6:9], v[150:153], v[228:231], v[6:9]
	v_mfma_f32_16x16x32_bf16 v[2:5], v[158:161], v[228:231], v[2:5]
	s_barrier
	s_setprio 0
	s_add_i32 s63, 0, 0x18000
	v_add_u32_e32 v0, s63, v221
	s_add_i32 s64, 0, 0x1c000
	ds_read_b128 v[106:109], v0
	ds_read_b128 v[110:113], v0 offset:1024
	ds_read_b128 v[126:129], v0 offset:2048
	ds_read_b128 v[134:137], v0 offset:3072
	v_add_u32_e32 v0, s64, v221
	ds_read_b128 v[146:149], v0
	ds_read_b128 v[150:153], v0 offset:1024
	ds_read_b128 v[154:157], v0 offset:2048
	ds_read_b128 v[158:161], v0 offset:3072
	s_add_u32 s44, s50, 0xb0000
	s_addc_u32 s45, s51, 0
	s_mov_b32 m0, s55
	v_lshl_add_u64 v[246:247], s[44:45], 0, v[210:211]
	ds_read_b128 v[162:165], v222 offset:32768
	ds_read_b128 v[166:169], v222 offset:33792
	ds_read_b128 v[170:173], v222 offset:34816
	ds_read_b128 v[174:177], v222 offset:35840
	ds_read_b128 v[178:181], v222 offset:36864
	ds_read_b128 v[182:185], v222 offset:37888
	ds_read_b128 v[224:227], v222 offset:38912
	ds_read_b128 v[228:231], v222 offset:39936
	global_load_lds_dwordx4 v[246:247], off
	v_lshl_add_u64 v[246:247], s[44:45], 0, v[206:207]
	s_mov_b32 m0, s56
	s_nop 0
	global_load_lds_dwordx4 v[246:247], off
	s_waitcnt vmcnt(8)
	s_waitcnt lgkmcnt(0)
	s_setprio 1
	s_barrier
	v_mfma_f32_16x16x32_bf16 v[142:145], v[106:109], v[162:165], v[142:145]
	v_mfma_f32_16x16x32_bf16 v[138:141], v[126:129], v[162:165], v[138:141]
	v_mfma_f32_16x16x32_bf16 v[118:121], v[106:109], v[170:173], v[118:121]
	v_mfma_f32_16x16x32_bf16 v[114:117], v[126:129], v[170:173], v[114:117]
	v_mfma_f32_16x16x32_bf16 v[94:97], v[106:109], v[178:181], v[94:97]
	v_mfma_f32_16x16x32_bf16 v[90:93], v[126:129], v[178:181], v[90:93]
	v_mfma_f32_16x16x32_bf16 v[78:81], v[106:109], v[224:227], v[78:81]
	v_mfma_f32_16x16x32_bf16 v[74:77], v[126:129], v[224:227], v[74:77]
	v_mfma_f32_16x16x32_bf16 v[142:145], v[110:113], v[166:169], v[142:145]
	v_mfma_f32_16x16x32_bf16 v[138:141], v[134:137], v[166:169], v[138:141]
	v_mfma_f32_16x16x32_bf16 v[118:121], v[110:113], v[174:177], v[118:121]
	v_mfma_f32_16x16x32_bf16 v[114:117], v[134:137], v[174:177], v[114:117]
	v_mfma_f32_16x16x32_bf16 v[94:97], v[110:113], v[182:185], v[94:97]
	v_mfma_f32_16x16x32_bf16 v[90:93], v[134:137], v[182:185], v[90:93]
	v_mfma_f32_16x16x32_bf16 v[78:81], v[110:113], v[228:231], v[78:81]
	v_mfma_f32_16x16x32_bf16 v[74:77], v[134:137], v[228:231], v[74:77]
	v_mfma_f32_16x16x32_bf16 v[130:133], v[146:149], v[162:165], v[130:133]
	v_mfma_f32_16x16x32_bf16 v[122:125], v[154:157], v[162:165], v[122:125]
	v_mfma_f32_16x16x32_bf16 v[102:105], v[146:149], v[170:173], v[102:105]
	v_mfma_f32_16x16x32_bf16 v[98:101], v[154:157], v[170:173], v[98:101]
	v_mfma_f32_16x16x32_bf16 v[86:89], v[146:149], v[178:181], v[86:89]
	v_mfma_f32_16x16x32_bf16 v[82:85], v[154:157], v[178:181], v[82:85]
	v_mfma_f32_16x16x32_bf16 v[70:73], v[146:149], v[224:227], v[70:73]
	v_mfma_f32_16x16x32_bf16 v[66:69], v[154:157], v[224:227], v[66:69]
	v_mfma_f32_16x16x32_bf16 v[130:133], v[150:153], v[166:169], v[130:133]
	v_mfma_f32_16x16x32_bf16 v[122:125], v[158:161], v[166:169], v[122:125]
	v_mfma_f32_16x16x32_bf16 v[102:105], v[150:153], v[174:177], v[102:105]
	v_mfma_f32_16x16x32_bf16 v[98:101], v[158:161], v[174:177], v[98:101]
	v_mfma_f32_16x16x32_bf16 v[86:89], v[150:153], v[182:185], v[86:89]
	v_mfma_f32_16x16x32_bf16 v[82:85], v[158:161], v[182:185], v[82:85]
	v_mfma_f32_16x16x32_bf16 v[70:73], v[150:153], v[228:231], v[70:73]
	v_mfma_f32_16x16x32_bf16 v[66:69], v[158:161], v[228:231], v[66:69]
	s_barrier
	s_setprio 0
	s_add_i32 s44, s63, s52
	v_lshl_add_u64 v[216:217], v[216:217], 0, s[16:17]
	s_mov_b32 m0, s44
	ds_read_b128 v[162:165], v222 offset:49152
	ds_read_b128 v[166:169], v222 offset:50176
	ds_read_b128 v[170:173], v222 offset:51200
	ds_read_b128 v[174:177], v222 offset:52224
	ds_read_b128 v[178:181], v222 offset:53248
	ds_read_b128 v[182:185], v222 offset:54272
	ds_read_b128 v[224:227], v222 offset:55296
	ds_read_b128 v[228:231], v222 offset:56320
	global_load_lds_dwordx4 v[216:217], off
	s_add_i32 m0, s44, 0x2000
	s_add_u32 s44, s48, 0xb0080
	v_lshl_add_u64 v[216:217], v[240:241], 0, s[16:17]
	s_addc_u32 s45, s49, 0
	s_add_i32 s48, s64, s52
	global_load_lds_dwordx4 v[216:217], off
	v_lshl_add_u64 v[216:217], s[44:45], 0, v[208:209]
	s_mov_b32 m0, s48
	s_nop 0
	global_load_lds_dwordx4 v[216:217], off
	v_lshl_add_u64 v[216:217], s[44:45], 0, v[204:205]
	s_add_i32 m0, s48, 0x2000
	s_nop 0
	global_load_lds_dwordx4 v[216:217], off
	v_lshl_add_u64 v[216:217], v[242:243], 0, s[16:17]
	s_mov_b32 m0, s59
	s_nop 0
	global_load_lds_dwordx4 v[216:217], off
	v_lshl_add_u64 v[216:217], v[244:245], 0, s[16:17]
	s_mov_b32 m0, s60
	s_nop 0
	global_load_lds_dwordx4 v[216:217], off
	s_waitcnt vmcnt(8)
	s_waitcnt lgkmcnt(0)
	s_setprio 1
	s_barrier
	v_mfma_f32_16x16x32_bf16 v[62:65], v[106:109], v[162:165], v[62:65]
	v_mfma_f32_16x16x32_bf16 v[58:61], v[126:129], v[162:165], v[58:61]
	v_mfma_f32_16x16x32_bf16 v[46:49], v[106:109], v[170:173], v[46:49]
	v_mfma_f32_16x16x32_bf16 v[42:45], v[126:129], v[170:173], v[42:45]
	v_mfma_f32_16x16x32_bf16 v[30:33], v[106:109], v[178:181], v[30:33]
	v_mfma_f32_16x16x32_bf16 v[26:29], v[126:129], v[178:181], v[26:29]
	v_mfma_f32_16x16x32_bf16 v[14:17], v[106:109], v[224:227], v[14:17]
	v_mfma_f32_16x16x32_bf16 v[10:13], v[126:129], v[224:227], v[10:13]
	v_mfma_f32_16x16x32_bf16 v[62:65], v[110:113], v[166:169], v[62:65]
	v_mfma_f32_16x16x32_bf16 v[58:61], v[134:137], v[166:169], v[58:61]
	v_mfma_f32_16x16x32_bf16 v[46:49], v[110:113], v[174:177], v[46:49]
	v_mfma_f32_16x16x32_bf16 v[42:45], v[134:137], v[174:177], v[42:45]
	v_mfma_f32_16x16x32_bf16 v[30:33], v[110:113], v[182:185], v[30:33]
	v_mfma_f32_16x16x32_bf16 v[26:29], v[134:137], v[182:185], v[26:29]
	v_mfma_f32_16x16x32_bf16 v[14:17], v[110:113], v[228:231], v[14:17]
	v_mfma_f32_16x16x32_bf16 v[10:13], v[134:137], v[228:231], v[10:13]
	v_mfma_f32_16x16x32_bf16 v[54:57], v[146:149], v[162:165], v[54:57]
	v_mfma_f32_16x16x32_bf16 v[50:53], v[154:157], v[162:165], v[50:53]
	v_mfma_f32_16x16x32_bf16 v[38:41], v[146:149], v[170:173], v[38:41]
	v_mfma_f32_16x16x32_bf16 v[34:37], v[154:157], v[170:173], v[34:37]
	v_mfma_f32_16x16x32_bf16 v[22:25], v[146:149], v[178:181], v[22:25]
	v_mfma_f32_16x16x32_bf16 v[18:21], v[154:157], v[178:181], v[18:21]
	v_mfma_f32_16x16x32_bf16 v[6:9], v[146:149], v[224:227], v[6:9]
	v_mfma_f32_16x16x32_bf16 v[2:5], v[154:157], v[224:227], v[2:5]
	v_mfma_f32_16x16x32_bf16 v[54:57], v[150:153], v[166:169], v[54:57]
	v_mfma_f32_16x16x32_bf16 v[50:53], v[158:161], v[166:169], v[50:53]
	v_mfma_f32_16x16x32_bf16 v[38:41], v[150:153], v[174:177], v[38:41]
	v_mfma_f32_16x16x32_bf16 v[34:37], v[158:161], v[174:177], v[34:37]
	v_mfma_f32_16x16x32_bf16 v[22:25], v[150:153], v[182:185], v[22:25]
	v_mfma_f32_16x16x32_bf16 v[18:21], v[158:161], v[182:185], v[18:21]
	v_mfma_f32_16x16x32_bf16 v[6:9], v[150:153], v[228:231], v[6:9]
	v_mfma_f32_16x16x32_bf16 v[2:5], v[158:161], v[228:231], v[2:5]
	s_barrier
	s_setprio 0
	s_add_i32 s62, s62, 2
	s_add_u32 s7, s7, 0x100
	s_addc_u32 s47, s47, 0
	s_cmp_gt_u32 s62, 41
	s_mov_b64 s[44:45], s[0:1]
.LBB0_1088:
	s_add_u32 s0, s44, 0x100
	s_addc_u32 s1, s45, 0
	s_add_i32 s63, 0, 0x10000
	s_cmp_eq_u32 s62, 40
	s_cselect_b32 s51, s41, s1
	s_cselect_b32 s50, s40, s0
	v_add_u32_e32 v0, s63, v221
	s_cselect_b32 s49, s43, s47
	s_cselect_b32 s48, s42, s7
	s_add_i32 s64, 0, 0x14000
	ds_read_b128 v[106:109], v0
	ds_read_b128 v[110:113], v0 offset:1024
	ds_read_b128 v[126:129], v0 offset:2048
	ds_read_b128 v[134:137], v0 offset:3072
	v_add_u32_e32 v0, s64, v221
	ds_read_b128 v[146:149], v0
	ds_read_b128 v[150:153], v0 offset:1024
	ds_read_b128 v[154:157], v0 offset:2048
	ds_read_b128 v[158:161], v0 offset:3072
	v_lshl_add_u64 v[216:217], s[44:45], 0, v[212:213]
	s_add_i32 m0, s53, 0xc000
	ds_read_b128 v[162:165], v222
	ds_read_b128 v[166:169], v222 offset:1024
	ds_read_b128 v[170:173], v222 offset:2048
	ds_read_b128 v[174:177], v222 offset:3072
	ds_read_b128 v[178:181], v222 offset:4096
	ds_read_b128 v[182:185], v222 offset:5120
	ds_read_b128 v[224:227], v222 offset:6144
	ds_read_b128 v[228:231], v222 offset:7168
	global_load_lds_dwordx4 v[216:217], off
	v_lshl_add_u64 v[216:217], s[44:45], 0, v[214:215]
	s_add_i32 m0, s53, 0xe000
	s_nop 0
	global_load_lds_dwordx4 v[216:217], off
	s_waitcnt vmcnt(8)
	s_waitcnt lgkmcnt(0)
	s_setprio 1
	s_barrier
	v_mfma_f32_16x16x32_bf16 v[142:145], v[106:109], v[162:165], v[142:145]
	v_mfma_f32_16x16x32_bf16 v[138:141], v[126:129], v[162:165], v[138:141]
	v_mfma_f32_16x16x32_bf16 v[118:121], v[106:109], v[170:173], v[118:121]
	v_mfma_f32_16x16x32_bf16 v[114:117], v[126:129], v[170:173], v[114:117]
	v_mfma_f32_16x16x32_bf16 v[94:97], v[106:109], v[178:181], v[94:97]
	v_mfma_f32_16x16x32_bf16 v[90:93], v[126:129], v[178:181], v[90:93]
	v_mfma_f32_16x16x32_bf16 v[78:81], v[106:109], v[224:227], v[78:81]
	v_mfma_f32_16x16x32_bf16 v[74:77], v[126:129], v[224:227], v[74:77]
	v_mfma_f32_16x16x32_bf16 v[142:145], v[110:113], v[166:169], v[142:145]
	v_mfma_f32_16x16x32_bf16 v[138:141], v[134:137], v[166:169], v[138:141]
	v_mfma_f32_16x16x32_bf16 v[118:121], v[110:113], v[174:177], v[118:121]
	v_mfma_f32_16x16x32_bf16 v[114:117], v[134:137], v[174:177], v[114:117]
	v_mfma_f32_16x16x32_bf16 v[94:97], v[110:113], v[182:185], v[94:97]
	v_mfma_f32_16x16x32_bf16 v[90:93], v[134:137], v[182:185], v[90:93]
	v_mfma_f32_16x16x32_bf16 v[78:81], v[110:113], v[228:231], v[78:81]
	v_mfma_f32_16x16x32_bf16 v[74:77], v[134:137], v[228:231], v[74:77]
	v_mfma_f32_16x16x32_bf16 v[130:133], v[146:149], v[162:165], v[130:133]
	v_mfma_f32_16x16x32_bf16 v[122:125], v[154:157], v[162:165], v[122:125]
	v_mfma_f32_16x16x32_bf16 v[102:105], v[146:149], v[170:173], v[102:105]
	v_mfma_f32_16x16x32_bf16 v[98:101], v[154:157], v[170:173], v[98:101]
	v_mfma_f32_16x16x32_bf16 v[86:89], v[146:149], v[178:181], v[86:89]
	v_mfma_f32_16x16x32_bf16 v[82:85], v[154:157], v[178:181], v[82:85]
	v_mfma_f32_16x16x32_bf16 v[70:73], v[146:149], v[224:227], v[70:73]
	v_mfma_f32_16x16x32_bf16 v[66:69], v[154:157], v[224:227], v[66:69]
	v_mfma_f32_16x16x32_bf16 v[130:133], v[150:153], v[166:169], v[130:133]
	v_mfma_f32_16x16x32_bf16 v[122:125], v[158:161], v[166:169], v[122:125]
	v_mfma_f32_16x16x32_bf16 v[102:105], v[150:153], v[174:177], v[102:105]
	v_mfma_f32_16x16x32_bf16 v[98:101], v[158:161], v[174:177], v[98:101]
	v_mfma_f32_16x16x32_bf16 v[86:89], v[150:153], v[182:185], v[86:89]
	v_mfma_f32_16x16x32_bf16 v[82:85], v[158:161], v[182:185], v[82:85]
	v_mfma_f32_16x16x32_bf16 v[70:73], v[150:153], v[228:231], v[70:73]
	v_mfma_f32_16x16x32_bf16 v[66:69], v[158:161], v[228:231], v[66:69]
	s_barrier
	s_setprio 0
	s_add_i32 s44, s63, s52
	v_lshl_add_u64 v[216:217], s[48:49], 0, v[208:209]
	s_mov_b32 m0, s44
	ds_read_b128 v[162:165], v222 offset:16384
	ds_read_b128 v[166:169], v222 offset:17408
	ds_read_b128 v[170:173], v222 offset:18432
	ds_read_b128 v[174:177], v222 offset:19456
	ds_read_b128 v[178:181], v222 offset:20480
	ds_read_b128 v[182:185], v222 offset:21504
	ds_read_b128 v[224:227], v222 offset:22528
	ds_read_b128 v[228:231], v222 offset:23552
	global_load_lds_dwordx4 v[216:217], off
	s_add_i32 m0, s44, 0x2000
	s_add_u32 s44, s48, 0xb0000
	v_lshl_add_u64 v[240:241], s[48:49], 0, v[204:205]
	s_addc_u32 s45, s49, 0
	s_add_i32 s63, s64, s52
	global_load_lds_dwordx4 v[240:241], off
	v_lshl_add_u64 v[242:243], s[44:45], 0, v[208:209]
	s_mov_b32 m0, s63
	v_lshl_add_u64 v[244:245], s[50:51], 0, v[206:207]
	global_load_lds_dwordx4 v[242:243], off
	v_lshl_add_u64 v[242:243], s[44:45], 0, v[204:205]
	s_add_i32 m0, s63, 0x2000
	s_nop 0
	global_load_lds_dwordx4 v[242:243], off
	v_lshl_add_u64 v[242:243], s[50:51], 0, v[210:211]
	s_mov_b32 m0, s53
	s_nop 0
	global_load_lds_dwordx4 v[242:243], off
	s_mov_b32 m0, s54
	s_nop 0
	global_load_lds_dwordx4 v[244:245], off
	s_waitcnt vmcnt(8)
	s_waitcnt lgkmcnt(0)
	s_setprio 1
	s_barrier
	v_mfma_f32_16x16x32_bf16 v[62:65], v[106:109], v[162:165], v[62:65]
	v_mfma_f32_16x16x32_bf16 v[58:61], v[126:129], v[162:165], v[58:61]
	v_mfma_f32_16x16x32_bf16 v[46:49], v[106:109], v[170:173], v[46:49]
	v_mfma_f32_16x16x32_bf16 v[42:45], v[126:129], v[170:173], v[42:45]
	v_mfma_f32_16x16x32_bf16 v[30:33], v[106:109], v[178:181], v[30:33]
	v_mfma_f32_16x16x32_bf16 v[26:29], v[126:129], v[178:181], v[26:29]
	v_mfma_f32_16x16x32_bf16 v[14:17], v[106:109], v[224:227], v[14:17]
	v_mfma_f32_16x16x32_bf16 v[10:13], v[126:129], v[224:227], v[10:13]
	v_mfma_f32_16x16x32_bf16 v[62:65], v[110:113], v[166:169], v[62:65]
	v_mfma_f32_16x16x32_bf16 v[58:61], v[134:137], v[166:169], v[58:61]
	v_mfma_f32_16x16x32_bf16 v[46:49], v[110:113], v[174:177], v[46:49]
	v_mfma_f32_16x16x32_bf16 v[42:45], v[134:137], v[174:177], v[42:45]
	v_mfma_f32_16x16x32_bf16 v[30:33], v[110:113], v[182:185], v[30:33]
	v_mfma_f32_16x16x32_bf16 v[26:29], v[134:137], v[182:185], v[26:29]
	v_mfma_f32_16x16x32_bf16 v[14:17], v[110:113], v[228:231], v[14:17]
	v_mfma_f32_16x16x32_bf16 v[10:13], v[134:137], v[228:231], v[10:13]
	v_mfma_f32_16x16x32_bf16 v[54:57], v[146:149], v[162:165], v[54:57]
	v_mfma_f32_16x16x32_bf16 v[50:53], v[154:157], v[162:165], v[50:53]
	v_mfma_f32_16x16x32_bf16 v[38:41], v[146:149], v[170:173], v[38:41]
	v_mfma_f32_16x16x32_bf16 v[34:37], v[154:157], v[170:173], v[34:37]
	v_mfma_f32_16x16x32_bf16 v[22:25], v[146:149], v[178:181], v[22:25]
	v_mfma_f32_16x16x32_bf16 v[18:21], v[154:157], v[178:181], v[18:21]
	v_mfma_f32_16x16x32_bf16 v[6:9], v[146:149], v[224:227], v[6:9]
	v_mfma_f32_16x16x32_bf16 v[2:5], v[154:157], v[224:227], v[2:5]
	v_mfma_f32_16x16x32_bf16 v[54:57], v[150:153], v[166:169], v[54:57]
	v_mfma_f32_16x16x32_bf16 v[50:53], v[158:161], v[166:169], v[50:53]
	v_mfma_f32_16x16x32_bf16 v[38:41], v[150:153], v[174:177], v[38:41]
	v_mfma_f32_16x16x32_bf16 v[34:37], v[158:161], v[174:177], v[34:37]
	v_mfma_f32_16x16x32_bf16 v[22:25], v[150:153], v[182:185], v[22:25]
	v_mfma_f32_16x16x32_bf16 v[18:21], v[158:161], v[182:185], v[18:21]
	v_mfma_f32_16x16x32_bf16 v[6:9], v[150:153], v[228:231], v[6:9]
	v_mfma_f32_16x16x32_bf16 v[2:5], v[158:161], v[228:231], v[2:5]
	s_barrier
	s_setprio 0
	s_add_i32 s63, 0, 0x18000
	v_add_u32_e32 v0, s63, v221
	s_add_i32 s64, 0, 0x1c000
	ds_read_b128 v[106:109], v0
	ds_read_b128 v[110:113], v0 offset:1024
	ds_read_b128 v[126:129], v0 offset:2048
	ds_read_b128 v[134:137], v0 offset:3072
	v_add_u32_e32 v0, s64, v221
	ds_read_b128 v[146:149], v0
	ds_read_b128 v[150:153], v0 offset:1024
	ds_read_b128 v[154:157], v0 offset:2048
	ds_read_b128 v[158:161], v0 offset:3072
	s_add_u32 s44, s50, 0xb0000
	s_addc_u32 s45, s51, 0
	s_mov_b32 m0, s55
	v_lshl_add_u64 v[246:247], s[44:45], 0, v[210:211]
	ds_read_b128 v[162:165], v222 offset:32768
	ds_read_b128 v[166:169], v222 offset:33792
	ds_read_b128 v[170:173], v222 offset:34816
	ds_read_b128 v[174:177], v222 offset:35840
	ds_read_b128 v[178:181], v222 offset:36864
	ds_read_b128 v[182:185], v222 offset:37888
	ds_read_b128 v[224:227], v222 offset:38912
	ds_read_b128 v[228:231], v222 offset:39936
	global_load_lds_dwordx4 v[246:247], off
	v_lshl_add_u64 v[246:247], s[44:45], 0, v[206:207]
	s_mov_b32 m0, s56
	s_nop 0
	global_load_lds_dwordx4 v[246:247], off
	s_waitcnt vmcnt(8)
	s_waitcnt lgkmcnt(0)
	s_setprio 1
	s_barrier
	v_mfma_f32_16x16x32_bf16 v[142:145], v[106:109], v[162:165], v[142:145]
	v_mfma_f32_16x16x32_bf16 v[138:141], v[126:129], v[162:165], v[138:141]
	v_mfma_f32_16x16x32_bf16 v[118:121], v[106:109], v[170:173], v[118:121]
	v_mfma_f32_16x16x32_bf16 v[114:117], v[126:129], v[170:173], v[114:117]
	v_mfma_f32_16x16x32_bf16 v[94:97], v[106:109], v[178:181], v[94:97]
	v_mfma_f32_16x16x32_bf16 v[90:93], v[126:129], v[178:181], v[90:93]
	v_mfma_f32_16x16x32_bf16 v[78:81], v[106:109], v[224:227], v[78:81]
	v_mfma_f32_16x16x32_bf16 v[74:77], v[126:129], v[224:227], v[74:77]
	v_mfma_f32_16x16x32_bf16 v[142:145], v[110:113], v[166:169], v[142:145]
	v_mfma_f32_16x16x32_bf16 v[138:141], v[134:137], v[166:169], v[138:141]
	v_mfma_f32_16x16x32_bf16 v[118:121], v[110:113], v[174:177], v[118:121]
	v_mfma_f32_16x16x32_bf16 v[114:117], v[134:137], v[174:177], v[114:117]
	v_mfma_f32_16x16x32_bf16 v[94:97], v[110:113], v[182:185], v[94:97]
	v_mfma_f32_16x16x32_bf16 v[90:93], v[134:137], v[182:185], v[90:93]
	v_mfma_f32_16x16x32_bf16 v[78:81], v[110:113], v[228:231], v[78:81]
	v_mfma_f32_16x16x32_bf16 v[74:77], v[134:137], v[228:231], v[74:77]
	v_mfma_f32_16x16x32_bf16 v[130:133], v[146:149], v[162:165], v[130:133]
	v_mfma_f32_16x16x32_bf16 v[122:125], v[154:157], v[162:165], v[122:125]
	v_mfma_f32_16x16x32_bf16 v[102:105], v[146:149], v[170:173], v[102:105]
	v_mfma_f32_16x16x32_bf16 v[98:101], v[154:157], v[170:173], v[98:101]
	v_mfma_f32_16x16x32_bf16 v[86:89], v[146:149], v[178:181], v[86:89]
	v_mfma_f32_16x16x32_bf16 v[82:85], v[154:157], v[178:181], v[82:85]
	v_mfma_f32_16x16x32_bf16 v[70:73], v[146:149], v[224:227], v[70:73]
	v_mfma_f32_16x16x32_bf16 v[66:69], v[154:157], v[224:227], v[66:69]
	v_mfma_f32_16x16x32_bf16 v[130:133], v[150:153], v[166:169], v[130:133]
	v_mfma_f32_16x16x32_bf16 v[122:125], v[158:161], v[166:169], v[122:125]
	v_mfma_f32_16x16x32_bf16 v[102:105], v[150:153], v[174:177], v[102:105]
	v_mfma_f32_16x16x32_bf16 v[98:101], v[158:161], v[174:177], v[98:101]
	v_mfma_f32_16x16x32_bf16 v[86:89], v[150:153], v[182:185], v[86:89]
	v_mfma_f32_16x16x32_bf16 v[82:85], v[158:161], v[182:185], v[82:85]
	v_mfma_f32_16x16x32_bf16 v[70:73], v[150:153], v[228:231], v[70:73]
	v_mfma_f32_16x16x32_bf16 v[66:69], v[158:161], v[228:231], v[66:69]
	s_barrier
	s_setprio 0
	s_add_i32 s44, s63, s52
	v_lshl_add_u64 v[216:217], v[216:217], 0, s[16:17]
	s_mov_b32 m0, s44
	ds_read_b128 v[162:165], v222 offset:49152
	ds_read_b128 v[166:169], v222 offset:50176
	ds_read_b128 v[170:173], v222 offset:51200
	ds_read_b128 v[174:177], v222 offset:52224
	ds_read_b128 v[178:181], v222 offset:53248
	ds_read_b128 v[182:185], v222 offset:54272
	ds_read_b128 v[224:227], v222 offset:55296
	ds_read_b128 v[228:231], v222 offset:56320
	global_load_lds_dwordx4 v[216:217], off
	s_add_i32 m0, s44, 0x2000
	s_add_u32 s44, s48, 0xb0080
	v_lshl_add_u64 v[216:217], v[240:241], 0, s[16:17]
	s_addc_u32 s45, s49, 0
	s_add_i32 s48, s64, s52
	global_load_lds_dwordx4 v[216:217], off
	v_lshl_add_u64 v[216:217], s[44:45], 0, v[208:209]
	s_mov_b32 m0, s48
	s_nop 0
	global_load_lds_dwordx4 v[216:217], off
	v_lshl_add_u64 v[216:217], s[44:45], 0, v[204:205]
	s_add_i32 m0, s48, 0x2000
	s_nop 0
	global_load_lds_dwordx4 v[216:217], off
	v_lshl_add_u64 v[216:217], v[242:243], 0, s[16:17]
	s_mov_b32 m0, s59
	s_nop 0
	global_load_lds_dwordx4 v[216:217], off
	v_lshl_add_u64 v[216:217], v[244:245], 0, s[16:17]
	s_mov_b32 m0, s60
	s_nop 0
	global_load_lds_dwordx4 v[216:217], off
	s_waitcnt vmcnt(8)
	s_waitcnt lgkmcnt(0)
	s_setprio 1
	s_barrier
	v_mfma_f32_16x16x32_bf16 v[62:65], v[106:109], v[162:165], v[62:65]
	v_mfma_f32_16x16x32_bf16 v[58:61], v[126:129], v[162:165], v[58:61]
	v_mfma_f32_16x16x32_bf16 v[46:49], v[106:109], v[170:173], v[46:49]
	v_mfma_f32_16x16x32_bf16 v[42:45], v[126:129], v[170:173], v[42:45]
	v_mfma_f32_16x16x32_bf16 v[30:33], v[106:109], v[178:181], v[30:33]
	v_mfma_f32_16x16x32_bf16 v[26:29], v[126:129], v[178:181], v[26:29]
	v_mfma_f32_16x16x32_bf16 v[14:17], v[106:109], v[224:227], v[14:17]
	v_mfma_f32_16x16x32_bf16 v[10:13], v[126:129], v[224:227], v[10:13]
	v_mfma_f32_16x16x32_bf16 v[62:65], v[110:113], v[166:169], v[62:65]
	v_mfma_f32_16x16x32_bf16 v[58:61], v[134:137], v[166:169], v[58:61]
	v_mfma_f32_16x16x32_bf16 v[46:49], v[110:113], v[174:177], v[46:49]
	v_mfma_f32_16x16x32_bf16 v[42:45], v[134:137], v[174:177], v[42:45]
	v_mfma_f32_16x16x32_bf16 v[30:33], v[110:113], v[182:185], v[30:33]
	v_mfma_f32_16x16x32_bf16 v[26:29], v[134:137], v[182:185], v[26:29]
	v_mfma_f32_16x16x32_bf16 v[14:17], v[110:113], v[228:231], v[14:17]
	v_mfma_f32_16x16x32_bf16 v[10:13], v[134:137], v[228:231], v[10:13]
	v_mfma_f32_16x16x32_bf16 v[54:57], v[146:149], v[162:165], v[54:57]
	v_mfma_f32_16x16x32_bf16 v[50:53], v[154:157], v[162:165], v[50:53]
	v_mfma_f32_16x16x32_bf16 v[38:41], v[146:149], v[170:173], v[38:41]
	v_mfma_f32_16x16x32_bf16 v[34:37], v[154:157], v[170:173], v[34:37]
	v_mfma_f32_16x16x32_bf16 v[22:25], v[146:149], v[178:181], v[22:25]
	v_mfma_f32_16x16x32_bf16 v[18:21], v[154:157], v[178:181], v[18:21]
	v_mfma_f32_16x16x32_bf16 v[6:9], v[146:149], v[224:227], v[6:9]
	v_mfma_f32_16x16x32_bf16 v[2:5], v[154:157], v[224:227], v[2:5]
	v_mfma_f32_16x16x32_bf16 v[54:57], v[150:153], v[166:169], v[54:57]
	v_mfma_f32_16x16x32_bf16 v[50:53], v[158:161], v[166:169], v[50:53]
	v_mfma_f32_16x16x32_bf16 v[38:41], v[150:153], v[174:177], v[38:41]
	v_mfma_f32_16x16x32_bf16 v[34:37], v[158:161], v[174:177], v[34:37]
	v_mfma_f32_16x16x32_bf16 v[22:25], v[150:153], v[182:185], v[22:25]
	v_mfma_f32_16x16x32_bf16 v[18:21], v[158:161], v[182:185], v[18:21]
	v_mfma_f32_16x16x32_bf16 v[6:9], v[150:153], v[228:231], v[6:9]
	v_mfma_f32_16x16x32_bf16 v[2:5], v[158:161], v[228:231], v[2:5]
	s_barrier
	s_setprio 0
	s_add_i32 s62, s62, 2
	s_add_u32 s7, s7, 0x100
	s_addc_u32 s47, s47, 0
	s_cmp_gt_u32 s62, 41
	s_mov_b64 s[44:45], s[0:1]
	s_cbranch_scc0 .LBB0_1088
	s_and_b64 vcc, exec, s[22:23]
	s_cbranch_vccz .LBB0_1091
	s_barrier

.LBB0_1107:
	s_or_b64 exec, exec, s[0:1]
	s_and_b64 vcc, exec, s[38:39]
	s_mov_b64 s[0:1], -1
	s_cbranch_vccnz .LBB0_1076
	s_mov_b32 s63, 0
	s_andn2_b64 vcc, exec, s[20:21]
	s_cbranch_vccnz .LBB0_1075
	s_mov_b32 s63, 1
	s_branch .LBB0_1075

.LBB0_1180:
	v_readlane_b32 s42, v251, 49
	v_mov_b32_e32 v135, v1
	v_readlane_b32 s43, v251, 50
	v_mov_b32_e32 v131, v1
	v_readlane_b32 s40, v251, 45
	v_lshl_add_u64 v[8:9], s[42:43], 0, v[134:135]
	s_waitcnt vmcnt(0)
	v_bfe_u32 v159, v7, 4, 2
	v_lshl_add_u64 v[10:11], s[42:43], 0, v[130:131]
	v_mov_b32_e32 v137, v1
	v_readlane_b32 s41, v251, 46
	v_and_b32_e32 v158, 15, v7
	v_lshlrev_b32_e32 v16, 4, v159
	v_lshlrev_b32_e32 v7, 2, v7
	s_add_i32 m0, s57, 0x18000
	v_lshl_add_u64 v[8:9], v[8:9], 0, s[16:17]
	v_lshl_add_u64 v[12:13], s[40:41], 0, v[136:137]
	v_mov_b32_e32 v133, v1
	s_lshl_b32 s61, s6, 6
	v_lshl_or_b32 v16, v158, 6, v16
	s_lshl_b32 s6, s6, 13
	v_and_b32_e32 v7, 32, v7
	s_waitcnt vmcnt(2)
	s_barrier
	global_load_lds_dwordx4 v[8:9], off
	v_lshl_add_u64 v[8:9], v[10:11], 0, s[16:17]
	s_add_i32 m0, s57, 0x1a000
	s_add_i32 s63, s57, 0x8000
	v_lshl_add_u64 v[14:15], s[40:41], 0, v[132:133]
	v_bitop3_b32 v17, v16, s6, v7 bitop3:0xde
	global_load_lds_dwordx4 v[8:9], off
	v_lshl_add_u64 v[8:9], v[12:13], 0, s[16:17]
	s_mov_b32 m0, s63
	s_add_i32 s64, s57, 0xa000
	v_readlane_b32 s6, v251, 51
	global_load_lds_dwordx4 v[8:9], off
	v_lshl_add_u64 v[8:9], v[14:15], 0, s[16:17]
	s_mov_b32 m0, s64
	v_readlane_b32 s7, v251, 52
	global_load_lds_dwordx4 v[8:9], off
	s_add_i32 m0, s57, 0x1c000
	v_lshl_add_u64 v[8:9], s[6:7], 0, v[134:135]
	global_load_lds_dwordx4 v[8:9], off
	v_lshl_add_u64 v[8:9], s[6:7], 0, v[130:131]
	s_add_i32 m0, s57, 0x1e000
	s_lshl_b32 s5, s5, 5
	global_load_lds_dwordx4 v[8:9], off
	s_and_b32 s62, s5, 0x60
	s_lshl_b32 s5, s62, 7
	v_bitop3_b32 v160, v16, s5, v7 bitop3:0xde
	v_lshlrev_b32_e32 v7, 14, v5
	v_and_b32_e32 v7, 0xffff8000, v7
	v_lshl_add_u32 v4, v4, 11, v7
	v_and_b32_e32 v5, 1, v5
	v_lshl_or_b32 v4, v5, 6, v4
	v_lshl_add_u32 v138, v6, 1, v4
	v_lshlrev_b32_e32 v4, 14, v0
	v_and_b32_e32 v4, 0xffff8000, v4
	s_waitcnt vmcnt(6)
	v_lshl_add_u32 v2, v2, 11, v4
	v_and_b32_e32 v0, 1, v0
	s_cmpk_lt_u32 s4, 0x100
	v_lshl_or_b32 v0, v0, 6, v2
	v_readlane_b32 s20, v251, 41
	s_cselect_b64 s[18:19], -1, 0
	v_mov_b32_e32 v139, v1
	v_lshl_add_u32 v140, v3, 1, v0
	v_mov_b32_e32 v141, v1
	s_mov_b32 s4, 0
	v_add_u32_e32 v161, 0, v17
	v_readlane_b32 s6, v251, 22
	s_mov_b32 s5, s20
	s_barrier
	v_readlane_b32 s21, v251, 42
	s_mov_b32 s54, 0
	s_branch .LBB0_1183

.LBB0_1185:
	s_ashr_i32 s23, s22, 31
	s_lshl_b64 s[44:45], s[22:23], 19
	s_add_u32 s44, s96, s44
	s_addc_u32 s45, s97, s45
	s_and_b64 s[46:47], s[38:39], exec
	s_cselect_b32 s7, s45, s41
	s_cselect_b32 s23, s44, s40
	s_ashr_i32 s21, s20, 31
	s_lshl_b64 s[46:47], s[20:21], 19
	s_add_u32 s46, s86, s46
	s_addc_u32 s47, s87, s47
	s_and_b64 s[48:49], s[38:39], exec
	s_cselect_b32 s21, s47, s43
	s_cselect_b32 s50, s46, s42
	s_add_u32 s40, s40, 0x40080
	s_addc_u32 s41, s41, 0
	s_add_u32 s51, s42, 0x100
	s_addc_u32 s52, s43, 0
	s_mov_b32 s53, -2
	s_cmp_eq_u32 s54, 0
	s_cbranch_scc1 .Lrb7_skip
	s_barrier
.Lrb7_skip:
	s_add_u32 s42, s40, 0xfffc0080
	s_addc_u32 s43, s41, -1
	s_add_i32 s54, 0, 0x10000
	s_cmp_eq_u32 s53, 12
	s_cselect_b32 s49, s7, s43
	s_cselect_b32 s48, s23, s42
	v_add_u32_e32 v0, s54, v160
	s_cselect_b32 s43, s21, s52
	s_cselect_b32 s42, s50, s51
	s_add_i32 s65, 0, 0x14000
	ds_read_b128 v[142:145], v0
	ds_read_b128 v[146:149], v0 offset:1024
	ds_read_b128 v[150:153], v0 offset:2048
	ds_read_b128 v[154:157], v0 offset:3072
	v_add_u32_e32 v0, s65, v160
	ds_read_b128 v[162:165], v0
	ds_read_b128 v[166:169], v0 offset:1024
	ds_read_b128 v[170:173], v0 offset:2048
	ds_read_b128 v[174:177], v0 offset:3072
	v_lshl_add_u64 v[228:229], s[40:41], 0, v[138:139]
	s_add_i32 m0, s57, 0xc000
	ds_read_b128 v[178:181], v161
	ds_read_b128 v[182:185], v161 offset:1024
	ds_read_b128 v[204:207], v161 offset:2048
	ds_read_b128 v[208:211], v161 offset:3072
	ds_read_b128 v[212:215], v161 offset:4096
	ds_read_b128 v[216:219], v161 offset:5120
	ds_read_b128 v[220:223], v161 offset:6144
	ds_read_b128 v[224:227], v161 offset:7168
	global_load_lds_dwordx4 v[228:229], off
	v_lshl_add_u64 v[228:229], s[40:41], 0, v[140:141]
	s_add_i32 m0, s57, 0xe000
	s_nop 0
	global_load_lds_dwordx4 v[228:229], off
	s_waitcnt vmcnt(8)
	s_waitcnt lgkmcnt(0)
	s_setprio 1
	s_barrier
	v_mfma_f32_16x16x32_bf16 v[126:129], v[142:145], v[178:181], 0
	v_mfma_f32_16x16x32_bf16 v[122:125], v[150:153], v[178:181], 0
	v_mfma_f32_16x16x32_bf16 v[110:113], v[142:145], v[204:207], 0
	v_mfma_f32_16x16x32_bf16 v[106:109], v[150:153], v[204:207], 0
	v_mfma_f32_16x16x32_bf16 v[94:97], v[142:145], v[212:215], 0
	v_mfma_f32_16x16x32_bf16 v[90:93], v[150:153], v[212:215], 0
	v_mfma_f32_16x16x32_bf16 v[78:81], v[142:145], v[220:223], 0
	v_mfma_f32_16x16x32_bf16 v[74:77], v[150:153], v[220:223], 0
	v_mfma_f32_16x16x32_bf16 v[126:129], v[146:149], v[182:185], v[126:129]
	v_mfma_f32_16x16x32_bf16 v[122:125], v[154:157], v[182:185], v[122:125]
	v_mfma_f32_16x16x32_bf16 v[110:113], v[146:149], v[208:211], v[110:113]
	v_mfma_f32_16x16x32_bf16 v[106:109], v[154:157], v[208:211], v[106:109]
	v_mfma_f32_16x16x32_bf16 v[94:97], v[146:149], v[216:219], v[94:97]
	v_mfma_f32_16x16x32_bf16 v[90:93], v[154:157], v[216:219], v[90:93]
	v_mfma_f32_16x16x32_bf16 v[78:81], v[146:149], v[224:227], v[78:81]
	v_mfma_f32_16x16x32_bf16 v[74:77], v[154:157], v[224:227], v[74:77]
	v_mfma_f32_16x16x32_bf16 v[118:121], v[162:165], v[178:181], 0
	v_mfma_f32_16x16x32_bf16 v[114:117], v[170:173], v[178:181], 0
	v_mfma_f32_16x16x32_bf16 v[102:105], v[162:165], v[204:207], 0
	v_mfma_f32_16x16x32_bf16 v[98:101], v[170:173], v[204:207], 0
	v_mfma_f32_16x16x32_bf16 v[86:89], v[162:165], v[212:215], 0
	v_mfma_f32_16x16x32_bf16 v[82:85], v[170:173], v[212:215], 0
	v_mfma_f32_16x16x32_bf16 v[70:73], v[162:165], v[220:223], 0
	v_mfma_f32_16x16x32_bf16 v[66:69], v[170:173], v[220:223], 0
	v_mfma_f32_16x16x32_bf16 v[118:121], v[166:169], v[182:185], v[118:121]
	v_mfma_f32_16x16x32_bf16 v[114:117], v[174:177], v[182:185], v[114:117]
	v_mfma_f32_16x16x32_bf16 v[102:105], v[166:169], v[208:211], v[102:105]
	v_mfma_f32_16x16x32_bf16 v[98:101], v[174:177], v[208:211], v[98:101]
	v_mfma_f32_16x16x32_bf16 v[86:89], v[166:169], v[216:219], v[86:89]
	v_mfma_f32_16x16x32_bf16 v[82:85], v[174:177], v[216:219], v[82:85]
	v_mfma_f32_16x16x32_bf16 v[70:73], v[166:169], v[224:227], v[70:73]
	v_mfma_f32_16x16x32_bf16 v[66:69], v[174:177], v[224:227], v[66:69]
	s_barrier
	s_setprio 0
	s_add_i32 s54, s54, s56
	v_lshl_add_u64 v[228:229], s[42:43], 0, v[134:135]
	s_mov_b32 m0, s54
	ds_read_b128 v[178:181], v161 offset:16384
	ds_read_b128 v[182:185], v161 offset:17408
	ds_read_b128 v[204:207], v161 offset:18432
	ds_read_b128 v[208:211], v161 offset:19456
	ds_read_b128 v[212:215], v161 offset:20480
	ds_read_b128 v[216:219], v161 offset:21504
	ds_read_b128 v[220:223], v161 offset:22528
	ds_read_b128 v[224:227], v161 offset:23552
	global_load_lds_dwordx4 v[228:229], off
	s_add_i32 m0, s54, 0x2000
	s_add_u32 s54, s42, 0x40000
	v_lshl_add_u64 v[230:231], s[42:43], 0, v[130:131]
	s_addc_u32 s55, s43, 0
	s_add_i32 s65, s65, s56
	global_load_lds_dwordx4 v[230:231], off
	v_lshl_add_u64 v[240:241], s[54:55], 0, v[134:135]
	s_mov_b32 m0, s65
	v_lshl_add_u64 v[242:243], s[48:49], 0, v[132:133]
	global_load_lds_dwordx4 v[240:241], off
	v_lshl_add_u64 v[240:241], s[54:55], 0, v[130:131]
	s_add_i32 m0, s65, 0x2000
	s_nop 0
	global_load_lds_dwordx4 v[240:241], off
	v_lshl_add_u64 v[240:241], s[48:49], 0, v[136:137]
	s_mov_b32 m0, s57
	s_nop 0
	global_load_lds_dwordx4 v[240:241], off
	s_mov_b32 m0, s58
	s_nop 0
	global_load_lds_dwordx4 v[242:243], off
	s_waitcnt vmcnt(8)
	s_waitcnt lgkmcnt(0)
	s_setprio 1
	s_barrier
	v_mfma_f32_16x16x32_bf16 v[62:65], v[142:145], v[178:181], 0
	v_mfma_f32_16x16x32_bf16 v[58:61], v[150:153], v[178:181], 0
	v_mfma_f32_16x16x32_bf16 v[46:49], v[142:145], v[204:207], 0
	v_mfma_f32_16x16x32_bf16 v[42:45], v[150:153], v[204:207], 0
	v_mfma_f32_16x16x32_bf16 v[30:33], v[142:145], v[212:215], 0
	v_mfma_f32_16x16x32_bf16 v[26:29], v[150:153], v[212:215], 0
	v_mfma_f32_16x16x32_bf16 v[14:17], v[142:145], v[220:223], 0
	v_mfma_f32_16x16x32_bf16 v[10:13], v[150:153], v[220:223], 0
	v_mfma_f32_16x16x32_bf16 v[62:65], v[146:149], v[182:185], v[62:65]
	v_mfma_f32_16x16x32_bf16 v[58:61], v[154:157], v[182:185], v[58:61]
	v_mfma_f32_16x16x32_bf16 v[46:49], v[146:149], v[208:211], v[46:49]
	v_mfma_f32_16x16x32_bf16 v[42:45], v[154:157], v[208:211], v[42:45]
	v_mfma_f32_16x16x32_bf16 v[30:33], v[146:149], v[216:219], v[30:33]
	v_mfma_f32_16x16x32_bf16 v[26:29], v[154:157], v[216:219], v[26:29]
	v_mfma_f32_16x16x32_bf16 v[14:17], v[146:149], v[224:227], v[14:17]
	v_mfma_f32_16x16x32_bf16 v[10:13], v[154:157], v[224:227], v[10:13]
	v_mfma_f32_16x16x32_bf16 v[54:57], v[162:165], v[178:181], 0
	v_mfma_f32_16x16x32_bf16 v[50:53], v[170:173], v[178:181], 0
	v_mfma_f32_16x16x32_bf16 v[38:41], v[162:165], v[204:207], 0
	v_mfma_f32_16x16x32_bf16 v[34:37], v[170:173], v[204:207], 0
	v_mfma_f32_16x16x32_bf16 v[22:25], v[162:165], v[212:215], 0
	v_mfma_f32_16x16x32_bf16 v[18:21], v[170:173], v[212:215], 0
	v_mfma_f32_16x16x32_bf16 v[6:9], v[162:165], v[220:223], 0
	v_mfma_f32_16x16x32_bf16 v[2:5], v[170:173], v[220:223], 0
	v_mfma_f32_16x16x32_bf16 v[54:57], v[166:169], v[182:185], v[54:57]
	v_mfma_f32_16x16x32_bf16 v[50:53], v[174:177], v[182:185], v[50:53]
	v_mfma_f32_16x16x32_bf16 v[38:41], v[166:169], v[208:211], v[38:41]
	v_mfma_f32_16x16x32_bf16 v[34:37], v[174:177], v[208:211], v[34:37]
	v_mfma_f32_16x16x32_bf16 v[22:25], v[166:169], v[216:219], v[22:25]
	v_mfma_f32_16x16x32_bf16 v[18:21], v[174:177], v[216:219], v[18:21]
	v_mfma_f32_16x16x32_bf16 v[6:9], v[166:169], v[224:227], v[6:9]
	v_mfma_f32_16x16x32_bf16 v[2:5], v[174:177], v[224:227], v[2:5]
	s_barrier
	s_setprio 0
	s_add_i32 s54, 0, 0x18000
	v_add_u32_e32 v0, s54, v160
	s_add_i32 s55, 0, 0x1c000
	ds_read_b128 v[142:145], v0
	ds_read_b128 v[146:149], v0 offset:1024
	ds_read_b128 v[150:153], v0 offset:2048
	ds_read_b128 v[154:157], v0 offset:3072
	v_add_u32_e32 v0, s55, v160
	ds_read_b128 v[162:165], v0
	ds_read_b128 v[166:169], v0 offset:1024
	ds_read_b128 v[170:173], v0 offset:2048
	ds_read_b128 v[174:177], v0 offset:3072
	s_add_u32 s48, s48, 0x40000
	s_addc_u32 s49, s49, 0
	s_mov_b32 m0, s59
	v_lshl_add_u64 v[244:245], s[48:49], 0, v[136:137]
	ds_read_b128 v[178:181], v161 offset:32768
	ds_read_b128 v[182:185], v161 offset:33792
	ds_read_b128 v[204:207], v161 offset:34816
	ds_read_b128 v[208:211], v161 offset:35840
	ds_read_b128 v[212:215], v161 offset:36864
	ds_read_b128 v[216:219], v161 offset:37888
	ds_read_b128 v[220:223], v161 offset:38912
	ds_read_b128 v[224:227], v161 offset:39936
	global_load_lds_dwordx4 v[244:245], off
	v_lshl_add_u64 v[244:245], s[48:49], 0, v[132:133]
	s_mov_b32 m0, s60
	s_nop 0
	global_load_lds_dwordx4 v[244:245], off
	s_waitcnt vmcnt(8)
	s_waitcnt lgkmcnt(0)
	s_setprio 1
	s_barrier
	v_mfma_f32_16x16x32_bf16 v[126:129], v[142:145], v[178:181], v[126:129]
	v_mfma_f32_16x16x32_bf16 v[122:125], v[150:153], v[178:181], v[122:125]
	v_mfma_f32_16x16x32_bf16 v[110:113], v[142:145], v[204:207], v[110:113]
	v_mfma_f32_16x16x32_bf16 v[106:109], v[150:153], v[204:207], v[106:109]
	v_mfma_f32_16x16x32_bf16 v[94:97], v[142:145], v[212:215], v[94:97]
	v_mfma_f32_16x16x32_bf16 v[90:93], v[150:153], v[212:215], v[90:93]
	v_mfma_f32_16x16x32_bf16 v[78:81], v[142:145], v[220:223], v[78:81]
	v_mfma_f32_16x16x32_bf16 v[74:77], v[150:153], v[220:223], v[74:77]
	v_mfma_f32_16x16x32_bf16 v[126:129], v[146:149], v[182:185], v[126:129]
	v_mfma_f32_16x16x32_bf16 v[122:125], v[154:157], v[182:185], v[122:125]
	v_mfma_f32_16x16x32_bf16 v[110:113], v[146:149], v[208:211], v[110:113]
	v_mfma_f32_16x16x32_bf16 v[106:109], v[154:157], v[208:211], v[106:109]
	v_mfma_f32_16x16x32_bf16 v[94:97], v[146:149], v[216:219], v[94:97]
	v_mfma_f32_16x16x32_bf16 v[90:93], v[154:157], v[216:219], v[90:93]
	v_mfma_f32_16x16x32_bf16 v[78:81], v[146:149], v[224:227], v[78:81]
	v_mfma_f32_16x16x32_bf16 v[74:77], v[154:157], v[224:227], v[74:77]
	v_mfma_f32_16x16x32_bf16 v[118:121], v[162:165], v[178:181], v[118:121]
	v_mfma_f32_16x16x32_bf16 v[114:117], v[170:173], v[178:181], v[114:117]
	v_mfma_f32_16x16x32_bf16 v[102:105], v[162:165], v[204:207], v[102:105]
	v_mfma_f32_16x16x32_bf16 v[98:101], v[170:173], v[204:207], v[98:101]
	v_mfma_f32_16x16x32_bf16 v[86:89], v[162:165], v[212:215], v[86:89]
	v_mfma_f32_16x16x32_bf16 v[82:85], v[170:173], v[212:215], v[82:85]
	v_mfma_f32_16x16x32_bf16 v[70:73], v[162:165], v[220:223], v[70:73]
	v_mfma_f32_16x16x32_bf16 v[66:69], v[170:173], v[220:223], v[66:69]
	v_mfma_f32_16x16x32_bf16 v[118:121], v[166:169], v[182:185], v[118:121]
	v_mfma_f32_16x16x32_bf16 v[114:117], v[174:177], v[182:185], v[114:117]
	v_mfma_f32_16x16x32_bf16 v[102:105], v[166:169], v[208:211], v[102:105]
	v_mfma_f32_16x16x32_bf16 v[98:101], v[174:177], v[208:211], v[98:101]
	v_mfma_f32_16x16x32_bf16 v[86:89], v[166:169], v[216:219], v[86:89]
	v_mfma_f32_16x16x32_bf16 v[82:85], v[174:177], v[216:219], v[82:85]
	v_mfma_f32_16x16x32_bf16 v[70:73], v[166:169], v[224:227], v[70:73]
	v_mfma_f32_16x16x32_bf16 v[66:69], v[174:177], v[224:227], v[66:69]
	s_barrier
	s_setprio 0
	s_add_i32 s48, s54, s56
	v_lshl_add_u64 v[228:229], v[228:229], 0, s[16:17]
	s_mov_b32 m0, s48
	ds_read_b128 v[178:181], v161 offset:49152
	ds_read_b128 v[182:185], v161 offset:50176
	ds_read_b128 v[204:207], v161 offset:51200
	ds_read_b128 v[208:211], v161 offset:52224
	ds_read_b128 v[212:215], v161 offset:53248
	ds_read_b128 v[216:219], v161 offset:54272
	ds_read_b128 v[220:223], v161 offset:55296
	ds_read_b128 v[224:227], v161 offset:56320
	global_load_lds_dwordx4 v[228:229], off
	s_add_i32 m0, s48, 0x2000
	s_add_u32 s42, s42, 0x40080
	v_lshl_add_u64 v[228:229], v[230:231], 0, s[16:17]
	s_addc_u32 s43, s43, 0
	s_add_i32 s48, s55, s56
	global_load_lds_dwordx4 v[228:229], off
	v_lshl_add_u64 v[228:229], s[42:43], 0, v[134:135]
	s_mov_b32 m0, s48
	s_nop 0
	global_load_lds_dwordx4 v[228:229], off
	v_lshl_add_u64 v[228:229], s[42:43], 0, v[130:131]
	s_add_i32 m0, s48, 0x2000
	s_nop 0
	global_load_lds_dwordx4 v[228:229], off
	v_lshl_add_u64 v[228:229], v[240:241], 0, s[16:17]
	s_mov_b32 m0, s63
	s_nop 0
	global_load_lds_dwordx4 v[228:229], off
	v_lshl_add_u64 v[228:229], v[242:243], 0, s[16:17]
	s_mov_b32 m0, s64
	s_nop 0
	global_load_lds_dwordx4 v[228:229], off
	s_waitcnt vmcnt(8)
	s_waitcnt lgkmcnt(0)
	s_setprio 1
	s_barrier
	v_mfma_f32_16x16x32_bf16 v[62:65], v[142:145], v[178:181], v[62:65]
	v_mfma_f32_16x16x32_bf16 v[58:61], v[150:153], v[178:181], v[58:61]
	v_mfma_f32_16x16x32_bf16 v[46:49], v[142:145], v[204:207], v[46:49]
	v_mfma_f32_16x16x32_bf16 v[42:45], v[150:153], v[204:207], v[42:45]
	v_mfma_f32_16x16x32_bf16 v[30:33], v[142:145], v[212:215], v[30:33]
	v_mfma_f32_16x16x32_bf16 v[26:29], v[150:153], v[212:215], v[26:29]
	v_mfma_f32_16x16x32_bf16 v[14:17], v[142:145], v[220:223], v[14:17]
	v_mfma_f32_16x16x32_bf16 v[10:13], v[150:153], v[220:223], v[10:13]
	v_mfma_f32_16x16x32_bf16 v[62:65], v[146:149], v[182:185], v[62:65]
	v_mfma_f32_16x16x32_bf16 v[58:61], v[154:157], v[182:185], v[58:61]
	v_mfma_f32_16x16x32_bf16 v[46:49], v[146:149], v[208:211], v[46:49]
	v_mfma_f32_16x16x32_bf16 v[42:45], v[154:157], v[208:211], v[42:45]
	v_mfma_f32_16x16x32_bf16 v[30:33], v[146:149], v[216:219], v[30:33]
	v_mfma_f32_16x16x32_bf16 v[26:29], v[154:157], v[216:219], v[26:29]
	v_mfma_f32_16x16x32_bf16 v[14:17], v[146:149], v[224:227], v[14:17]
	v_mfma_f32_16x16x32_bf16 v[10:13], v[154:157], v[224:227], v[10:13]
	v_mfma_f32_16x16x32_bf16 v[54:57], v[162:165], v[178:181], v[54:57]
	v_mfma_f32_16x16x32_bf16 v[50:53], v[170:173], v[178:181], v[50:53]
	v_mfma_f32_16x16x32_bf16 v[38:41], v[162:165], v[204:207], v[38:41]
	v_mfma_f32_16x16x32_bf16 v[34:37], v[170:173], v[204:207], v[34:37]
	v_mfma_f32_16x16x32_bf16 v[22:25], v[162:165], v[212:215], v[22:25]
	v_mfma_f32_16x16x32_bf16 v[18:21], v[170:173], v[212:215], v[18:21]
	v_mfma_f32_16x16x32_bf16 v[6:9], v[162:165], v[220:223], v[6:9]
	v_mfma_f32_16x16x32_bf16 v[2:5], v[170:173], v[220:223], v[2:5]
	v_mfma_f32_16x16x32_bf16 v[54:57], v[166:169], v[182:185], v[54:57]
	v_mfma_f32_16x16x32_bf16 v[50:53], v[174:177], v[182:185], v[50:53]
	v_mfma_f32_16x16x32_bf16 v[38:41], v[166:169], v[208:211], v[38:41]
	v_mfma_f32_16x16x32_bf16 v[34:37], v[174:177], v[208:211], v[34:37]
	v_mfma_f32_16x16x32_bf16 v[22:25], v[166:169], v[216:219], v[22:25]
	v_mfma_f32_16x16x32_bf16 v[18:21], v[174:177], v[216:219], v[18:21]
	v_mfma_f32_16x16x32_bf16 v[6:9], v[166:169], v[224:227], v[6:9]
	v_mfma_f32_16x16x32_bf16 v[2:5], v[174:177], v[224:227], v[2:5]
	s_barrier
	s_setprio 0
	s_add_i32 s53, s53, 2
	s_add_u32 s40, s40, 0x100
	s_addc_u32 s41, s41, 0
	s_add_u32 s51, s51, 0x100
	s_addc_u32 s52, s52, 0
	s_cmp_gt_u32 s53, 13
.LBB0_1186:
	s_add_u32 s42, s40, 0xfffc0080
	s_addc_u32 s43, s41, -1
	s_add_i32 s54, 0, 0x10000
	s_cmp_eq_u32 s53, 12
	s_cselect_b32 s49, s7, s43
	s_cselect_b32 s48, s23, s42
	v_add_u32_e32 v0, s54, v160
	s_cselect_b32 s43, s21, s52
	s_cselect_b32 s42, s50, s51
	s_add_i32 s65, 0, 0x14000
	ds_read_b128 v[142:145], v0
	ds_read_b128 v[146:149], v0 offset:1024
	ds_read_b128 v[150:153], v0 offset:2048
	ds_read_b128 v[154:157], v0 offset:3072
	v_add_u32_e32 v0, s65, v160
	ds_read_b128 v[162:165], v0
	ds_read_b128 v[166:169], v0 offset:1024
	ds_read_b128 v[170:173], v0 offset:2048
	ds_read_b128 v[174:177], v0 offset:3072
	v_lshl_add_u64 v[228:229], s[40:41], 0, v[138:139]
	s_add_i32 m0, s57, 0xc000
	ds_read_b128 v[178:181], v161
	ds_read_b128 v[182:185], v161 offset:1024
	ds_read_b128 v[204:207], v161 offset:2048
	ds_read_b128 v[208:211], v161 offset:3072
	ds_read_b128 v[212:215], v161 offset:4096
	ds_read_b128 v[216:219], v161 offset:5120
	ds_read_b128 v[220:223], v161 offset:6144
	ds_read_b128 v[224:227], v161 offset:7168
	global_load_lds_dwordx4 v[228:229], off
	v_lshl_add_u64 v[228:229], s[40:41], 0, v[140:141]
	s_add_i32 m0, s57, 0xe000
	s_nop 0
	global_load_lds_dwordx4 v[228:229], off
	s_waitcnt vmcnt(8)
	s_waitcnt lgkmcnt(0)
	s_setprio 1
	s_barrier
	v_mfma_f32_16x16x32_bf16 v[126:129], v[142:145], v[178:181], v[126:129]
	v_mfma_f32_16x16x32_bf16 v[122:125], v[150:153], v[178:181], v[122:125]
	v_mfma_f32_16x16x32_bf16 v[110:113], v[142:145], v[204:207], v[110:113]
	v_mfma_f32_16x16x32_bf16 v[106:109], v[150:153], v[204:207], v[106:109]
	v_mfma_f32_16x16x32_bf16 v[94:97], v[142:145], v[212:215], v[94:97]
	v_mfma_f32_16x16x32_bf16 v[90:93], v[150:153], v[212:215], v[90:93]
	v_mfma_f32_16x16x32_bf16 v[78:81], v[142:145], v[220:223], v[78:81]
	v_mfma_f32_16x16x32_bf16 v[74:77], v[150:153], v[220:223], v[74:77]
	v_mfma_f32_16x16x32_bf16 v[126:129], v[146:149], v[182:185], v[126:129]
	v_mfma_f32_16x16x32_bf16 v[122:125], v[154:157], v[182:185], v[122:125]
	v_mfma_f32_16x16x32_bf16 v[110:113], v[146:149], v[208:211], v[110:113]
	v_mfma_f32_16x16x32_bf16 v[106:109], v[154:157], v[208:211], v[106:109]
	v_mfma_f32_16x16x32_bf16 v[94:97], v[146:149], v[216:219], v[94:97]
	v_mfma_f32_16x16x32_bf16 v[90:93], v[154:157], v[216:219], v[90:93]
	v_mfma_f32_16x16x32_bf16 v[78:81], v[146:149], v[224:227], v[78:81]
	v_mfma_f32_16x16x32_bf16 v[74:77], v[154:157], v[224:227], v[74:77]
	v_mfma_f32_16x16x32_bf16 v[118:121], v[162:165], v[178:181], v[118:121]
	v_mfma_f32_16x16x32_bf16 v[114:117], v[170:173], v[178:181], v[114:117]
	v_mfma_f32_16x16x32_bf16 v[102:105], v[162:165], v[204:207], v[102:105]
	v_mfma_f32_16x16x32_bf16 v[98:101], v[170:173], v[204:207], v[98:101]
	v_mfma_f32_16x16x32_bf16 v[86:89], v[162:165], v[212:215], v[86:89]
	v_mfma_f32_16x16x32_bf16 v[82:85], v[170:173], v[212:215], v[82:85]
	v_mfma_f32_16x16x32_bf16 v[70:73], v[162:165], v[220:223], v[70:73]
	v_mfma_f32_16x16x32_bf16 v[66:69], v[170:173], v[220:223], v[66:69]
	v_mfma_f32_16x16x32_bf16 v[118:121], v[166:169], v[182:185], v[118:121]
	v_mfma_f32_16x16x32_bf16 v[114:117], v[174:177], v[182:185], v[114:117]
	v_mfma_f32_16x16x32_bf16 v[102:105], v[166:169], v[208:211], v[102:105]
	v_mfma_f32_16x16x32_bf16 v[98:101], v[174:177], v[208:211], v[98:101]
	v_mfma_f32_16x16x32_bf16 v[86:89], v[166:169], v[216:219], v[86:89]
	v_mfma_f32_16x16x32_bf16 v[82:85], v[174:177], v[216:219], v[82:85]
	v_mfma_f32_16x16x32_bf16 v[70:73], v[166:169], v[224:227], v[70:73]
	v_mfma_f32_16x16x32_bf16 v[66:69], v[174:177], v[224:227], v[66:69]
	s_barrier
	s_setprio 0
	s_add_i32 s54, s54, s56
	v_lshl_add_u64 v[228:229], s[42:43], 0, v[134:135]
	s_mov_b32 m0, s54
	ds_read_b128 v[178:181], v161 offset:16384
	ds_read_b128 v[182:185], v161 offset:17408
	ds_read_b128 v[204:207], v161 offset:18432
	ds_read_b128 v[208:211], v161 offset:19456
	ds_read_b128 v[212:215], v161 offset:20480
	ds_read_b128 v[216:219], v161 offset:21504
	ds_read_b128 v[220:223], v161 offset:22528
	ds_read_b128 v[224:227], v161 offset:23552
	global_load_lds_dwordx4 v[228:229], off
	s_add_i32 m0, s54, 0x2000
	s_add_u32 s54, s42, 0x40000
	v_lshl_add_u64 v[230:231], s[42:43], 0, v[130:131]
	s_addc_u32 s55, s43, 0
	s_add_i32 s65, s65, s56
	global_load_lds_dwordx4 v[230:231], off
	v_lshl_add_u64 v[240:241], s[54:55], 0, v[134:135]
	s_mov_b32 m0, s65
	v_lshl_add_u64 v[242:243], s[48:49], 0, v[132:133]
	global_load_lds_dwordx4 v[240:241], off
	v_lshl_add_u64 v[240:241], s[54:55], 0, v[130:131]
	s_add_i32 m0, s65, 0x2000
	s_nop 0
	global_load_lds_dwordx4 v[240:241], off
	v_lshl_add_u64 v[240:241], s[48:49], 0, v[136:137]
	s_mov_b32 m0, s57
	s_nop 0
	global_load_lds_dwordx4 v[240:241], off
	s_mov_b32 m0, s58
	s_nop 0
	global_load_lds_dwordx4 v[242:243], off
	s_waitcnt vmcnt(8)
	s_waitcnt lgkmcnt(0)
	s_setprio 1
	s_barrier
	v_mfma_f32_16x16x32_bf16 v[62:65], v[142:145], v[178:181], v[62:65]
	v_mfma_f32_16x16x32_bf16 v[58:61], v[150:153], v[178:181], v[58:61]
	v_mfma_f32_16x16x32_bf16 v[46:49], v[142:145], v[204:207], v[46:49]
	v_mfma_f32_16x16x32_bf16 v[42:45], v[150:153], v[204:207], v[42:45]
	v_mfma_f32_16x16x32_bf16 v[30:33], v[142:145], v[212:215], v[30:33]
	v_mfma_f32_16x16x32_bf16 v[26:29], v[150:153], v[212:215], v[26:29]
	v_mfma_f32_16x16x32_bf16 v[14:17], v[142:145], v[220:223], v[14:17]
	v_mfma_f32_16x16x32_bf16 v[10:13], v[150:153], v[220:223], v[10:13]
	v_mfma_f32_16x16x32_bf16 v[62:65], v[146:149], v[182:185], v[62:65]
	v_mfma_f32_16x16x32_bf16 v[58:61], v[154:157], v[182:185], v[58:61]
	v_mfma_f32_16x16x32_bf16 v[46:49], v[146:149], v[208:211], v[46:49]
	v_mfma_f32_16x16x32_bf16 v[42:45], v[154:157], v[208:211], v[42:45]
	v_mfma_f32_16x16x32_bf16 v[30:33], v[146:149], v[216:219], v[30:33]
	v_mfma_f32_16x16x32_bf16 v[26:29], v[154:157], v[216:219], v[26:29]
	v_mfma_f32_16x16x32_bf16 v[14:17], v[146:149], v[224:227], v[14:17]
	v_mfma_f32_16x16x32_bf16 v[10:13], v[154:157], v[224:227], v[10:13]
	v_mfma_f32_16x16x32_bf16 v[54:57], v[162:165], v[178:181], v[54:57]
	v_mfma_f32_16x16x32_bf16 v[50:53], v[170:173], v[178:181], v[50:53]
	v_mfma_f32_16x16x32_bf16 v[38:41], v[162:165], v[204:207], v[38:41]
	v_mfma_f32_16x16x32_bf16 v[34:37], v[170:173], v[204:207], v[34:37]
	v_mfma_f32_16x16x32_bf16 v[22:25], v[162:165], v[212:215], v[22:25]
	v_mfma_f32_16x16x32_bf16 v[18:21], v[170:173], v[212:215], v[18:21]
	v_mfma_f32_16x16x32_bf16 v[6:9], v[162:165], v[220:223], v[6:9]
	v_mfma_f32_16x16x32_bf16 v[2:5], v[170:173], v[220:223], v[2:5]
	v_mfma_f32_16x16x32_bf16 v[54:57], v[166:169], v[182:185], v[54:57]
	v_mfma_f32_16x16x32_bf16 v[50:53], v[174:177], v[182:185], v[50:53]
	v_mfma_f32_16x16x32_bf16 v[38:41], v[166:169], v[208:211], v[38:41]
	v_mfma_f32_16x16x32_bf16 v[34:37], v[174:177], v[208:211], v[34:37]
	v_mfma_f32_16x16x32_bf16 v[22:25], v[166:169], v[216:219], v[22:25]
	v_mfma_f32_16x16x32_bf16 v[18:21], v[174:177], v[216:219], v[18:21]
	v_mfma_f32_16x16x32_bf16 v[6:9], v[166:169], v[224:227], v[6:9]
	v_mfma_f32_16x16x32_bf16 v[2:5], v[174:177], v[224:227], v[2:5]
	s_barrier
	s_setprio 0
	s_add_i32 s54, 0, 0x18000
	v_add_u32_e32 v0, s54, v160
	s_add_i32 s55, 0, 0x1c000
	ds_read_b128 v[142:145], v0
	ds_read_b128 v[146:149], v0 offset:1024
	ds_read_b128 v[150:153], v0 offset:2048
	ds_read_b128 v[154:157], v0 offset:3072
	v_add_u32_e32 v0, s55, v160
	ds_read_b128 v[162:165], v0
	ds_read_b128 v[166:169], v0 offset:1024
	ds_read_b128 v[170:173], v0 offset:2048
	ds_read_b128 v[174:177], v0 offset:3072
	s_add_u32 s48, s48, 0x40000
	s_addc_u32 s49, s49, 0
	s_mov_b32 m0, s59
	v_lshl_add_u64 v[244:245], s[48:49], 0, v[136:137]
	ds_read_b128 v[178:181], v161 offset:32768
	ds_read_b128 v[182:185], v161 offset:33792
	ds_read_b128 v[204:207], v161 offset:34816
	ds_read_b128 v[208:211], v161 offset:35840
	ds_read_b128 v[212:215], v161 offset:36864
	ds_read_b128 v[216:219], v161 offset:37888
	ds_read_b128 v[220:223], v161 offset:38912
	ds_read_b128 v[224:227], v161 offset:39936
	global_load_lds_dwordx4 v[244:245], off
	v_lshl_add_u64 v[244:245], s[48:49], 0, v[132:133]
	s_mov_b32 m0, s60
	s_nop 0
	global_load_lds_dwordx4 v[244:245], off
	s_waitcnt vmcnt(8)
	s_waitcnt lgkmcnt(0)
	s_setprio 1
	s_barrier
	v_mfma_f32_16x16x32_bf16 v[126:129], v[142:145], v[178:181], v[126:129]
	v_mfma_f32_16x16x32_bf16 v[122:125], v[150:153], v[178:181], v[122:125]
	v_mfma_f32_16x16x32_bf16 v[110:113], v[142:145], v[204:207], v[110:113]
	v_mfma_f32_16x16x32_bf16 v[106:109], v[150:153], v[204:207], v[106:109]
	v_mfma_f32_16x16x32_bf16 v[94:97], v[142:145], v[212:215], v[94:97]
	v_mfma_f32_16x16x32_bf16 v[90:93], v[150:153], v[212:215], v[90:93]
	v_mfma_f32_16x16x32_bf16 v[78:81], v[142:145], v[220:223], v[78:81]
	v_mfma_f32_16x16x32_bf16 v[74:77], v[150:153], v[220:223], v[74:77]
	v_mfma_f32_16x16x32_bf16 v[126:129], v[146:149], v[182:185], v[126:129]
	v_mfma_f32_16x16x32_bf16 v[122:125], v[154:157], v[182:185], v[122:125]
	v_mfma_f32_16x16x32_bf16 v[110:113], v[146:149], v[208:211], v[110:113]
	v_mfma_f32_16x16x32_bf16 v[106:109], v[154:157], v[208:211], v[106:109]
	v_mfma_f32_16x16x32_bf16 v[94:97], v[146:149], v[216:219], v[94:97]
	v_mfma_f32_16x16x32_bf16 v[90:93], v[154:157], v[216:219], v[90:93]
	v_mfma_f32_16x16x32_bf16 v[78:81], v[146:149], v[224:227], v[78:81]
	v_mfma_f32_16x16x32_bf16 v[74:77], v[154:157], v[224:227], v[74:77]
	v_mfma_f32_16x16x32_bf16 v[118:121], v[162:165], v[178:181], v[118:121]
	v_mfma_f32_16x16x32_bf16 v[114:117], v[170:173], v[178:181], v[114:117]
	v_mfma_f32_16x16x32_bf16 v[102:105], v[162:165], v[204:207], v[102:105]
	v_mfma_f32_16x16x32_bf16 v[98:101], v[170:173], v[204:207], v[98:101]
	v_mfma_f32_16x16x32_bf16 v[86:89], v[162:165], v[212:215], v[86:89]
	v_mfma_f32_16x16x32_bf16 v[82:85], v[170:173], v[212:215], v[82:85]
	v_mfma_f32_16x16x32_bf16 v[70:73], v[162:165], v[220:223], v[70:73]
	v_mfma_f32_16x16x32_bf16 v[66:69], v[170:173], v[220:223], v[66:69]
	v_mfma_f32_16x16x32_bf16 v[118:121], v[166:169], v[182:185], v[118:121]
	v_mfma_f32_16x16x32_bf16 v[114:117], v[174:177], v[182:185], v[114:117]
	v_mfma_f32_16x16x32_bf16 v[102:105], v[166:169], v[208:211], v[102:105]
	v_mfma_f32_16x16x32_bf16 v[98:101], v[174:177], v[208:211], v[98:101]
	v_mfma_f32_16x16x32_bf16 v[86:89], v[166:169], v[216:219], v[86:89]
	v_mfma_f32_16x16x32_bf16 v[82:85], v[174:177], v[216:219], v[82:85]
	v_mfma_f32_16x16x32_bf16 v[70:73], v[166:169], v[224:227], v[70:73]
	v_mfma_f32_16x16x32_bf16 v[66:69], v[174:177], v[224:227], v[66:69]
	s_barrier
	s_setprio 0
	s_add_i32 s48, s54, s56
	v_lshl_add_u64 v[228:229], v[228:229], 0, s[16:17]
	s_mov_b32 m0, s48
	ds_read_b128 v[178:181], v161 offset:49152
	ds_read_b128 v[182:185], v161 offset:50176
	ds_read_b128 v[204:207], v161 offset:51200
	ds_read_b128 v[208:211], v161 offset:52224
	ds_read_b128 v[212:215], v161 offset:53248
	ds_read_b128 v[216:219], v161 offset:54272
	ds_read_b128 v[220:223], v161 offset:55296
	ds_read_b128 v[224:227], v161 offset:56320
	global_load_lds_dwordx4 v[228:229], off
	s_add_i32 m0, s48, 0x2000
	s_add_u32 s42, s42, 0x40080
	v_lshl_add_u64 v[228:229], v[230:231], 0, s[16:17]
	s_addc_u32 s43, s43, 0
	s_add_i32 s48, s55, s56
	global_load_lds_dwordx4 v[228:229], off
	v_lshl_add_u64 v[228:229], s[42:43], 0, v[134:135]
	s_mov_b32 m0, s48
	s_nop 0
	global_load_lds_dwordx4 v[228:229], off
	v_lshl_add_u64 v[228:229], s[42:43], 0, v[130:131]
	s_add_i32 m0, s48, 0x2000
	s_nop 0
	global_load_lds_dwordx4 v[228:229], off
	v_lshl_add_u64 v[228:229], v[240:241], 0, s[16:17]
	s_mov_b32 m0, s63
	s_nop 0
	global_load_lds_dwordx4 v[228:229], off
	v_lshl_add_u64 v[228:229], v[242:243], 0, s[16:17]
	s_mov_b32 m0, s64
	s_nop 0
	global_load_lds_dwordx4 v[228:229], off
	s_waitcnt vmcnt(8)
	s_waitcnt lgkmcnt(0)
	s_setprio 1
	s_barrier
	v_mfma_f32_16x16x32_bf16 v[62:65], v[142:145], v[178:181], v[62:65]
	v_mfma_f32_16x16x32_bf16 v[58:61], v[150:153], v[178:181], v[58:61]
	v_mfma_f32_16x16x32_bf16 v[46:49], v[142:145], v[204:207], v[46:49]
	v_mfma_f32_16x16x32_bf16 v[42:45], v[150:153], v[204:207], v[42:45]
	v_mfma_f32_16x16x32_bf16 v[30:33], v[142:145], v[212:215], v[30:33]
	v_mfma_f32_16x16x32_bf16 v[26:29], v[150:153], v[212:215], v[26:29]
	v_mfma_f32_16x16x32_bf16 v[14:17], v[142:145], v[220:223], v[14:17]
	v_mfma_f32_16x16x32_bf16 v[10:13], v[150:153], v[220:223], v[10:13]
	v_mfma_f32_16x16x32_bf16 v[62:65], v[146:149], v[182:185], v[62:65]
	v_mfma_f32_16x16x32_bf16 v[58:61], v[154:157], v[182:185], v[58:61]
	v_mfma_f32_16x16x32_bf16 v[46:49], v[146:149], v[208:211], v[46:49]
	v_mfma_f32_16x16x32_bf16 v[42:45], v[154:157], v[208:211], v[42:45]
	v_mfma_f32_16x16x32_bf16 v[30:33], v[146:149], v[216:219], v[30:33]
	v_mfma_f32_16x16x32_bf16 v[26:29], v[154:157], v[216:219], v[26:29]
	v_mfma_f32_16x16x32_bf16 v[14:17], v[146:149], v[224:227], v[14:17]
	v_mfma_f32_16x16x32_bf16 v[10:13], v[154:157], v[224:227], v[10:13]
	v_mfma_f32_16x16x32_bf16 v[54:57], v[162:165], v[178:181], v[54:57]
	v_mfma_f32_16x16x32_bf16 v[50:53], v[170:173], v[178:181], v[50:53]
	v_mfma_f32_16x16x32_bf16 v[38:41], v[162:165], v[204:207], v[38:41]
	v_mfma_f32_16x16x32_bf16 v[34:37], v[170:173], v[204:207], v[34:37]
	v_mfma_f32_16x16x32_bf16 v[22:25], v[162:165], v[212:215], v[22:25]
	v_mfma_f32_16x16x32_bf16 v[18:21], v[170:173], v[212:215], v[18:21]
	v_mfma_f32_16x16x32_bf16 v[6:9], v[162:165], v[220:223], v[6:9]
	v_mfma_f32_16x16x32_bf16 v[2:5], v[170:173], v[220:223], v[2:5]
	v_mfma_f32_16x16x32_bf16 v[54:57], v[166:169], v[182:185], v[54:57]
	v_mfma_f32_16x16x32_bf16 v[50:53], v[174:177], v[182:185], v[50:53]
	v_mfma_f32_16x16x32_bf16 v[38:41], v[166:169], v[208:211], v[38:41]
	v_mfma_f32_16x16x32_bf16 v[34:37], v[174:177], v[208:211], v[34:37]
	v_mfma_f32_16x16x32_bf16 v[22:25], v[166:169], v[216:219], v[22:25]
	v_mfma_f32_16x16x32_bf16 v[18:21], v[174:177], v[216:219], v[18:21]
	v_mfma_f32_16x16x32_bf16 v[6:9], v[166:169], v[224:227], v[6:9]
	v_mfma_f32_16x16x32_bf16 v[2:5], v[174:177], v[224:227], v[2:5]
	s_barrier
	s_setprio 0
	s_add_i32 s53, s53, 2
	s_add_u32 s40, s40, 0x100
	s_addc_u32 s41, s41, 0
	s_add_u32 s51, s51, 0x100
	s_addc_u32 s52, s52, 0
	s_cmp_gt_u32 s53, 13
	s_cbranch_scc0 .LBB0_1186
	s_and_b64 vcc, exec, s[18:19]
	s_cbranch_vccz .LBB0_1189
	s_barrier

.LBB0_1226:
	s_andn2_b64 vcc, exec, s[38:39]
	s_mov_b64 s[38:39], -1
	s_cbranch_vccnz .LBB0_1182
	s_mov_b32 s54, 0
	s_andn2_b64 vcc, exec, s[0:1]
	s_cbranch_vccnz .LBB0_1181
	s_mov_b32 s54, 1
	s_branch .LBB0_1181
